# v18 + GEMM M-phase head: s_setprio 1 moved in front of the hand-off barrier and the redundant post-barrier lgkmcnt wait dropped (two fewer instructions between barrier release and the first MFMA)
# speedup vs baseline: 1.0022x; 1.0022x over previous
; #define PG8_STAGE(bufoff, gbase, voff) do { _Pragma("unroll") for (int _i = 0; _i < 2; ++_i) \
;         dma16((const char*)(gbase), (voff)[_i], ldsb + (bufoff) + ldsw + _i * 8192); } while (0)
; #define PG8_LDA(dst, b, h) do { const int a1_ = opqv(aoff0) ^ 64; _Pragma("unroll") for (int m = 0; m < 4; ++m) { dst[m][0] = *(const LAS bf16x8*)(lds + PG8_SA(b, h) + aoff0 + m * 2048); dst[m][1] = *(const LAS bf16x8*)(lds + PG8_SA(b, h) + a1_ + m * 2048); } } while (0)
; #define PG8_LDB(dst, b, h) do { const int b1_ = opqv(boff0) ^ 64; _Pragma("unroll") for (int n = 0; n < 2; ++n) { dst[n][0] = *(const LAS bf16x8*)(lds + PG8_SB(b, h) + boff0 + n * 2048); dst[n][1] = *(const LAS bf16x8*)(lds + PG8_SB(b, h) + b1_ + n * 2048); } } while (0)
; #define PG8_MMA(ai, bj, At, Bt) do { __builtin_amdgcn_s_setprio(1); _Pragma("unroll") for (int m = 0; m < 4; ++m) _Pragma("unroll") for (int n = 0; n < 2; ++n) _Pragma("unroll") for (int k = 0; k < 2; ++k) \
;         acc[ai][bj][m][n] = __builtin_amdgcn_mfma_f32_16x16x32_bf16(Bt[n][k], At[m][k], acc[ai][bj][m][n], 0, 0, 0); __builtin_amdgcn_s_setprio(0); } while (0)
; #define PG8_WAIT_V(n) asm volatile("s_waitcnt vmcnt(" #n ")" ::: "memory")
; template <class Epi>
; __device__ __forceinline__ void gemm_phase(LAS unsigned char* lds, const Gemm g, const StaticOrder& S, const Epi& E, int wave_) {
;     ...
;             PG8_STAGE(PG8_SA(1, 1), a1 + hstepA, voffA); PG8_LDB(B0, 0, 0); PG8_LDB(B1, 0, 1); PG8_SCHED; PG8_LDA(At, 0, 0);
;             PG8_WAIT_V(8); PG8_WAIT_L(0); PG8_BAR; PG8_MMA(0, 0, At, B0); PG8_MMA(0, 1, At, B1); PG8_BAR; PG8_SCHED;
;             PG8_STAGE(PG8_SB(0, 0), b2, voffB); PG8_STAGE(PG8_SB(0, 1), b2 + hstepB, voffB); PG8_STAGE(PG8_SA(0, 0), a2, voffA); PG8_LDA(At, 0, 1);
;             PG8_WAIT_V(8); PG8_WAIT_L(0); PG8_BAR; PG8_MMA(1, 0, At, B0); PG8_MMA(1, 1, At, B1); PG8_BAR; PG8_SCHED;
;             PG8_STAGE(PG8_SA(0, 1), a2 + hstepA, voffA); PG8_LDB(B0, 1, 0); PG8_LDB(B1, 1, 1); PG8_SCHED; PG8_LDA(At, 1, 0);
;             PG8_WAIT_V(8); PG8_WAIT_L(0); PG8_BAR; PG8_MMA(0, 0, At, B0); PG8_MMA(0, 1, At, B1); PG8_BAR; PG8_SCHED;
;             PG8_STAGE(PG8_SB(1, 0), b3, voffB); PG8_STAGE(PG8_SB(1, 1), b3 + hstepB, voffB); PG8_STAGE(PG8_SA(1, 0), a3, voffA); PG8_LDA(At, 1, 1);
;             PG8_WAIT_V(8); PG8_WAIT_L(0); PG8_BAR; PG8_MMA(1, 0, At, B0); PG8_MMA(1, 1, At, B1); PG8_BAR; PG8_SCHED;
.LBB0_190:
	s_ashr_i32 s7, s6, 31
	s_lshl_b64 s[8:9], s[6:7], 20
	s_add_u32 s8, s16, s8
	s_addc_u32 s9, s17, s9
	s_and_b64 s[10:11], s[40:41], exec
	s_cselect_b32 s7, s9, s19
	s_cselect_b32 s45, s8, s18
	s_ashr_i32 s5, s4, 31
	s_lshl_b64 s[10:11], s[4:5], 20
	s_add_u32 s10, s21, s10
	s_addc_u32 s11, s30, s11
	s_and_b64 s[24:25], s[40:41], exec
	s_cselect_b32 s5, s11, s13
	s_cselect_b32 s46, s10, s12
	s_add_u32 s47, s12, 0x100
	s_addc_u32 s48, s13, 0
	s_add_u32 s12, s18, 0x80080
	s_addc_u32 s13, s19, 0
	s_mov_b32 s49, -2
	s_add_u32 s18, s12, 0xfff80080
	s_addc_u32 s19, s13, -1
	s_cmp_eq_u32 s49, 28
	s_cselect_b32 s26, s45, s18
	v_mov_b32_e32 v128, v139
	s_cselect_b32 s27, s7, s19
	s_cselect_b32 s24, s46, s47
	s_cselect_b32 s25, s5, s48
	s_add_u32 s18, s26, 0x80
	v_xad_u32 v128, v128, 64, s23
	v_add_u32_e32 v141, s23, v139
	s_addc_u32 s19, s27, 0
	ds_read_b128 v[130:133], v141
	ds_read_b128 v[142:145], v141 offset:2048
	ds_read_b128 v[146:149], v128
	ds_read_b128 v[150:153], v128 offset:2048
	v_mov_b32_e32 v128, v139
	s_add_i32 s52, 0, 0x14000
	v_add_u32_e32 v141, s52, v139
	v_xad_u32 v128, v128, 64, s52
	ds_read_b128 v[154:157], v141
	ds_read_b128 v[158:161], v141 offset:2048
	ds_read_b128 v[162:165], v128
	ds_read_b128 v[166:169], v128 offset:2048
	v_mov_b32_e32 v128, v138
	v_add_u32_e32 v141, 0, v138
	v_xad_u32 v128, v128, 64, 0
	ds_read_b128 v[170:173], v141
	ds_read_b128 v[174:177], v141 offset:2048
	ds_read_b128 v[178:181], v128
	ds_read_b128 v[192:195], v128 offset:2048
	ds_read_b128 v[196:199], v141 offset:4096
	ds_read_b128 v[200:203], v141 offset:6144
	ds_read_b128 v[204:207], v128 offset:4096
	ds_read_b128 v[208:211], v128 offset:6144
	s_mov_b32 m0, s14
	s_nop 0
	global_load_lds_dwordx4 v129, s[12:13]
	s_mov_b32 m0, s15
	s_nop 0
	global_load_lds_dwordx4 v135, s[12:13]
	s_waitcnt vmcnt(8)
	s_waitcnt lgkmcnt(0)
	s_setprio 1
	s_barrier
	v_mfma_f32_16x16x32_bf16 v[124:127], v[130:133], v[170:173], 0
	v_mfma_f32_16x16x32_bf16 v[120:123], v[142:145], v[170:173], 0
	v_mfma_f32_16x16x32_bf16 v[112:115], v[130:133], v[174:177], 0
	v_mfma_f32_16x16x32_bf16 v[104:107], v[142:145], v[174:177], 0
	v_mfma_f32_16x16x32_bf16 v[96:99], v[130:133], v[196:199], 0
	v_mfma_f32_16x16x32_bf16 v[88:91], v[142:145], v[196:199], 0
	v_mfma_f32_16x16x32_bf16 v[80:83], v[130:133], v[200:203], 0
	v_mfma_f32_16x16x32_bf16 v[72:75], v[142:145], v[200:203], 0
	v_mfma_f32_16x16x32_bf16 v[124:127], v[146:149], v[178:181], v[124:127]
	v_mfma_f32_16x16x32_bf16 v[120:123], v[150:153], v[178:181], v[120:123]
	v_mfma_f32_16x16x32_bf16 v[112:115], v[146:149], v[192:195], v[112:115]
	v_mfma_f32_16x16x32_bf16 v[104:107], v[150:153], v[192:195], v[104:107]
	v_mfma_f32_16x16x32_bf16 v[96:99], v[146:149], v[204:207], v[96:99]
	v_mfma_f32_16x16x32_bf16 v[88:91], v[150:153], v[204:207], v[88:91]
	v_mfma_f32_16x16x32_bf16 v[80:83], v[146:149], v[208:211], v[80:83]
	v_mfma_f32_16x16x32_bf16 v[72:75], v[150:153], v[208:211], v[72:75]
	s_setprio 0
	s_setprio 1
	v_mfma_f32_16x16x32_bf16 v[116:119], v[154:157], v[170:173], 0
	v_mfma_f32_16x16x32_bf16 v[108:111], v[158:161], v[170:173], 0
	v_mfma_f32_16x16x32_bf16 v[100:103], v[154:157], v[174:177], 0
	v_mfma_f32_16x16x32_bf16 v[92:95], v[158:161], v[174:177], 0
	v_mfma_f32_16x16x32_bf16 v[84:87], v[154:157], v[196:199], 0
	v_mfma_f32_16x16x32_bf16 v[76:79], v[158:161], v[196:199], 0
	v_mfma_f32_16x16x32_bf16 v[68:71], v[154:157], v[200:203], 0
	v_mfma_f32_16x16x32_bf16 v[64:67], v[158:161], v[200:203], 0
	v_mfma_f32_16x16x32_bf16 v[116:119], v[162:165], v[178:181], v[116:119]
	v_mfma_f32_16x16x32_bf16 v[108:111], v[166:169], v[178:181], v[108:111]
	v_mfma_f32_16x16x32_bf16 v[100:103], v[162:165], v[192:195], v[100:103]
	v_mfma_f32_16x16x32_bf16 v[92:95], v[166:169], v[192:195], v[92:95]
	v_mfma_f32_16x16x32_bf16 v[84:87], v[162:165], v[204:207], v[84:87]
	v_mfma_f32_16x16x32_bf16 v[76:79], v[166:169], v[204:207], v[76:79]
	v_mfma_f32_16x16x32_bf16 v[68:71], v[162:165], v[208:211], v[68:71]
	v_mfma_f32_16x16x32_bf16 v[64:67], v[166:169], v[208:211], v[64:67]
	s_setprio 0
	s_barrier
	s_add_u32 s54, s24, 0x80000
	s_addc_u32 s55, s25, 0
	v_mov_b32_e32 v128, v138
	s_nop 0
	s_nop 0
	s_nop 0
	v_xad_u32 v128, v128, 64, 0
	ds_read_b128 v[170:173], v141 offset:16384
	ds_read_b128 v[174:177], v141 offset:18432
	ds_read_b128 v[178:181], v128 offset:16384
	ds_read_b128 v[192:195], v128 offset:18432
	ds_read_b128 v[196:199], v141 offset:20480
	ds_read_b128 v[200:203], v141 offset:22528
	ds_read_b128 v[204:207], v128 offset:20480
	ds_read_b128 v[208:211], v128 offset:22528
	s_mov_b32 m0, s80
	s_nop 0
	global_load_lds_dwordx4 v134, s[24:25]
	s_mov_b32 m0, s81
	s_nop 0
	global_load_lds_dwordx4 v136, s[24:25]
	s_mov_b32 m0, s29
	s_nop 0
	global_load_lds_dwordx4 v134, s[54:55]
	s_mov_b32 m0, s88
	s_nop 0
	global_load_lds_dwordx4 v136, s[54:55]
	s_mov_b32 m0, s76
	s_nop 0
	global_load_lds_dwordx4 v129, s[26:27]
	s_mov_b32 m0, s89
	s_nop 0
	global_load_lds_dwordx4 v135, s[26:27]
	s_waitcnt vmcnt(8)
	s_waitcnt lgkmcnt(0)
	s_setprio 1
	s_barrier
; #define PG8_STAGE(bufoff, gbase, voff) do { _Pragma("unroll") for (int _i = 0; _i < 2; ++_i) \
;         dma16((const char*)(gbase), (voff)[_i], ldsb + (bufoff) + ldsw + _i * 8192); } while (0)
; #define PG8_LDA(dst, b, h) do { const int a1_ = opqv(aoff0) ^ 64; _Pragma("unroll") for (int m = 0; m < 4; ++m) { dst[m][0] = *(const LAS bf16x8*)(lds + PG8_SA(b, h) + aoff0 + m * 2048); dst[m][1] = *(const LAS bf16x8*)(lds + PG8_SA(b, h) + a1_ + m * 2048); } } while (0)
; #define PG8_LDB(dst, b, h) do { const int b1_ = opqv(boff0) ^ 64; _Pragma("unroll") for (int n = 0; n < 2; ++n) { dst[n][0] = *(const LAS bf16x8*)(lds + PG8_SB(b, h) + boff0 + n * 2048); dst[n][1] = *(const LAS bf16x8*)(lds + PG8_SB(b, h) + b1_ + n * 2048); } } while (0)
; #define PG8_MMA(ai, bj, At, Bt) do { __builtin_amdgcn_s_setprio(1); _Pragma("unroll") for (int m = 0; m < 4; ++m) _Pragma("unroll") for (int n = 0; n < 2; ++n) _Pragma("unroll") for (int k = 0; k < 2; ++k) \
;         acc[ai][bj][m][n] = __builtin_amdgcn_mfma_f32_16x16x32_bf16(Bt[n][k], At[m][k], acc[ai][bj][m][n], 0, 0, 0); __builtin_amdgcn_s_setprio(0); } while (0)
; #define PG8_WAIT_V(n) asm volatile("s_waitcnt vmcnt(" #n ")" ::: "memory")
; template <class Epi>
; __device__ __forceinline__ void gemm_phase(LAS unsigned char* lds, const Gemm g, const StaticOrder& S, const Epi& E, int wave_) {
;     ...
;             PG8_STAGE(PG8_SA(1, 1), a1 + hstepA, voffA); PG8_LDB(B0, 0, 0); PG8_LDB(B1, 0, 1); PG8_SCHED; PG8_LDA(At, 0, 0);
;             PG8_WAIT_V(8); PG8_WAIT_L(0); PG8_BAR; PG8_MMA(0, 0, At, B0); PG8_MMA(0, 1, At, B1); PG8_BAR; PG8_SCHED;
;             PG8_STAGE(PG8_SB(0, 0), b2, voffB); PG8_STAGE(PG8_SB(0, 1), b2 + hstepB, voffB); PG8_STAGE(PG8_SA(0, 0), a2, voffA); PG8_LDA(At, 0, 1);
;             PG8_WAIT_V(8); PG8_WAIT_L(0); PG8_BAR; PG8_MMA(1, 0, At, B0); PG8_MMA(1, 1, At, B1); PG8_BAR; PG8_SCHED;
;             PG8_STAGE(PG8_SA(0, 1), a2 + hstepA, voffA); PG8_LDB(B0, 1, 0); PG8_LDB(B1, 1, 1); PG8_SCHED; PG8_LDA(At, 1, 0);
;             PG8_WAIT_V(8); PG8_WAIT_L(0); PG8_BAR; PG8_MMA(0, 0, At, B0); PG8_MMA(0, 1, At, B1); PG8_BAR; PG8_SCHED;
;             PG8_STAGE(PG8_SB(1, 0), b3, voffB); PG8_STAGE(PG8_SB(1, 1), b3 + hstepB, voffB); PG8_STAGE(PG8_SA(1, 0), a3, voffA); PG8_LDA(At, 1, 1);
;             PG8_WAIT_V(8); PG8_WAIT_L(0); PG8_BAR; PG8_MMA(1, 0, At, B0); PG8_MMA(1, 1, At, B1); PG8_BAR; PG8_SCHED;
	v_mfma_f32_16x16x32_bf16 v[60:63], v[130:133], v[170:173], 0
	v_mfma_f32_16x16x32_bf16 v[56:59], v[142:145], v[170:173], 0
	v_mfma_f32_16x16x32_bf16 v[48:51], v[130:133], v[174:177], 0
	v_mfma_f32_16x16x32_bf16 v[40:43], v[142:145], v[174:177], 0
	v_mfma_f32_16x16x32_bf16 v[32:35], v[130:133], v[196:199], 0
	v_mfma_f32_16x16x32_bf16 v[24:27], v[142:145], v[196:199], 0
	v_mfma_f32_16x16x32_bf16 v[16:19], v[130:133], v[200:203], 0
	v_mfma_f32_16x16x32_bf16 v[8:11], v[142:145], v[200:203], 0
	v_mfma_f32_16x16x32_bf16 v[60:63], v[146:149], v[178:181], v[60:63]
	v_mfma_f32_16x16x32_bf16 v[56:59], v[150:153], v[178:181], v[56:59]
	v_mfma_f32_16x16x32_bf16 v[48:51], v[146:149], v[192:195], v[48:51]
	v_mfma_f32_16x16x32_bf16 v[40:43], v[150:153], v[192:195], v[40:43]
	v_mfma_f32_16x16x32_bf16 v[32:35], v[146:149], v[204:207], v[32:35]
	v_mfma_f32_16x16x32_bf16 v[24:27], v[150:153], v[204:207], v[24:27]
	v_mfma_f32_16x16x32_bf16 v[16:19], v[146:149], v[208:211], v[16:19]
	v_mfma_f32_16x16x32_bf16 v[8:11], v[150:153], v[208:211], v[8:11]
	s_setprio 0
	s_setprio 1
	v_mfma_f32_16x16x32_bf16 v[52:55], v[154:157], v[170:173], 0
	v_mfma_f32_16x16x32_bf16 v[44:47], v[158:161], v[170:173], 0
	v_mfma_f32_16x16x32_bf16 v[36:39], v[154:157], v[174:177], 0
	v_mfma_f32_16x16x32_bf16 v[28:31], v[158:161], v[174:177], 0
	v_mfma_f32_16x16x32_bf16 v[20:23], v[154:157], v[196:199], 0
	v_mfma_f32_16x16x32_bf16 v[12:15], v[158:161], v[196:199], 0
	v_mfma_f32_16x16x32_bf16 v[4:7], v[154:157], v[200:203], 0
	v_mfma_f32_16x16x32_bf16 v[0:3], v[158:161], v[200:203], 0
	v_mfma_f32_16x16x32_bf16 v[52:55], v[162:165], v[178:181], v[52:55]
	v_mfma_f32_16x16x32_bf16 v[44:47], v[166:169], v[178:181], v[44:47]
	v_mfma_f32_16x16x32_bf16 v[36:39], v[162:165], v[192:195], v[36:39]
	v_mfma_f32_16x16x32_bf16 v[28:31], v[166:169], v[192:195], v[28:31]
	v_mfma_f32_16x16x32_bf16 v[20:23], v[162:165], v[204:207], v[20:23]
	v_mfma_f32_16x16x32_bf16 v[12:15], v[166:169], v[204:207], v[12:15]
	v_mfma_f32_16x16x32_bf16 v[4:7], v[162:165], v[208:211], v[4:7]
	v_mfma_f32_16x16x32_bf16 v[0:3], v[166:169], v[208:211], v[0:3]
	s_setprio 0
	s_barrier
	s_add_u32 s26, s26, 0x80000
	s_addc_u32 s27, s27, 0
	s_mov_b32 m0, s1
	s_nop 0
	global_load_lds_dwordx4 v129, s[26:27]
	v_mov_b32_e32 v128, v139
	s_mov_b32 m0, s69
	s_nop 0
	global_load_lds_dwordx4 v135, s[26:27]
	v_add_u32_e32 v142, s34, v139
	v_xad_u32 v128, v128, 64, s34
	ds_read_b128 v[130:133], v142
	ds_read_b128 v[142:145], v142 offset:2048
	ds_read_b128 v[146:149], v128
	ds_read_b128 v[150:153], v128 offset:2048
	v_mov_b32_e32 v128, v139
	s_add_i32 s26, 0, 0x1c000
	v_add_u32_e32 v158, s26, v139
	v_xad_u32 v128, v128, 64, s26
	ds_read_b128 v[154:157], v158
	ds_read_b128 v[158:161], v158 offset:2048
	ds_read_b128 v[162:165], v128
	ds_read_b128 v[166:169], v128 offset:2048
	v_mov_b32_e32 v128, v138
	s_nop 0
	v_xad_u32 v128, v128, 64, 0
	ds_read_b128 v[170:173], v141 offset:32768
	ds_read_b128 v[174:177], v141 offset:34816
	ds_read_b128 v[178:181], v128 offset:32768
	ds_read_b128 v[192:195], v128 offset:34816
	ds_read_b128 v[196:199], v141 offset:36864
	ds_read_b128 v[200:203], v141 offset:38912
	ds_read_b128 v[204:207], v128 offset:36864
	ds_read_b128 v[208:211], v128 offset:38912
	s_waitcnt vmcnt(8)
	s_waitcnt lgkmcnt(0)
	s_setprio 1
	s_barrier
	v_mfma_f32_16x16x32_bf16 v[124:127], v[130:133], v[170:173], v[124:127]
	v_mfma_f32_16x16x32_bf16 v[120:123], v[142:145], v[170:173], v[120:123]
	v_mfma_f32_16x16x32_bf16 v[112:115], v[130:133], v[174:177], v[112:115]
	v_mfma_f32_16x16x32_bf16 v[104:107], v[142:145], v[174:177], v[104:107]
	v_mfma_f32_16x16x32_bf16 v[96:99], v[130:133], v[196:199], v[96:99]
	v_mfma_f32_16x16x32_bf16 v[88:91], v[142:145], v[196:199], v[88:91]
	v_mfma_f32_16x16x32_bf16 v[80:83], v[130:133], v[200:203], v[80:83]
	v_mfma_f32_16x16x32_bf16 v[72:75], v[142:145], v[200:203], v[72:75]
	v_mfma_f32_16x16x32_bf16 v[124:127], v[146:149], v[178:181], v[124:127]
	v_mfma_f32_16x16x32_bf16 v[120:123], v[150:153], v[178:181], v[120:123]
	v_mfma_f32_16x16x32_bf16 v[112:115], v[146:149], v[192:195], v[112:115]
	v_mfma_f32_16x16x32_bf16 v[104:107], v[150:153], v[192:195], v[104:107]
	v_mfma_f32_16x16x32_bf16 v[96:99], v[146:149], v[204:207], v[96:99]
	v_mfma_f32_16x16x32_bf16 v[88:91], v[150:153], v[204:207], v[88:91]
	v_mfma_f32_16x16x32_bf16 v[80:83], v[146:149], v[208:211], v[80:83]
	v_mfma_f32_16x16x32_bf16 v[72:75], v[150:153], v[208:211], v[72:75]
	s_setprio 0
	s_setprio 1
	v_mfma_f32_16x16x32_bf16 v[116:119], v[154:157], v[170:173], v[116:119]
	s_add_u32 s26, s24, 0x80
	s_addc_u32 s27, s25, 0
	v_mfma_f32_16x16x32_bf16 v[108:111], v[158:161], v[170:173], v[108:111]
	v_mfma_f32_16x16x32_bf16 v[100:103], v[154:157], v[174:177], v[100:103]
	v_mfma_f32_16x16x32_bf16 v[92:95], v[158:161], v[174:177], v[92:95]
	v_mfma_f32_16x16x32_bf16 v[84:87], v[154:157], v[196:199], v[84:87]
	v_mfma_f32_16x16x32_bf16 v[76:79], v[158:161], v[196:199], v[76:79]
	v_mfma_f32_16x16x32_bf16 v[68:71], v[154:157], v[200:203], v[68:71]
	v_mfma_f32_16x16x32_bf16 v[64:67], v[158:161], v[200:203], v[64:67]
	v_mfma_f32_16x16x32_bf16 v[116:119], v[162:165], v[178:181], v[116:119]
	v_mfma_f32_16x16x32_bf16 v[108:111], v[166:169], v[178:181], v[108:111]
	v_mfma_f32_16x16x32_bf16 v[100:103], v[162:165], v[192:195], v[100:103]
	v_mfma_f32_16x16x32_bf16 v[92:95], v[166:169], v[192:195], v[92:95]
	v_mfma_f32_16x16x32_bf16 v[84:87], v[162:165], v[204:207], v[84:87]
	v_mfma_f32_16x16x32_bf16 v[76:79], v[166:169], v[204:207], v[76:79]
	v_mfma_f32_16x16x32_bf16 v[68:71], v[162:165], v[208:211], v[68:71]
	v_mfma_f32_16x16x32_bf16 v[64:67], v[166:169], v[208:211], v[64:67]
	s_setprio 0
	s_barrier
; #define PG8_STAGE(bufoff, gbase, voff) do { _Pragma("unroll") for (int _i = 0; _i < 2; ++_i) \
;         dma16((const char*)(gbase), (voff)[_i], ldsb + (bufoff) + ldsw + _i * 8192); } while (0)
; #define PG8_LDA(dst, b, h) do { const int a1_ = opqv(aoff0) ^ 64; _Pragma("unroll") for (int m = 0; m < 4; ++m) { dst[m][0] = *(const LAS bf16x8*)(lds + PG8_SA(b, h) + aoff0 + m * 2048); dst[m][1] = *(const LAS bf16x8*)(lds + PG8_SA(b, h) + a1_ + m * 2048); } } while (0)
; #define PG8_WAIT_V(n) asm volatile("s_waitcnt vmcnt(" #n ")" ::: "memory")
; template <class Epi>
; __device__ __forceinline__ void gemm_phase(LAS unsigned char* lds, const Gemm g, const StaticOrder& S, const Epi& E, int wave_) {
;     ...
;     for (;;) {
;         const bool has_next = S.next(ui + 1, nxt);
;         const char* nA = has_next ? (const char*)g.A + (size_t)nxt.pm * tstepA : cA; const char* nB = has_next ? (const char*)g.Bt + (size_t)nxt.pn * tstepB : cB;
; #pragma unroll 1
;         for (int t = 0; t < nt; t += 2) {
;             const bool last = (t == nt - 2);
;             const char* a1 = cA + (size_t)(t + 1) * kstep;
;             const char* a2 = last ? nA : cA + (size_t)(t + 2) * kstep; const char* b2 = last ? nB : cB + (size_t)(t + 2) * kstep;
;             const char* a3 = a2 + kstep; const char* b3 = b2 + kstep;
;             PG8_STAGE(PG8_SA(1, 1), a1 + hstepA, voffA); PG8_LDB(B0, 0, 0); PG8_LDB(B1, 0, 1); PG8_SCHED; PG8_LDA(At, 0, 0);
;             PG8_WAIT_V(8); PG8_WAIT_L(0); PG8_BAR; PG8_MMA(0, 0, At, B0); PG8_MMA(0, 1, At, B1); PG8_BAR; PG8_SCHED;
;             PG8_STAGE(PG8_SB(0, 0), b2, voffB); PG8_STAGE(PG8_SB(0, 1), b2 + hstepB, voffB); PG8_STAGE(PG8_SA(0, 0), a2, voffA); PG8_LDA(At, 0, 1);
;             PG8_WAIT_V(8); PG8_WAIT_L(0); PG8_BAR; PG8_MMA(1, 0, At, B0); PG8_MMA(1, 1, At, B1); PG8_BAR; PG8_SCHED;
;             PG8_STAGE(PG8_SA(0, 1), a2 + hstepA, voffA); PG8_LDB(B0, 1, 0); PG8_LDB(B1, 1, 1); PG8_SCHED; PG8_LDA(At, 1, 0);
;             PG8_WAIT_V(8); PG8_WAIT_L(0); PG8_BAR; PG8_MMA(0, 0, At, B0); PG8_MMA(0, 1, At, B1); PG8_BAR; PG8_SCHED;
;             PG8_STAGE(PG8_SB(1, 0), b3, voffB); PG8_STAGE(PG8_SB(1, 1), b3 + hstepB, voffB); PG8_STAGE(PG8_SA(1, 0), a3, voffA); PG8_LDA(At, 1, 1);
;             PG8_WAIT_V(8); PG8_WAIT_L(0); PG8_BAR; PG8_MMA(1, 0, At, B0); PG8_MMA(1, 1, At, B1); PG8_BAR; PG8_SCHED;
;         }
	s_add_u32 s24, s24, 0x80080
	s_addc_u32 s25, s25, 0
	v_mov_b32_e32 v128, v138
	s_nop 0
	s_nop 0
	v_xad_u32 v128, v128, 64, 0
	ds_read_b128 v[170:173], v141 offset:49152
	ds_read_b128 v[174:177], v141 offset:51200
	ds_read_b128 v[178:181], v128 offset:49152
	ds_read_b128 v[192:195], v128 offset:51200
	ds_read_b128 v[196:199], v141 offset:53248
	ds_read_b128 v[200:203], v141 offset:55296
	ds_read_b128 v[204:207], v128 offset:53248
	ds_read_b128 v[208:211], v128 offset:55296
	s_mov_b32 m0, s35
	s_nop 0
	global_load_lds_dwordx4 v134, s[26:27]
	s_mov_b32 m0, s33
	s_nop 0
	global_load_lds_dwordx4 v136, s[26:27]
	s_mov_b32 m0, s77
	s_nop 0
	global_load_lds_dwordx4 v134, s[24:25]
	s_mov_b32 m0, s3
	s_nop 0
	global_load_lds_dwordx4 v136, s[24:25]
	s_mov_b32 m0, s22
	s_nop 0
	global_load_lds_dwordx4 v129, s[18:19]
	s_mov_b32 m0, s2
	s_nop 0
	global_load_lds_dwordx4 v135, s[18:19]
	s_waitcnt vmcnt(8)
	s_waitcnt lgkmcnt(0)
	s_setprio 1
	s_barrier
	v_mfma_f32_16x16x32_bf16 v[60:63], v[130:133], v[170:173], v[60:63]
	v_mfma_f32_16x16x32_bf16 v[56:59], v[142:145], v[170:173], v[56:59]
	v_mfma_f32_16x16x32_bf16 v[48:51], v[130:133], v[174:177], v[48:51]
	v_mfma_f32_16x16x32_bf16 v[40:43], v[142:145], v[174:177], v[40:43]
	v_mfma_f32_16x16x32_bf16 v[32:35], v[130:133], v[196:199], v[32:35]
	v_mfma_f32_16x16x32_bf16 v[24:27], v[142:145], v[196:199], v[24:27]
	v_mfma_f32_16x16x32_bf16 v[16:19], v[130:133], v[200:203], v[16:19]
	v_mfma_f32_16x16x32_bf16 v[8:11], v[142:145], v[200:203], v[8:11]
	v_mfma_f32_16x16x32_bf16 v[60:63], v[146:149], v[178:181], v[60:63]
	v_mfma_f32_16x16x32_bf16 v[56:59], v[150:153], v[178:181], v[56:59]
	v_mfma_f32_16x16x32_bf16 v[48:51], v[146:149], v[192:195], v[48:51]
	v_mfma_f32_16x16x32_bf16 v[40:43], v[150:153], v[192:195], v[40:43]
	v_mfma_f32_16x16x32_bf16 v[32:35], v[146:149], v[204:207], v[32:35]
	v_mfma_f32_16x16x32_bf16 v[24:27], v[150:153], v[204:207], v[24:27]
	v_mfma_f32_16x16x32_bf16 v[16:19], v[146:149], v[208:211], v[16:19]
	v_mfma_f32_16x16x32_bf16 v[8:11], v[150:153], v[208:211], v[8:11]
	s_setprio 0
	s_setprio 1
	v_mfma_f32_16x16x32_bf16 v[52:55], v[154:157], v[170:173], v[52:55]
	v_mfma_f32_16x16x32_bf16 v[44:47], v[158:161], v[170:173], v[44:47]
	v_mfma_f32_16x16x32_bf16 v[36:39], v[154:157], v[174:177], v[36:39]
	v_mfma_f32_16x16x32_bf16 v[28:31], v[158:161], v[174:177], v[28:31]
	v_mfma_f32_16x16x32_bf16 v[20:23], v[154:157], v[196:199], v[20:23]
	v_mfma_f32_16x16x32_bf16 v[12:15], v[158:161], v[196:199], v[12:15]
	v_mfma_f32_16x16x32_bf16 v[4:7], v[154:157], v[200:203], v[4:7]
	v_mfma_f32_16x16x32_bf16 v[0:3], v[158:161], v[200:203], v[0:3]
	v_mfma_f32_16x16x32_bf16 v[52:55], v[162:165], v[178:181], v[52:55]
	v_mfma_f32_16x16x32_bf16 v[44:47], v[166:169], v[178:181], v[44:47]
	v_mfma_f32_16x16x32_bf16 v[36:39], v[162:165], v[192:195], v[36:39]
	v_mfma_f32_16x16x32_bf16 v[28:31], v[166:169], v[192:195], v[28:31]
	v_mfma_f32_16x16x32_bf16 v[20:23], v[162:165], v[204:207], v[20:23]
	v_mfma_f32_16x16x32_bf16 v[12:15], v[166:169], v[204:207], v[12:15]
	v_mfma_f32_16x16x32_bf16 v[4:7], v[162:165], v[208:211], v[4:7]
	v_mfma_f32_16x16x32_bf16 v[0:3], v[166:169], v[208:211], v[0:3]
	s_setprio 0
	s_barrier
	s_add_i32 s49, s49, 2
	s_add_u32 s47, s47, 0x100
	s_addc_u32 s48, s48, 0
	s_add_u32 s12, s12, 0x100
	s_addc_u32 s13, s13, 0
	s_cmp_gt_u32 s49, 29
	s_cbranch_scc0 .LBB0_191
	s_branch .Lpeel_exit_8
.LBB0_191:
	s_add_u32 s18, s12, 0xfff80080
	s_addc_u32 s19, s13, -1
	s_cmp_eq_u32 s49, 28
	s_cselect_b32 s26, s45, s18
	v_mov_b32_e32 v128, v139
	s_cselect_b32 s27, s7, s19
	s_cselect_b32 s24, s46, s47
	s_cselect_b32 s25, s5, s48
	s_add_u32 s18, s26, 0x80
	v_xad_u32 v128, v128, 64, s23
	v_add_u32_e32 v141, s23, v139
	s_addc_u32 s19, s27, 0
	ds_read_b128 v[130:133], v141
	ds_read_b128 v[142:145], v141 offset:2048
	ds_read_b128 v[146:149], v128
	ds_read_b128 v[150:153], v128 offset:2048
	v_mov_b32_e32 v128, v139
	s_add_i32 s52, 0, 0x14000
	v_add_u32_e32 v141, s52, v139
	v_xad_u32 v128, v128, 64, s52
	ds_read_b128 v[154:157], v141
	ds_read_b128 v[158:161], v141 offset:2048
	ds_read_b128 v[162:165], v128
	ds_read_b128 v[166:169], v128 offset:2048
	v_mov_b32_e32 v128, v138
	v_add_u32_e32 v141, 0, v138
	v_xad_u32 v128, v128, 64, 0
	ds_read_b128 v[170:173], v141
	ds_read_b128 v[174:177], v141 offset:2048
	ds_read_b128 v[178:181], v128
	ds_read_b128 v[192:195], v128 offset:2048
	ds_read_b128 v[196:199], v141 offset:4096
	ds_read_b128 v[200:203], v141 offset:6144
	ds_read_b128 v[204:207], v128 offset:4096
	ds_read_b128 v[208:211], v128 offset:6144
	s_mov_b32 m0, s14
	s_nop 0
	global_load_lds_dwordx4 v129, s[12:13]
	s_mov_b32 m0, s15
	s_nop 0
	global_load_lds_dwordx4 v135, s[12:13]
	s_waitcnt vmcnt(8)
	s_waitcnt lgkmcnt(0)
	s_setprio 1
	s_barrier
; #define PG8_STAGE(bufoff, gbase, voff) do { _Pragma("unroll") for (int _i = 0; _i < 2; ++_i) \
;         dma16((const char*)(gbase), (voff)[_i], ldsb + (bufoff) + ldsw + _i * 8192); } while (0)
; #define PG8_LDA(dst, b, h) do { const int a1_ = opqv(aoff0) ^ 64; _Pragma("unroll") for (int m = 0; m < 4; ++m) { dst[m][0] = *(const LAS bf16x8*)(lds + PG8_SA(b, h) + aoff0 + m * 2048); dst[m][1] = *(const LAS bf16x8*)(lds + PG8_SA(b, h) + a1_ + m * 2048); } } while (0)
; #define PG8_LDB(dst, b, h) do { const int b1_ = opqv(boff0) ^ 64; _Pragma("unroll") for (int n = 0; n < 2; ++n) { dst[n][0] = *(const LAS bf16x8*)(lds + PG8_SB(b, h) + boff0 + n * 2048); dst[n][1] = *(const LAS bf16x8*)(lds + PG8_SB(b, h) + b1_ + n * 2048); } } while (0)
; #define PG8_MMA(ai, bj, At, Bt) do { __builtin_amdgcn_s_setprio(1); _Pragma("unroll") for (int m = 0; m < 4; ++m) _Pragma("unroll") for (int n = 0; n < 2; ++n) _Pragma("unroll") for (int k = 0; k < 2; ++k) \
;         acc[ai][bj][m][n] = __builtin_amdgcn_mfma_f32_16x16x32_bf16(Bt[n][k], At[m][k], acc[ai][bj][m][n], 0, 0, 0); __builtin_amdgcn_s_setprio(0); } while (0)
; #define PG8_WAIT_V(n) asm volatile("s_waitcnt vmcnt(" #n ")" ::: "memory")
; template <class Epi>
; __device__ __forceinline__ void gemm_phase(LAS unsigned char* lds, const Gemm g, const StaticOrder& S, const Epi& E, int wave_) {
;     ...
;             PG8_STAGE(PG8_SA(1, 1), a1 + hstepA, voffA); PG8_LDB(B0, 0, 0); PG8_LDB(B1, 0, 1); PG8_SCHED; PG8_LDA(At, 0, 0);
;             PG8_WAIT_V(8); PG8_WAIT_L(0); PG8_BAR; PG8_MMA(0, 0, At, B0); PG8_MMA(0, 1, At, B1); PG8_BAR; PG8_SCHED;
;             PG8_STAGE(PG8_SB(0, 0), b2, voffB); PG8_STAGE(PG8_SB(0, 1), b2 + hstepB, voffB); PG8_STAGE(PG8_SA(0, 0), a2, voffA); PG8_LDA(At, 0, 1);
;             PG8_WAIT_V(8); PG8_WAIT_L(0); PG8_BAR; PG8_MMA(1, 0, At, B0); PG8_MMA(1, 1, At, B1); PG8_BAR; PG8_SCHED;
;             PG8_STAGE(PG8_SA(0, 1), a2 + hstepA, voffA); PG8_LDB(B0, 1, 0); PG8_LDB(B1, 1, 1); PG8_SCHED; PG8_LDA(At, 1, 0);
;             PG8_WAIT_V(8); PG8_WAIT_L(0); PG8_BAR; PG8_MMA(0, 0, At, B0); PG8_MMA(0, 1, At, B1); PG8_BAR; PG8_SCHED;
;             PG8_STAGE(PG8_SB(1, 0), b3, voffB); PG8_STAGE(PG8_SB(1, 1), b3 + hstepB, voffB); PG8_STAGE(PG8_SA(1, 0), a3, voffA); PG8_LDA(At, 1, 1);
;             PG8_WAIT_V(8); PG8_WAIT_L(0); PG8_BAR; PG8_MMA(1, 0, At, B0); PG8_MMA(1, 1, At, B1); PG8_BAR; PG8_SCHED;
	v_mfma_f32_16x16x32_bf16 v[124:127], v[130:133], v[170:173], v[124:127]
	v_mfma_f32_16x16x32_bf16 v[120:123], v[142:145], v[170:173], v[120:123]
	v_mfma_f32_16x16x32_bf16 v[112:115], v[130:133], v[174:177], v[112:115]
	v_mfma_f32_16x16x32_bf16 v[104:107], v[142:145], v[174:177], v[104:107]
	v_mfma_f32_16x16x32_bf16 v[96:99], v[130:133], v[196:199], v[96:99]
	v_mfma_f32_16x16x32_bf16 v[88:91], v[142:145], v[196:199], v[88:91]
	v_mfma_f32_16x16x32_bf16 v[80:83], v[130:133], v[200:203], v[80:83]
	v_mfma_f32_16x16x32_bf16 v[72:75], v[142:145], v[200:203], v[72:75]
	v_mfma_f32_16x16x32_bf16 v[124:127], v[146:149], v[178:181], v[124:127]
	v_mfma_f32_16x16x32_bf16 v[120:123], v[150:153], v[178:181], v[120:123]
	v_mfma_f32_16x16x32_bf16 v[112:115], v[146:149], v[192:195], v[112:115]
	v_mfma_f32_16x16x32_bf16 v[104:107], v[150:153], v[192:195], v[104:107]
	v_mfma_f32_16x16x32_bf16 v[96:99], v[146:149], v[204:207], v[96:99]
	v_mfma_f32_16x16x32_bf16 v[88:91], v[150:153], v[204:207], v[88:91]
	v_mfma_f32_16x16x32_bf16 v[80:83], v[146:149], v[208:211], v[80:83]
	v_mfma_f32_16x16x32_bf16 v[72:75], v[150:153], v[208:211], v[72:75]
	s_setprio 0
	s_setprio 1
	v_mfma_f32_16x16x32_bf16 v[116:119], v[154:157], v[170:173], v[116:119]
	v_mfma_f32_16x16x32_bf16 v[108:111], v[158:161], v[170:173], v[108:111]
	v_mfma_f32_16x16x32_bf16 v[100:103], v[154:157], v[174:177], v[100:103]
	v_mfma_f32_16x16x32_bf16 v[92:95], v[158:161], v[174:177], v[92:95]
	v_mfma_f32_16x16x32_bf16 v[84:87], v[154:157], v[196:199], v[84:87]
	v_mfma_f32_16x16x32_bf16 v[76:79], v[158:161], v[196:199], v[76:79]
	v_mfma_f32_16x16x32_bf16 v[68:71], v[154:157], v[200:203], v[68:71]
	v_mfma_f32_16x16x32_bf16 v[64:67], v[158:161], v[200:203], v[64:67]
	v_mfma_f32_16x16x32_bf16 v[116:119], v[162:165], v[178:181], v[116:119]
	v_mfma_f32_16x16x32_bf16 v[108:111], v[166:169], v[178:181], v[108:111]
	v_mfma_f32_16x16x32_bf16 v[100:103], v[162:165], v[192:195], v[100:103]
	v_mfma_f32_16x16x32_bf16 v[92:95], v[166:169], v[192:195], v[92:95]
	v_mfma_f32_16x16x32_bf16 v[84:87], v[162:165], v[204:207], v[84:87]
	v_mfma_f32_16x16x32_bf16 v[76:79], v[166:169], v[204:207], v[76:79]
	v_mfma_f32_16x16x32_bf16 v[68:71], v[162:165], v[208:211], v[68:71]
	v_mfma_f32_16x16x32_bf16 v[64:67], v[166:169], v[208:211], v[64:67]
	s_setprio 0
	s_barrier
	s_add_u32 s54, s24, 0x80000
	s_addc_u32 s55, s25, 0
	v_mov_b32_e32 v128, v138
	s_nop 0
	s_nop 0
	s_nop 0
	v_xad_u32 v128, v128, 64, 0
	ds_read_b128 v[170:173], v141 offset:16384
	ds_read_b128 v[174:177], v141 offset:18432
	ds_read_b128 v[178:181], v128 offset:16384
	ds_read_b128 v[192:195], v128 offset:18432
	ds_read_b128 v[196:199], v141 offset:20480
	ds_read_b128 v[200:203], v141 offset:22528
	ds_read_b128 v[204:207], v128 offset:20480
	ds_read_b128 v[208:211], v128 offset:22528
	s_mov_b32 m0, s80
	s_nop 0
	global_load_lds_dwordx4 v134, s[24:25]
	s_mov_b32 m0, s81
	s_nop 0
	global_load_lds_dwordx4 v136, s[24:25]
	s_mov_b32 m0, s29
	s_nop 0
	global_load_lds_dwordx4 v134, s[54:55]
	s_mov_b32 m0, s88
	s_nop 0
	global_load_lds_dwordx4 v136, s[54:55]
	s_mov_b32 m0, s76
	s_nop 0
	global_load_lds_dwordx4 v129, s[26:27]
	s_mov_b32 m0, s89
	s_nop 0
	global_load_lds_dwordx4 v135, s[26:27]
	s_waitcnt vmcnt(8)
	s_waitcnt lgkmcnt(0)
	s_setprio 1
	s_barrier
	v_mfma_f32_16x16x32_bf16 v[60:63], v[130:133], v[170:173], v[60:63]
	v_mfma_f32_16x16x32_bf16 v[56:59], v[142:145], v[170:173], v[56:59]
	v_mfma_f32_16x16x32_bf16 v[48:51], v[130:133], v[174:177], v[48:51]
	v_mfma_f32_16x16x32_bf16 v[40:43], v[142:145], v[174:177], v[40:43]
	v_mfma_f32_16x16x32_bf16 v[32:35], v[130:133], v[196:199], v[32:35]
	v_mfma_f32_16x16x32_bf16 v[24:27], v[142:145], v[196:199], v[24:27]
	v_mfma_f32_16x16x32_bf16 v[16:19], v[130:133], v[200:203], v[16:19]
	v_mfma_f32_16x16x32_bf16 v[8:11], v[142:145], v[200:203], v[8:11]
	v_mfma_f32_16x16x32_bf16 v[60:63], v[146:149], v[178:181], v[60:63]
	v_mfma_f32_16x16x32_bf16 v[56:59], v[150:153], v[178:181], v[56:59]
	v_mfma_f32_16x16x32_bf16 v[48:51], v[146:149], v[192:195], v[48:51]
	v_mfma_f32_16x16x32_bf16 v[40:43], v[150:153], v[192:195], v[40:43]
	v_mfma_f32_16x16x32_bf16 v[32:35], v[146:149], v[204:207], v[32:35]
	v_mfma_f32_16x16x32_bf16 v[24:27], v[150:153], v[204:207], v[24:27]
	v_mfma_f32_16x16x32_bf16 v[16:19], v[146:149], v[208:211], v[16:19]
	v_mfma_f32_16x16x32_bf16 v[8:11], v[150:153], v[208:211], v[8:11]
	s_setprio 0
	s_setprio 1
	v_mfma_f32_16x16x32_bf16 v[52:55], v[154:157], v[170:173], v[52:55]
	v_mfma_f32_16x16x32_bf16 v[44:47], v[158:161], v[170:173], v[44:47]
	v_mfma_f32_16x16x32_bf16 v[36:39], v[154:157], v[174:177], v[36:39]
	v_mfma_f32_16x16x32_bf16 v[28:31], v[158:161], v[174:177], v[28:31]
	v_mfma_f32_16x16x32_bf16 v[20:23], v[154:157], v[196:199], v[20:23]
	v_mfma_f32_16x16x32_bf16 v[12:15], v[158:161], v[196:199], v[12:15]
	v_mfma_f32_16x16x32_bf16 v[4:7], v[154:157], v[200:203], v[4:7]
	v_mfma_f32_16x16x32_bf16 v[0:3], v[158:161], v[200:203], v[0:3]
	v_mfma_f32_16x16x32_bf16 v[52:55], v[162:165], v[178:181], v[52:55]
	v_mfma_f32_16x16x32_bf16 v[44:47], v[166:169], v[178:181], v[44:47]
	v_mfma_f32_16x16x32_bf16 v[36:39], v[162:165], v[192:195], v[36:39]
	v_mfma_f32_16x16x32_bf16 v[28:31], v[166:169], v[192:195], v[28:31]
	v_mfma_f32_16x16x32_bf16 v[20:23], v[162:165], v[204:207], v[20:23]
	v_mfma_f32_16x16x32_bf16 v[12:15], v[166:169], v[204:207], v[12:15]
	v_mfma_f32_16x16x32_bf16 v[4:7], v[162:165], v[208:211], v[4:7]
	v_mfma_f32_16x16x32_bf16 v[0:3], v[166:169], v[208:211], v[0:3]
	s_setprio 0
	s_barrier
; #define PG8_STAGE(bufoff, gbase, voff) do { _Pragma("unroll") for (int _i = 0; _i < 2; ++_i) \
;         dma16((const char*)(gbase), (voff)[_i], ldsb + (bufoff) + ldsw + _i * 8192); } while (0)
; #define PG8_LDA(dst, b, h) do { const int a1_ = opqv(aoff0) ^ 64; _Pragma("unroll") for (int m = 0; m < 4; ++m) { dst[m][0] = *(const LAS bf16x8*)(lds + PG8_SA(b, h) + aoff0 + m * 2048); dst[m][1] = *(const LAS bf16x8*)(lds + PG8_SA(b, h) + a1_ + m * 2048); } } while (0)
; #define PG8_LDB(dst, b, h) do { const int b1_ = opqv(boff0) ^ 64; _Pragma("unroll") for (int n = 0; n < 2; ++n) { dst[n][0] = *(const LAS bf16x8*)(lds + PG8_SB(b, h) + boff0 + n * 2048); dst[n][1] = *(const LAS bf16x8*)(lds + PG8_SB(b, h) + b1_ + n * 2048); } } while (0)
; #define PG8_MMA(ai, bj, At, Bt) do { __builtin_amdgcn_s_setprio(1); _Pragma("unroll") for (int m = 0; m < 4; ++m) _Pragma("unroll") for (int n = 0; n < 2; ++n) _Pragma("unroll") for (int k = 0; k < 2; ++k) \
;         acc[ai][bj][m][n] = __builtin_amdgcn_mfma_f32_16x16x32_bf16(Bt[n][k], At[m][k], acc[ai][bj][m][n], 0, 0, 0); __builtin_amdgcn_s_setprio(0); } while (0)
; #define PG8_WAIT_V(n) asm volatile("s_waitcnt vmcnt(" #n ")" ::: "memory")
; #define PG8_WAIT_L(n) asm volatile("s_waitcnt lgkmcnt(" #n ")" ::: "memory")
; #define PG8_BAR __builtin_amdgcn_s_barrier()
; #define PG8_SCHED __builtin_amdgcn_sched_barrier(0)
; template <class Epi>
; __device__ __forceinline__ void gemm_phase(LAS unsigned char* lds, const Gemm g, const StaticOrder& S, const Epi& E, int wave_) {
;     ...
;             PG8_STAGE(PG8_SA(0, 1), a2 + hstepA, voffA); PG8_LDB(B0, 1, 0); PG8_LDB(B1, 1, 1); PG8_SCHED; PG8_LDA(At, 1, 0);
;             PG8_WAIT_V(8); PG8_WAIT_L(0); PG8_BAR; PG8_MMA(0, 0, At, B0); PG8_MMA(0, 1, At, B1); PG8_BAR; PG8_SCHED;
;             PG8_STAGE(PG8_SB(1, 0), b3, voffB); PG8_STAGE(PG8_SB(1, 1), b3 + hstepB, voffB); PG8_STAGE(PG8_SA(1, 0), a3, voffA); PG8_LDA(At, 1, 1);
;             PG8_WAIT_V(8); PG8_WAIT_L(0); PG8_BAR; PG8_MMA(1, 0, At, B0); PG8_MMA(1, 1, At, B1); PG8_BAR; PG8_SCHED;
;         }
	s_add_u32 s26, s26, 0x80000
	s_addc_u32 s27, s27, 0
	s_mov_b32 m0, s1
	s_nop 0
	global_load_lds_dwordx4 v129, s[26:27]
	v_mov_b32_e32 v128, v139
	s_mov_b32 m0, s69
	s_nop 0
	global_load_lds_dwordx4 v135, s[26:27]
	v_add_u32_e32 v142, s34, v139
	v_xad_u32 v128, v128, 64, s34
	ds_read_b128 v[130:133], v142
	ds_read_b128 v[142:145], v142 offset:2048
	ds_read_b128 v[146:149], v128
	ds_read_b128 v[150:153], v128 offset:2048
	v_mov_b32_e32 v128, v139
	s_add_i32 s26, 0, 0x1c000
	v_add_u32_e32 v158, s26, v139
	v_xad_u32 v128, v128, 64, s26
	ds_read_b128 v[154:157], v158
	ds_read_b128 v[158:161], v158 offset:2048
	ds_read_b128 v[162:165], v128
	ds_read_b128 v[166:169], v128 offset:2048
	v_mov_b32_e32 v128, v138
	s_nop 0
	v_xad_u32 v128, v128, 64, 0
	ds_read_b128 v[170:173], v141 offset:32768
	ds_read_b128 v[174:177], v141 offset:34816
	ds_read_b128 v[178:181], v128 offset:32768
	ds_read_b128 v[192:195], v128 offset:34816
	ds_read_b128 v[196:199], v141 offset:36864
	ds_read_b128 v[200:203], v141 offset:38912
	ds_read_b128 v[204:207], v128 offset:36864
	ds_read_b128 v[208:211], v128 offset:38912
	s_waitcnt vmcnt(8)
	s_waitcnt lgkmcnt(0)
	s_setprio 1
	s_barrier
	v_mfma_f32_16x16x32_bf16 v[124:127], v[130:133], v[170:173], v[124:127]
	v_mfma_f32_16x16x32_bf16 v[120:123], v[142:145], v[170:173], v[120:123]
	v_mfma_f32_16x16x32_bf16 v[112:115], v[130:133], v[174:177], v[112:115]
	v_mfma_f32_16x16x32_bf16 v[104:107], v[142:145], v[174:177], v[104:107]
	v_mfma_f32_16x16x32_bf16 v[96:99], v[130:133], v[196:199], v[96:99]
	v_mfma_f32_16x16x32_bf16 v[88:91], v[142:145], v[196:199], v[88:91]
	v_mfma_f32_16x16x32_bf16 v[80:83], v[130:133], v[200:203], v[80:83]
	v_mfma_f32_16x16x32_bf16 v[72:75], v[142:145], v[200:203], v[72:75]
	v_mfma_f32_16x16x32_bf16 v[124:127], v[146:149], v[178:181], v[124:127]
	v_mfma_f32_16x16x32_bf16 v[120:123], v[150:153], v[178:181], v[120:123]
	v_mfma_f32_16x16x32_bf16 v[112:115], v[146:149], v[192:195], v[112:115]
	v_mfma_f32_16x16x32_bf16 v[104:107], v[150:153], v[192:195], v[104:107]
	v_mfma_f32_16x16x32_bf16 v[96:99], v[146:149], v[204:207], v[96:99]
	v_mfma_f32_16x16x32_bf16 v[88:91], v[150:153], v[204:207], v[88:91]
	v_mfma_f32_16x16x32_bf16 v[80:83], v[146:149], v[208:211], v[80:83]
	v_mfma_f32_16x16x32_bf16 v[72:75], v[150:153], v[208:211], v[72:75]
	s_setprio 0
	s_setprio 1
	v_mfma_f32_16x16x32_bf16 v[116:119], v[154:157], v[170:173], v[116:119]
	s_add_u32 s26, s24, 0x80
	s_addc_u32 s27, s25, 0
	v_mfma_f32_16x16x32_bf16 v[108:111], v[158:161], v[170:173], v[108:111]
	v_mfma_f32_16x16x32_bf16 v[100:103], v[154:157], v[174:177], v[100:103]
	v_mfma_f32_16x16x32_bf16 v[92:95], v[158:161], v[174:177], v[92:95]
	v_mfma_f32_16x16x32_bf16 v[84:87], v[154:157], v[196:199], v[84:87]
	v_mfma_f32_16x16x32_bf16 v[76:79], v[158:161], v[196:199], v[76:79]
	v_mfma_f32_16x16x32_bf16 v[68:71], v[154:157], v[200:203], v[68:71]
	v_mfma_f32_16x16x32_bf16 v[64:67], v[158:161], v[200:203], v[64:67]
	v_mfma_f32_16x16x32_bf16 v[116:119], v[162:165], v[178:181], v[116:119]
	v_mfma_f32_16x16x32_bf16 v[108:111], v[166:169], v[178:181], v[108:111]
	v_mfma_f32_16x16x32_bf16 v[100:103], v[162:165], v[192:195], v[100:103]
	v_mfma_f32_16x16x32_bf16 v[92:95], v[166:169], v[192:195], v[92:95]
	v_mfma_f32_16x16x32_bf16 v[84:87], v[162:165], v[204:207], v[84:87]
	v_mfma_f32_16x16x32_bf16 v[76:79], v[166:169], v[204:207], v[76:79]
	v_mfma_f32_16x16x32_bf16 v[68:71], v[162:165], v[208:211], v[68:71]
	v_mfma_f32_16x16x32_bf16 v[64:67], v[166:169], v[208:211], v[64:67]
	s_setprio 0
	s_barrier
	s_add_u32 s24, s24, 0x80080
	s_addc_u32 s25, s25, 0
	v_mov_b32_e32 v128, v138
	s_nop 0
	s_nop 0
	v_xad_u32 v128, v128, 64, 0
	ds_read_b128 v[170:173], v141 offset:49152
	ds_read_b128 v[174:177], v141 offset:51200
	ds_read_b128 v[178:181], v128 offset:49152
	ds_read_b128 v[192:195], v128 offset:51200
	ds_read_b128 v[196:199], v141 offset:53248
	ds_read_b128 v[200:203], v141 offset:55296
	ds_read_b128 v[204:207], v128 offset:53248
	ds_read_b128 v[208:211], v128 offset:55296
	s_mov_b32 m0, s35
	s_nop 0
	global_load_lds_dwordx4 v134, s[26:27]
	s_mov_b32 m0, s33
	s_nop 0
	global_load_lds_dwordx4 v136, s[26:27]
	s_mov_b32 m0, s77
	s_nop 0
	global_load_lds_dwordx4 v134, s[24:25]
	s_mov_b32 m0, s3
	s_nop 0
	global_load_lds_dwordx4 v136, s[24:25]
	s_mov_b32 m0, s22
	s_nop 0
	global_load_lds_dwordx4 v129, s[18:19]
	s_mov_b32 m0, s2
	s_nop 0
	global_load_lds_dwordx4 v135, s[18:19]
	s_waitcnt vmcnt(8)
	s_waitcnt lgkmcnt(0)
	s_setprio 1
	s_barrier
	v_mfma_f32_16x16x32_bf16 v[60:63], v[130:133], v[170:173], v[60:63]
	v_mfma_f32_16x16x32_bf16 v[56:59], v[142:145], v[170:173], v[56:59]
	v_mfma_f32_16x16x32_bf16 v[48:51], v[130:133], v[174:177], v[48:51]
	v_mfma_f32_16x16x32_bf16 v[40:43], v[142:145], v[174:177], v[40:43]
	v_mfma_f32_16x16x32_bf16 v[32:35], v[130:133], v[196:199], v[32:35]
	v_mfma_f32_16x16x32_bf16 v[24:27], v[142:145], v[196:199], v[24:27]
	v_mfma_f32_16x16x32_bf16 v[16:19], v[130:133], v[200:203], v[16:19]
	v_mfma_f32_16x16x32_bf16 v[8:11], v[142:145], v[200:203], v[8:11]
	v_mfma_f32_16x16x32_bf16 v[60:63], v[146:149], v[178:181], v[60:63]
	v_mfma_f32_16x16x32_bf16 v[56:59], v[150:153], v[178:181], v[56:59]
	v_mfma_f32_16x16x32_bf16 v[48:51], v[146:149], v[192:195], v[48:51]
	v_mfma_f32_16x16x32_bf16 v[40:43], v[150:153], v[192:195], v[40:43]
	v_mfma_f32_16x16x32_bf16 v[32:35], v[146:149], v[204:207], v[32:35]
	v_mfma_f32_16x16x32_bf16 v[24:27], v[150:153], v[204:207], v[24:27]
	v_mfma_f32_16x16x32_bf16 v[16:19], v[146:149], v[208:211], v[16:19]
	v_mfma_f32_16x16x32_bf16 v[8:11], v[150:153], v[208:211], v[8:11]
	s_setprio 0
	s_setprio 1
	v_mfma_f32_16x16x32_bf16 v[52:55], v[154:157], v[170:173], v[52:55]
	v_mfma_f32_16x16x32_bf16 v[44:47], v[158:161], v[170:173], v[44:47]
	v_mfma_f32_16x16x32_bf16 v[36:39], v[154:157], v[174:177], v[36:39]
	v_mfma_f32_16x16x32_bf16 v[28:31], v[158:161], v[174:177], v[28:31]
	v_mfma_f32_16x16x32_bf16 v[20:23], v[154:157], v[196:199], v[20:23]
	v_mfma_f32_16x16x32_bf16 v[12:15], v[158:161], v[196:199], v[12:15]
	v_mfma_f32_16x16x32_bf16 v[4:7], v[154:157], v[200:203], v[4:7]
	v_mfma_f32_16x16x32_bf16 v[0:3], v[158:161], v[200:203], v[0:3]
	v_mfma_f32_16x16x32_bf16 v[52:55], v[162:165], v[178:181], v[52:55]
	v_mfma_f32_16x16x32_bf16 v[44:47], v[166:169], v[178:181], v[44:47]
	v_mfma_f32_16x16x32_bf16 v[36:39], v[162:165], v[192:195], v[36:39]
	v_mfma_f32_16x16x32_bf16 v[28:31], v[166:169], v[192:195], v[28:31]
	v_mfma_f32_16x16x32_bf16 v[20:23], v[162:165], v[204:207], v[20:23]
	v_mfma_f32_16x16x32_bf16 v[12:15], v[166:169], v[204:207], v[12:15]
	v_mfma_f32_16x16x32_bf16 v[4:7], v[162:165], v[208:211], v[4:7]
	v_mfma_f32_16x16x32_bf16 v[0:3], v[166:169], v[208:211], v[0:3]
	s_setprio 0
	s_barrier
	s_add_i32 s49, s49, 2
	s_add_u32 s47, s47, 0x100
	s_addc_u32 s48, s48, 0
	s_add_u32 s12, s12, 0x100
	s_addc_u32 s13, s13, 0
	s_cmp_gt_u32 s49, 29
	s_cbranch_scc0 .LBB0_191

; #define PG8_STAGE(bufoff, gbase, voff) do { _Pragma("unroll") for (int _i = 0; _i < 2; ++_i) \
;         dma16((const char*)(gbase), (voff)[_i], ldsb + (bufoff) + ldsw + _i * 8192); } while (0)
; #define PG8_LDA(dst, b, h) do { const int a1_ = opqv(aoff0) ^ 64; _Pragma("unroll") for (int m = 0; m < 4; ++m) { dst[m][0] = *(const LAS bf16x8*)(lds + PG8_SA(b, h) + aoff0 + m * 2048); dst[m][1] = *(const LAS bf16x8*)(lds + PG8_SA(b, h) + a1_ + m * 2048); } } while (0)
; #define PG8_LDB(dst, b, h) do { const int b1_ = opqv(boff0) ^ 64; _Pragma("unroll") for (int n = 0; n < 2; ++n) { dst[n][0] = *(const LAS bf16x8*)(lds + PG8_SB(b, h) + boff0 + n * 2048); dst[n][1] = *(const LAS bf16x8*)(lds + PG8_SB(b, h) + b1_ + n * 2048); } } while (0)
; #define PG8_MMA(ai, bj, At, Bt) do { __builtin_amdgcn_s_setprio(1); _Pragma("unroll") for (int m = 0; m < 4; ++m) _Pragma("unroll") for (int n = 0; n < 2; ++n) _Pragma("unroll") for (int k = 0; k < 2; ++k) \
;         acc[ai][bj][m][n] = __builtin_amdgcn_mfma_f32_16x16x32_bf16(Bt[n][k], At[m][k], acc[ai][bj][m][n], 0, 0, 0); __builtin_amdgcn_s_setprio(0); } while (0)
; #define PG8_WAIT_V(n) asm volatile("s_waitcnt vmcnt(" #n ")" ::: "memory")
; template <class Epi>
; __device__ __forceinline__ void gemm_phase(LAS unsigned char* lds, const Gemm g, const StaticOrder& S, const Epi& E, int wave_) {
;     ...
;             PG8_STAGE(PG8_SA(1, 1), a1 + hstepA, voffA); PG8_LDB(B0, 0, 0); PG8_LDB(B1, 0, 1); PG8_SCHED; PG8_LDA(At, 0, 0);
;             PG8_WAIT_V(8); PG8_WAIT_L(0); PG8_BAR; PG8_MMA(0, 0, At, B0); PG8_MMA(0, 1, At, B1); PG8_BAR; PG8_SCHED;
;             PG8_STAGE(PG8_SB(0, 0), b2, voffB); PG8_STAGE(PG8_SB(0, 1), b2 + hstepB, voffB); PG8_STAGE(PG8_SA(0, 0), a2, voffA); PG8_LDA(At, 0, 1);
;             PG8_WAIT_V(8); PG8_WAIT_L(0); PG8_BAR; PG8_MMA(1, 0, At, B0); PG8_MMA(1, 1, At, B1); PG8_BAR; PG8_SCHED;
;             PG8_STAGE(PG8_SA(0, 1), a2 + hstepA, voffA); PG8_LDB(B0, 1, 0); PG8_LDB(B1, 1, 1); PG8_SCHED; PG8_LDA(At, 1, 0);
;             PG8_WAIT_V(8); PG8_WAIT_L(0); PG8_BAR; PG8_MMA(0, 0, At, B0); PG8_MMA(0, 1, At, B1); PG8_BAR; PG8_SCHED;
;             PG8_STAGE(PG8_SB(1, 0), b3, voffB); PG8_STAGE(PG8_SB(1, 1), b3 + hstepB, voffB); PG8_STAGE(PG8_SA(1, 0), a3, voffA); PG8_LDA(At, 1, 1);
;             PG8_WAIT_V(8); PG8_WAIT_L(0); PG8_BAR; PG8_MMA(1, 0, At, B0); PG8_MMA(1, 1, At, B1); PG8_BAR; PG8_SCHED;
.LBB0_573:
	s_ashr_i32 s11, s10, 31
	s_lshl_b64 s[16:17], s[10:11], 20
	s_add_u32 s18, s21, s16
	s_addc_u32 s19, s44, s17
	s_and_b64 s[16:17], s[42:43], exec
	s_cselect_b32 s11, s19, s27
	s_cselect_b32 s16, s18, s26
	s_ashr_i32 s9, s8, 31
	s_lshl_b64 s[24:25], s[8:9], 20
	s_add_u32 s24, s45, s24
	s_addc_u32 s25, s46, s25
	s_and_b64 s[30:31], s[42:43], exec
	s_cselect_b32 s9, s25, s13
	s_cselect_b32 s17, s24, s12
	s_add_u32 s52, s12, 0x100
	s_addc_u32 s56, s13, 0
	s_add_u32 s12, s26, 0x80080
	s_addc_u32 s13, s27, 0
	s_mov_b32 s57, -2
	s_add_u32 s26, s12, 0xfff80080
	s_addc_u32 s27, s13, -1
	s_cmp_eq_u32 s57, 28
	s_cselect_b32 s36, s16, s26
	v_mov_b32_e32 v128, v144
	s_cselect_b32 s37, s11, s27
	s_cselect_b32 s30, s17, s52
	s_cselect_b32 s31, s9, s56
	s_add_u32 s26, s36, 0x80
	v_add_u32_e32 v137, s23, v144
	v_xad_u32 v136, v128, 64, s23
	s_addc_u32 s27, s37, 0
	ds_read_b128 v[128:131], v137
	ds_read_b128 v[146:149], v137 offset:2048
	ds_read_b128 v[150:153], v136
	ds_read_b128 v[154:157], v136 offset:2048
	v_mov_b32_e32 v136, v144
	s_add_i32 s58, 0, 0x14000
	v_add_u32_e32 v137, s58, v144
	v_xad_u32 v136, v136, 64, s58
	ds_read_b128 v[158:161], v137
	ds_read_b128 v[162:165], v137 offset:2048
	ds_read_b128 v[166:169], v136
	ds_read_b128 v[170:173], v136 offset:2048
	v_mov_b32_e32 v136, v143
	v_add_u32_e32 v137, 0, v143
	v_xad_u32 v136, v136, 64, 0
	ds_read_b128 v[174:177], v137
	ds_read_b128 v[178:181], v137 offset:2048
	ds_read_b128 v[192:195], v136
	ds_read_b128 v[196:199], v136 offset:2048
	ds_read_b128 v[200:203], v137 offset:4096
	ds_read_b128 v[204:207], v137 offset:6144
	ds_read_b128 v[208:211], v136 offset:4096
	ds_read_b128 v[212:215], v136 offset:6144
	s_mov_b32 m0, s14
	s_nop 0
	global_load_lds_dwordx4 v138, s[12:13]
	s_mov_b32 m0, s15
	s_nop 0
	global_load_lds_dwordx4 v140, s[12:13]
	s_waitcnt vmcnt(8)
	s_waitcnt lgkmcnt(0)
	s_setprio 1
	s_barrier
	v_mfma_f32_16x16x32_bf16 v[124:127], v[128:131], v[174:177], 0
	v_mfma_f32_16x16x32_bf16 v[120:123], v[146:149], v[174:177], 0
	v_mfma_f32_16x16x32_bf16 v[108:111], v[128:131], v[178:181], 0
	v_mfma_f32_16x16x32_bf16 v[104:107], v[146:149], v[178:181], 0
	v_mfma_f32_16x16x32_bf16 v[92:95], v[128:131], v[200:203], 0
	v_mfma_f32_16x16x32_bf16 v[88:91], v[146:149], v[200:203], 0
	v_mfma_f32_16x16x32_bf16 v[76:79], v[128:131], v[204:207], 0
	v_mfma_f32_16x16x32_bf16 v[72:75], v[146:149], v[204:207], 0
	v_mfma_f32_16x16x32_bf16 v[124:127], v[150:153], v[192:195], v[124:127]
	v_mfma_f32_16x16x32_bf16 v[120:123], v[154:157], v[192:195], v[120:123]
	v_mfma_f32_16x16x32_bf16 v[108:111], v[150:153], v[196:199], v[108:111]
	v_mfma_f32_16x16x32_bf16 v[104:107], v[154:157], v[196:199], v[104:107]
	v_mfma_f32_16x16x32_bf16 v[92:95], v[150:153], v[208:211], v[92:95]
	v_mfma_f32_16x16x32_bf16 v[88:91], v[154:157], v[208:211], v[88:91]
	v_mfma_f32_16x16x32_bf16 v[76:79], v[150:153], v[212:215], v[76:79]
	v_mfma_f32_16x16x32_bf16 v[72:75], v[154:157], v[212:215], v[72:75]
	s_setprio 0
	s_setprio 1
	v_mfma_f32_16x16x32_bf16 v[116:119], v[158:161], v[174:177], 0
	v_mfma_f32_16x16x32_bf16 v[112:115], v[162:165], v[174:177], 0
	v_mfma_f32_16x16x32_bf16 v[100:103], v[158:161], v[178:181], 0
	v_mfma_f32_16x16x32_bf16 v[96:99], v[162:165], v[178:181], 0
	v_mfma_f32_16x16x32_bf16 v[84:87], v[158:161], v[200:203], 0
	v_mfma_f32_16x16x32_bf16 v[80:83], v[162:165], v[200:203], 0
	v_mfma_f32_16x16x32_bf16 v[68:71], v[158:161], v[204:207], 0
	v_mfma_f32_16x16x32_bf16 v[64:67], v[162:165], v[204:207], 0
	v_mfma_f32_16x16x32_bf16 v[116:119], v[166:169], v[192:195], v[116:119]
	v_mfma_f32_16x16x32_bf16 v[112:115], v[170:173], v[192:195], v[112:115]
	v_mfma_f32_16x16x32_bf16 v[100:103], v[166:169], v[196:199], v[100:103]
	v_mfma_f32_16x16x32_bf16 v[96:99], v[170:173], v[196:199], v[96:99]
	v_mfma_f32_16x16x32_bf16 v[84:87], v[166:169], v[208:211], v[84:87]
	v_mfma_f32_16x16x32_bf16 v[80:83], v[170:173], v[208:211], v[80:83]
	v_mfma_f32_16x16x32_bf16 v[68:71], v[166:169], v[212:215], v[68:71]
	v_mfma_f32_16x16x32_bf16 v[64:67], v[170:173], v[212:215], v[64:67]
	s_setprio 0
	s_barrier
	v_mov_b32_e32 v136, v143
	s_add_u32 s58, s30, 0x80000
	s_addc_u32 s59, s31, 0
	s_nop 0
	s_nop 0
	s_nop 0
	v_xad_u32 v136, v136, 64, 0
	ds_read_b128 v[174:177], v137 offset:16384
	ds_read_b128 v[178:181], v137 offset:18432
	ds_read_b128 v[192:195], v136 offset:16384
	ds_read_b128 v[196:199], v136 offset:18432
	ds_read_b128 v[200:203], v137 offset:20480
	ds_read_b128 v[204:207], v137 offset:22528
	ds_read_b128 v[208:211], v136 offset:20480
	ds_read_b128 v[212:215], v136 offset:22528
	s_mov_b32 m0, s80
	s_nop 0
	global_load_lds_dwordx4 v139, s[30:31]
	s_mov_b32 m0, s81
	s_nop 0
	global_load_lds_dwordx4 v141, s[30:31]
	s_mov_b32 m0, s29
	s_nop 0
	global_load_lds_dwordx4 v139, s[58:59]
	s_mov_b32 m0, s88
	s_nop 0
	global_load_lds_dwordx4 v141, s[58:59]
	s_mov_b32 m0, s76
	s_nop 0
	global_load_lds_dwordx4 v138, s[36:37]
	s_mov_b32 m0, s89
	s_nop 0
	global_load_lds_dwordx4 v140, s[36:37]
	s_waitcnt vmcnt(8)
	s_waitcnt lgkmcnt(0)
	s_setprio 1
	s_barrier
; #define PG8_STAGE(bufoff, gbase, voff) do { _Pragma("unroll") for (int _i = 0; _i < 2; ++_i) \
;         dma16((const char*)(gbase), (voff)[_i], ldsb + (bufoff) + ldsw + _i * 8192); } while (0)
; #define PG8_LDA(dst, b, h) do { const int a1_ = opqv(aoff0) ^ 64; _Pragma("unroll") for (int m = 0; m < 4; ++m) { dst[m][0] = *(const LAS bf16x8*)(lds + PG8_SA(b, h) + aoff0 + m * 2048); dst[m][1] = *(const LAS bf16x8*)(lds + PG8_SA(b, h) + a1_ + m * 2048); } } while (0)
; #define PG8_LDB(dst, b, h) do { const int b1_ = opqv(boff0) ^ 64; _Pragma("unroll") for (int n = 0; n < 2; ++n) { dst[n][0] = *(const LAS bf16x8*)(lds + PG8_SB(b, h) + boff0 + n * 2048); dst[n][1] = *(const LAS bf16x8*)(lds + PG8_SB(b, h) + b1_ + n * 2048); } } while (0)
; #define PG8_MMA(ai, bj, At, Bt) do { __builtin_amdgcn_s_setprio(1); _Pragma("unroll") for (int m = 0; m < 4; ++m) _Pragma("unroll") for (int n = 0; n < 2; ++n) _Pragma("unroll") for (int k = 0; k < 2; ++k) \
;         acc[ai][bj][m][n] = __builtin_amdgcn_mfma_f32_16x16x32_bf16(Bt[n][k], At[m][k], acc[ai][bj][m][n], 0, 0, 0); __builtin_amdgcn_s_setprio(0); } while (0)
; #define PG8_WAIT_V(n) asm volatile("s_waitcnt vmcnt(" #n ")" ::: "memory")
; template <class Epi>
; __device__ __forceinline__ void gemm_phase(LAS unsigned char* lds, const Gemm g, const StaticOrder& S, const Epi& E, int wave_) {
;     ...
;             PG8_STAGE(PG8_SA(1, 1), a1 + hstepA, voffA); PG8_LDB(B0, 0, 0); PG8_LDB(B1, 0, 1); PG8_SCHED; PG8_LDA(At, 0, 0);
;             PG8_WAIT_V(8); PG8_WAIT_L(0); PG8_BAR; PG8_MMA(0, 0, At, B0); PG8_MMA(0, 1, At, B1); PG8_BAR; PG8_SCHED;
;             PG8_STAGE(PG8_SB(0, 0), b2, voffB); PG8_STAGE(PG8_SB(0, 1), b2 + hstepB, voffB); PG8_STAGE(PG8_SA(0, 0), a2, voffA); PG8_LDA(At, 0, 1);
;             PG8_WAIT_V(8); PG8_WAIT_L(0); PG8_BAR; PG8_MMA(1, 0, At, B0); PG8_MMA(1, 1, At, B1); PG8_BAR; PG8_SCHED;
;             PG8_STAGE(PG8_SA(0, 1), a2 + hstepA, voffA); PG8_LDB(B0, 1, 0); PG8_LDB(B1, 1, 1); PG8_SCHED; PG8_LDA(At, 1, 0);
;             PG8_WAIT_V(8); PG8_WAIT_L(0); PG8_BAR; PG8_MMA(0, 0, At, B0); PG8_MMA(0, 1, At, B1); PG8_BAR; PG8_SCHED;
;             PG8_STAGE(PG8_SB(1, 0), b3, voffB); PG8_STAGE(PG8_SB(1, 1), b3 + hstepB, voffB); PG8_STAGE(PG8_SA(1, 0), a3, voffA); PG8_LDA(At, 1, 1);
;             PG8_WAIT_V(8); PG8_WAIT_L(0); PG8_BAR; PG8_MMA(1, 0, At, B0); PG8_MMA(1, 1, At, B1); PG8_BAR; PG8_SCHED;
	v_mfma_f32_16x16x32_bf16 v[60:63], v[128:131], v[174:177], 0
	v_mfma_f32_16x16x32_bf16 v[56:59], v[146:149], v[174:177], 0
	v_mfma_f32_16x16x32_bf16 v[44:47], v[128:131], v[178:181], 0
	v_mfma_f32_16x16x32_bf16 v[40:43], v[146:149], v[178:181], 0
	v_mfma_f32_16x16x32_bf16 v[28:31], v[128:131], v[200:203], 0
	v_mfma_f32_16x16x32_bf16 v[24:27], v[146:149], v[200:203], 0
	v_mfma_f32_16x16x32_bf16 v[12:15], v[128:131], v[204:207], 0
	v_mfma_f32_16x16x32_bf16 v[8:11], v[146:149], v[204:207], 0
	v_mfma_f32_16x16x32_bf16 v[60:63], v[150:153], v[192:195], v[60:63]
	v_mfma_f32_16x16x32_bf16 v[56:59], v[154:157], v[192:195], v[56:59]
	v_mfma_f32_16x16x32_bf16 v[44:47], v[150:153], v[196:199], v[44:47]
	v_mfma_f32_16x16x32_bf16 v[40:43], v[154:157], v[196:199], v[40:43]
	v_mfma_f32_16x16x32_bf16 v[28:31], v[150:153], v[208:211], v[28:31]
	v_mfma_f32_16x16x32_bf16 v[24:27], v[154:157], v[208:211], v[24:27]
	v_mfma_f32_16x16x32_bf16 v[12:15], v[150:153], v[212:215], v[12:15]
	v_mfma_f32_16x16x32_bf16 v[8:11], v[154:157], v[212:215], v[8:11]
	s_setprio 0
	s_setprio 1
	v_mfma_f32_16x16x32_bf16 v[52:55], v[158:161], v[174:177], 0
	v_mfma_f32_16x16x32_bf16 v[48:51], v[162:165], v[174:177], 0
	v_mfma_f32_16x16x32_bf16 v[36:39], v[158:161], v[178:181], 0
	v_mfma_f32_16x16x32_bf16 v[32:35], v[162:165], v[178:181], 0
	v_mfma_f32_16x16x32_bf16 v[20:23], v[158:161], v[200:203], 0
	v_mfma_f32_16x16x32_bf16 v[16:19], v[162:165], v[200:203], 0
	v_mfma_f32_16x16x32_bf16 v[4:7], v[158:161], v[204:207], 0
	v_mfma_f32_16x16x32_bf16 v[0:3], v[162:165], v[204:207], 0
	v_mfma_f32_16x16x32_bf16 v[52:55], v[166:169], v[192:195], v[52:55]
	v_mfma_f32_16x16x32_bf16 v[48:51], v[170:173], v[192:195], v[48:51]
	v_mfma_f32_16x16x32_bf16 v[36:39], v[166:169], v[196:199], v[36:39]
	v_mfma_f32_16x16x32_bf16 v[32:35], v[170:173], v[196:199], v[32:35]
	v_mfma_f32_16x16x32_bf16 v[20:23], v[166:169], v[208:211], v[20:23]
	v_mfma_f32_16x16x32_bf16 v[16:19], v[170:173], v[208:211], v[16:19]
	v_mfma_f32_16x16x32_bf16 v[4:7], v[166:169], v[212:215], v[4:7]
	v_mfma_f32_16x16x32_bf16 v[0:3], v[170:173], v[212:215], v[0:3]
	s_setprio 0
	s_barrier
	s_add_u32 s36, s36, 0x80000
	s_addc_u32 s37, s37, 0
	s_mov_b32 m0, s1
	s_nop 0
	global_load_lds_dwordx4 v138, s[36:37]
	v_mov_b32_e32 v128, v144
	s_mov_b32 m0, s69
	s_nop 0
	global_load_lds_dwordx4 v140, s[36:37]
	v_add_u32_e32 v146, s34, v144
	v_xad_u32 v136, v128, 64, s34
	ds_read_b128 v[128:131], v146
	ds_read_b128 v[146:149], v146 offset:2048
	ds_read_b128 v[150:153], v136
	ds_read_b128 v[154:157], v136 offset:2048
	v_mov_b32_e32 v136, v144
	s_add_i32 s36, 0, 0x1c000
	v_add_u32_e32 v162, s36, v144
	v_xad_u32 v136, v136, 64, s36
	ds_read_b128 v[158:161], v162
	ds_read_b128 v[162:165], v162 offset:2048
	ds_read_b128 v[166:169], v136
	ds_read_b128 v[170:173], v136 offset:2048
	v_mov_b32_e32 v136, v143
	s_nop 0
	v_xad_u32 v136, v136, 64, 0
	ds_read_b128 v[174:177], v137 offset:32768
	ds_read_b128 v[178:181], v137 offset:34816
	ds_read_b128 v[192:195], v136 offset:32768
	ds_read_b128 v[196:199], v136 offset:34816
	ds_read_b128 v[200:203], v137 offset:36864
	ds_read_b128 v[204:207], v137 offset:38912
	ds_read_b128 v[208:211], v136 offset:36864
	ds_read_b128 v[212:215], v136 offset:38912
	s_waitcnt vmcnt(8)
	s_waitcnt lgkmcnt(0)
	s_setprio 1
	s_barrier
	v_mfma_f32_16x16x32_bf16 v[124:127], v[128:131], v[174:177], v[124:127]
	v_mfma_f32_16x16x32_bf16 v[120:123], v[146:149], v[174:177], v[120:123]
	v_mfma_f32_16x16x32_bf16 v[108:111], v[128:131], v[178:181], v[108:111]
	v_mfma_f32_16x16x32_bf16 v[104:107], v[146:149], v[178:181], v[104:107]
	v_mfma_f32_16x16x32_bf16 v[92:95], v[128:131], v[200:203], v[92:95]
	v_mfma_f32_16x16x32_bf16 v[88:91], v[146:149], v[200:203], v[88:91]
	v_mfma_f32_16x16x32_bf16 v[76:79], v[128:131], v[204:207], v[76:79]
	v_mfma_f32_16x16x32_bf16 v[72:75], v[146:149], v[204:207], v[72:75]
	v_mfma_f32_16x16x32_bf16 v[124:127], v[150:153], v[192:195], v[124:127]
	v_mfma_f32_16x16x32_bf16 v[120:123], v[154:157], v[192:195], v[120:123]
	v_mfma_f32_16x16x32_bf16 v[108:111], v[150:153], v[196:199], v[108:111]
	v_mfma_f32_16x16x32_bf16 v[104:107], v[154:157], v[196:199], v[104:107]
	v_mfma_f32_16x16x32_bf16 v[92:95], v[150:153], v[208:211], v[92:95]
	v_mfma_f32_16x16x32_bf16 v[88:91], v[154:157], v[208:211], v[88:91]
	v_mfma_f32_16x16x32_bf16 v[76:79], v[150:153], v[212:215], v[76:79]
	v_mfma_f32_16x16x32_bf16 v[72:75], v[154:157], v[212:215], v[72:75]
	s_setprio 0
	s_setprio 1
	v_mfma_f32_16x16x32_bf16 v[116:119], v[158:161], v[174:177], v[116:119]
	s_add_u32 s36, s30, 0x80
	s_addc_u32 s37, s31, 0
	v_mfma_f32_16x16x32_bf16 v[112:115], v[162:165], v[174:177], v[112:115]
	v_mfma_f32_16x16x32_bf16 v[100:103], v[158:161], v[178:181], v[100:103]
	v_mfma_f32_16x16x32_bf16 v[96:99], v[162:165], v[178:181], v[96:99]
	v_mfma_f32_16x16x32_bf16 v[84:87], v[158:161], v[200:203], v[84:87]
	v_mfma_f32_16x16x32_bf16 v[80:83], v[162:165], v[200:203], v[80:83]
	v_mfma_f32_16x16x32_bf16 v[68:71], v[158:161], v[204:207], v[68:71]
	v_mfma_f32_16x16x32_bf16 v[64:67], v[162:165], v[204:207], v[64:67]
	v_mfma_f32_16x16x32_bf16 v[116:119], v[166:169], v[192:195], v[116:119]
	v_mfma_f32_16x16x32_bf16 v[112:115], v[170:173], v[192:195], v[112:115]
	v_mfma_f32_16x16x32_bf16 v[100:103], v[166:169], v[196:199], v[100:103]
	v_mfma_f32_16x16x32_bf16 v[96:99], v[170:173], v[196:199], v[96:99]
	v_mfma_f32_16x16x32_bf16 v[84:87], v[166:169], v[208:211], v[84:87]
	v_mfma_f32_16x16x32_bf16 v[80:83], v[170:173], v[208:211], v[80:83]
	v_mfma_f32_16x16x32_bf16 v[68:71], v[166:169], v[212:215], v[68:71]
	v_mfma_f32_16x16x32_bf16 v[64:67], v[170:173], v[212:215], v[64:67]
	s_setprio 0
	s_barrier
; #define PG8_STAGE(bufoff, gbase, voff) do { _Pragma("unroll") for (int _i = 0; _i < 2; ++_i) \
;         dma16((const char*)(gbase), (voff)[_i], ldsb + (bufoff) + ldsw + _i * 8192); } while (0)
; #define PG8_LDA(dst, b, h) do { const int a1_ = opqv(aoff0) ^ 64; _Pragma("unroll") for (int m = 0; m < 4; ++m) { dst[m][0] = *(const LAS bf16x8*)(lds + PG8_SA(b, h) + aoff0 + m * 2048); dst[m][1] = *(const LAS bf16x8*)(lds + PG8_SA(b, h) + a1_ + m * 2048); } } while (0)
; #define PG8_WAIT_V(n) asm volatile("s_waitcnt vmcnt(" #n ")" ::: "memory")
; template <class Epi>
; __device__ __forceinline__ void gemm_phase(LAS unsigned char* lds, const Gemm g, const StaticOrder& S, const Epi& E, int wave_) {
;     ...
;     for (;;) {
;         const bool has_next = S.next(ui + 1, nxt);
;         const char* nA = has_next ? (const char*)g.A + (size_t)nxt.pm * tstepA : cA; const char* nB = has_next ? (const char*)g.Bt + (size_t)nxt.pn * tstepB : cB;
; #pragma unroll 1
;         for (int t = 0; t < nt; t += 2) {
;             const bool last = (t == nt - 2);
;             const char* a1 = cA + (size_t)(t + 1) * kstep;
;             const char* a2 = last ? nA : cA + (size_t)(t + 2) * kstep; const char* b2 = last ? nB : cB + (size_t)(t + 2) * kstep;
;             const char* a3 = a2 + kstep; const char* b3 = b2 + kstep;
;             PG8_STAGE(PG8_SA(1, 1), a1 + hstepA, voffA); PG8_LDB(B0, 0, 0); PG8_LDB(B1, 0, 1); PG8_SCHED; PG8_LDA(At, 0, 0);
;             PG8_WAIT_V(8); PG8_WAIT_L(0); PG8_BAR; PG8_MMA(0, 0, At, B0); PG8_MMA(0, 1, At, B1); PG8_BAR; PG8_SCHED;
;             PG8_STAGE(PG8_SB(0, 0), b2, voffB); PG8_STAGE(PG8_SB(0, 1), b2 + hstepB, voffB); PG8_STAGE(PG8_SA(0, 0), a2, voffA); PG8_LDA(At, 0, 1);
;             PG8_WAIT_V(8); PG8_WAIT_L(0); PG8_BAR; PG8_MMA(1, 0, At, B0); PG8_MMA(1, 1, At, B1); PG8_BAR; PG8_SCHED;
;             PG8_STAGE(PG8_SA(0, 1), a2 + hstepA, voffA); PG8_LDB(B0, 1, 0); PG8_LDB(B1, 1, 1); PG8_SCHED; PG8_LDA(At, 1, 0);
;             PG8_WAIT_V(8); PG8_WAIT_L(0); PG8_BAR; PG8_MMA(0, 0, At, B0); PG8_MMA(0, 1, At, B1); PG8_BAR; PG8_SCHED;
;             PG8_STAGE(PG8_SB(1, 0), b3, voffB); PG8_STAGE(PG8_SB(1, 1), b3 + hstepB, voffB); PG8_STAGE(PG8_SA(1, 0), a3, voffA); PG8_LDA(At, 1, 1);
;             PG8_WAIT_V(8); PG8_WAIT_L(0); PG8_BAR; PG8_MMA(1, 0, At, B0); PG8_MMA(1, 1, At, B1); PG8_BAR; PG8_SCHED;
;         }
	s_add_u32 s30, s30, 0x80080
	s_addc_u32 s31, s31, 0
	v_mov_b32_e32 v136, v143
	s_nop 0
	s_nop 0
	v_xad_u32 v136, v136, 64, 0
	ds_read_b128 v[174:177], v137 offset:49152
	ds_read_b128 v[178:181], v137 offset:51200
	ds_read_b128 v[192:195], v136 offset:49152
	ds_read_b128 v[196:199], v136 offset:51200
	ds_read_b128 v[200:203], v137 offset:53248
	ds_read_b128 v[204:207], v137 offset:55296
	ds_read_b128 v[208:211], v136 offset:53248
	ds_read_b128 v[212:215], v136 offset:55296
	s_mov_b32 m0, s35
	s_nop 0
	global_load_lds_dwordx4 v139, s[36:37]
	s_mov_b32 m0, s33
	s_nop 0
	global_load_lds_dwordx4 v141, s[36:37]
	s_mov_b32 m0, s77
	s_nop 0
	global_load_lds_dwordx4 v139, s[30:31]
	s_mov_b32 m0, s3
	s_nop 0
	global_load_lds_dwordx4 v141, s[30:31]
	s_mov_b32 m0, s22
	s_nop 0
	global_load_lds_dwordx4 v138, s[26:27]
	s_mov_b32 m0, s2
	s_nop 0
	global_load_lds_dwordx4 v140, s[26:27]
	s_waitcnt vmcnt(8)
	s_waitcnt lgkmcnt(0)
	s_setprio 1
	s_barrier
	v_mfma_f32_16x16x32_bf16 v[60:63], v[128:131], v[174:177], v[60:63]
	v_mfma_f32_16x16x32_bf16 v[56:59], v[146:149], v[174:177], v[56:59]
	v_mfma_f32_16x16x32_bf16 v[44:47], v[128:131], v[178:181], v[44:47]
	v_mfma_f32_16x16x32_bf16 v[40:43], v[146:149], v[178:181], v[40:43]
	v_mfma_f32_16x16x32_bf16 v[28:31], v[128:131], v[200:203], v[28:31]
	v_mfma_f32_16x16x32_bf16 v[24:27], v[146:149], v[200:203], v[24:27]
	v_mfma_f32_16x16x32_bf16 v[12:15], v[128:131], v[204:207], v[12:15]
	v_mfma_f32_16x16x32_bf16 v[8:11], v[146:149], v[204:207], v[8:11]
	v_mfma_f32_16x16x32_bf16 v[60:63], v[150:153], v[192:195], v[60:63]
	v_mfma_f32_16x16x32_bf16 v[56:59], v[154:157], v[192:195], v[56:59]
	v_mfma_f32_16x16x32_bf16 v[44:47], v[150:153], v[196:199], v[44:47]
	v_mfma_f32_16x16x32_bf16 v[40:43], v[154:157], v[196:199], v[40:43]
	v_mfma_f32_16x16x32_bf16 v[28:31], v[150:153], v[208:211], v[28:31]
	v_mfma_f32_16x16x32_bf16 v[24:27], v[154:157], v[208:211], v[24:27]
	v_mfma_f32_16x16x32_bf16 v[12:15], v[150:153], v[212:215], v[12:15]
	v_mfma_f32_16x16x32_bf16 v[8:11], v[154:157], v[212:215], v[8:11]
	s_setprio 0
	s_setprio 1
	v_mfma_f32_16x16x32_bf16 v[52:55], v[158:161], v[174:177], v[52:55]
	v_mfma_f32_16x16x32_bf16 v[48:51], v[162:165], v[174:177], v[48:51]
	v_mfma_f32_16x16x32_bf16 v[36:39], v[158:161], v[178:181], v[36:39]
	v_mfma_f32_16x16x32_bf16 v[32:35], v[162:165], v[178:181], v[32:35]
	v_mfma_f32_16x16x32_bf16 v[20:23], v[158:161], v[200:203], v[20:23]
	v_mfma_f32_16x16x32_bf16 v[16:19], v[162:165], v[200:203], v[16:19]
	v_mfma_f32_16x16x32_bf16 v[4:7], v[158:161], v[204:207], v[4:7]
	v_mfma_f32_16x16x32_bf16 v[0:3], v[162:165], v[204:207], v[0:3]
	v_mfma_f32_16x16x32_bf16 v[52:55], v[166:169], v[192:195], v[52:55]
	v_mfma_f32_16x16x32_bf16 v[48:51], v[170:173], v[192:195], v[48:51]
	v_mfma_f32_16x16x32_bf16 v[36:39], v[166:169], v[196:199], v[36:39]
	v_mfma_f32_16x16x32_bf16 v[32:35], v[170:173], v[196:199], v[32:35]
	v_mfma_f32_16x16x32_bf16 v[20:23], v[166:169], v[208:211], v[20:23]
	v_mfma_f32_16x16x32_bf16 v[16:19], v[170:173], v[208:211], v[16:19]
	v_mfma_f32_16x16x32_bf16 v[4:7], v[166:169], v[212:215], v[4:7]
	v_mfma_f32_16x16x32_bf16 v[0:3], v[170:173], v[212:215], v[0:3]
	s_setprio 0
	s_barrier
	s_add_i32 s57, s57, 2
	s_add_u32 s52, s52, 0x100
	s_addc_u32 s56, s56, 0
	s_add_u32 s12, s12, 0x100
	s_addc_u32 s13, s13, 0
	s_cmp_gt_u32 s57, 29
	s_cbranch_scc0 .LBB0_574
	s_branch .Lpeel_exit_7
.LBB0_574:
	s_add_u32 s26, s12, 0xfff80080
	s_addc_u32 s27, s13, -1
	s_cmp_eq_u32 s57, 28
	s_cselect_b32 s36, s16, s26
	v_mov_b32_e32 v128, v144
	s_cselect_b32 s37, s11, s27
	s_cselect_b32 s30, s17, s52
	s_cselect_b32 s31, s9, s56
	s_add_u32 s26, s36, 0x80
	v_add_u32_e32 v137, s23, v144
	v_xad_u32 v136, v128, 64, s23
	s_addc_u32 s27, s37, 0
	ds_read_b128 v[128:131], v137
	ds_read_b128 v[146:149], v137 offset:2048
	ds_read_b128 v[150:153], v136
	ds_read_b128 v[154:157], v136 offset:2048
	v_mov_b32_e32 v136, v144
	s_add_i32 s58, 0, 0x14000
	v_add_u32_e32 v137, s58, v144
	v_xad_u32 v136, v136, 64, s58
	ds_read_b128 v[158:161], v137
	ds_read_b128 v[162:165], v137 offset:2048
	ds_read_b128 v[166:169], v136
	ds_read_b128 v[170:173], v136 offset:2048
	v_mov_b32_e32 v136, v143
	v_add_u32_e32 v137, 0, v143
	v_xad_u32 v136, v136, 64, 0
	ds_read_b128 v[174:177], v137
	ds_read_b128 v[178:181], v137 offset:2048
	ds_read_b128 v[192:195], v136
	ds_read_b128 v[196:199], v136 offset:2048
	ds_read_b128 v[200:203], v137 offset:4096
	ds_read_b128 v[204:207], v137 offset:6144
	ds_read_b128 v[208:211], v136 offset:4096
	ds_read_b128 v[212:215], v136 offset:6144
	s_mov_b32 m0, s14
	s_nop 0
	global_load_lds_dwordx4 v138, s[12:13]
	s_mov_b32 m0, s15
	s_nop 0
	global_load_lds_dwordx4 v140, s[12:13]
	s_waitcnt vmcnt(8)
	s_waitcnt lgkmcnt(0)
	s_setprio 1
	s_barrier
; #define PG8_STAGE(bufoff, gbase, voff) do { _Pragma("unroll") for (int _i = 0; _i < 2; ++_i) \
;         dma16((const char*)(gbase), (voff)[_i], ldsb + (bufoff) + ldsw + _i * 8192); } while (0)
; #define PG8_LDA(dst, b, h) do { const int a1_ = opqv(aoff0) ^ 64; _Pragma("unroll") for (int m = 0; m < 4; ++m) { dst[m][0] = *(const LAS bf16x8*)(lds + PG8_SA(b, h) + aoff0 + m * 2048); dst[m][1] = *(const LAS bf16x8*)(lds + PG8_SA(b, h) + a1_ + m * 2048); } } while (0)
; #define PG8_MMA(ai, bj, At, Bt) do { __builtin_amdgcn_s_setprio(1); _Pragma("unroll") for (int m = 0; m < 4; ++m) _Pragma("unroll") for (int n = 0; n < 2; ++n) _Pragma("unroll") for (int k = 0; k < 2; ++k) \
;         acc[ai][bj][m][n] = __builtin_amdgcn_mfma_f32_16x16x32_bf16(Bt[n][k], At[m][k], acc[ai][bj][m][n], 0, 0, 0); __builtin_amdgcn_s_setprio(0); } while (0)
; #define PG8_WAIT_V(n) asm volatile("s_waitcnt vmcnt(" #n ")" ::: "memory")
; #define PG8_WAIT_L(n) asm volatile("s_waitcnt lgkmcnt(" #n ")" ::: "memory")
; #define PG8_BAR __builtin_amdgcn_s_barrier()
; #define PG8_SCHED __builtin_amdgcn_sched_barrier(0)
; template <class Epi>
; __device__ __forceinline__ void gemm_phase(LAS unsigned char* lds, const Gemm g, const StaticOrder& S, const Epi& E, int wave_) {
;     ...
;             PG8_WAIT_V(8); PG8_WAIT_L(0); PG8_BAR; PG8_MMA(0, 0, At, B0); PG8_MMA(0, 1, At, B1); PG8_BAR; PG8_SCHED;
;             PG8_STAGE(PG8_SB(0, 0), b2, voffB); PG8_STAGE(PG8_SB(0, 1), b2 + hstepB, voffB); PG8_STAGE(PG8_SA(0, 0), a2, voffA); PG8_LDA(At, 0, 1);
;             PG8_WAIT_V(8); PG8_WAIT_L(0); PG8_BAR; PG8_MMA(1, 0, At, B0); PG8_MMA(1, 1, At, B1); PG8_BAR; PG8_SCHED;
	v_mfma_f32_16x16x32_bf16 v[124:127], v[128:131], v[174:177], v[124:127]
	v_mfma_f32_16x16x32_bf16 v[120:123], v[146:149], v[174:177], v[120:123]
	v_mfma_f32_16x16x32_bf16 v[108:111], v[128:131], v[178:181], v[108:111]
	v_mfma_f32_16x16x32_bf16 v[104:107], v[146:149], v[178:181], v[104:107]
	v_mfma_f32_16x16x32_bf16 v[92:95], v[128:131], v[200:203], v[92:95]
	v_mfma_f32_16x16x32_bf16 v[88:91], v[146:149], v[200:203], v[88:91]
	v_mfma_f32_16x16x32_bf16 v[76:79], v[128:131], v[204:207], v[76:79]
	v_mfma_f32_16x16x32_bf16 v[72:75], v[146:149], v[204:207], v[72:75]
	v_mfma_f32_16x16x32_bf16 v[124:127], v[150:153], v[192:195], v[124:127]
	v_mfma_f32_16x16x32_bf16 v[120:123], v[154:157], v[192:195], v[120:123]
	v_mfma_f32_16x16x32_bf16 v[108:111], v[150:153], v[196:199], v[108:111]
	v_mfma_f32_16x16x32_bf16 v[104:107], v[154:157], v[196:199], v[104:107]
	v_mfma_f32_16x16x32_bf16 v[92:95], v[150:153], v[208:211], v[92:95]
	v_mfma_f32_16x16x32_bf16 v[88:91], v[154:157], v[208:211], v[88:91]
	v_mfma_f32_16x16x32_bf16 v[76:79], v[150:153], v[212:215], v[76:79]
	v_mfma_f32_16x16x32_bf16 v[72:75], v[154:157], v[212:215], v[72:75]
	s_setprio 0
	s_setprio 1
	v_mfma_f32_16x16x32_bf16 v[116:119], v[158:161], v[174:177], v[116:119]
	v_mfma_f32_16x16x32_bf16 v[112:115], v[162:165], v[174:177], v[112:115]
	v_mfma_f32_16x16x32_bf16 v[100:103], v[158:161], v[178:181], v[100:103]
	v_mfma_f32_16x16x32_bf16 v[96:99], v[162:165], v[178:181], v[96:99]
	v_mfma_f32_16x16x32_bf16 v[84:87], v[158:161], v[200:203], v[84:87]
	v_mfma_f32_16x16x32_bf16 v[80:83], v[162:165], v[200:203], v[80:83]
	v_mfma_f32_16x16x32_bf16 v[68:71], v[158:161], v[204:207], v[68:71]
	v_mfma_f32_16x16x32_bf16 v[64:67], v[162:165], v[204:207], v[64:67]
	v_mfma_f32_16x16x32_bf16 v[116:119], v[166:169], v[192:195], v[116:119]
	v_mfma_f32_16x16x32_bf16 v[112:115], v[170:173], v[192:195], v[112:115]
	v_mfma_f32_16x16x32_bf16 v[100:103], v[166:169], v[196:199], v[100:103]
	v_mfma_f32_16x16x32_bf16 v[96:99], v[170:173], v[196:199], v[96:99]
	v_mfma_f32_16x16x32_bf16 v[84:87], v[166:169], v[208:211], v[84:87]
	v_mfma_f32_16x16x32_bf16 v[80:83], v[170:173], v[208:211], v[80:83]
	v_mfma_f32_16x16x32_bf16 v[68:71], v[166:169], v[212:215], v[68:71]
	v_mfma_f32_16x16x32_bf16 v[64:67], v[170:173], v[212:215], v[64:67]
	s_setprio 0
	s_barrier
	v_mov_b32_e32 v136, v143
	s_add_u32 s58, s30, 0x80000
	s_addc_u32 s59, s31, 0
	s_nop 0
	s_nop 0
	s_nop 0
	v_xad_u32 v136, v136, 64, 0
	ds_read_b128 v[174:177], v137 offset:16384
	ds_read_b128 v[178:181], v137 offset:18432
	ds_read_b128 v[192:195], v136 offset:16384
	ds_read_b128 v[196:199], v136 offset:18432
	ds_read_b128 v[200:203], v137 offset:20480
	ds_read_b128 v[204:207], v137 offset:22528
	ds_read_b128 v[208:211], v136 offset:20480
	ds_read_b128 v[212:215], v136 offset:22528
	s_mov_b32 m0, s80
	s_nop 0
	global_load_lds_dwordx4 v139, s[30:31]
	s_mov_b32 m0, s81
	s_nop 0
	global_load_lds_dwordx4 v141, s[30:31]
	s_mov_b32 m0, s29
	s_nop 0
	global_load_lds_dwordx4 v139, s[58:59]
	s_mov_b32 m0, s88
	s_nop 0
	global_load_lds_dwordx4 v141, s[58:59]
	s_mov_b32 m0, s76
	s_nop 0
	global_load_lds_dwordx4 v138, s[36:37]
	s_mov_b32 m0, s89
	s_nop 0
	global_load_lds_dwordx4 v140, s[36:37]
	s_waitcnt vmcnt(8)
	s_waitcnt lgkmcnt(0)
	s_setprio 1
	s_barrier
	v_mfma_f32_16x16x32_bf16 v[60:63], v[128:131], v[174:177], v[60:63]
	v_mfma_f32_16x16x32_bf16 v[56:59], v[146:149], v[174:177], v[56:59]
	v_mfma_f32_16x16x32_bf16 v[44:47], v[128:131], v[178:181], v[44:47]
	v_mfma_f32_16x16x32_bf16 v[40:43], v[146:149], v[178:181], v[40:43]
	v_mfma_f32_16x16x32_bf16 v[28:31], v[128:131], v[200:203], v[28:31]
	v_mfma_f32_16x16x32_bf16 v[24:27], v[146:149], v[200:203], v[24:27]
	v_mfma_f32_16x16x32_bf16 v[12:15], v[128:131], v[204:207], v[12:15]
	v_mfma_f32_16x16x32_bf16 v[8:11], v[146:149], v[204:207], v[8:11]
	v_mfma_f32_16x16x32_bf16 v[60:63], v[150:153], v[192:195], v[60:63]
	v_mfma_f32_16x16x32_bf16 v[56:59], v[154:157], v[192:195], v[56:59]
	v_mfma_f32_16x16x32_bf16 v[44:47], v[150:153], v[196:199], v[44:47]
	v_mfma_f32_16x16x32_bf16 v[40:43], v[154:157], v[196:199], v[40:43]
	v_mfma_f32_16x16x32_bf16 v[28:31], v[150:153], v[208:211], v[28:31]
	v_mfma_f32_16x16x32_bf16 v[24:27], v[154:157], v[208:211], v[24:27]
	v_mfma_f32_16x16x32_bf16 v[12:15], v[150:153], v[212:215], v[12:15]
	v_mfma_f32_16x16x32_bf16 v[8:11], v[154:157], v[212:215], v[8:11]
	s_setprio 0
	s_setprio 1
	v_mfma_f32_16x16x32_bf16 v[52:55], v[158:161], v[174:177], v[52:55]
	v_mfma_f32_16x16x32_bf16 v[48:51], v[162:165], v[174:177], v[48:51]
	v_mfma_f32_16x16x32_bf16 v[36:39], v[158:161], v[178:181], v[36:39]
	v_mfma_f32_16x16x32_bf16 v[32:35], v[162:165], v[178:181], v[32:35]
	v_mfma_f32_16x16x32_bf16 v[20:23], v[158:161], v[200:203], v[20:23]
	v_mfma_f32_16x16x32_bf16 v[16:19], v[162:165], v[200:203], v[16:19]
	v_mfma_f32_16x16x32_bf16 v[4:7], v[158:161], v[204:207], v[4:7]
	v_mfma_f32_16x16x32_bf16 v[0:3], v[162:165], v[204:207], v[0:3]
	v_mfma_f32_16x16x32_bf16 v[52:55], v[166:169], v[192:195], v[52:55]
	v_mfma_f32_16x16x32_bf16 v[48:51], v[170:173], v[192:195], v[48:51]
	v_mfma_f32_16x16x32_bf16 v[36:39], v[166:169], v[196:199], v[36:39]
	v_mfma_f32_16x16x32_bf16 v[32:35], v[170:173], v[196:199], v[32:35]
	v_mfma_f32_16x16x32_bf16 v[20:23], v[166:169], v[208:211], v[20:23]
	v_mfma_f32_16x16x32_bf16 v[16:19], v[170:173], v[208:211], v[16:19]
	v_mfma_f32_16x16x32_bf16 v[4:7], v[166:169], v[212:215], v[4:7]
	v_mfma_f32_16x16x32_bf16 v[0:3], v[170:173], v[212:215], v[0:3]
	s_setprio 0
	s_barrier
; #define PG8_STAGE(bufoff, gbase, voff) do { _Pragma("unroll") for (int _i = 0; _i < 2; ++_i) \
;         dma16((const char*)(gbase), (voff)[_i], ldsb + (bufoff) + ldsw + _i * 8192); } while (0)
; #define PG8_LDA(dst, b, h) do { const int a1_ = opqv(aoff0) ^ 64; _Pragma("unroll") for (int m = 0; m < 4; ++m) { dst[m][0] = *(const LAS bf16x8*)(lds + PG8_SA(b, h) + aoff0 + m * 2048); dst[m][1] = *(const LAS bf16x8*)(lds + PG8_SA(b, h) + a1_ + m * 2048); } } while (0)
; #define PG8_LDB(dst, b, h) do { const int b1_ = opqv(boff0) ^ 64; _Pragma("unroll") for (int n = 0; n < 2; ++n) { dst[n][0] = *(const LAS bf16x8*)(lds + PG8_SB(b, h) + boff0 + n * 2048); dst[n][1] = *(const LAS bf16x8*)(lds + PG8_SB(b, h) + b1_ + n * 2048); } } while (0)
; #define PG8_MMA(ai, bj, At, Bt) do { __builtin_amdgcn_s_setprio(1); _Pragma("unroll") for (int m = 0; m < 4; ++m) _Pragma("unroll") for (int n = 0; n < 2; ++n) _Pragma("unroll") for (int k = 0; k < 2; ++k) \
;         acc[ai][bj][m][n] = __builtin_amdgcn_mfma_f32_16x16x32_bf16(Bt[n][k], At[m][k], acc[ai][bj][m][n], 0, 0, 0); __builtin_amdgcn_s_setprio(0); } while (0)
; #define PG8_WAIT_V(n) asm volatile("s_waitcnt vmcnt(" #n ")" ::: "memory")
; #define PG8_WAIT_L(n) asm volatile("s_waitcnt lgkmcnt(" #n ")" ::: "memory")
; #define PG8_BAR __builtin_amdgcn_s_barrier()
; #define PG8_SCHED __builtin_amdgcn_sched_barrier(0)
; template <class Epi>
; __device__ __forceinline__ void gemm_phase(LAS unsigned char* lds, const Gemm g, const StaticOrder& S, const Epi& E, int wave_) {
;     ...
;             PG8_STAGE(PG8_SA(0, 1), a2 + hstepA, voffA); PG8_LDB(B0, 1, 0); PG8_LDB(B1, 1, 1); PG8_SCHED; PG8_LDA(At, 1, 0);
;             PG8_WAIT_V(8); PG8_WAIT_L(0); PG8_BAR; PG8_MMA(0, 0, At, B0); PG8_MMA(0, 1, At, B1); PG8_BAR; PG8_SCHED;
;             PG8_STAGE(PG8_SB(1, 0), b3, voffB); PG8_STAGE(PG8_SB(1, 1), b3 + hstepB, voffB); PG8_STAGE(PG8_SA(1, 0), a3, voffA); PG8_LDA(At, 1, 1);
;             PG8_WAIT_V(8); PG8_WAIT_L(0); PG8_BAR; PG8_MMA(1, 0, At, B0); PG8_MMA(1, 1, At, B1); PG8_BAR; PG8_SCHED;
;         }
	s_add_u32 s36, s36, 0x80000
	s_addc_u32 s37, s37, 0
	s_mov_b32 m0, s1
	s_nop 0
	global_load_lds_dwordx4 v138, s[36:37]
	v_mov_b32_e32 v128, v144
	s_mov_b32 m0, s69
	s_nop 0
	global_load_lds_dwordx4 v140, s[36:37]
	v_add_u32_e32 v146, s34, v144
	v_xad_u32 v136, v128, 64, s34
	ds_read_b128 v[128:131], v146
	ds_read_b128 v[146:149], v146 offset:2048
	ds_read_b128 v[150:153], v136
	ds_read_b128 v[154:157], v136 offset:2048
	v_mov_b32_e32 v136, v144
	s_add_i32 s36, 0, 0x1c000
	v_add_u32_e32 v162, s36, v144
	v_xad_u32 v136, v136, 64, s36
	ds_read_b128 v[158:161], v162
	ds_read_b128 v[162:165], v162 offset:2048
	ds_read_b128 v[166:169], v136
	ds_read_b128 v[170:173], v136 offset:2048
	v_mov_b32_e32 v136, v143
	s_nop 0
	v_xad_u32 v136, v136, 64, 0
	ds_read_b128 v[174:177], v137 offset:32768
	ds_read_b128 v[178:181], v137 offset:34816
	ds_read_b128 v[192:195], v136 offset:32768
	ds_read_b128 v[196:199], v136 offset:34816
	ds_read_b128 v[200:203], v137 offset:36864
	ds_read_b128 v[204:207], v137 offset:38912
	ds_read_b128 v[208:211], v136 offset:36864
	ds_read_b128 v[212:215], v136 offset:38912
	s_waitcnt vmcnt(8)
	s_waitcnt lgkmcnt(0)
	s_setprio 1
	s_barrier
	v_mfma_f32_16x16x32_bf16 v[124:127], v[128:131], v[174:177], v[124:127]
	v_mfma_f32_16x16x32_bf16 v[120:123], v[146:149], v[174:177], v[120:123]
	v_mfma_f32_16x16x32_bf16 v[108:111], v[128:131], v[178:181], v[108:111]
	v_mfma_f32_16x16x32_bf16 v[104:107], v[146:149], v[178:181], v[104:107]
	v_mfma_f32_16x16x32_bf16 v[92:95], v[128:131], v[200:203], v[92:95]
	v_mfma_f32_16x16x32_bf16 v[88:91], v[146:149], v[200:203], v[88:91]
	v_mfma_f32_16x16x32_bf16 v[76:79], v[128:131], v[204:207], v[76:79]
	v_mfma_f32_16x16x32_bf16 v[72:75], v[146:149], v[204:207], v[72:75]
	v_mfma_f32_16x16x32_bf16 v[124:127], v[150:153], v[192:195], v[124:127]
	v_mfma_f32_16x16x32_bf16 v[120:123], v[154:157], v[192:195], v[120:123]
	v_mfma_f32_16x16x32_bf16 v[108:111], v[150:153], v[196:199], v[108:111]
	v_mfma_f32_16x16x32_bf16 v[104:107], v[154:157], v[196:199], v[104:107]
	v_mfma_f32_16x16x32_bf16 v[92:95], v[150:153], v[208:211], v[92:95]
	v_mfma_f32_16x16x32_bf16 v[88:91], v[154:157], v[208:211], v[88:91]
	v_mfma_f32_16x16x32_bf16 v[76:79], v[150:153], v[212:215], v[76:79]
	v_mfma_f32_16x16x32_bf16 v[72:75], v[154:157], v[212:215], v[72:75]
	s_setprio 0
	s_setprio 1
	v_mfma_f32_16x16x32_bf16 v[116:119], v[158:161], v[174:177], v[116:119]
	s_add_u32 s36, s30, 0x80
	s_addc_u32 s37, s31, 0
	v_mfma_f32_16x16x32_bf16 v[112:115], v[162:165], v[174:177], v[112:115]
	v_mfma_f32_16x16x32_bf16 v[100:103], v[158:161], v[178:181], v[100:103]
	v_mfma_f32_16x16x32_bf16 v[96:99], v[162:165], v[178:181], v[96:99]
	v_mfma_f32_16x16x32_bf16 v[84:87], v[158:161], v[200:203], v[84:87]
	v_mfma_f32_16x16x32_bf16 v[80:83], v[162:165], v[200:203], v[80:83]
	v_mfma_f32_16x16x32_bf16 v[68:71], v[158:161], v[204:207], v[68:71]
	v_mfma_f32_16x16x32_bf16 v[64:67], v[162:165], v[204:207], v[64:67]
	v_mfma_f32_16x16x32_bf16 v[116:119], v[166:169], v[192:195], v[116:119]
	v_mfma_f32_16x16x32_bf16 v[112:115], v[170:173], v[192:195], v[112:115]
	v_mfma_f32_16x16x32_bf16 v[100:103], v[166:169], v[196:199], v[100:103]
	v_mfma_f32_16x16x32_bf16 v[96:99], v[170:173], v[196:199], v[96:99]
	v_mfma_f32_16x16x32_bf16 v[84:87], v[166:169], v[208:211], v[84:87]
	v_mfma_f32_16x16x32_bf16 v[80:83], v[170:173], v[208:211], v[80:83]
	v_mfma_f32_16x16x32_bf16 v[68:71], v[166:169], v[212:215], v[68:71]
	v_mfma_f32_16x16x32_bf16 v[64:67], v[170:173], v[212:215], v[64:67]
	s_setprio 0
	s_barrier
	s_add_u32 s30, s30, 0x80080
	s_addc_u32 s31, s31, 0
	v_mov_b32_e32 v136, v143
	s_nop 0
	s_nop 0
	v_xad_u32 v136, v136, 64, 0
	ds_read_b128 v[174:177], v137 offset:49152
	ds_read_b128 v[178:181], v137 offset:51200
	ds_read_b128 v[192:195], v136 offset:49152
	ds_read_b128 v[196:199], v136 offset:51200
	ds_read_b128 v[200:203], v137 offset:53248
	ds_read_b128 v[204:207], v137 offset:55296
	ds_read_b128 v[208:211], v136 offset:53248
	ds_read_b128 v[212:215], v136 offset:55296
	s_mov_b32 m0, s35
	s_nop 0
	global_load_lds_dwordx4 v139, s[36:37]
	s_mov_b32 m0, s33
	s_nop 0
	global_load_lds_dwordx4 v141, s[36:37]
	s_mov_b32 m0, s77
	s_nop 0
	global_load_lds_dwordx4 v139, s[30:31]
	s_mov_b32 m0, s3
	s_nop 0
	global_load_lds_dwordx4 v141, s[30:31]
	s_mov_b32 m0, s22
	s_nop 0
	global_load_lds_dwordx4 v138, s[26:27]
	s_mov_b32 m0, s2
	s_nop 0
	global_load_lds_dwordx4 v140, s[26:27]
	s_waitcnt vmcnt(8)
	s_waitcnt lgkmcnt(0)
	s_setprio 1
	s_barrier
	v_mfma_f32_16x16x32_bf16 v[60:63], v[128:131], v[174:177], v[60:63]
	v_mfma_f32_16x16x32_bf16 v[56:59], v[146:149], v[174:177], v[56:59]
	v_mfma_f32_16x16x32_bf16 v[44:47], v[128:131], v[178:181], v[44:47]
	v_mfma_f32_16x16x32_bf16 v[40:43], v[146:149], v[178:181], v[40:43]
	v_mfma_f32_16x16x32_bf16 v[28:31], v[128:131], v[200:203], v[28:31]
	v_mfma_f32_16x16x32_bf16 v[24:27], v[146:149], v[200:203], v[24:27]
	v_mfma_f32_16x16x32_bf16 v[12:15], v[128:131], v[204:207], v[12:15]
	v_mfma_f32_16x16x32_bf16 v[8:11], v[146:149], v[204:207], v[8:11]
	v_mfma_f32_16x16x32_bf16 v[60:63], v[150:153], v[192:195], v[60:63]
	v_mfma_f32_16x16x32_bf16 v[56:59], v[154:157], v[192:195], v[56:59]
	v_mfma_f32_16x16x32_bf16 v[44:47], v[150:153], v[196:199], v[44:47]
	v_mfma_f32_16x16x32_bf16 v[40:43], v[154:157], v[196:199], v[40:43]
	v_mfma_f32_16x16x32_bf16 v[28:31], v[150:153], v[208:211], v[28:31]
	v_mfma_f32_16x16x32_bf16 v[24:27], v[154:157], v[208:211], v[24:27]
	v_mfma_f32_16x16x32_bf16 v[12:15], v[150:153], v[212:215], v[12:15]
	v_mfma_f32_16x16x32_bf16 v[8:11], v[154:157], v[212:215], v[8:11]
	s_setprio 0
	s_setprio 1
	v_mfma_f32_16x16x32_bf16 v[52:55], v[158:161], v[174:177], v[52:55]
	v_mfma_f32_16x16x32_bf16 v[48:51], v[162:165], v[174:177], v[48:51]
	v_mfma_f32_16x16x32_bf16 v[36:39], v[158:161], v[178:181], v[36:39]
	v_mfma_f32_16x16x32_bf16 v[32:35], v[162:165], v[178:181], v[32:35]
	v_mfma_f32_16x16x32_bf16 v[20:23], v[158:161], v[200:203], v[20:23]
	v_mfma_f32_16x16x32_bf16 v[16:19], v[162:165], v[200:203], v[16:19]
	v_mfma_f32_16x16x32_bf16 v[4:7], v[158:161], v[204:207], v[4:7]
	v_mfma_f32_16x16x32_bf16 v[0:3], v[162:165], v[204:207], v[0:3]
	v_mfma_f32_16x16x32_bf16 v[52:55], v[166:169], v[192:195], v[52:55]
	v_mfma_f32_16x16x32_bf16 v[48:51], v[170:173], v[192:195], v[48:51]
	v_mfma_f32_16x16x32_bf16 v[36:39], v[166:169], v[196:199], v[36:39]
	v_mfma_f32_16x16x32_bf16 v[32:35], v[170:173], v[196:199], v[32:35]
	v_mfma_f32_16x16x32_bf16 v[20:23], v[166:169], v[208:211], v[20:23]
	v_mfma_f32_16x16x32_bf16 v[16:19], v[170:173], v[208:211], v[16:19]
	v_mfma_f32_16x16x32_bf16 v[4:7], v[166:169], v[212:215], v[4:7]
	v_mfma_f32_16x16x32_bf16 v[0:3], v[170:173], v[212:215], v[0:3]
	s_setprio 0
	s_barrier
	s_add_i32 s57, s57, 2
	s_add_u32 s52, s52, 0x100
	s_addc_u32 s56, s56, 0
	s_add_u32 s12, s12, 0x100
	s_addc_u32 s13, s13, 0
	s_cmp_gt_u32 s57, 29
	s_cbranch_scc0 .LBB0_574

; #define PG8_STAGE(bufoff, gbase, voff) do { _Pragma("unroll") for (int _i = 0; _i < 2; ++_i) \
;         dma16((const char*)(gbase), (voff)[_i], ldsb + (bufoff) + ldsw + _i * 8192); } while (0)
; #define PG8_LDA(dst, b, h) do { const int a1_ = opqv(aoff0) ^ 64; _Pragma("unroll") for (int m = 0; m < 4; ++m) { dst[m][0] = *(const LAS bf16x8*)(lds + PG8_SA(b, h) + aoff0 + m * 2048); dst[m][1] = *(const LAS bf16x8*)(lds + PG8_SA(b, h) + a1_ + m * 2048); } } while (0)
; #define PG8_LDB(dst, b, h) do { const int b1_ = opqv(boff0) ^ 64; _Pragma("unroll") for (int n = 0; n < 2; ++n) { dst[n][0] = *(const LAS bf16x8*)(lds + PG8_SB(b, h) + boff0 + n * 2048); dst[n][1] = *(const LAS bf16x8*)(lds + PG8_SB(b, h) + b1_ + n * 2048); } } while (0)
; #define PG8_MMA(ai, bj, At, Bt) do { __builtin_amdgcn_s_setprio(1); _Pragma("unroll") for (int m = 0; m < 4; ++m) _Pragma("unroll") for (int n = 0; n < 2; ++n) _Pragma("unroll") for (int k = 0; k < 2; ++k) \
;         acc[ai][bj][m][n] = __builtin_amdgcn_mfma_f32_16x16x32_bf16(Bt[n][k], At[m][k], acc[ai][bj][m][n], 0, 0, 0); __builtin_amdgcn_s_setprio(0); } while (0)
; #define PG8_WAIT_V(n) asm volatile("s_waitcnt vmcnt(" #n ")" ::: "memory")
; #define PG8_BAR __builtin_amdgcn_s_barrier()
; template <class Epi>
; __device__ __forceinline__ void gemm_phase(LAS unsigned char* lds, const Gemm g, const StaticOrder& S, const Epi& E, int wave_) {
;     ...
;         const bool has_next = S.next(ui + 1, nxt);
;         const char* nA = has_next ? (const char*)g.A + (size_t)nxt.pm * tstepA : cA; const char* nB = has_next ? (const char*)g.Bt + (size_t)nxt.pn * tstepB : cB;
; #pragma unroll 1
;         for (int t = 0; t < nt; t += 2) {
;             const bool last = (t == nt - 2);
;             const char* a1 = cA + (size_t)(t + 1) * kstep;
;             const char* a2 = last ? nA : cA + (size_t)(t + 2) * kstep; const char* b2 = last ? nB : cB + (size_t)(t + 2) * kstep;
;             const char* a3 = a2 + kstep; const char* b3 = b2 + kstep;
;             PG8_STAGE(PG8_SA(1, 1), a1 + hstepA, voffA); PG8_LDB(B0, 0, 0); PG8_LDB(B1, 0, 1); PG8_SCHED; PG8_LDA(At, 0, 0);
;             PG8_WAIT_V(8); PG8_WAIT_L(0); PG8_BAR; PG8_MMA(0, 0, At, B0); PG8_MMA(0, 1, At, B1); PG8_BAR; PG8_SCHED;
;             PG8_STAGE(PG8_SB(0, 0), b2, voffB); PG8_STAGE(PG8_SB(0, 1), b2 + hstepB, voffB); PG8_STAGE(PG8_SA(0, 0), a2, voffA); PG8_LDA(At, 0, 1);
.LBB0_743:
	s_ashr_i32 s19, s18, 31
	s_lshl_b64 s[16:17], s[18:19], 19
	s_add_u32 s24, s21, s16
	s_addc_u32 s25, s46, s17
	s_and_b64 s[16:17], s[40:41], exec
	s_cselect_b32 s16, s25, s31
	s_cselect_b32 s17, s24, s30
	s_ashr_i32 s11, s10, 31
	s_lshl_b64 s[26:27], s[10:11], 18
	s_add_u32 s26, s47, s26
	s_addc_u32 s27, s48, s27
	s_and_b64 s[36:37], s[40:41], exec
	s_cselect_b32 s11, s27, s13
	s_cselect_b32 s19, s26, s12
	s_add_u32 s52, s12, 0x100
	s_addc_u32 s56, s13, 0
	s_add_u32 s12, s30, 0x40080
	s_addc_u32 s13, s31, 0
	s_mov_b32 s57, -2
	s_add_u32 s30, s12, 0xfffc0080
	s_addc_u32 s31, s13, -1
	s_cmp_eq_u32 s57, 4
	s_cselect_b32 s42, s17, s30
	s_cselect_b32 s43, s16, s31
	s_cselect_b32 s36, s19, s52
	s_cselect_b32 s37, s11, s56
	s_add_u32 s30, s42, 0x80
	v_mov_b32_e32 v128, v180
	s_addc_u32 s31, s43, 0
	v_add_u32_e32 v132, s23, v180
	v_xad_u32 v144, v128, 64, s23
	v_mov_b32_e32 v148, v180
	s_add_i32 s58, 0, 0x14000
	ds_read_b128 v[128:131], v132
	ds_read_b128 v[132:135], v132 offset:2048
	ds_read_b128 v[140:143], v144
	ds_read_b128 v[144:147], v144 offset:2048
	v_add_u32_e32 v152, s58, v180
	v_xad_u32 v160, v148, 64, s58
	ds_read_b128 v[148:151], v152
	ds_read_b128 v[152:155], v152 offset:2048
	ds_read_b128 v[156:159], v160
	ds_read_b128 v[160:163], v160 offset:2048
	v_mov_b32_e32 v164, v179
	v_add_u32_e32 v182, 0, v179
	v_xad_u32 v172, v164, 64, 0
	ds_read_b128 v[164:167], v182
	ds_read_b128 v[168:171], v182 offset:2048
	ds_read_b128 v[192:195], v172
	ds_read_b128 v[196:199], v172 offset:2048
	ds_read_b128 v[200:203], v182 offset:4096
	ds_read_b128 v[204:207], v182 offset:6144
	ds_read_b128 v[208:211], v172 offset:4096
	ds_read_b128 v[212:215], v172 offset:6144
	s_mov_b32 m0, s14
	s_nop 0
	global_load_lds_dwordx4 v137, s[12:13]
	s_mov_b32 m0, s15
	s_nop 0
	global_load_lds_dwordx4 v176, s[12:13]
	s_waitcnt vmcnt(8)
	s_waitcnt lgkmcnt(0)
	s_setprio 1
	s_barrier
	v_mfma_f32_16x16x32_bf16 v[124:127], v[128:131], v[164:167], 0
	v_mfma_f32_16x16x32_bf16 v[120:123], v[132:135], v[164:167], 0
	v_mfma_f32_16x16x32_bf16 v[108:111], v[128:131], v[168:171], 0
	v_mfma_f32_16x16x32_bf16 v[104:107], v[132:135], v[168:171], 0
	v_mfma_f32_16x16x32_bf16 v[92:95], v[128:131], v[200:203], 0
	v_mfma_f32_16x16x32_bf16 v[88:91], v[132:135], v[200:203], 0
	v_mfma_f32_16x16x32_bf16 v[76:79], v[128:131], v[204:207], 0
	v_mfma_f32_16x16x32_bf16 v[72:75], v[132:135], v[204:207], 0
	v_mfma_f32_16x16x32_bf16 v[124:127], v[140:143], v[192:195], v[124:127]
	v_mfma_f32_16x16x32_bf16 v[120:123], v[144:147], v[192:195], v[120:123]
	v_mfma_f32_16x16x32_bf16 v[108:111], v[140:143], v[196:199], v[108:111]
	v_mfma_f32_16x16x32_bf16 v[104:107], v[144:147], v[196:199], v[104:107]
	v_mfma_f32_16x16x32_bf16 v[92:95], v[140:143], v[208:211], v[92:95]
	v_mfma_f32_16x16x32_bf16 v[88:91], v[144:147], v[208:211], v[88:91]
	v_mfma_f32_16x16x32_bf16 v[76:79], v[140:143], v[212:215], v[76:79]
	v_mfma_f32_16x16x32_bf16 v[72:75], v[144:147], v[212:215], v[72:75]
	s_setprio 0
	s_setprio 1
	v_mfma_f32_16x16x32_bf16 v[116:119], v[148:151], v[164:167], 0
	v_mfma_f32_16x16x32_bf16 v[112:115], v[152:155], v[164:167], 0
	v_mfma_f32_16x16x32_bf16 v[100:103], v[148:151], v[168:171], 0
	v_mfma_f32_16x16x32_bf16 v[96:99], v[152:155], v[168:171], 0
	v_mfma_f32_16x16x32_bf16 v[84:87], v[148:151], v[200:203], 0
	v_mfma_f32_16x16x32_bf16 v[80:83], v[152:155], v[200:203], 0
	v_mfma_f32_16x16x32_bf16 v[68:71], v[148:151], v[204:207], 0
	v_mfma_f32_16x16x32_bf16 v[64:67], v[152:155], v[204:207], 0
	v_mfma_f32_16x16x32_bf16 v[116:119], v[156:159], v[192:195], v[116:119]
	v_mfma_f32_16x16x32_bf16 v[112:115], v[160:163], v[192:195], v[112:115]
	v_mfma_f32_16x16x32_bf16 v[100:103], v[156:159], v[196:199], v[100:103]
	v_mfma_f32_16x16x32_bf16 v[96:99], v[160:163], v[196:199], v[96:99]
	v_mfma_f32_16x16x32_bf16 v[84:87], v[156:159], v[208:211], v[84:87]
	v_mfma_f32_16x16x32_bf16 v[80:83], v[160:163], v[208:211], v[80:83]
	v_mfma_f32_16x16x32_bf16 v[68:71], v[156:159], v[212:215], v[68:71]
	v_mfma_f32_16x16x32_bf16 v[64:67], v[160:163], v[212:215], v[64:67]
	s_setprio 0
	s_barrier
	v_mov_b32_e32 v164, v179
	s_add_u32 s58, s36, 0x20000
	s_addc_u32 s59, s37, 0
	s_nop 0
	s_nop 0
	s_nop 0
	v_xad_u32 v172, v164, 64, 0
	ds_read_b128 v[164:167], v182 offset:16384
	ds_read_b128 v[168:171], v182 offset:18432
	ds_read_b128 v[192:195], v172 offset:16384
	ds_read_b128 v[196:199], v172 offset:18432
	ds_read_b128 v[200:203], v182 offset:20480
	ds_read_b128 v[204:207], v182 offset:22528
	ds_read_b128 v[208:211], v172 offset:20480
	ds_read_b128 v[212:215], v172 offset:22528
	s_mov_b32 m0, s80
	s_nop 0
	global_load_lds_dwordx4 v175, s[36:37]
	s_mov_b32 m0, s81
	s_nop 0
	global_load_lds_dwordx4 v177, s[36:37]
	s_mov_b32 m0, s29
	s_nop 0
	global_load_lds_dwordx4 v175, s[58:59]
	s_mov_b32 m0, s88
	s_nop 0
	global_load_lds_dwordx4 v177, s[58:59]
	s_mov_b32 m0, s76
	s_nop 0
	global_load_lds_dwordx4 v137, s[42:43]
	s_mov_b32 m0, s89
	s_nop 0
	global_load_lds_dwordx4 v176, s[42:43]
	s_waitcnt vmcnt(8)
	s_waitcnt lgkmcnt(0)
	s_setprio 1
	s_barrier
; #define PG8_STAGE(bufoff, gbase, voff) do { _Pragma("unroll") for (int _i = 0; _i < 2; ++_i) \
;         dma16((const char*)(gbase), (voff)[_i], ldsb + (bufoff) + ldsw + _i * 8192); } while (0)
; #define PG8_LDA(dst, b, h) do { const int a1_ = opqv(aoff0) ^ 64; _Pragma("unroll") for (int m = 0; m < 4; ++m) { dst[m][0] = *(const LAS bf16x8*)(lds + PG8_SA(b, h) + aoff0 + m * 2048); dst[m][1] = *(const LAS bf16x8*)(lds + PG8_SA(b, h) + a1_ + m * 2048); } } while (0)
; #define PG8_LDB(dst, b, h) do { const int b1_ = opqv(boff0) ^ 64; _Pragma("unroll") for (int n = 0; n < 2; ++n) { dst[n][0] = *(const LAS bf16x8*)(lds + PG8_SB(b, h) + boff0 + n * 2048); dst[n][1] = *(const LAS bf16x8*)(lds + PG8_SB(b, h) + b1_ + n * 2048); } } while (0)
; #define PG8_MMA(ai, bj, At, Bt) do { __builtin_amdgcn_s_setprio(1); _Pragma("unroll") for (int m = 0; m < 4; ++m) _Pragma("unroll") for (int n = 0; n < 2; ++n) _Pragma("unroll") for (int k = 0; k < 2; ++k) \
;         acc[ai][bj][m][n] = __builtin_amdgcn_mfma_f32_16x16x32_bf16(Bt[n][k], At[m][k], acc[ai][bj][m][n], 0, 0, 0); __builtin_amdgcn_s_setprio(0); } while (0)
; #define PG8_WAIT_V(n) asm volatile("s_waitcnt vmcnt(" #n ")" ::: "memory")
; #define PG8_WAIT_L(n) asm volatile("s_waitcnt lgkmcnt(" #n ")" ::: "memory")
; #define PG8_BAR __builtin_amdgcn_s_barrier()
; #define PG8_SCHED __builtin_amdgcn_sched_barrier(0)
; template <class Epi>
; __device__ __forceinline__ void gemm_phase(LAS unsigned char* lds, const Gemm g, const StaticOrder& S, const Epi& E, int wave_) {
;     ...
;             PG8_WAIT_V(8); PG8_WAIT_L(0); PG8_BAR; PG8_MMA(1, 0, At, B0); PG8_MMA(1, 1, At, B1); PG8_BAR; PG8_SCHED;
;             PG8_STAGE(PG8_SA(0, 1), a2 + hstepA, voffA); PG8_LDB(B0, 1, 0); PG8_LDB(B1, 1, 1); PG8_SCHED; PG8_LDA(At, 1, 0);
;             PG8_WAIT_V(8); PG8_WAIT_L(0); PG8_BAR; PG8_MMA(0, 0, At, B0); PG8_MMA(0, 1, At, B1); PG8_BAR; PG8_SCHED;
	v_mfma_f32_16x16x32_bf16 v[60:63], v[128:131], v[164:167], 0
	v_mfma_f32_16x16x32_bf16 v[56:59], v[132:135], v[164:167], 0
	v_mfma_f32_16x16x32_bf16 v[44:47], v[128:131], v[168:171], 0
	v_mfma_f32_16x16x32_bf16 v[40:43], v[132:135], v[168:171], 0
	v_mfma_f32_16x16x32_bf16 v[28:31], v[128:131], v[200:203], 0
	v_mfma_f32_16x16x32_bf16 v[24:27], v[132:135], v[200:203], 0
	v_mfma_f32_16x16x32_bf16 v[12:15], v[128:131], v[204:207], 0
	v_mfma_f32_16x16x32_bf16 v[8:11], v[132:135], v[204:207], 0
	v_mfma_f32_16x16x32_bf16 v[60:63], v[140:143], v[192:195], v[60:63]
	v_mfma_f32_16x16x32_bf16 v[56:59], v[144:147], v[192:195], v[56:59]
	v_mfma_f32_16x16x32_bf16 v[44:47], v[140:143], v[196:199], v[44:47]
	v_mfma_f32_16x16x32_bf16 v[40:43], v[144:147], v[196:199], v[40:43]
	v_mfma_f32_16x16x32_bf16 v[28:31], v[140:143], v[208:211], v[28:31]
	v_mfma_f32_16x16x32_bf16 v[24:27], v[144:147], v[208:211], v[24:27]
	v_mfma_f32_16x16x32_bf16 v[12:15], v[140:143], v[212:215], v[12:15]
	v_mfma_f32_16x16x32_bf16 v[8:11], v[144:147], v[212:215], v[8:11]
	s_setprio 0
	s_setprio 1
	v_mfma_f32_16x16x32_bf16 v[52:55], v[148:151], v[164:167], 0
	v_mfma_f32_16x16x32_bf16 v[48:51], v[152:155], v[164:167], 0
	v_mfma_f32_16x16x32_bf16 v[36:39], v[148:151], v[168:171], 0
	v_mfma_f32_16x16x32_bf16 v[32:35], v[152:155], v[168:171], 0
	v_mfma_f32_16x16x32_bf16 v[20:23], v[148:151], v[200:203], 0
	v_mfma_f32_16x16x32_bf16 v[16:19], v[152:155], v[200:203], 0
	v_mfma_f32_16x16x32_bf16 v[4:7], v[148:151], v[204:207], 0
	v_mfma_f32_16x16x32_bf16 v[0:3], v[152:155], v[204:207], 0
	v_mfma_f32_16x16x32_bf16 v[52:55], v[156:159], v[192:195], v[52:55]
	v_mfma_f32_16x16x32_bf16 v[48:51], v[160:163], v[192:195], v[48:51]
	v_mfma_f32_16x16x32_bf16 v[36:39], v[156:159], v[196:199], v[36:39]
	v_mfma_f32_16x16x32_bf16 v[32:35], v[160:163], v[196:199], v[32:35]
	v_mfma_f32_16x16x32_bf16 v[20:23], v[156:159], v[208:211], v[20:23]
	v_mfma_f32_16x16x32_bf16 v[16:19], v[160:163], v[208:211], v[16:19]
	v_mfma_f32_16x16x32_bf16 v[4:7], v[156:159], v[212:215], v[4:7]
	v_mfma_f32_16x16x32_bf16 v[0:3], v[160:163], v[212:215], v[0:3]
	s_setprio 0
	s_barrier
	s_add_u32 s42, s42, 0x40000
	s_addc_u32 s43, s43, 0
	s_mov_b32 m0, s1
	s_nop 0
	global_load_lds_dwordx4 v137, s[42:43]
	v_mov_b32_e32 v128, v180
	s_mov_b32 m0, s69
	s_nop 0
	global_load_lds_dwordx4 v176, s[42:43]
	v_add_u32_e32 v132, s34, v180
	v_xad_u32 v144, v128, 64, s34
	v_mov_b32_e32 v148, v180
	s_add_i32 s42, 0, 0x1c000
	ds_read_b128 v[128:131], v132
	ds_read_b128 v[132:135], v132 offset:2048
	ds_read_b128 v[140:143], v144
	ds_read_b128 v[144:147], v144 offset:2048
	v_add_u32_e32 v152, s42, v180
	v_xad_u32 v160, v148, 64, s42
	ds_read_b128 v[148:151], v152
	ds_read_b128 v[152:155], v152 offset:2048
	ds_read_b128 v[156:159], v160
	ds_read_b128 v[160:163], v160 offset:2048
	v_mov_b32_e32 v164, v179
	s_nop 0
	v_xad_u32 v172, v164, 64, 0
	ds_read_b128 v[164:167], v182 offset:32768
	ds_read_b128 v[168:171], v182 offset:34816
	ds_read_b128 v[192:195], v172 offset:32768
	ds_read_b128 v[196:199], v172 offset:34816
	ds_read_b128 v[200:203], v182 offset:36864
	ds_read_b128 v[204:207], v182 offset:38912
	ds_read_b128 v[208:211], v172 offset:36864
	ds_read_b128 v[212:215], v172 offset:38912
	s_waitcnt vmcnt(8)
	s_waitcnt lgkmcnt(0)
	s_setprio 1
	s_barrier
	v_mfma_f32_16x16x32_bf16 v[124:127], v[128:131], v[164:167], v[124:127]
	v_mfma_f32_16x16x32_bf16 v[120:123], v[132:135], v[164:167], v[120:123]
	v_mfma_f32_16x16x32_bf16 v[108:111], v[128:131], v[168:171], v[108:111]
	v_mfma_f32_16x16x32_bf16 v[104:107], v[132:135], v[168:171], v[104:107]
	v_mfma_f32_16x16x32_bf16 v[92:95], v[128:131], v[200:203], v[92:95]
	v_mfma_f32_16x16x32_bf16 v[88:91], v[132:135], v[200:203], v[88:91]
	v_mfma_f32_16x16x32_bf16 v[76:79], v[128:131], v[204:207], v[76:79]
	v_mfma_f32_16x16x32_bf16 v[72:75], v[132:135], v[204:207], v[72:75]
	v_mfma_f32_16x16x32_bf16 v[124:127], v[140:143], v[192:195], v[124:127]
	v_mfma_f32_16x16x32_bf16 v[120:123], v[144:147], v[192:195], v[120:123]
	v_mfma_f32_16x16x32_bf16 v[108:111], v[140:143], v[196:199], v[108:111]
	v_mfma_f32_16x16x32_bf16 v[104:107], v[144:147], v[196:199], v[104:107]
	v_mfma_f32_16x16x32_bf16 v[92:95], v[140:143], v[208:211], v[92:95]
	v_mfma_f32_16x16x32_bf16 v[88:91], v[144:147], v[208:211], v[88:91]
	v_mfma_f32_16x16x32_bf16 v[76:79], v[140:143], v[212:215], v[76:79]
	v_mfma_f32_16x16x32_bf16 v[72:75], v[144:147], v[212:215], v[72:75]
	s_setprio 0
	s_setprio 1
	v_mfma_f32_16x16x32_bf16 v[116:119], v[148:151], v[164:167], v[116:119]
	s_add_u32 s42, s36, 0x80
	s_addc_u32 s43, s37, 0
	v_mfma_f32_16x16x32_bf16 v[112:115], v[152:155], v[164:167], v[112:115]
	v_mfma_f32_16x16x32_bf16 v[100:103], v[148:151], v[168:171], v[100:103]
	v_mfma_f32_16x16x32_bf16 v[96:99], v[152:155], v[168:171], v[96:99]
	v_mfma_f32_16x16x32_bf16 v[84:87], v[148:151], v[200:203], v[84:87]
	v_mfma_f32_16x16x32_bf16 v[80:83], v[152:155], v[200:203], v[80:83]
	v_mfma_f32_16x16x32_bf16 v[68:71], v[148:151], v[204:207], v[68:71]
	v_mfma_f32_16x16x32_bf16 v[64:67], v[152:155], v[204:207], v[64:67]
	v_mfma_f32_16x16x32_bf16 v[116:119], v[156:159], v[192:195], v[116:119]
	v_mfma_f32_16x16x32_bf16 v[112:115], v[160:163], v[192:195], v[112:115]
	v_mfma_f32_16x16x32_bf16 v[100:103], v[156:159], v[196:199], v[100:103]
	v_mfma_f32_16x16x32_bf16 v[96:99], v[160:163], v[196:199], v[96:99]
	v_mfma_f32_16x16x32_bf16 v[84:87], v[156:159], v[208:211], v[84:87]
	v_mfma_f32_16x16x32_bf16 v[80:83], v[160:163], v[208:211], v[80:83]
	v_mfma_f32_16x16x32_bf16 v[68:71], v[156:159], v[212:215], v[68:71]
	v_mfma_f32_16x16x32_bf16 v[64:67], v[160:163], v[212:215], v[64:67]
	s_setprio 0
	s_barrier
; #define PG8_STAGE(bufoff, gbase, voff) do { _Pragma("unroll") for (int _i = 0; _i < 2; ++_i) \
;         dma16((const char*)(gbase), (voff)[_i], ldsb + (bufoff) + ldsw + _i * 8192); } while (0)
; #define PG8_LDA(dst, b, h) do { const int a1_ = opqv(aoff0) ^ 64; _Pragma("unroll") for (int m = 0; m < 4; ++m) { dst[m][0] = *(const LAS bf16x8*)(lds + PG8_SA(b, h) + aoff0 + m * 2048); dst[m][1] = *(const LAS bf16x8*)(lds + PG8_SA(b, h) + a1_ + m * 2048); } } while (0)
; #define PG8_LDB(dst, b, h) do { const int b1_ = opqv(boff0) ^ 64; _Pragma("unroll") for (int n = 0; n < 2; ++n) { dst[n][0] = *(const LAS bf16x8*)(lds + PG8_SB(b, h) + boff0 + n * 2048); dst[n][1] = *(const LAS bf16x8*)(lds + PG8_SB(b, h) + b1_ + n * 2048); } } while (0)
; #define PG8_WAIT_V(n) asm volatile("s_waitcnt vmcnt(" #n ")" ::: "memory")
; template <class Epi>
; __device__ __forceinline__ void gemm_phase(LAS unsigned char* lds, const Gemm g, const StaticOrder& S, const Epi& E, int wave_) {
;     ...
;         for (int t = 0; t < nt; t += 2) {
;             const bool last = (t == nt - 2);
;             const char* a1 = cA + (size_t)(t + 1) * kstep;
;             const char* a2 = last ? nA : cA + (size_t)(t + 2) * kstep; const char* b2 = last ? nB : cB + (size_t)(t + 2) * kstep;
;             const char* a3 = a2 + kstep; const char* b3 = b2 + kstep;
;             PG8_STAGE(PG8_SA(1, 1), a1 + hstepA, voffA); PG8_LDB(B0, 0, 0); PG8_LDB(B1, 0, 1); PG8_SCHED; PG8_LDA(At, 0, 0);
;             PG8_WAIT_V(8); PG8_WAIT_L(0); PG8_BAR; PG8_MMA(0, 0, At, B0); PG8_MMA(0, 1, At, B1); PG8_BAR; PG8_SCHED;
;             PG8_STAGE(PG8_SB(0, 0), b2, voffB); PG8_STAGE(PG8_SB(0, 1), b2 + hstepB, voffB); PG8_STAGE(PG8_SA(0, 0), a2, voffA); PG8_LDA(At, 0, 1);
;             PG8_WAIT_V(8); PG8_WAIT_L(0); PG8_BAR; PG8_MMA(1, 0, At, B0); PG8_MMA(1, 1, At, B1); PG8_BAR; PG8_SCHED;
;             PG8_STAGE(PG8_SA(0, 1), a2 + hstepA, voffA); PG8_LDB(B0, 1, 0); PG8_LDB(B1, 1, 1); PG8_SCHED; PG8_LDA(At, 1, 0);
;             PG8_WAIT_V(8); PG8_WAIT_L(0); PG8_BAR; PG8_MMA(0, 0, At, B0); PG8_MMA(0, 1, At, B1); PG8_BAR; PG8_SCHED;
;             PG8_STAGE(PG8_SB(1, 0), b3, voffB); PG8_STAGE(PG8_SB(1, 1), b3 + hstepB, voffB); PG8_STAGE(PG8_SA(1, 0), a3, voffA); PG8_LDA(At, 1, 1);
;             PG8_WAIT_V(8); PG8_WAIT_L(0); PG8_BAR; PG8_MMA(1, 0, At, B0); PG8_MMA(1, 1, At, B1); PG8_BAR; PG8_SCHED;
	s_add_u32 s36, s36, 0x20080
	s_addc_u32 s37, s37, 0
	v_mov_b32_e32 v164, v179
	s_nop 0
	s_nop 0
	v_xad_u32 v172, v164, 64, 0
	ds_read_b128 v[164:167], v182 offset:49152
	ds_read_b128 v[168:171], v182 offset:51200
	ds_read_b128 v[192:195], v172 offset:49152
	ds_read_b128 v[196:199], v172 offset:51200
	ds_read_b128 v[200:203], v182 offset:53248
	ds_read_b128 v[204:207], v182 offset:55296
	ds_read_b128 v[208:211], v172 offset:53248
	ds_read_b128 v[212:215], v172 offset:55296
	s_mov_b32 m0, s35
	s_nop 0
	global_load_lds_dwordx4 v175, s[42:43]
	s_mov_b32 m0, s33
	s_nop 0
	global_load_lds_dwordx4 v177, s[42:43]
	s_mov_b32 m0, s77
	s_nop 0
	global_load_lds_dwordx4 v175, s[36:37]
	s_mov_b32 m0, s3
	s_nop 0
	global_load_lds_dwordx4 v177, s[36:37]
	s_mov_b32 m0, s22
	s_nop 0
	global_load_lds_dwordx4 v137, s[30:31]
	s_mov_b32 m0, s2
	s_nop 0
	global_load_lds_dwordx4 v176, s[30:31]
	s_waitcnt vmcnt(8)
	s_waitcnt lgkmcnt(0)
	s_setprio 1
	s_barrier
	v_mfma_f32_16x16x32_bf16 v[60:63], v[128:131], v[164:167], v[60:63]
	v_mfma_f32_16x16x32_bf16 v[56:59], v[132:135], v[164:167], v[56:59]
	v_mfma_f32_16x16x32_bf16 v[44:47], v[128:131], v[168:171], v[44:47]
	v_mfma_f32_16x16x32_bf16 v[40:43], v[132:135], v[168:171], v[40:43]
	v_mfma_f32_16x16x32_bf16 v[28:31], v[128:131], v[200:203], v[28:31]
	v_mfma_f32_16x16x32_bf16 v[24:27], v[132:135], v[200:203], v[24:27]
	v_mfma_f32_16x16x32_bf16 v[12:15], v[128:131], v[204:207], v[12:15]
	v_mfma_f32_16x16x32_bf16 v[8:11], v[132:135], v[204:207], v[8:11]
	v_mfma_f32_16x16x32_bf16 v[60:63], v[140:143], v[192:195], v[60:63]
	v_mfma_f32_16x16x32_bf16 v[56:59], v[144:147], v[192:195], v[56:59]
	v_mfma_f32_16x16x32_bf16 v[44:47], v[140:143], v[196:199], v[44:47]
	v_mfma_f32_16x16x32_bf16 v[40:43], v[144:147], v[196:199], v[40:43]
	v_mfma_f32_16x16x32_bf16 v[28:31], v[140:143], v[208:211], v[28:31]
	v_mfma_f32_16x16x32_bf16 v[24:27], v[144:147], v[208:211], v[24:27]
	v_mfma_f32_16x16x32_bf16 v[12:15], v[140:143], v[212:215], v[12:15]
	v_mfma_f32_16x16x32_bf16 v[8:11], v[144:147], v[212:215], v[8:11]
	s_setprio 0
	s_setprio 1
	v_mfma_f32_16x16x32_bf16 v[52:55], v[148:151], v[164:167], v[52:55]
	v_mfma_f32_16x16x32_bf16 v[48:51], v[152:155], v[164:167], v[48:51]
	v_mfma_f32_16x16x32_bf16 v[36:39], v[148:151], v[168:171], v[36:39]
	v_mfma_f32_16x16x32_bf16 v[32:35], v[152:155], v[168:171], v[32:35]
	v_mfma_f32_16x16x32_bf16 v[20:23], v[148:151], v[200:203], v[20:23]
	v_mfma_f32_16x16x32_bf16 v[16:19], v[152:155], v[200:203], v[16:19]
	v_mfma_f32_16x16x32_bf16 v[4:7], v[148:151], v[204:207], v[4:7]
	v_mfma_f32_16x16x32_bf16 v[0:3], v[152:155], v[204:207], v[0:3]
	v_mfma_f32_16x16x32_bf16 v[52:55], v[156:159], v[192:195], v[52:55]
	v_mfma_f32_16x16x32_bf16 v[48:51], v[160:163], v[192:195], v[48:51]
	v_mfma_f32_16x16x32_bf16 v[36:39], v[156:159], v[196:199], v[36:39]
	v_mfma_f32_16x16x32_bf16 v[32:35], v[160:163], v[196:199], v[32:35]
	v_mfma_f32_16x16x32_bf16 v[20:23], v[156:159], v[208:211], v[20:23]
	v_mfma_f32_16x16x32_bf16 v[16:19], v[160:163], v[208:211], v[16:19]
	v_mfma_f32_16x16x32_bf16 v[4:7], v[156:159], v[212:215], v[4:7]
	v_mfma_f32_16x16x32_bf16 v[0:3], v[160:163], v[212:215], v[0:3]
	s_setprio 0
	s_barrier
	s_add_i32 s57, s57, 2
	s_add_u32 s52, s52, 0x100
	s_addc_u32 s56, s56, 0
	s_add_u32 s12, s12, 0x100
	s_addc_u32 s13, s13, 0
	s_cmp_gt_u32 s57, 5
	s_cbranch_scc0 .LBB0_744
	s_branch .Lpeel_exit_6
.LBB0_744:
	s_add_u32 s30, s12, 0xfffc0080
	s_addc_u32 s31, s13, -1
	s_cmp_eq_u32 s57, 4
	s_cselect_b32 s42, s17, s30
	s_cselect_b32 s43, s16, s31
	s_cselect_b32 s36, s19, s52
	s_cselect_b32 s37, s11, s56
	s_add_u32 s30, s42, 0x80
	v_mov_b32_e32 v128, v180
	s_addc_u32 s31, s43, 0
	v_add_u32_e32 v132, s23, v180
	v_xad_u32 v144, v128, 64, s23
	v_mov_b32_e32 v148, v180
	s_add_i32 s58, 0, 0x14000
	ds_read_b128 v[128:131], v132
	ds_read_b128 v[132:135], v132 offset:2048
	ds_read_b128 v[140:143], v144
	ds_read_b128 v[144:147], v144 offset:2048
	v_add_u32_e32 v152, s58, v180
	v_xad_u32 v160, v148, 64, s58
	ds_read_b128 v[148:151], v152
	ds_read_b128 v[152:155], v152 offset:2048
	ds_read_b128 v[156:159], v160
	ds_read_b128 v[160:163], v160 offset:2048
	v_mov_b32_e32 v164, v179
	v_add_u32_e32 v182, 0, v179
	v_xad_u32 v172, v164, 64, 0
	ds_read_b128 v[164:167], v182
	ds_read_b128 v[168:171], v182 offset:2048
	ds_read_b128 v[192:195], v172
	ds_read_b128 v[196:199], v172 offset:2048
	ds_read_b128 v[200:203], v182 offset:4096
	ds_read_b128 v[204:207], v182 offset:6144
	ds_read_b128 v[208:211], v172 offset:4096
	ds_read_b128 v[212:215], v172 offset:6144
	s_mov_b32 m0, s14
	s_nop 0
	global_load_lds_dwordx4 v137, s[12:13]
	s_mov_b32 m0, s15
	s_nop 0
	global_load_lds_dwordx4 v176, s[12:13]
	s_waitcnt vmcnt(8)
	s_waitcnt lgkmcnt(0)
	s_setprio 1
	s_barrier
; #define PG8_STAGE(bufoff, gbase, voff) do { _Pragma("unroll") for (int _i = 0; _i < 2; ++_i) \
;         dma16((const char*)(gbase), (voff)[_i], ldsb + (bufoff) + ldsw + _i * 8192); } while (0)
; #define PG8_LDA(dst, b, h) do { const int a1_ = opqv(aoff0) ^ 64; _Pragma("unroll") for (int m = 0; m < 4; ++m) { dst[m][0] = *(const LAS bf16x8*)(lds + PG8_SA(b, h) + aoff0 + m * 2048); dst[m][1] = *(const LAS bf16x8*)(lds + PG8_SA(b, h) + a1_ + m * 2048); } } while (0)
; #define PG8_MMA(ai, bj, At, Bt) do { __builtin_amdgcn_s_setprio(1); _Pragma("unroll") for (int m = 0; m < 4; ++m) _Pragma("unroll") for (int n = 0; n < 2; ++n) _Pragma("unroll") for (int k = 0; k < 2; ++k) \
;         acc[ai][bj][m][n] = __builtin_amdgcn_mfma_f32_16x16x32_bf16(Bt[n][k], At[m][k], acc[ai][bj][m][n], 0, 0, 0); __builtin_amdgcn_s_setprio(0); } while (0)
; #define PG8_WAIT_V(n) asm volatile("s_waitcnt vmcnt(" #n ")" ::: "memory")
; #define PG8_WAIT_L(n) asm volatile("s_waitcnt lgkmcnt(" #n ")" ::: "memory")
; #define PG8_BAR __builtin_amdgcn_s_barrier()
; #define PG8_SCHED __builtin_amdgcn_sched_barrier(0)
; template <class Epi>
; __device__ __forceinline__ void gemm_phase(LAS unsigned char* lds, const Gemm g, const StaticOrder& S, const Epi& E, int wave_) {
;     ...
;             PG8_WAIT_V(8); PG8_WAIT_L(0); PG8_BAR; PG8_MMA(0, 0, At, B0); PG8_MMA(0, 1, At, B1); PG8_BAR; PG8_SCHED;
;             PG8_STAGE(PG8_SB(0, 0), b2, voffB); PG8_STAGE(PG8_SB(0, 1), b2 + hstepB, voffB); PG8_STAGE(PG8_SA(0, 0), a2, voffA); PG8_LDA(At, 0, 1);
;             PG8_WAIT_V(8); PG8_WAIT_L(0); PG8_BAR; PG8_MMA(1, 0, At, B0); PG8_MMA(1, 1, At, B1); PG8_BAR; PG8_SCHED;
	v_mfma_f32_16x16x32_bf16 v[124:127], v[128:131], v[164:167], v[124:127]
	v_mfma_f32_16x16x32_bf16 v[120:123], v[132:135], v[164:167], v[120:123]
	v_mfma_f32_16x16x32_bf16 v[108:111], v[128:131], v[168:171], v[108:111]
	v_mfma_f32_16x16x32_bf16 v[104:107], v[132:135], v[168:171], v[104:107]
	v_mfma_f32_16x16x32_bf16 v[92:95], v[128:131], v[200:203], v[92:95]
	v_mfma_f32_16x16x32_bf16 v[88:91], v[132:135], v[200:203], v[88:91]
	v_mfma_f32_16x16x32_bf16 v[76:79], v[128:131], v[204:207], v[76:79]
	v_mfma_f32_16x16x32_bf16 v[72:75], v[132:135], v[204:207], v[72:75]
	v_mfma_f32_16x16x32_bf16 v[124:127], v[140:143], v[192:195], v[124:127]
	v_mfma_f32_16x16x32_bf16 v[120:123], v[144:147], v[192:195], v[120:123]
	v_mfma_f32_16x16x32_bf16 v[108:111], v[140:143], v[196:199], v[108:111]
	v_mfma_f32_16x16x32_bf16 v[104:107], v[144:147], v[196:199], v[104:107]
	v_mfma_f32_16x16x32_bf16 v[92:95], v[140:143], v[208:211], v[92:95]
	v_mfma_f32_16x16x32_bf16 v[88:91], v[144:147], v[208:211], v[88:91]
	v_mfma_f32_16x16x32_bf16 v[76:79], v[140:143], v[212:215], v[76:79]
	v_mfma_f32_16x16x32_bf16 v[72:75], v[144:147], v[212:215], v[72:75]
	s_setprio 0
	s_setprio 1
	v_mfma_f32_16x16x32_bf16 v[116:119], v[148:151], v[164:167], v[116:119]
	v_mfma_f32_16x16x32_bf16 v[112:115], v[152:155], v[164:167], v[112:115]
	v_mfma_f32_16x16x32_bf16 v[100:103], v[148:151], v[168:171], v[100:103]
	v_mfma_f32_16x16x32_bf16 v[96:99], v[152:155], v[168:171], v[96:99]
	v_mfma_f32_16x16x32_bf16 v[84:87], v[148:151], v[200:203], v[84:87]
	v_mfma_f32_16x16x32_bf16 v[80:83], v[152:155], v[200:203], v[80:83]
	v_mfma_f32_16x16x32_bf16 v[68:71], v[148:151], v[204:207], v[68:71]
	v_mfma_f32_16x16x32_bf16 v[64:67], v[152:155], v[204:207], v[64:67]
	v_mfma_f32_16x16x32_bf16 v[116:119], v[156:159], v[192:195], v[116:119]
	v_mfma_f32_16x16x32_bf16 v[112:115], v[160:163], v[192:195], v[112:115]
	v_mfma_f32_16x16x32_bf16 v[100:103], v[156:159], v[196:199], v[100:103]
	v_mfma_f32_16x16x32_bf16 v[96:99], v[160:163], v[196:199], v[96:99]
	v_mfma_f32_16x16x32_bf16 v[84:87], v[156:159], v[208:211], v[84:87]
	v_mfma_f32_16x16x32_bf16 v[80:83], v[160:163], v[208:211], v[80:83]
	v_mfma_f32_16x16x32_bf16 v[68:71], v[156:159], v[212:215], v[68:71]
	v_mfma_f32_16x16x32_bf16 v[64:67], v[160:163], v[212:215], v[64:67]
	s_setprio 0
	s_barrier
	v_mov_b32_e32 v164, v179
	s_add_u32 s58, s36, 0x20000
	s_addc_u32 s59, s37, 0
	s_nop 0
	s_nop 0
	s_nop 0
	v_xad_u32 v172, v164, 64, 0
	ds_read_b128 v[164:167], v182 offset:16384
	ds_read_b128 v[168:171], v182 offset:18432
	ds_read_b128 v[192:195], v172 offset:16384
	ds_read_b128 v[196:199], v172 offset:18432
	ds_read_b128 v[200:203], v182 offset:20480
	ds_read_b128 v[204:207], v182 offset:22528
	ds_read_b128 v[208:211], v172 offset:20480
	ds_read_b128 v[212:215], v172 offset:22528
	s_mov_b32 m0, s80
	s_nop 0
	global_load_lds_dwordx4 v175, s[36:37]
	s_mov_b32 m0, s81
	s_nop 0
	global_load_lds_dwordx4 v177, s[36:37]
	s_mov_b32 m0, s29
	s_nop 0
	global_load_lds_dwordx4 v175, s[58:59]
	s_mov_b32 m0, s88
	s_nop 0
	global_load_lds_dwordx4 v177, s[58:59]
	s_mov_b32 m0, s76
	s_nop 0
	global_load_lds_dwordx4 v137, s[42:43]
	s_mov_b32 m0, s89
	s_nop 0
	global_load_lds_dwordx4 v176, s[42:43]
	s_waitcnt vmcnt(8)
	s_waitcnt lgkmcnt(0)
	s_setprio 1
	s_barrier
	v_mfma_f32_16x16x32_bf16 v[60:63], v[128:131], v[164:167], v[60:63]
	v_mfma_f32_16x16x32_bf16 v[56:59], v[132:135], v[164:167], v[56:59]
	v_mfma_f32_16x16x32_bf16 v[44:47], v[128:131], v[168:171], v[44:47]
	v_mfma_f32_16x16x32_bf16 v[40:43], v[132:135], v[168:171], v[40:43]
	v_mfma_f32_16x16x32_bf16 v[28:31], v[128:131], v[200:203], v[28:31]
	v_mfma_f32_16x16x32_bf16 v[24:27], v[132:135], v[200:203], v[24:27]
	v_mfma_f32_16x16x32_bf16 v[12:15], v[128:131], v[204:207], v[12:15]
	v_mfma_f32_16x16x32_bf16 v[8:11], v[132:135], v[204:207], v[8:11]
	v_mfma_f32_16x16x32_bf16 v[60:63], v[140:143], v[192:195], v[60:63]
	v_mfma_f32_16x16x32_bf16 v[56:59], v[144:147], v[192:195], v[56:59]
	v_mfma_f32_16x16x32_bf16 v[44:47], v[140:143], v[196:199], v[44:47]
	v_mfma_f32_16x16x32_bf16 v[40:43], v[144:147], v[196:199], v[40:43]
	v_mfma_f32_16x16x32_bf16 v[28:31], v[140:143], v[208:211], v[28:31]
	v_mfma_f32_16x16x32_bf16 v[24:27], v[144:147], v[208:211], v[24:27]
	v_mfma_f32_16x16x32_bf16 v[12:15], v[140:143], v[212:215], v[12:15]
	v_mfma_f32_16x16x32_bf16 v[8:11], v[144:147], v[212:215], v[8:11]
	s_setprio 0
	s_setprio 1
	v_mfma_f32_16x16x32_bf16 v[52:55], v[148:151], v[164:167], v[52:55]
	v_mfma_f32_16x16x32_bf16 v[48:51], v[152:155], v[164:167], v[48:51]
	v_mfma_f32_16x16x32_bf16 v[36:39], v[148:151], v[168:171], v[36:39]
	v_mfma_f32_16x16x32_bf16 v[32:35], v[152:155], v[168:171], v[32:35]
	v_mfma_f32_16x16x32_bf16 v[20:23], v[148:151], v[200:203], v[20:23]
	v_mfma_f32_16x16x32_bf16 v[16:19], v[152:155], v[200:203], v[16:19]
	v_mfma_f32_16x16x32_bf16 v[4:7], v[148:151], v[204:207], v[4:7]
	v_mfma_f32_16x16x32_bf16 v[0:3], v[152:155], v[204:207], v[0:3]
	v_mfma_f32_16x16x32_bf16 v[52:55], v[156:159], v[192:195], v[52:55]
	v_mfma_f32_16x16x32_bf16 v[48:51], v[160:163], v[192:195], v[48:51]
	v_mfma_f32_16x16x32_bf16 v[36:39], v[156:159], v[196:199], v[36:39]
	v_mfma_f32_16x16x32_bf16 v[32:35], v[160:163], v[196:199], v[32:35]
	v_mfma_f32_16x16x32_bf16 v[20:23], v[156:159], v[208:211], v[20:23]
	v_mfma_f32_16x16x32_bf16 v[16:19], v[160:163], v[208:211], v[16:19]
	v_mfma_f32_16x16x32_bf16 v[4:7], v[156:159], v[212:215], v[4:7]
	v_mfma_f32_16x16x32_bf16 v[0:3], v[160:163], v[212:215], v[0:3]
	s_setprio 0
	s_barrier
; #define PG8_STAGE(bufoff, gbase, voff) do { _Pragma("unroll") for (int _i = 0; _i < 2; ++_i) \
;         dma16((const char*)(gbase), (voff)[_i], ldsb + (bufoff) + ldsw + _i * 8192); } while (0)
; #define PG8_LDA(dst, b, h) do { const int a1_ = opqv(aoff0) ^ 64; _Pragma("unroll") for (int m = 0; m < 4; ++m) { dst[m][0] = *(const LAS bf16x8*)(lds + PG8_SA(b, h) + aoff0 + m * 2048); dst[m][1] = *(const LAS bf16x8*)(lds + PG8_SA(b, h) + a1_ + m * 2048); } } while (0)
; #define PG8_LDB(dst, b, h) do { const int b1_ = opqv(boff0) ^ 64; _Pragma("unroll") for (int n = 0; n < 2; ++n) { dst[n][0] = *(const LAS bf16x8*)(lds + PG8_SB(b, h) + boff0 + n * 2048); dst[n][1] = *(const LAS bf16x8*)(lds + PG8_SB(b, h) + b1_ + n * 2048); } } while (0)
; #define PG8_MMA(ai, bj, At, Bt) do { __builtin_amdgcn_s_setprio(1); _Pragma("unroll") for (int m = 0; m < 4; ++m) _Pragma("unroll") for (int n = 0; n < 2; ++n) _Pragma("unroll") for (int k = 0; k < 2; ++k) \
;         acc[ai][bj][m][n] = __builtin_amdgcn_mfma_f32_16x16x32_bf16(Bt[n][k], At[m][k], acc[ai][bj][m][n], 0, 0, 0); __builtin_amdgcn_s_setprio(0); } while (0)
; #define PG8_WAIT_V(n) asm volatile("s_waitcnt vmcnt(" #n ")" ::: "memory")
; #define PG8_WAIT_L(n) asm volatile("s_waitcnt lgkmcnt(" #n ")" ::: "memory")
; #define PG8_BAR __builtin_amdgcn_s_barrier()
; #define PG8_SCHED __builtin_amdgcn_sched_barrier(0)
; template <class Epi>
; __device__ __forceinline__ void gemm_phase(LAS unsigned char* lds, const Gemm g, const StaticOrder& S, const Epi& E, int wave_) {
;     ...
;             PG8_STAGE(PG8_SA(0, 1), a2 + hstepA, voffA); PG8_LDB(B0, 1, 0); PG8_LDB(B1, 1, 1); PG8_SCHED; PG8_LDA(At, 1, 0);
;             PG8_WAIT_V(8); PG8_WAIT_L(0); PG8_BAR; PG8_MMA(0, 0, At, B0); PG8_MMA(0, 1, At, B1); PG8_BAR; PG8_SCHED;
;             PG8_STAGE(PG8_SB(1, 0), b3, voffB); PG8_STAGE(PG8_SB(1, 1), b3 + hstepB, voffB); PG8_STAGE(PG8_SA(1, 0), a3, voffA); PG8_LDA(At, 1, 1);
;             PG8_WAIT_V(8); PG8_WAIT_L(0); PG8_BAR; PG8_MMA(1, 0, At, B0); PG8_MMA(1, 1, At, B1); PG8_BAR; PG8_SCHED;
;         }
	s_add_u32 s42, s42, 0x40000
	s_addc_u32 s43, s43, 0
	s_mov_b32 m0, s1
	s_nop 0
	global_load_lds_dwordx4 v137, s[42:43]
	v_mov_b32_e32 v128, v180
	s_mov_b32 m0, s69
	s_nop 0
	global_load_lds_dwordx4 v176, s[42:43]
	v_add_u32_e32 v132, s34, v180
	v_xad_u32 v144, v128, 64, s34
	v_mov_b32_e32 v148, v180
	s_add_i32 s42, 0, 0x1c000
	ds_read_b128 v[128:131], v132
	ds_read_b128 v[132:135], v132 offset:2048
	ds_read_b128 v[140:143], v144
	ds_read_b128 v[144:147], v144 offset:2048
	v_add_u32_e32 v152, s42, v180
	v_xad_u32 v160, v148, 64, s42
	ds_read_b128 v[148:151], v152
	ds_read_b128 v[152:155], v152 offset:2048
	ds_read_b128 v[156:159], v160
	ds_read_b128 v[160:163], v160 offset:2048
	v_mov_b32_e32 v164, v179
	s_nop 0
	v_xad_u32 v172, v164, 64, 0
	ds_read_b128 v[164:167], v182 offset:32768
	ds_read_b128 v[168:171], v182 offset:34816
	ds_read_b128 v[192:195], v172 offset:32768
	ds_read_b128 v[196:199], v172 offset:34816
	ds_read_b128 v[200:203], v182 offset:36864
	ds_read_b128 v[204:207], v182 offset:38912
	ds_read_b128 v[208:211], v172 offset:36864
	ds_read_b128 v[212:215], v172 offset:38912
	s_waitcnt vmcnt(8)
	s_waitcnt lgkmcnt(0)
	s_setprio 1
	s_barrier
	v_mfma_f32_16x16x32_bf16 v[124:127], v[128:131], v[164:167], v[124:127]
	v_mfma_f32_16x16x32_bf16 v[120:123], v[132:135], v[164:167], v[120:123]
	v_mfma_f32_16x16x32_bf16 v[108:111], v[128:131], v[168:171], v[108:111]
	v_mfma_f32_16x16x32_bf16 v[104:107], v[132:135], v[168:171], v[104:107]
	v_mfma_f32_16x16x32_bf16 v[92:95], v[128:131], v[200:203], v[92:95]
	v_mfma_f32_16x16x32_bf16 v[88:91], v[132:135], v[200:203], v[88:91]
	v_mfma_f32_16x16x32_bf16 v[76:79], v[128:131], v[204:207], v[76:79]
	v_mfma_f32_16x16x32_bf16 v[72:75], v[132:135], v[204:207], v[72:75]
	v_mfma_f32_16x16x32_bf16 v[124:127], v[140:143], v[192:195], v[124:127]
	v_mfma_f32_16x16x32_bf16 v[120:123], v[144:147], v[192:195], v[120:123]
	v_mfma_f32_16x16x32_bf16 v[108:111], v[140:143], v[196:199], v[108:111]
	v_mfma_f32_16x16x32_bf16 v[104:107], v[144:147], v[196:199], v[104:107]
	v_mfma_f32_16x16x32_bf16 v[92:95], v[140:143], v[208:211], v[92:95]
	v_mfma_f32_16x16x32_bf16 v[88:91], v[144:147], v[208:211], v[88:91]
	v_mfma_f32_16x16x32_bf16 v[76:79], v[140:143], v[212:215], v[76:79]
	v_mfma_f32_16x16x32_bf16 v[72:75], v[144:147], v[212:215], v[72:75]
	s_setprio 0
	s_setprio 1
	v_mfma_f32_16x16x32_bf16 v[116:119], v[148:151], v[164:167], v[116:119]
	s_add_u32 s42, s36, 0x80
	s_addc_u32 s43, s37, 0
	v_mfma_f32_16x16x32_bf16 v[112:115], v[152:155], v[164:167], v[112:115]
	v_mfma_f32_16x16x32_bf16 v[100:103], v[148:151], v[168:171], v[100:103]
	v_mfma_f32_16x16x32_bf16 v[96:99], v[152:155], v[168:171], v[96:99]
	v_mfma_f32_16x16x32_bf16 v[84:87], v[148:151], v[200:203], v[84:87]
	v_mfma_f32_16x16x32_bf16 v[80:83], v[152:155], v[200:203], v[80:83]
	v_mfma_f32_16x16x32_bf16 v[68:71], v[148:151], v[204:207], v[68:71]
	v_mfma_f32_16x16x32_bf16 v[64:67], v[152:155], v[204:207], v[64:67]
	v_mfma_f32_16x16x32_bf16 v[116:119], v[156:159], v[192:195], v[116:119]
	v_mfma_f32_16x16x32_bf16 v[112:115], v[160:163], v[192:195], v[112:115]
	v_mfma_f32_16x16x32_bf16 v[100:103], v[156:159], v[196:199], v[100:103]
	v_mfma_f32_16x16x32_bf16 v[96:99], v[160:163], v[196:199], v[96:99]
	v_mfma_f32_16x16x32_bf16 v[84:87], v[156:159], v[208:211], v[84:87]
	v_mfma_f32_16x16x32_bf16 v[80:83], v[160:163], v[208:211], v[80:83]
	v_mfma_f32_16x16x32_bf16 v[68:71], v[156:159], v[212:215], v[68:71]
	v_mfma_f32_16x16x32_bf16 v[64:67], v[160:163], v[212:215], v[64:67]
	s_setprio 0
	s_barrier
	s_add_u32 s36, s36, 0x20080
	s_addc_u32 s37, s37, 0
	v_mov_b32_e32 v164, v179
	s_nop 0
	s_nop 0
	v_xad_u32 v172, v164, 64, 0
	ds_read_b128 v[164:167], v182 offset:49152
	ds_read_b128 v[168:171], v182 offset:51200
	ds_read_b128 v[192:195], v172 offset:49152
	ds_read_b128 v[196:199], v172 offset:51200
	ds_read_b128 v[200:203], v182 offset:53248
	ds_read_b128 v[204:207], v182 offset:55296
	ds_read_b128 v[208:211], v172 offset:53248
	ds_read_b128 v[212:215], v172 offset:55296
	s_mov_b32 m0, s35
	s_nop 0
	global_load_lds_dwordx4 v175, s[42:43]
	s_mov_b32 m0, s33
	s_nop 0
	global_load_lds_dwordx4 v177, s[42:43]
	s_mov_b32 m0, s77
	s_nop 0
	global_load_lds_dwordx4 v175, s[36:37]
	s_mov_b32 m0, s3
	s_nop 0
	global_load_lds_dwordx4 v177, s[36:37]
	s_mov_b32 m0, s22
	s_nop 0
	global_load_lds_dwordx4 v137, s[30:31]
	s_mov_b32 m0, s2
	s_nop 0
	global_load_lds_dwordx4 v176, s[30:31]
	s_waitcnt vmcnt(8)
	s_waitcnt lgkmcnt(0)
	s_setprio 1
	s_barrier
	v_mfma_f32_16x16x32_bf16 v[60:63], v[128:131], v[164:167], v[60:63]
	v_mfma_f32_16x16x32_bf16 v[56:59], v[132:135], v[164:167], v[56:59]
	v_mfma_f32_16x16x32_bf16 v[44:47], v[128:131], v[168:171], v[44:47]
	v_mfma_f32_16x16x32_bf16 v[40:43], v[132:135], v[168:171], v[40:43]
	v_mfma_f32_16x16x32_bf16 v[28:31], v[128:131], v[200:203], v[28:31]
	v_mfma_f32_16x16x32_bf16 v[24:27], v[132:135], v[200:203], v[24:27]
	v_mfma_f32_16x16x32_bf16 v[12:15], v[128:131], v[204:207], v[12:15]
	v_mfma_f32_16x16x32_bf16 v[8:11], v[132:135], v[204:207], v[8:11]
	v_mfma_f32_16x16x32_bf16 v[60:63], v[140:143], v[192:195], v[60:63]
	v_mfma_f32_16x16x32_bf16 v[56:59], v[144:147], v[192:195], v[56:59]
	v_mfma_f32_16x16x32_bf16 v[44:47], v[140:143], v[196:199], v[44:47]
	v_mfma_f32_16x16x32_bf16 v[40:43], v[144:147], v[196:199], v[40:43]
	v_mfma_f32_16x16x32_bf16 v[28:31], v[140:143], v[208:211], v[28:31]
	v_mfma_f32_16x16x32_bf16 v[24:27], v[144:147], v[208:211], v[24:27]
	v_mfma_f32_16x16x32_bf16 v[12:15], v[140:143], v[212:215], v[12:15]
	v_mfma_f32_16x16x32_bf16 v[8:11], v[144:147], v[212:215], v[8:11]
	s_setprio 0
	s_setprio 1
	v_mfma_f32_16x16x32_bf16 v[52:55], v[148:151], v[164:167], v[52:55]
	v_mfma_f32_16x16x32_bf16 v[48:51], v[152:155], v[164:167], v[48:51]
	v_mfma_f32_16x16x32_bf16 v[36:39], v[148:151], v[168:171], v[36:39]
	v_mfma_f32_16x16x32_bf16 v[32:35], v[152:155], v[168:171], v[32:35]
	v_mfma_f32_16x16x32_bf16 v[20:23], v[148:151], v[200:203], v[20:23]
	v_mfma_f32_16x16x32_bf16 v[16:19], v[152:155], v[200:203], v[16:19]
	v_mfma_f32_16x16x32_bf16 v[4:7], v[148:151], v[204:207], v[4:7]
	v_mfma_f32_16x16x32_bf16 v[0:3], v[152:155], v[204:207], v[0:3]
	v_mfma_f32_16x16x32_bf16 v[52:55], v[156:159], v[192:195], v[52:55]
	v_mfma_f32_16x16x32_bf16 v[48:51], v[160:163], v[192:195], v[48:51]
	v_mfma_f32_16x16x32_bf16 v[36:39], v[156:159], v[196:199], v[36:39]
	v_mfma_f32_16x16x32_bf16 v[32:35], v[160:163], v[196:199], v[32:35]
	v_mfma_f32_16x16x32_bf16 v[20:23], v[156:159], v[208:211], v[20:23]
	v_mfma_f32_16x16x32_bf16 v[16:19], v[160:163], v[208:211], v[16:19]
	v_mfma_f32_16x16x32_bf16 v[4:7], v[156:159], v[212:215], v[4:7]
	v_mfma_f32_16x16x32_bf16 v[0:3], v[160:163], v[212:215], v[0:3]
	s_setprio 0
	s_barrier
	s_add_i32 s57, s57, 2
	s_add_u32 s52, s52, 0x100
	s_addc_u32 s56, s56, 0
	s_add_u32 s12, s12, 0x100
	s_addc_u32 s13, s13, 0
	s_cmp_gt_u32 s57, 5
	s_cbranch_scc0 .LBB0_744

; #define PG8_STAGE(bufoff, gbase, voff) do { _Pragma("unroll") for (int _i = 0; _i < 2; ++_i) \
;         dma16((const char*)(gbase), (voff)[_i], ldsb + (bufoff) + ldsw + _i * 8192); } while (0)
; #define PG8_LDA(dst, b, h) do { const int a1_ = opqv(aoff0) ^ 64; _Pragma("unroll") for (int m = 0; m < 4; ++m) { dst[m][0] = *(const LAS bf16x8*)(lds + PG8_SA(b, h) + aoff0 + m * 2048); dst[m][1] = *(const LAS bf16x8*)(lds + PG8_SA(b, h) + a1_ + m * 2048); } } while (0)
; #define PG8_LDB(dst, b, h) do { const int b1_ = opqv(boff0) ^ 64; _Pragma("unroll") for (int n = 0; n < 2; ++n) { dst[n][0] = *(const LAS bf16x8*)(lds + PG8_SB(b, h) + boff0 + n * 2048); dst[n][1] = *(const LAS bf16x8*)(lds + PG8_SB(b, h) + b1_ + n * 2048); } } while (0)
; #define PG8_MMA(ai, bj, At, Bt) do { __builtin_amdgcn_s_setprio(1); _Pragma("unroll") for (int m = 0; m < 4; ++m) _Pragma("unroll") for (int n = 0; n < 2; ++n) _Pragma("unroll") for (int k = 0; k < 2; ++k) \
;         acc[ai][bj][m][n] = __builtin_amdgcn_mfma_f32_16x16x32_bf16(Bt[n][k], At[m][k], acc[ai][bj][m][n], 0, 0, 0); __builtin_amdgcn_s_setprio(0); } while (0)
; #define PG8_WAIT_V(n) asm volatile("s_waitcnt vmcnt(" #n ")" ::: "memory")
; #define PG8_BAR __builtin_amdgcn_s_barrier()
; template <class Epi>
; __device__ __forceinline__ void gemm_phase(LAS unsigned char* lds, const Gemm g, const StaticOrder& S, const Epi& E, int wave_) {
;     ...
;         const bool has_next = S.next(ui + 1, nxt);
;         const char* nA = has_next ? (const char*)g.A + (size_t)nxt.pm * tstepA : cA; const char* nB = has_next ? (const char*)g.Bt + (size_t)nxt.pn * tstepB : cB;
; #pragma unroll 1
;         for (int t = 0; t < nt; t += 2) {
;             const bool last = (t == nt - 2);
;             const char* a1 = cA + (size_t)(t + 1) * kstep;
;             const char* a2 = last ? nA : cA + (size_t)(t + 2) * kstep; const char* b2 = last ? nB : cB + (size_t)(t + 2) * kstep;
;             const char* a3 = a2 + kstep; const char* b3 = b2 + kstep;
;             PG8_STAGE(PG8_SA(1, 1), a1 + hstepA, voffA); PG8_LDB(B0, 0, 0); PG8_LDB(B1, 0, 1); PG8_SCHED; PG8_LDA(At, 0, 0);
;             PG8_WAIT_V(8); PG8_WAIT_L(0); PG8_BAR; PG8_MMA(0, 0, At, B0); PG8_MMA(0, 1, At, B1); PG8_BAR; PG8_SCHED;
;             PG8_STAGE(PG8_SB(0, 0), b2, voffB); PG8_STAGE(PG8_SB(0, 1), b2 + hstepB, voffB); PG8_STAGE(PG8_SA(0, 0), a2, voffA); PG8_LDA(At, 0, 1);
.LBB0_795:
	s_ashr_i32 s19, s18, 31
	s_lshl_b64 s[16:17], s[18:19], 19
	s_add_u32 s24, s21, s16
	s_addc_u32 s25, s44, s17
	s_and_b64 s[16:17], s[40:41], exec
	s_cselect_b32 s16, s25, s31
	s_cselect_b32 s17, s24, s30
	s_ashr_i32 s11, s10, 31
	s_lshl_b64 s[26:27], s[10:11], 18
	s_add_u32 s26, s45, s26
	s_addc_u32 s27, s46, s27
	s_and_b64 s[36:37], s[40:41], exec
	s_cselect_b32 s11, s27, s13
	s_cselect_b32 s19, s26, s12
	s_add_u32 s52, s12, 0x100
	s_addc_u32 s54, s13, 0
	s_add_u32 s12, s30, 0x40080
	s_addc_u32 s13, s31, 0
	s_mov_b32 s55, -2
	s_add_u32 s30, s12, 0xfffc0080
	s_addc_u32 s31, s13, -1
	s_cmp_eq_u32 s55, 4
	s_cselect_b32 s42, s17, s30
	s_cselect_b32 s43, s16, s31
	s_cselect_b32 s36, s19, s52
	s_cselect_b32 s37, s11, s54
	s_add_u32 s30, s42, 0x80
	v_mov_b32_e32 v130, v161
	s_addc_u32 s31, s43, 0
	v_add_u32_e32 v134, s23, v161
	v_xad_u32 v142, v130, 64, s23
	v_mov_b32_e32 v146, v161
	s_add_i32 s56, 0, 0x14000
	ds_read_b128 v[130:133], v134
	ds_read_b128 v[134:137], v134 offset:2048
	ds_read_b128 v[138:141], v142
	ds_read_b128 v[142:145], v142 offset:2048
	v_add_u32_e32 v150, s56, v161
	v_xad_u32 v154, v146, 64, s56
	ds_read_b128 v[146:149], v150
	ds_read_b128 v[150:153], v150 offset:2048
	ds_read_b128 v[162:165], v154
	ds_read_b128 v[166:169], v154 offset:2048
	v_mov_b32_e32 v154, v160
	v_add_u32_e32 v155, 0, v160
	v_xad_u32 v154, v154, 64, 0
	ds_read_b128 v[176:179], v155
	ds_read_b128 v[180:183], v155 offset:2048
	ds_read_b128 v[192:195], v154
	ds_read_b128 v[196:199], v154 offset:2048
	ds_read_b128 v[200:203], v155 offset:4096
	ds_read_b128 v[204:207], v155 offset:6144
	ds_read_b128 v[208:211], v154 offset:4096
	ds_read_b128 v[212:215], v154 offset:6144
	s_mov_b32 m0, s14
	s_nop 0
	global_load_lds_dwordx4 v129, s[12:13]
	s_mov_b32 m0, s15
	s_nop 0
	global_load_lds_dwordx4 v157, s[12:13]
	s_waitcnt vmcnt(8)
	s_waitcnt lgkmcnt(0)
	s_setprio 1
	s_barrier
	v_mfma_f32_16x16x32_bf16 v[124:127], v[130:133], v[176:179], 0
	v_mfma_f32_16x16x32_bf16 v[120:123], v[134:137], v[176:179], 0
	v_mfma_f32_16x16x32_bf16 v[108:111], v[130:133], v[180:183], 0
	v_mfma_f32_16x16x32_bf16 v[104:107], v[134:137], v[180:183], 0
	v_mfma_f32_16x16x32_bf16 v[92:95], v[130:133], v[200:203], 0
	v_mfma_f32_16x16x32_bf16 v[88:91], v[134:137], v[200:203], 0
	v_mfma_f32_16x16x32_bf16 v[76:79], v[130:133], v[204:207], 0
	v_mfma_f32_16x16x32_bf16 v[72:75], v[134:137], v[204:207], 0
	v_mfma_f32_16x16x32_bf16 v[124:127], v[138:141], v[192:195], v[124:127]
	v_mfma_f32_16x16x32_bf16 v[120:123], v[142:145], v[192:195], v[120:123]
	v_mfma_f32_16x16x32_bf16 v[108:111], v[138:141], v[196:199], v[108:111]
	v_mfma_f32_16x16x32_bf16 v[104:107], v[142:145], v[196:199], v[104:107]
	v_mfma_f32_16x16x32_bf16 v[92:95], v[138:141], v[208:211], v[92:95]
	v_mfma_f32_16x16x32_bf16 v[88:91], v[142:145], v[208:211], v[88:91]
	v_mfma_f32_16x16x32_bf16 v[76:79], v[138:141], v[212:215], v[76:79]
	v_mfma_f32_16x16x32_bf16 v[72:75], v[142:145], v[212:215], v[72:75]
	s_setprio 0
	s_setprio 1
	v_mfma_f32_16x16x32_bf16 v[116:119], v[146:149], v[176:179], 0
	v_mfma_f32_16x16x32_bf16 v[112:115], v[150:153], v[176:179], 0
	v_mfma_f32_16x16x32_bf16 v[100:103], v[146:149], v[180:183], 0
	v_mfma_f32_16x16x32_bf16 v[96:99], v[150:153], v[180:183], 0
	v_mfma_f32_16x16x32_bf16 v[84:87], v[146:149], v[200:203], 0
	v_mfma_f32_16x16x32_bf16 v[80:83], v[150:153], v[200:203], 0
	v_mfma_f32_16x16x32_bf16 v[68:71], v[146:149], v[204:207], 0
	v_mfma_f32_16x16x32_bf16 v[64:67], v[150:153], v[204:207], 0
	v_mfma_f32_16x16x32_bf16 v[116:119], v[162:165], v[192:195], v[116:119]
	v_mfma_f32_16x16x32_bf16 v[112:115], v[166:169], v[192:195], v[112:115]
	v_mfma_f32_16x16x32_bf16 v[100:103], v[162:165], v[196:199], v[100:103]
	v_mfma_f32_16x16x32_bf16 v[96:99], v[166:169], v[196:199], v[96:99]
	v_mfma_f32_16x16x32_bf16 v[84:87], v[162:165], v[208:211], v[84:87]
	v_mfma_f32_16x16x32_bf16 v[80:83], v[166:169], v[208:211], v[80:83]
	v_mfma_f32_16x16x32_bf16 v[68:71], v[162:165], v[212:215], v[68:71]
	v_mfma_f32_16x16x32_bf16 v[64:67], v[166:169], v[212:215], v[64:67]
	s_setprio 0
	s_barrier
	v_mov_b32_e32 v154, v160
	s_add_u32 s56, s36, 0x20000
	s_addc_u32 s57, s37, 0
	s_nop 0
	s_nop 0
	s_nop 0
	v_xad_u32 v154, v154, 64, 0
	ds_read_b128 v[176:179], v155 offset:16384
	ds_read_b128 v[180:183], v155 offset:18432
	ds_read_b128 v[192:195], v154 offset:16384
	ds_read_b128 v[196:199], v154 offset:18432
	ds_read_b128 v[200:203], v155 offset:20480
	ds_read_b128 v[204:207], v155 offset:22528
	ds_read_b128 v[208:211], v154 offset:20480
	ds_read_b128 v[212:215], v154 offset:22528
	s_mov_b32 m0, s80
	s_nop 0
	global_load_lds_dwordx4 v156, s[36:37]
	s_mov_b32 m0, s81
	s_nop 0
	global_load_lds_dwordx4 v158, s[36:37]
	s_mov_b32 m0, s29
	s_nop 0
	global_load_lds_dwordx4 v156, s[56:57]
	s_mov_b32 m0, s88
	s_nop 0
	global_load_lds_dwordx4 v158, s[56:57]
	s_mov_b32 m0, s76
	s_nop 0
	global_load_lds_dwordx4 v129, s[42:43]
	s_mov_b32 m0, s89
	s_nop 0
	global_load_lds_dwordx4 v157, s[42:43]
	s_waitcnt vmcnt(8)
	s_waitcnt lgkmcnt(0)
	s_setprio 1
	s_barrier
; #define PG8_STAGE(bufoff, gbase, voff) do { _Pragma("unroll") for (int _i = 0; _i < 2; ++_i) \
;         dma16((const char*)(gbase), (voff)[_i], ldsb + (bufoff) + ldsw + _i * 8192); } while (0)
; #define PG8_LDA(dst, b, h) do { const int a1_ = opqv(aoff0) ^ 64; _Pragma("unroll") for (int m = 0; m < 4; ++m) { dst[m][0] = *(const LAS bf16x8*)(lds + PG8_SA(b, h) + aoff0 + m * 2048); dst[m][1] = *(const LAS bf16x8*)(lds + PG8_SA(b, h) + a1_ + m * 2048); } } while (0)
; #define PG8_LDB(dst, b, h) do { const int b1_ = opqv(boff0) ^ 64; _Pragma("unroll") for (int n = 0; n < 2; ++n) { dst[n][0] = *(const LAS bf16x8*)(lds + PG8_SB(b, h) + boff0 + n * 2048); dst[n][1] = *(const LAS bf16x8*)(lds + PG8_SB(b, h) + b1_ + n * 2048); } } while (0)
; #define PG8_MMA(ai, bj, At, Bt) do { __builtin_amdgcn_s_setprio(1); _Pragma("unroll") for (int m = 0; m < 4; ++m) _Pragma("unroll") for (int n = 0; n < 2; ++n) _Pragma("unroll") for (int k = 0; k < 2; ++k) \
;         acc[ai][bj][m][n] = __builtin_amdgcn_mfma_f32_16x16x32_bf16(Bt[n][k], At[m][k], acc[ai][bj][m][n], 0, 0, 0); __builtin_amdgcn_s_setprio(0); } while (0)
; #define PG8_WAIT_V(n) asm volatile("s_waitcnt vmcnt(" #n ")" ::: "memory")
; #define PG8_WAIT_L(n) asm volatile("s_waitcnt lgkmcnt(" #n ")" ::: "memory")
; #define PG8_BAR __builtin_amdgcn_s_barrier()
; #define PG8_SCHED __builtin_amdgcn_sched_barrier(0)
; template <class Epi>
; __device__ __forceinline__ void gemm_phase(LAS unsigned char* lds, const Gemm g, const StaticOrder& S, const Epi& E, int wave_) {
;     ...
;             PG8_WAIT_V(8); PG8_WAIT_L(0); PG8_BAR; PG8_MMA(1, 0, At, B0); PG8_MMA(1, 1, At, B1); PG8_BAR; PG8_SCHED;
;             PG8_STAGE(PG8_SA(0, 1), a2 + hstepA, voffA); PG8_LDB(B0, 1, 0); PG8_LDB(B1, 1, 1); PG8_SCHED; PG8_LDA(At, 1, 0);
;             PG8_WAIT_V(8); PG8_WAIT_L(0); PG8_BAR; PG8_MMA(0, 0, At, B0); PG8_MMA(0, 1, At, B1); PG8_BAR; PG8_SCHED;
	v_mfma_f32_16x16x32_bf16 v[60:63], v[130:133], v[176:179], 0
	v_mfma_f32_16x16x32_bf16 v[56:59], v[134:137], v[176:179], 0
	v_mfma_f32_16x16x32_bf16 v[44:47], v[130:133], v[180:183], 0
	v_mfma_f32_16x16x32_bf16 v[40:43], v[134:137], v[180:183], 0
	v_mfma_f32_16x16x32_bf16 v[28:31], v[130:133], v[200:203], 0
	v_mfma_f32_16x16x32_bf16 v[24:27], v[134:137], v[200:203], 0
	v_mfma_f32_16x16x32_bf16 v[12:15], v[130:133], v[204:207], 0
	v_mfma_f32_16x16x32_bf16 v[8:11], v[134:137], v[204:207], 0
	v_mfma_f32_16x16x32_bf16 v[60:63], v[138:141], v[192:195], v[60:63]
	v_mfma_f32_16x16x32_bf16 v[56:59], v[142:145], v[192:195], v[56:59]
	v_mfma_f32_16x16x32_bf16 v[44:47], v[138:141], v[196:199], v[44:47]
	v_mfma_f32_16x16x32_bf16 v[40:43], v[142:145], v[196:199], v[40:43]
	v_mfma_f32_16x16x32_bf16 v[28:31], v[138:141], v[208:211], v[28:31]
	v_mfma_f32_16x16x32_bf16 v[24:27], v[142:145], v[208:211], v[24:27]
	v_mfma_f32_16x16x32_bf16 v[12:15], v[138:141], v[212:215], v[12:15]
	v_mfma_f32_16x16x32_bf16 v[8:11], v[142:145], v[212:215], v[8:11]
	s_setprio 0
	s_setprio 1
	v_mfma_f32_16x16x32_bf16 v[52:55], v[146:149], v[176:179], 0
	v_mfma_f32_16x16x32_bf16 v[48:51], v[150:153], v[176:179], 0
	v_mfma_f32_16x16x32_bf16 v[36:39], v[146:149], v[180:183], 0
	v_mfma_f32_16x16x32_bf16 v[32:35], v[150:153], v[180:183], 0
	v_mfma_f32_16x16x32_bf16 v[20:23], v[146:149], v[200:203], 0
	v_mfma_f32_16x16x32_bf16 v[16:19], v[150:153], v[200:203], 0
	v_mfma_f32_16x16x32_bf16 v[4:7], v[146:149], v[204:207], 0
	v_mfma_f32_16x16x32_bf16 v[0:3], v[150:153], v[204:207], 0
	v_mfma_f32_16x16x32_bf16 v[52:55], v[162:165], v[192:195], v[52:55]
	v_mfma_f32_16x16x32_bf16 v[48:51], v[166:169], v[192:195], v[48:51]
	v_mfma_f32_16x16x32_bf16 v[36:39], v[162:165], v[196:199], v[36:39]
	v_mfma_f32_16x16x32_bf16 v[32:35], v[166:169], v[196:199], v[32:35]
	v_mfma_f32_16x16x32_bf16 v[20:23], v[162:165], v[208:211], v[20:23]
	v_mfma_f32_16x16x32_bf16 v[16:19], v[166:169], v[208:211], v[16:19]
	v_mfma_f32_16x16x32_bf16 v[4:7], v[162:165], v[212:215], v[4:7]
	v_mfma_f32_16x16x32_bf16 v[0:3], v[166:169], v[212:215], v[0:3]
	s_setprio 0
	s_barrier
	s_add_u32 s42, s42, 0x40000
	s_addc_u32 s43, s43, 0
	s_mov_b32 m0, s1
	s_nop 0
	global_load_lds_dwordx4 v129, s[42:43]
	v_mov_b32_e32 v130, v161
	s_mov_b32 m0, s69
	s_nop 0
	global_load_lds_dwordx4 v157, s[42:43]
	v_add_u32_e32 v134, s34, v161
	v_xad_u32 v142, v130, 64, s34
	v_mov_b32_e32 v146, v161
	s_add_i32 s42, 0, 0x1c000
	ds_read_b128 v[130:133], v134
	ds_read_b128 v[134:137], v134 offset:2048
	ds_read_b128 v[138:141], v142
	ds_read_b128 v[142:145], v142 offset:2048
	v_add_u32_e32 v150, s42, v161
	v_xad_u32 v154, v146, 64, s42
	ds_read_b128 v[146:149], v150
	ds_read_b128 v[150:153], v150 offset:2048
	ds_read_b128 v[162:165], v154
	ds_read_b128 v[166:169], v154 offset:2048
	v_mov_b32_e32 v154, v160
	s_nop 0
	v_xad_u32 v154, v154, 64, 0
	ds_read_b128 v[176:179], v155 offset:32768
	ds_read_b128 v[180:183], v155 offset:34816
	ds_read_b128 v[192:195], v154 offset:32768
	ds_read_b128 v[196:199], v154 offset:34816
	ds_read_b128 v[200:203], v155 offset:36864
	ds_read_b128 v[204:207], v155 offset:38912
	ds_read_b128 v[208:211], v154 offset:36864
	ds_read_b128 v[212:215], v154 offset:38912
	s_waitcnt vmcnt(8)
	s_waitcnt lgkmcnt(0)
	s_setprio 1
	s_barrier
	v_mfma_f32_16x16x32_bf16 v[124:127], v[130:133], v[176:179], v[124:127]
	v_mfma_f32_16x16x32_bf16 v[120:123], v[134:137], v[176:179], v[120:123]
	v_mfma_f32_16x16x32_bf16 v[108:111], v[130:133], v[180:183], v[108:111]
	v_mfma_f32_16x16x32_bf16 v[104:107], v[134:137], v[180:183], v[104:107]
	v_mfma_f32_16x16x32_bf16 v[92:95], v[130:133], v[200:203], v[92:95]
	v_mfma_f32_16x16x32_bf16 v[88:91], v[134:137], v[200:203], v[88:91]
	v_mfma_f32_16x16x32_bf16 v[76:79], v[130:133], v[204:207], v[76:79]
	v_mfma_f32_16x16x32_bf16 v[72:75], v[134:137], v[204:207], v[72:75]
	v_mfma_f32_16x16x32_bf16 v[124:127], v[138:141], v[192:195], v[124:127]
	v_mfma_f32_16x16x32_bf16 v[120:123], v[142:145], v[192:195], v[120:123]
	v_mfma_f32_16x16x32_bf16 v[108:111], v[138:141], v[196:199], v[108:111]
	v_mfma_f32_16x16x32_bf16 v[104:107], v[142:145], v[196:199], v[104:107]
	v_mfma_f32_16x16x32_bf16 v[92:95], v[138:141], v[208:211], v[92:95]
	v_mfma_f32_16x16x32_bf16 v[88:91], v[142:145], v[208:211], v[88:91]
	v_mfma_f32_16x16x32_bf16 v[76:79], v[138:141], v[212:215], v[76:79]
	v_mfma_f32_16x16x32_bf16 v[72:75], v[142:145], v[212:215], v[72:75]
	s_setprio 0
	s_setprio 1
	v_mfma_f32_16x16x32_bf16 v[116:119], v[146:149], v[176:179], v[116:119]
	s_add_u32 s42, s36, 0x80
	s_addc_u32 s43, s37, 0
	v_mfma_f32_16x16x32_bf16 v[112:115], v[150:153], v[176:179], v[112:115]
	v_mfma_f32_16x16x32_bf16 v[100:103], v[146:149], v[180:183], v[100:103]
	v_mfma_f32_16x16x32_bf16 v[96:99], v[150:153], v[180:183], v[96:99]
	v_mfma_f32_16x16x32_bf16 v[84:87], v[146:149], v[200:203], v[84:87]
	v_mfma_f32_16x16x32_bf16 v[80:83], v[150:153], v[200:203], v[80:83]
	v_mfma_f32_16x16x32_bf16 v[68:71], v[146:149], v[204:207], v[68:71]
	v_mfma_f32_16x16x32_bf16 v[64:67], v[150:153], v[204:207], v[64:67]
	v_mfma_f32_16x16x32_bf16 v[116:119], v[162:165], v[192:195], v[116:119]
	v_mfma_f32_16x16x32_bf16 v[112:115], v[166:169], v[192:195], v[112:115]
	v_mfma_f32_16x16x32_bf16 v[100:103], v[162:165], v[196:199], v[100:103]
	v_mfma_f32_16x16x32_bf16 v[96:99], v[166:169], v[196:199], v[96:99]
	v_mfma_f32_16x16x32_bf16 v[84:87], v[162:165], v[208:211], v[84:87]
	v_mfma_f32_16x16x32_bf16 v[80:83], v[166:169], v[208:211], v[80:83]
	v_mfma_f32_16x16x32_bf16 v[68:71], v[162:165], v[212:215], v[68:71]
	v_mfma_f32_16x16x32_bf16 v[64:67], v[166:169], v[212:215], v[64:67]
	s_setprio 0
	s_barrier
; #define PG8_STAGE(bufoff, gbase, voff) do { _Pragma("unroll") for (int _i = 0; _i < 2; ++_i) \
;         dma16((const char*)(gbase), (voff)[_i], ldsb + (bufoff) + ldsw + _i * 8192); } while (0)
; #define PG8_LDA(dst, b, h) do { const int a1_ = opqv(aoff0) ^ 64; _Pragma("unroll") for (int m = 0; m < 4; ++m) { dst[m][0] = *(const LAS bf16x8*)(lds + PG8_SA(b, h) + aoff0 + m * 2048); dst[m][1] = *(const LAS bf16x8*)(lds + PG8_SA(b, h) + a1_ + m * 2048); } } while (0)
; #define PG8_LDB(dst, b, h) do { const int b1_ = opqv(boff0) ^ 64; _Pragma("unroll") for (int n = 0; n < 2; ++n) { dst[n][0] = *(const LAS bf16x8*)(lds + PG8_SB(b, h) + boff0 + n * 2048); dst[n][1] = *(const LAS bf16x8*)(lds + PG8_SB(b, h) + b1_ + n * 2048); } } while (0)
; #define PG8_WAIT_V(n) asm volatile("s_waitcnt vmcnt(" #n ")" ::: "memory")
; template <class Epi>
; __device__ __forceinline__ void gemm_phase(LAS unsigned char* lds, const Gemm g, const StaticOrder& S, const Epi& E, int wave_) {
;     ...
;         for (int t = 0; t < nt; t += 2) {
;             const bool last = (t == nt - 2);
;             const char* a1 = cA + (size_t)(t + 1) * kstep;
;             const char* a2 = last ? nA : cA + (size_t)(t + 2) * kstep; const char* b2 = last ? nB : cB + (size_t)(t + 2) * kstep;
;             const char* a3 = a2 + kstep; const char* b3 = b2 + kstep;
;             PG8_STAGE(PG8_SA(1, 1), a1 + hstepA, voffA); PG8_LDB(B0, 0, 0); PG8_LDB(B1, 0, 1); PG8_SCHED; PG8_LDA(At, 0, 0);
;             PG8_WAIT_V(8); PG8_WAIT_L(0); PG8_BAR; PG8_MMA(0, 0, At, B0); PG8_MMA(0, 1, At, B1); PG8_BAR; PG8_SCHED;
;             PG8_STAGE(PG8_SB(0, 0), b2, voffB); PG8_STAGE(PG8_SB(0, 1), b2 + hstepB, voffB); PG8_STAGE(PG8_SA(0, 0), a2, voffA); PG8_LDA(At, 0, 1);
;             PG8_WAIT_V(8); PG8_WAIT_L(0); PG8_BAR; PG8_MMA(1, 0, At, B0); PG8_MMA(1, 1, At, B1); PG8_BAR; PG8_SCHED;
;             PG8_STAGE(PG8_SA(0, 1), a2 + hstepA, voffA); PG8_LDB(B0, 1, 0); PG8_LDB(B1, 1, 1); PG8_SCHED; PG8_LDA(At, 1, 0);
;             PG8_WAIT_V(8); PG8_WAIT_L(0); PG8_BAR; PG8_MMA(0, 0, At, B0); PG8_MMA(0, 1, At, B1); PG8_BAR; PG8_SCHED;
;             PG8_STAGE(PG8_SB(1, 0), b3, voffB); PG8_STAGE(PG8_SB(1, 1), b3 + hstepB, voffB); PG8_STAGE(PG8_SA(1, 0), a3, voffA); PG8_LDA(At, 1, 1);
;             PG8_WAIT_V(8); PG8_WAIT_L(0); PG8_BAR; PG8_MMA(1, 0, At, B0); PG8_MMA(1, 1, At, B1); PG8_BAR; PG8_SCHED;
	s_add_u32 s36, s36, 0x20080
	s_addc_u32 s37, s37, 0
	v_mov_b32_e32 v154, v160
	s_nop 0
	s_nop 0
	v_xad_u32 v154, v154, 64, 0
	ds_read_b128 v[176:179], v155 offset:49152
	ds_read_b128 v[180:183], v155 offset:51200
	ds_read_b128 v[192:195], v154 offset:49152
	ds_read_b128 v[196:199], v154 offset:51200
	ds_read_b128 v[200:203], v155 offset:53248
	ds_read_b128 v[204:207], v155 offset:55296
	ds_read_b128 v[208:211], v154 offset:53248
	ds_read_b128 v[212:215], v154 offset:55296
	s_mov_b32 m0, s35
	s_nop 0
	global_load_lds_dwordx4 v156, s[42:43]
	s_mov_b32 m0, s33
	s_nop 0
	global_load_lds_dwordx4 v158, s[42:43]
	s_mov_b32 m0, s77
	s_nop 0
	global_load_lds_dwordx4 v156, s[36:37]
	s_mov_b32 m0, s3
	s_nop 0
	global_load_lds_dwordx4 v158, s[36:37]
	s_mov_b32 m0, s22
	s_nop 0
	global_load_lds_dwordx4 v129, s[30:31]
	s_mov_b32 m0, s2
	s_nop 0
	global_load_lds_dwordx4 v157, s[30:31]
	s_waitcnt vmcnt(8)
	s_waitcnt lgkmcnt(0)
	s_setprio 1
	s_barrier
	v_mfma_f32_16x16x32_bf16 v[60:63], v[130:133], v[176:179], v[60:63]
	v_mfma_f32_16x16x32_bf16 v[56:59], v[134:137], v[176:179], v[56:59]
	v_mfma_f32_16x16x32_bf16 v[44:47], v[130:133], v[180:183], v[44:47]
	v_mfma_f32_16x16x32_bf16 v[40:43], v[134:137], v[180:183], v[40:43]
	v_mfma_f32_16x16x32_bf16 v[28:31], v[130:133], v[200:203], v[28:31]
	v_mfma_f32_16x16x32_bf16 v[24:27], v[134:137], v[200:203], v[24:27]
	v_mfma_f32_16x16x32_bf16 v[12:15], v[130:133], v[204:207], v[12:15]
	v_mfma_f32_16x16x32_bf16 v[8:11], v[134:137], v[204:207], v[8:11]
	v_mfma_f32_16x16x32_bf16 v[60:63], v[138:141], v[192:195], v[60:63]
	v_mfma_f32_16x16x32_bf16 v[56:59], v[142:145], v[192:195], v[56:59]
	v_mfma_f32_16x16x32_bf16 v[44:47], v[138:141], v[196:199], v[44:47]
	v_mfma_f32_16x16x32_bf16 v[40:43], v[142:145], v[196:199], v[40:43]
	v_mfma_f32_16x16x32_bf16 v[28:31], v[138:141], v[208:211], v[28:31]
	v_mfma_f32_16x16x32_bf16 v[24:27], v[142:145], v[208:211], v[24:27]
	v_mfma_f32_16x16x32_bf16 v[12:15], v[138:141], v[212:215], v[12:15]
	v_mfma_f32_16x16x32_bf16 v[8:11], v[142:145], v[212:215], v[8:11]
	s_setprio 0
	s_setprio 1
	v_mfma_f32_16x16x32_bf16 v[52:55], v[146:149], v[176:179], v[52:55]
	v_mfma_f32_16x16x32_bf16 v[48:51], v[150:153], v[176:179], v[48:51]
	v_mfma_f32_16x16x32_bf16 v[36:39], v[146:149], v[180:183], v[36:39]
	v_mfma_f32_16x16x32_bf16 v[32:35], v[150:153], v[180:183], v[32:35]
	v_mfma_f32_16x16x32_bf16 v[20:23], v[146:149], v[200:203], v[20:23]
	v_mfma_f32_16x16x32_bf16 v[16:19], v[150:153], v[200:203], v[16:19]
	v_mfma_f32_16x16x32_bf16 v[4:7], v[146:149], v[204:207], v[4:7]
	v_mfma_f32_16x16x32_bf16 v[0:3], v[150:153], v[204:207], v[0:3]
	v_mfma_f32_16x16x32_bf16 v[52:55], v[162:165], v[192:195], v[52:55]
	v_mfma_f32_16x16x32_bf16 v[48:51], v[166:169], v[192:195], v[48:51]
	v_mfma_f32_16x16x32_bf16 v[36:39], v[162:165], v[196:199], v[36:39]
	v_mfma_f32_16x16x32_bf16 v[32:35], v[166:169], v[196:199], v[32:35]
	v_mfma_f32_16x16x32_bf16 v[20:23], v[162:165], v[208:211], v[20:23]
	v_mfma_f32_16x16x32_bf16 v[16:19], v[166:169], v[208:211], v[16:19]
	v_mfma_f32_16x16x32_bf16 v[4:7], v[162:165], v[212:215], v[4:7]
	v_mfma_f32_16x16x32_bf16 v[0:3], v[166:169], v[212:215], v[0:3]
	s_setprio 0
	s_barrier
	s_add_i32 s55, s55, 2
	s_add_u32 s52, s52, 0x100
	s_addc_u32 s54, s54, 0
	s_add_u32 s12, s12, 0x100
	s_addc_u32 s13, s13, 0
	s_cmp_gt_u32 s55, 5
	s_cbranch_scc0 .LBB0_796
	s_branch .Lpeel_exit_5
.LBB0_796:
	s_add_u32 s30, s12, 0xfffc0080
	s_addc_u32 s31, s13, -1
	s_cmp_eq_u32 s55, 4
	s_cselect_b32 s42, s17, s30
	s_cselect_b32 s43, s16, s31
	s_cselect_b32 s36, s19, s52
	s_cselect_b32 s37, s11, s54
	s_add_u32 s30, s42, 0x80
	v_mov_b32_e32 v130, v161
	s_addc_u32 s31, s43, 0
	v_add_u32_e32 v134, s23, v161
	v_xad_u32 v142, v130, 64, s23
	v_mov_b32_e32 v146, v161
	s_add_i32 s56, 0, 0x14000
	ds_read_b128 v[130:133], v134
	ds_read_b128 v[134:137], v134 offset:2048
	ds_read_b128 v[138:141], v142
	ds_read_b128 v[142:145], v142 offset:2048
	v_add_u32_e32 v150, s56, v161
	v_xad_u32 v154, v146, 64, s56
	ds_read_b128 v[146:149], v150
	ds_read_b128 v[150:153], v150 offset:2048
	ds_read_b128 v[162:165], v154
	ds_read_b128 v[166:169], v154 offset:2048
	v_mov_b32_e32 v154, v160
	v_add_u32_e32 v155, 0, v160
	v_xad_u32 v154, v154, 64, 0
	ds_read_b128 v[176:179], v155
	ds_read_b128 v[180:183], v155 offset:2048
	ds_read_b128 v[192:195], v154
	ds_read_b128 v[196:199], v154 offset:2048
	ds_read_b128 v[200:203], v155 offset:4096
	ds_read_b128 v[204:207], v155 offset:6144
	ds_read_b128 v[208:211], v154 offset:4096
	ds_read_b128 v[212:215], v154 offset:6144
	s_mov_b32 m0, s14
	s_nop 0
	global_load_lds_dwordx4 v129, s[12:13]
	s_mov_b32 m0, s15
	s_nop 0
	global_load_lds_dwordx4 v157, s[12:13]
	s_waitcnt vmcnt(8)
	s_waitcnt lgkmcnt(0)
	s_setprio 1
	s_barrier
; #define PG8_STAGE(bufoff, gbase, voff) do { _Pragma("unroll") for (int _i = 0; _i < 2; ++_i) \
;         dma16((const char*)(gbase), (voff)[_i], ldsb + (bufoff) + ldsw + _i * 8192); } while (0)
; #define PG8_LDA(dst, b, h) do { const int a1_ = opqv(aoff0) ^ 64; _Pragma("unroll") for (int m = 0; m < 4; ++m) { dst[m][0] = *(const LAS bf16x8*)(lds + PG8_SA(b, h) + aoff0 + m * 2048); dst[m][1] = *(const LAS bf16x8*)(lds + PG8_SA(b, h) + a1_ + m * 2048); } } while (0)
; #define PG8_MMA(ai, bj, At, Bt) do { __builtin_amdgcn_s_setprio(1); _Pragma("unroll") for (int m = 0; m < 4; ++m) _Pragma("unroll") for (int n = 0; n < 2; ++n) _Pragma("unroll") for (int k = 0; k < 2; ++k) \
;         acc[ai][bj][m][n] = __builtin_amdgcn_mfma_f32_16x16x32_bf16(Bt[n][k], At[m][k], acc[ai][bj][m][n], 0, 0, 0); __builtin_amdgcn_s_setprio(0); } while (0)
; #define PG8_WAIT_V(n) asm volatile("s_waitcnt vmcnt(" #n ")" ::: "memory")
; #define PG8_WAIT_L(n) asm volatile("s_waitcnt lgkmcnt(" #n ")" ::: "memory")
; #define PG8_BAR __builtin_amdgcn_s_barrier()
; #define PG8_SCHED __builtin_amdgcn_sched_barrier(0)
; template <class Epi>
; __device__ __forceinline__ void gemm_phase(LAS unsigned char* lds, const Gemm g, const StaticOrder& S, const Epi& E, int wave_) {
;     ...
;             PG8_WAIT_V(8); PG8_WAIT_L(0); PG8_BAR; PG8_MMA(0, 0, At, B0); PG8_MMA(0, 1, At, B1); PG8_BAR; PG8_SCHED;
;             PG8_STAGE(PG8_SB(0, 0), b2, voffB); PG8_STAGE(PG8_SB(0, 1), b2 + hstepB, voffB); PG8_STAGE(PG8_SA(0, 0), a2, voffA); PG8_LDA(At, 0, 1);
;             PG8_WAIT_V(8); PG8_WAIT_L(0); PG8_BAR; PG8_MMA(1, 0, At, B0); PG8_MMA(1, 1, At, B1); PG8_BAR; PG8_SCHED;
	v_mfma_f32_16x16x32_bf16 v[124:127], v[130:133], v[176:179], v[124:127]
	v_mfma_f32_16x16x32_bf16 v[120:123], v[134:137], v[176:179], v[120:123]
	v_mfma_f32_16x16x32_bf16 v[108:111], v[130:133], v[180:183], v[108:111]
	v_mfma_f32_16x16x32_bf16 v[104:107], v[134:137], v[180:183], v[104:107]
	v_mfma_f32_16x16x32_bf16 v[92:95], v[130:133], v[200:203], v[92:95]
	v_mfma_f32_16x16x32_bf16 v[88:91], v[134:137], v[200:203], v[88:91]
	v_mfma_f32_16x16x32_bf16 v[76:79], v[130:133], v[204:207], v[76:79]
	v_mfma_f32_16x16x32_bf16 v[72:75], v[134:137], v[204:207], v[72:75]
	v_mfma_f32_16x16x32_bf16 v[124:127], v[138:141], v[192:195], v[124:127]
	v_mfma_f32_16x16x32_bf16 v[120:123], v[142:145], v[192:195], v[120:123]
	v_mfma_f32_16x16x32_bf16 v[108:111], v[138:141], v[196:199], v[108:111]
	v_mfma_f32_16x16x32_bf16 v[104:107], v[142:145], v[196:199], v[104:107]
	v_mfma_f32_16x16x32_bf16 v[92:95], v[138:141], v[208:211], v[92:95]
	v_mfma_f32_16x16x32_bf16 v[88:91], v[142:145], v[208:211], v[88:91]
	v_mfma_f32_16x16x32_bf16 v[76:79], v[138:141], v[212:215], v[76:79]
	v_mfma_f32_16x16x32_bf16 v[72:75], v[142:145], v[212:215], v[72:75]
	s_setprio 0
	s_setprio 1
	v_mfma_f32_16x16x32_bf16 v[116:119], v[146:149], v[176:179], v[116:119]
	v_mfma_f32_16x16x32_bf16 v[112:115], v[150:153], v[176:179], v[112:115]
	v_mfma_f32_16x16x32_bf16 v[100:103], v[146:149], v[180:183], v[100:103]
	v_mfma_f32_16x16x32_bf16 v[96:99], v[150:153], v[180:183], v[96:99]
	v_mfma_f32_16x16x32_bf16 v[84:87], v[146:149], v[200:203], v[84:87]
	v_mfma_f32_16x16x32_bf16 v[80:83], v[150:153], v[200:203], v[80:83]
	v_mfma_f32_16x16x32_bf16 v[68:71], v[146:149], v[204:207], v[68:71]
	v_mfma_f32_16x16x32_bf16 v[64:67], v[150:153], v[204:207], v[64:67]
	v_mfma_f32_16x16x32_bf16 v[116:119], v[162:165], v[192:195], v[116:119]
	v_mfma_f32_16x16x32_bf16 v[112:115], v[166:169], v[192:195], v[112:115]
	v_mfma_f32_16x16x32_bf16 v[100:103], v[162:165], v[196:199], v[100:103]
	v_mfma_f32_16x16x32_bf16 v[96:99], v[166:169], v[196:199], v[96:99]
	v_mfma_f32_16x16x32_bf16 v[84:87], v[162:165], v[208:211], v[84:87]
	v_mfma_f32_16x16x32_bf16 v[80:83], v[166:169], v[208:211], v[80:83]
	v_mfma_f32_16x16x32_bf16 v[68:71], v[162:165], v[212:215], v[68:71]
	v_mfma_f32_16x16x32_bf16 v[64:67], v[166:169], v[212:215], v[64:67]
	s_setprio 0
	s_barrier
	v_mov_b32_e32 v154, v160
	s_add_u32 s56, s36, 0x20000
	s_addc_u32 s57, s37, 0
	s_nop 0
	s_nop 0
	s_nop 0
	v_xad_u32 v154, v154, 64, 0
	ds_read_b128 v[176:179], v155 offset:16384
	ds_read_b128 v[180:183], v155 offset:18432
	ds_read_b128 v[192:195], v154 offset:16384
	ds_read_b128 v[196:199], v154 offset:18432
	ds_read_b128 v[200:203], v155 offset:20480
	ds_read_b128 v[204:207], v155 offset:22528
	ds_read_b128 v[208:211], v154 offset:20480
	ds_read_b128 v[212:215], v154 offset:22528
	s_mov_b32 m0, s80
	s_nop 0
	global_load_lds_dwordx4 v156, s[36:37]
	s_mov_b32 m0, s81
	s_nop 0
	global_load_lds_dwordx4 v158, s[36:37]
	s_mov_b32 m0, s29
	s_nop 0
	global_load_lds_dwordx4 v156, s[56:57]
	s_mov_b32 m0, s88
	s_nop 0
	global_load_lds_dwordx4 v158, s[56:57]
	s_mov_b32 m0, s76
	s_nop 0
	global_load_lds_dwordx4 v129, s[42:43]
	s_mov_b32 m0, s89
	s_nop 0
	global_load_lds_dwordx4 v157, s[42:43]
	s_waitcnt vmcnt(8)
	s_waitcnt lgkmcnt(0)
	s_setprio 1
	s_barrier
	v_mfma_f32_16x16x32_bf16 v[60:63], v[130:133], v[176:179], v[60:63]
	v_mfma_f32_16x16x32_bf16 v[56:59], v[134:137], v[176:179], v[56:59]
	v_mfma_f32_16x16x32_bf16 v[44:47], v[130:133], v[180:183], v[44:47]
	v_mfma_f32_16x16x32_bf16 v[40:43], v[134:137], v[180:183], v[40:43]
	v_mfma_f32_16x16x32_bf16 v[28:31], v[130:133], v[200:203], v[28:31]
	v_mfma_f32_16x16x32_bf16 v[24:27], v[134:137], v[200:203], v[24:27]
	v_mfma_f32_16x16x32_bf16 v[12:15], v[130:133], v[204:207], v[12:15]
	v_mfma_f32_16x16x32_bf16 v[8:11], v[134:137], v[204:207], v[8:11]
	v_mfma_f32_16x16x32_bf16 v[60:63], v[138:141], v[192:195], v[60:63]
	v_mfma_f32_16x16x32_bf16 v[56:59], v[142:145], v[192:195], v[56:59]
	v_mfma_f32_16x16x32_bf16 v[44:47], v[138:141], v[196:199], v[44:47]
	v_mfma_f32_16x16x32_bf16 v[40:43], v[142:145], v[196:199], v[40:43]
	v_mfma_f32_16x16x32_bf16 v[28:31], v[138:141], v[208:211], v[28:31]
	v_mfma_f32_16x16x32_bf16 v[24:27], v[142:145], v[208:211], v[24:27]
	v_mfma_f32_16x16x32_bf16 v[12:15], v[138:141], v[212:215], v[12:15]
	v_mfma_f32_16x16x32_bf16 v[8:11], v[142:145], v[212:215], v[8:11]
	s_setprio 0
	s_setprio 1
	v_mfma_f32_16x16x32_bf16 v[52:55], v[146:149], v[176:179], v[52:55]
	v_mfma_f32_16x16x32_bf16 v[48:51], v[150:153], v[176:179], v[48:51]
	v_mfma_f32_16x16x32_bf16 v[36:39], v[146:149], v[180:183], v[36:39]
	v_mfma_f32_16x16x32_bf16 v[32:35], v[150:153], v[180:183], v[32:35]
	v_mfma_f32_16x16x32_bf16 v[20:23], v[146:149], v[200:203], v[20:23]
	v_mfma_f32_16x16x32_bf16 v[16:19], v[150:153], v[200:203], v[16:19]
	v_mfma_f32_16x16x32_bf16 v[4:7], v[146:149], v[204:207], v[4:7]
	v_mfma_f32_16x16x32_bf16 v[0:3], v[150:153], v[204:207], v[0:3]
	v_mfma_f32_16x16x32_bf16 v[52:55], v[162:165], v[192:195], v[52:55]
	v_mfma_f32_16x16x32_bf16 v[48:51], v[166:169], v[192:195], v[48:51]
	v_mfma_f32_16x16x32_bf16 v[36:39], v[162:165], v[196:199], v[36:39]
	v_mfma_f32_16x16x32_bf16 v[32:35], v[166:169], v[196:199], v[32:35]
	v_mfma_f32_16x16x32_bf16 v[20:23], v[162:165], v[208:211], v[20:23]
	v_mfma_f32_16x16x32_bf16 v[16:19], v[166:169], v[208:211], v[16:19]
	v_mfma_f32_16x16x32_bf16 v[4:7], v[162:165], v[212:215], v[4:7]
	v_mfma_f32_16x16x32_bf16 v[0:3], v[166:169], v[212:215], v[0:3]
	s_setprio 0
	s_barrier
; #define PG8_STAGE(bufoff, gbase, voff) do { _Pragma("unroll") for (int _i = 0; _i < 2; ++_i) \
;         dma16((const char*)(gbase), (voff)[_i], ldsb + (bufoff) + ldsw + _i * 8192); } while (0)
; #define PG8_LDA(dst, b, h) do { const int a1_ = opqv(aoff0) ^ 64; _Pragma("unroll") for (int m = 0; m < 4; ++m) { dst[m][0] = *(const LAS bf16x8*)(lds + PG8_SA(b, h) + aoff0 + m * 2048); dst[m][1] = *(const LAS bf16x8*)(lds + PG8_SA(b, h) + a1_ + m * 2048); } } while (0)
; #define PG8_LDB(dst, b, h) do { const int b1_ = opqv(boff0) ^ 64; _Pragma("unroll") for (int n = 0; n < 2; ++n) { dst[n][0] = *(const LAS bf16x8*)(lds + PG8_SB(b, h) + boff0 + n * 2048); dst[n][1] = *(const LAS bf16x8*)(lds + PG8_SB(b, h) + b1_ + n * 2048); } } while (0)
; #define PG8_MMA(ai, bj, At, Bt) do { __builtin_amdgcn_s_setprio(1); _Pragma("unroll") for (int m = 0; m < 4; ++m) _Pragma("unroll") for (int n = 0; n < 2; ++n) _Pragma("unroll") for (int k = 0; k < 2; ++k) \
;         acc[ai][bj][m][n] = __builtin_amdgcn_mfma_f32_16x16x32_bf16(Bt[n][k], At[m][k], acc[ai][bj][m][n], 0, 0, 0); __builtin_amdgcn_s_setprio(0); } while (0)
; #define PG8_WAIT_V(n) asm volatile("s_waitcnt vmcnt(" #n ")" ::: "memory")
; #define PG8_WAIT_L(n) asm volatile("s_waitcnt lgkmcnt(" #n ")" ::: "memory")
; #define PG8_BAR __builtin_amdgcn_s_barrier()
; #define PG8_SCHED __builtin_amdgcn_sched_barrier(0)
; template <class Epi>
; __device__ __forceinline__ void gemm_phase(LAS unsigned char* lds, const Gemm g, const StaticOrder& S, const Epi& E, int wave_) {
;     ...
;             PG8_STAGE(PG8_SA(0, 1), a2 + hstepA, voffA); PG8_LDB(B0, 1, 0); PG8_LDB(B1, 1, 1); PG8_SCHED; PG8_LDA(At, 1, 0);
;             PG8_WAIT_V(8); PG8_WAIT_L(0); PG8_BAR; PG8_MMA(0, 0, At, B0); PG8_MMA(0, 1, At, B1); PG8_BAR; PG8_SCHED;
;             PG8_STAGE(PG8_SB(1, 0), b3, voffB); PG8_STAGE(PG8_SB(1, 1), b3 + hstepB, voffB); PG8_STAGE(PG8_SA(1, 0), a3, voffA); PG8_LDA(At, 1, 1);
;             PG8_WAIT_V(8); PG8_WAIT_L(0); PG8_BAR; PG8_MMA(1, 0, At, B0); PG8_MMA(1, 1, At, B1); PG8_BAR; PG8_SCHED;
;         }
	s_add_u32 s42, s42, 0x40000
	s_addc_u32 s43, s43, 0
	s_mov_b32 m0, s1
	s_nop 0
	global_load_lds_dwordx4 v129, s[42:43]
	v_mov_b32_e32 v130, v161
	s_mov_b32 m0, s69
	s_nop 0
	global_load_lds_dwordx4 v157, s[42:43]
	v_add_u32_e32 v134, s34, v161
	v_xad_u32 v142, v130, 64, s34
	v_mov_b32_e32 v146, v161
	s_add_i32 s42, 0, 0x1c000
	ds_read_b128 v[130:133], v134
	ds_read_b128 v[134:137], v134 offset:2048
	ds_read_b128 v[138:141], v142
	ds_read_b128 v[142:145], v142 offset:2048
	v_add_u32_e32 v150, s42, v161
	v_xad_u32 v154, v146, 64, s42
	ds_read_b128 v[146:149], v150
	ds_read_b128 v[150:153], v150 offset:2048
	ds_read_b128 v[162:165], v154
	ds_read_b128 v[166:169], v154 offset:2048
	v_mov_b32_e32 v154, v160
	s_nop 0
	v_xad_u32 v154, v154, 64, 0
	ds_read_b128 v[176:179], v155 offset:32768
	ds_read_b128 v[180:183], v155 offset:34816
	ds_read_b128 v[192:195], v154 offset:32768
	ds_read_b128 v[196:199], v154 offset:34816
	ds_read_b128 v[200:203], v155 offset:36864
	ds_read_b128 v[204:207], v155 offset:38912
	ds_read_b128 v[208:211], v154 offset:36864
	ds_read_b128 v[212:215], v154 offset:38912
	s_waitcnt vmcnt(8)
	s_waitcnt lgkmcnt(0)
	s_setprio 1
	s_barrier
	v_mfma_f32_16x16x32_bf16 v[124:127], v[130:133], v[176:179], v[124:127]
	v_mfma_f32_16x16x32_bf16 v[120:123], v[134:137], v[176:179], v[120:123]
	v_mfma_f32_16x16x32_bf16 v[108:111], v[130:133], v[180:183], v[108:111]
	v_mfma_f32_16x16x32_bf16 v[104:107], v[134:137], v[180:183], v[104:107]
	v_mfma_f32_16x16x32_bf16 v[92:95], v[130:133], v[200:203], v[92:95]
	v_mfma_f32_16x16x32_bf16 v[88:91], v[134:137], v[200:203], v[88:91]
	v_mfma_f32_16x16x32_bf16 v[76:79], v[130:133], v[204:207], v[76:79]
	v_mfma_f32_16x16x32_bf16 v[72:75], v[134:137], v[204:207], v[72:75]
	v_mfma_f32_16x16x32_bf16 v[124:127], v[138:141], v[192:195], v[124:127]
	v_mfma_f32_16x16x32_bf16 v[120:123], v[142:145], v[192:195], v[120:123]
	v_mfma_f32_16x16x32_bf16 v[108:111], v[138:141], v[196:199], v[108:111]
	v_mfma_f32_16x16x32_bf16 v[104:107], v[142:145], v[196:199], v[104:107]
	v_mfma_f32_16x16x32_bf16 v[92:95], v[138:141], v[208:211], v[92:95]
	v_mfma_f32_16x16x32_bf16 v[88:91], v[142:145], v[208:211], v[88:91]
	v_mfma_f32_16x16x32_bf16 v[76:79], v[138:141], v[212:215], v[76:79]
	v_mfma_f32_16x16x32_bf16 v[72:75], v[142:145], v[212:215], v[72:75]
	s_setprio 0
	s_setprio 1
	v_mfma_f32_16x16x32_bf16 v[116:119], v[146:149], v[176:179], v[116:119]
	s_add_u32 s42, s36, 0x80
	s_addc_u32 s43, s37, 0
	v_mfma_f32_16x16x32_bf16 v[112:115], v[150:153], v[176:179], v[112:115]
	v_mfma_f32_16x16x32_bf16 v[100:103], v[146:149], v[180:183], v[100:103]
	v_mfma_f32_16x16x32_bf16 v[96:99], v[150:153], v[180:183], v[96:99]
	v_mfma_f32_16x16x32_bf16 v[84:87], v[146:149], v[200:203], v[84:87]
	v_mfma_f32_16x16x32_bf16 v[80:83], v[150:153], v[200:203], v[80:83]
	v_mfma_f32_16x16x32_bf16 v[68:71], v[146:149], v[204:207], v[68:71]
	v_mfma_f32_16x16x32_bf16 v[64:67], v[150:153], v[204:207], v[64:67]
	v_mfma_f32_16x16x32_bf16 v[116:119], v[162:165], v[192:195], v[116:119]
	v_mfma_f32_16x16x32_bf16 v[112:115], v[166:169], v[192:195], v[112:115]
	v_mfma_f32_16x16x32_bf16 v[100:103], v[162:165], v[196:199], v[100:103]
	v_mfma_f32_16x16x32_bf16 v[96:99], v[166:169], v[196:199], v[96:99]
	v_mfma_f32_16x16x32_bf16 v[84:87], v[162:165], v[208:211], v[84:87]
	v_mfma_f32_16x16x32_bf16 v[80:83], v[166:169], v[208:211], v[80:83]
	v_mfma_f32_16x16x32_bf16 v[68:71], v[162:165], v[212:215], v[68:71]
	v_mfma_f32_16x16x32_bf16 v[64:67], v[166:169], v[212:215], v[64:67]
	s_setprio 0
	s_barrier
	s_add_u32 s36, s36, 0x20080
	s_addc_u32 s37, s37, 0
	v_mov_b32_e32 v154, v160
	s_nop 0
	s_nop 0
	v_xad_u32 v154, v154, 64, 0
	ds_read_b128 v[176:179], v155 offset:49152
	ds_read_b128 v[180:183], v155 offset:51200
	ds_read_b128 v[192:195], v154 offset:49152
	ds_read_b128 v[196:199], v154 offset:51200
	ds_read_b128 v[200:203], v155 offset:53248
	ds_read_b128 v[204:207], v155 offset:55296
	ds_read_b128 v[208:211], v154 offset:53248
	ds_read_b128 v[212:215], v154 offset:55296
	s_mov_b32 m0, s35
	s_nop 0
	global_load_lds_dwordx4 v156, s[42:43]
	s_mov_b32 m0, s33
	s_nop 0
	global_load_lds_dwordx4 v158, s[42:43]
	s_mov_b32 m0, s77
	s_nop 0
	global_load_lds_dwordx4 v156, s[36:37]
	s_mov_b32 m0, s3
	s_nop 0
	global_load_lds_dwordx4 v158, s[36:37]
	s_mov_b32 m0, s22
	s_nop 0
	global_load_lds_dwordx4 v129, s[30:31]
	s_mov_b32 m0, s2
	s_nop 0
	global_load_lds_dwordx4 v157, s[30:31]
	s_waitcnt vmcnt(8)
	s_waitcnt lgkmcnt(0)
	s_setprio 1
	s_barrier
	v_mfma_f32_16x16x32_bf16 v[60:63], v[130:133], v[176:179], v[60:63]
	v_mfma_f32_16x16x32_bf16 v[56:59], v[134:137], v[176:179], v[56:59]
	v_mfma_f32_16x16x32_bf16 v[44:47], v[130:133], v[180:183], v[44:47]
	v_mfma_f32_16x16x32_bf16 v[40:43], v[134:137], v[180:183], v[40:43]
	v_mfma_f32_16x16x32_bf16 v[28:31], v[130:133], v[200:203], v[28:31]
	v_mfma_f32_16x16x32_bf16 v[24:27], v[134:137], v[200:203], v[24:27]
	v_mfma_f32_16x16x32_bf16 v[12:15], v[130:133], v[204:207], v[12:15]
	v_mfma_f32_16x16x32_bf16 v[8:11], v[134:137], v[204:207], v[8:11]
	v_mfma_f32_16x16x32_bf16 v[60:63], v[138:141], v[192:195], v[60:63]
	v_mfma_f32_16x16x32_bf16 v[56:59], v[142:145], v[192:195], v[56:59]
	v_mfma_f32_16x16x32_bf16 v[44:47], v[138:141], v[196:199], v[44:47]
	v_mfma_f32_16x16x32_bf16 v[40:43], v[142:145], v[196:199], v[40:43]
	v_mfma_f32_16x16x32_bf16 v[28:31], v[138:141], v[208:211], v[28:31]
	v_mfma_f32_16x16x32_bf16 v[24:27], v[142:145], v[208:211], v[24:27]
	v_mfma_f32_16x16x32_bf16 v[12:15], v[138:141], v[212:215], v[12:15]
	v_mfma_f32_16x16x32_bf16 v[8:11], v[142:145], v[212:215], v[8:11]
	s_setprio 0
	s_setprio 1
	v_mfma_f32_16x16x32_bf16 v[52:55], v[146:149], v[176:179], v[52:55]
	v_mfma_f32_16x16x32_bf16 v[48:51], v[150:153], v[176:179], v[48:51]
	v_mfma_f32_16x16x32_bf16 v[36:39], v[146:149], v[180:183], v[36:39]
	v_mfma_f32_16x16x32_bf16 v[32:35], v[150:153], v[180:183], v[32:35]
	v_mfma_f32_16x16x32_bf16 v[20:23], v[146:149], v[200:203], v[20:23]
	v_mfma_f32_16x16x32_bf16 v[16:19], v[150:153], v[200:203], v[16:19]
	v_mfma_f32_16x16x32_bf16 v[4:7], v[146:149], v[204:207], v[4:7]
	v_mfma_f32_16x16x32_bf16 v[0:3], v[150:153], v[204:207], v[0:3]
	v_mfma_f32_16x16x32_bf16 v[52:55], v[162:165], v[192:195], v[52:55]
	v_mfma_f32_16x16x32_bf16 v[48:51], v[166:169], v[192:195], v[48:51]
	v_mfma_f32_16x16x32_bf16 v[36:39], v[162:165], v[196:199], v[36:39]
	v_mfma_f32_16x16x32_bf16 v[32:35], v[166:169], v[196:199], v[32:35]
	v_mfma_f32_16x16x32_bf16 v[20:23], v[162:165], v[208:211], v[20:23]
	v_mfma_f32_16x16x32_bf16 v[16:19], v[166:169], v[208:211], v[16:19]
	v_mfma_f32_16x16x32_bf16 v[4:7], v[162:165], v[212:215], v[4:7]
	v_mfma_f32_16x16x32_bf16 v[0:3], v[166:169], v[212:215], v[0:3]
	s_setprio 0
	s_barrier
	s_add_i32 s55, s55, 2
	s_add_u32 s52, s52, 0x100
	s_addc_u32 s54, s54, 0
	s_add_u32 s12, s12, 0x100
	s_addc_u32 s13, s13, 0
	s_cmp_gt_u32 s55, 5
	s_cbranch_scc0 .LBB0_796

; #define PG8_STAGE(bufoff, gbase, voff) do { _Pragma("unroll") for (int _i = 0; _i < 2; ++_i) \
;         dma16((const char*)(gbase), (voff)[_i], ldsb + (bufoff) + ldsw + _i * 8192); } while (0)
; #define PG8_LDA(dst, b, h) do { const int a1_ = opqv(aoff0) ^ 64; _Pragma("unroll") for (int m = 0; m < 4; ++m) { dst[m][0] = *(const LAS bf16x8*)(lds + PG8_SA(b, h) + aoff0 + m * 2048); dst[m][1] = *(const LAS bf16x8*)(lds + PG8_SA(b, h) + a1_ + m * 2048); } } while (0)
; #define PG8_LDB(dst, b, h) do { const int b1_ = opqv(boff0) ^ 64; _Pragma("unroll") for (int n = 0; n < 2; ++n) { dst[n][0] = *(const LAS bf16x8*)(lds + PG8_SB(b, h) + boff0 + n * 2048); dst[n][1] = *(const LAS bf16x8*)(lds + PG8_SB(b, h) + b1_ + n * 2048); } } while (0)
; #define PG8_MMA(ai, bj, At, Bt) do { __builtin_amdgcn_s_setprio(1); _Pragma("unroll") for (int m = 0; m < 4; ++m) _Pragma("unroll") for (int n = 0; n < 2; ++n) _Pragma("unroll") for (int k = 0; k < 2; ++k) \
;         acc[ai][bj][m][n] = __builtin_amdgcn_mfma_f32_16x16x32_bf16(Bt[n][k], At[m][k], acc[ai][bj][m][n], 0, 0, 0); __builtin_amdgcn_s_setprio(0); } while (0)
; #define PG8_WAIT_V(n) asm volatile("s_waitcnt vmcnt(" #n ")" ::: "memory")
; #define PG8_BAR __builtin_amdgcn_s_barrier()
; template <class Epi>
; __device__ __forceinline__ void gemm_phase(LAS unsigned char* lds, const Gemm g, const StaticOrder& S, const Epi& E, int wave_) {
;     ...
;         const bool has_next = S.next(ui + 1, nxt);
;         const char* nA = has_next ? (const char*)g.A + (size_t)nxt.pm * tstepA : cA; const char* nB = has_next ? (const char*)g.Bt + (size_t)nxt.pn * tstepB : cB;
; #pragma unroll 1
;         for (int t = 0; t < nt; t += 2) {
;             const bool last = (t == nt - 2);
;             const char* a1 = cA + (size_t)(t + 1) * kstep;
;             const char* a2 = last ? nA : cA + (size_t)(t + 2) * kstep; const char* b2 = last ? nB : cB + (size_t)(t + 2) * kstep;
;             const char* a3 = a2 + kstep; const char* b3 = b2 + kstep;
;             PG8_STAGE(PG8_SA(1, 1), a1 + hstepA, voffA); PG8_LDB(B0, 0, 0); PG8_LDB(B1, 0, 1); PG8_SCHED; PG8_LDA(At, 0, 0);
;             PG8_WAIT_V(8); PG8_WAIT_L(0); PG8_BAR; PG8_MMA(0, 0, At, B0); PG8_MMA(0, 1, At, B1); PG8_BAR; PG8_SCHED;
;             PG8_STAGE(PG8_SB(0, 0), b2, voffB); PG8_STAGE(PG8_SB(0, 1), b2 + hstepB, voffB); PG8_STAGE(PG8_SA(0, 0), a2, voffA); PG8_LDA(At, 0, 1);
.LBB0_1103:
	s_ashr_i32 s19, s18, 31
	s_lshl_b64 s[16:17], s[18:19], 20
	s_add_u32 s24, s21, s16
	s_addc_u32 s25, s46, s17
	s_and_b64 s[16:17], s[44:45], exec
	s_cselect_b32 s16, s25, s31
	s_cselect_b32 s17, s24, s30
	s_ashr_i32 s11, s10, 31
	s_lshl_b64 s[26:27], s[10:11], 20
	s_add_u32 s26, s47, s26
	s_addc_u32 s27, s48, s27
	s_and_b64 s[36:37], s[44:45], exec
	s_cselect_b32 s11, s27, s13
	s_cselect_b32 s19, s26, s12
	s_add_u32 s55, s12, 0x100
	s_addc_u32 s56, s13, 0
	s_add_u32 s12, s30, 0x80080
	s_addc_u32 s13, s31, 0
	s_mov_b32 s57, -2
	s_add_u32 s30, s12, 0xfff80080
	s_addc_u32 s31, s13, -1
	s_cmp_eq_u32 s57, 28
	s_cselect_b32 s40, s17, s30
	s_cselect_b32 s41, s16, s31
	s_cselect_b32 s36, s19, s55
	s_cselect_b32 s37, s11, s56
	s_add_u32 s30, s40, 0x80
	v_mov_b32_e32 v128, v172
	s_addc_u32 s31, s41, 0
	v_add_u32_e32 v132, s23, v172
	v_xad_u32 v140, v128, 64, s23
	v_mov_b32_e32 v144, v172
	s_add_i32 s60, 0, 0x14000
	ds_read_b128 v[128:131], v132
	ds_read_b128 v[132:135], v132 offset:2048
	ds_read_b128 v[136:139], v140
	ds_read_b128 v[140:143], v140 offset:2048
	v_add_u32_e32 v148, s60, v172
	v_xad_u32 v156, v144, 64, s60
	ds_read_b128 v[144:147], v148
	ds_read_b128 v[148:151], v148 offset:2048
	ds_read_b128 v[152:155], v156
	ds_read_b128 v[156:159], v156 offset:2048
	v_mov_b32_e32 v160, v171
	v_add_u32_e32 v183, 0, v171
	v_xad_u32 v182, v160, 64, 0
	ds_read_b128 v[160:163], v183
	ds_read_b128 v[174:177], v183 offset:2048
	ds_read_b128 v[178:181], v182
	ds_read_b128 v[192:195], v182 offset:2048
	ds_read_b128 v[196:199], v183 offset:4096
	ds_read_b128 v[200:203], v183 offset:6144
	ds_read_b128 v[204:207], v182 offset:4096
	ds_read_b128 v[208:211], v182 offset:6144
	s_mov_b32 m0, s14
	s_nop 0
	global_load_lds_dwordx4 v166, s[12:13]
	s_mov_b32 m0, s15
	s_nop 0
	global_load_lds_dwordx4 v168, s[12:13]
	s_waitcnt vmcnt(8)
	s_waitcnt lgkmcnt(0)
	s_setprio 1
	s_barrier
	v_mfma_f32_16x16x32_bf16 v[124:127], v[128:131], v[160:163], 0
	v_mfma_f32_16x16x32_bf16 v[120:123], v[132:135], v[160:163], 0
	v_mfma_f32_16x16x32_bf16 v[108:111], v[128:131], v[174:177], 0
	v_mfma_f32_16x16x32_bf16 v[104:107], v[132:135], v[174:177], 0
	v_mfma_f32_16x16x32_bf16 v[92:95], v[128:131], v[196:199], 0
	v_mfma_f32_16x16x32_bf16 v[88:91], v[132:135], v[196:199], 0
	v_mfma_f32_16x16x32_bf16 v[76:79], v[128:131], v[200:203], 0
	v_mfma_f32_16x16x32_bf16 v[72:75], v[132:135], v[200:203], 0
	v_mfma_f32_16x16x32_bf16 v[124:127], v[136:139], v[178:181], v[124:127]
	v_mfma_f32_16x16x32_bf16 v[120:123], v[140:143], v[178:181], v[120:123]
	v_mfma_f32_16x16x32_bf16 v[108:111], v[136:139], v[192:195], v[108:111]
	v_mfma_f32_16x16x32_bf16 v[104:107], v[140:143], v[192:195], v[104:107]
	v_mfma_f32_16x16x32_bf16 v[92:95], v[136:139], v[204:207], v[92:95]
	v_mfma_f32_16x16x32_bf16 v[88:91], v[140:143], v[204:207], v[88:91]
	v_mfma_f32_16x16x32_bf16 v[76:79], v[136:139], v[208:211], v[76:79]
	v_mfma_f32_16x16x32_bf16 v[72:75], v[140:143], v[208:211], v[72:75]
	s_setprio 0
	s_setprio 1
	v_mfma_f32_16x16x32_bf16 v[116:119], v[144:147], v[160:163], 0
	v_mfma_f32_16x16x32_bf16 v[112:115], v[148:151], v[160:163], 0
	v_mfma_f32_16x16x32_bf16 v[100:103], v[144:147], v[174:177], 0
	v_mfma_f32_16x16x32_bf16 v[96:99], v[148:151], v[174:177], 0
	v_mfma_f32_16x16x32_bf16 v[84:87], v[144:147], v[196:199], 0
	v_mfma_f32_16x16x32_bf16 v[80:83], v[148:151], v[196:199], 0
	v_mfma_f32_16x16x32_bf16 v[68:71], v[144:147], v[200:203], 0
	v_mfma_f32_16x16x32_bf16 v[64:67], v[148:151], v[200:203], 0
	v_mfma_f32_16x16x32_bf16 v[116:119], v[152:155], v[178:181], v[116:119]
	v_mfma_f32_16x16x32_bf16 v[112:115], v[156:159], v[178:181], v[112:115]
	v_mfma_f32_16x16x32_bf16 v[100:103], v[152:155], v[192:195], v[100:103]
	v_mfma_f32_16x16x32_bf16 v[96:99], v[156:159], v[192:195], v[96:99]
	v_mfma_f32_16x16x32_bf16 v[84:87], v[152:155], v[204:207], v[84:87]
	v_mfma_f32_16x16x32_bf16 v[80:83], v[156:159], v[204:207], v[80:83]
	v_mfma_f32_16x16x32_bf16 v[68:71], v[152:155], v[208:211], v[68:71]
	v_mfma_f32_16x16x32_bf16 v[64:67], v[156:159], v[208:211], v[64:67]
	s_setprio 0
	s_barrier
	v_mov_b32_e32 v160, v171
	s_add_u32 s60, s36, 0x80000
	s_addc_u32 s61, s37, 0
	s_nop 0
	s_nop 0
	s_nop 0
	v_xad_u32 v182, v160, 64, 0
	ds_read_b128 v[160:163], v183 offset:16384
	ds_read_b128 v[174:177], v183 offset:18432
	ds_read_b128 v[178:181], v182 offset:16384
	ds_read_b128 v[192:195], v182 offset:18432
	ds_read_b128 v[196:199], v183 offset:20480
	ds_read_b128 v[200:203], v183 offset:22528
	ds_read_b128 v[204:207], v182 offset:20480
	ds_read_b128 v[208:211], v182 offset:22528
	s_mov_b32 m0, s80
	s_nop 0
	global_load_lds_dwordx4 v167, s[36:37]
	s_mov_b32 m0, s81
	s_nop 0
	global_load_lds_dwordx4 v169, s[36:37]
	s_mov_b32 m0, s29
	s_nop 0
	global_load_lds_dwordx4 v167, s[60:61]
	s_mov_b32 m0, s88
	s_nop 0
	global_load_lds_dwordx4 v169, s[60:61]
	s_mov_b32 m0, s76
	s_nop 0
	global_load_lds_dwordx4 v166, s[40:41]
	s_mov_b32 m0, s89
	s_nop 0
	global_load_lds_dwordx4 v168, s[40:41]
	s_waitcnt vmcnt(8)
	s_waitcnt lgkmcnt(0)
	s_setprio 1
	s_barrier
; #define PG8_STAGE(bufoff, gbase, voff) do { _Pragma("unroll") for (int _i = 0; _i < 2; ++_i) \
;         dma16((const char*)(gbase), (voff)[_i], ldsb + (bufoff) + ldsw + _i * 8192); } while (0)
; #define PG8_LDA(dst, b, h) do { const int a1_ = opqv(aoff0) ^ 64; _Pragma("unroll") for (int m = 0; m < 4; ++m) { dst[m][0] = *(const LAS bf16x8*)(lds + PG8_SA(b, h) + aoff0 + m * 2048); dst[m][1] = *(const LAS bf16x8*)(lds + PG8_SA(b, h) + a1_ + m * 2048); } } while (0)
; #define PG8_LDB(dst, b, h) do { const int b1_ = opqv(boff0) ^ 64; _Pragma("unroll") for (int n = 0; n < 2; ++n) { dst[n][0] = *(const LAS bf16x8*)(lds + PG8_SB(b, h) + boff0 + n * 2048); dst[n][1] = *(const LAS bf16x8*)(lds + PG8_SB(b, h) + b1_ + n * 2048); } } while (0)
; #define PG8_MMA(ai, bj, At, Bt) do { __builtin_amdgcn_s_setprio(1); _Pragma("unroll") for (int m = 0; m < 4; ++m) _Pragma("unroll") for (int n = 0; n < 2; ++n) _Pragma("unroll") for (int k = 0; k < 2; ++k) \
;         acc[ai][bj][m][n] = __builtin_amdgcn_mfma_f32_16x16x32_bf16(Bt[n][k], At[m][k], acc[ai][bj][m][n], 0, 0, 0); __builtin_amdgcn_s_setprio(0); } while (0)
; #define PG8_WAIT_V(n) asm volatile("s_waitcnt vmcnt(" #n ")" ::: "memory")
; #define PG8_WAIT_L(n) asm volatile("s_waitcnt lgkmcnt(" #n ")" ::: "memory")
; #define PG8_BAR __builtin_amdgcn_s_barrier()
; #define PG8_SCHED __builtin_amdgcn_sched_barrier(0)
; template <class Epi>
; __device__ __forceinline__ void gemm_phase(LAS unsigned char* lds, const Gemm g, const StaticOrder& S, const Epi& E, int wave_) {
;     ...
;             PG8_WAIT_V(8); PG8_WAIT_L(0); PG8_BAR; PG8_MMA(1, 0, At, B0); PG8_MMA(1, 1, At, B1); PG8_BAR; PG8_SCHED;
;             PG8_STAGE(PG8_SA(0, 1), a2 + hstepA, voffA); PG8_LDB(B0, 1, 0); PG8_LDB(B1, 1, 1); PG8_SCHED; PG8_LDA(At, 1, 0);
;             PG8_WAIT_V(8); PG8_WAIT_L(0); PG8_BAR; PG8_MMA(0, 0, At, B0); PG8_MMA(0, 1, At, B1); PG8_BAR; PG8_SCHED;
	v_mfma_f32_16x16x32_bf16 v[60:63], v[128:131], v[160:163], 0
	v_mfma_f32_16x16x32_bf16 v[56:59], v[132:135], v[160:163], 0
	v_mfma_f32_16x16x32_bf16 v[44:47], v[128:131], v[174:177], 0
	v_mfma_f32_16x16x32_bf16 v[40:43], v[132:135], v[174:177], 0
	v_mfma_f32_16x16x32_bf16 v[28:31], v[128:131], v[196:199], 0
	v_mfma_f32_16x16x32_bf16 v[24:27], v[132:135], v[196:199], 0
	v_mfma_f32_16x16x32_bf16 v[12:15], v[128:131], v[200:203], 0
	v_mfma_f32_16x16x32_bf16 v[8:11], v[132:135], v[200:203], 0
	v_mfma_f32_16x16x32_bf16 v[60:63], v[136:139], v[178:181], v[60:63]
	v_mfma_f32_16x16x32_bf16 v[56:59], v[140:143], v[178:181], v[56:59]
	v_mfma_f32_16x16x32_bf16 v[44:47], v[136:139], v[192:195], v[44:47]
	v_mfma_f32_16x16x32_bf16 v[40:43], v[140:143], v[192:195], v[40:43]
	v_mfma_f32_16x16x32_bf16 v[28:31], v[136:139], v[204:207], v[28:31]
	v_mfma_f32_16x16x32_bf16 v[24:27], v[140:143], v[204:207], v[24:27]
	v_mfma_f32_16x16x32_bf16 v[12:15], v[136:139], v[208:211], v[12:15]
	v_mfma_f32_16x16x32_bf16 v[8:11], v[140:143], v[208:211], v[8:11]
	s_setprio 0
	s_setprio 1
	v_mfma_f32_16x16x32_bf16 v[52:55], v[144:147], v[160:163], 0
	v_mfma_f32_16x16x32_bf16 v[48:51], v[148:151], v[160:163], 0
	v_mfma_f32_16x16x32_bf16 v[36:39], v[144:147], v[174:177], 0
	v_mfma_f32_16x16x32_bf16 v[32:35], v[148:151], v[174:177], 0
	v_mfma_f32_16x16x32_bf16 v[20:23], v[144:147], v[196:199], 0
	v_mfma_f32_16x16x32_bf16 v[16:19], v[148:151], v[196:199], 0
	v_mfma_f32_16x16x32_bf16 v[4:7], v[144:147], v[200:203], 0
	v_mfma_f32_16x16x32_bf16 v[0:3], v[148:151], v[200:203], 0
	v_mfma_f32_16x16x32_bf16 v[52:55], v[152:155], v[178:181], v[52:55]
	v_mfma_f32_16x16x32_bf16 v[48:51], v[156:159], v[178:181], v[48:51]
	v_mfma_f32_16x16x32_bf16 v[36:39], v[152:155], v[192:195], v[36:39]
	v_mfma_f32_16x16x32_bf16 v[32:35], v[156:159], v[192:195], v[32:35]
	v_mfma_f32_16x16x32_bf16 v[20:23], v[152:155], v[204:207], v[20:23]
	v_mfma_f32_16x16x32_bf16 v[16:19], v[156:159], v[204:207], v[16:19]
	v_mfma_f32_16x16x32_bf16 v[4:7], v[152:155], v[208:211], v[4:7]
	v_mfma_f32_16x16x32_bf16 v[0:3], v[156:159], v[208:211], v[0:3]
	s_setprio 0
	s_barrier
	s_add_u32 s40, s40, 0x80000
	s_addc_u32 s41, s41, 0
	s_mov_b32 m0, s1
	s_nop 0
	global_load_lds_dwordx4 v166, s[40:41]
	v_mov_b32_e32 v128, v172
	s_mov_b32 m0, s69
	s_nop 0
	global_load_lds_dwordx4 v168, s[40:41]
	v_add_u32_e32 v132, s34, v172
	v_xad_u32 v140, v128, 64, s34
	v_mov_b32_e32 v144, v172
	s_add_i32 s40, 0, 0x1c000
	ds_read_b128 v[128:131], v132
	ds_read_b128 v[132:135], v132 offset:2048
	ds_read_b128 v[136:139], v140
	ds_read_b128 v[140:143], v140 offset:2048
	v_add_u32_e32 v148, s40, v172
	v_xad_u32 v156, v144, 64, s40
	ds_read_b128 v[144:147], v148
	ds_read_b128 v[148:151], v148 offset:2048
	ds_read_b128 v[152:155], v156
	ds_read_b128 v[156:159], v156 offset:2048
	v_mov_b32_e32 v160, v171
	s_nop 0
	v_xad_u32 v182, v160, 64, 0
	ds_read_b128 v[160:163], v183 offset:32768
	ds_read_b128 v[174:177], v183 offset:34816
	ds_read_b128 v[178:181], v182 offset:32768
	ds_read_b128 v[192:195], v182 offset:34816
	ds_read_b128 v[196:199], v183 offset:36864
	ds_read_b128 v[200:203], v183 offset:38912
	ds_read_b128 v[204:207], v182 offset:36864
	ds_read_b128 v[208:211], v182 offset:38912
	s_waitcnt vmcnt(8)
	s_waitcnt lgkmcnt(0)
	s_setprio 1
	s_barrier
	v_mfma_f32_16x16x32_bf16 v[124:127], v[128:131], v[160:163], v[124:127]
	v_mfma_f32_16x16x32_bf16 v[120:123], v[132:135], v[160:163], v[120:123]
	v_mfma_f32_16x16x32_bf16 v[108:111], v[128:131], v[174:177], v[108:111]
	v_mfma_f32_16x16x32_bf16 v[104:107], v[132:135], v[174:177], v[104:107]
	v_mfma_f32_16x16x32_bf16 v[92:95], v[128:131], v[196:199], v[92:95]
	v_mfma_f32_16x16x32_bf16 v[88:91], v[132:135], v[196:199], v[88:91]
	v_mfma_f32_16x16x32_bf16 v[76:79], v[128:131], v[200:203], v[76:79]
	v_mfma_f32_16x16x32_bf16 v[72:75], v[132:135], v[200:203], v[72:75]
	v_mfma_f32_16x16x32_bf16 v[124:127], v[136:139], v[178:181], v[124:127]
	v_mfma_f32_16x16x32_bf16 v[120:123], v[140:143], v[178:181], v[120:123]
	v_mfma_f32_16x16x32_bf16 v[108:111], v[136:139], v[192:195], v[108:111]
	v_mfma_f32_16x16x32_bf16 v[104:107], v[140:143], v[192:195], v[104:107]
	v_mfma_f32_16x16x32_bf16 v[92:95], v[136:139], v[204:207], v[92:95]
	v_mfma_f32_16x16x32_bf16 v[88:91], v[140:143], v[204:207], v[88:91]
	v_mfma_f32_16x16x32_bf16 v[76:79], v[136:139], v[208:211], v[76:79]
	v_mfma_f32_16x16x32_bf16 v[72:75], v[140:143], v[208:211], v[72:75]
	s_setprio 0
	s_setprio 1
	v_mfma_f32_16x16x32_bf16 v[116:119], v[144:147], v[160:163], v[116:119]
	s_add_u32 s40, s36, 0x80
	s_addc_u32 s41, s37, 0
	v_mfma_f32_16x16x32_bf16 v[112:115], v[148:151], v[160:163], v[112:115]
	v_mfma_f32_16x16x32_bf16 v[100:103], v[144:147], v[174:177], v[100:103]
	v_mfma_f32_16x16x32_bf16 v[96:99], v[148:151], v[174:177], v[96:99]
	v_mfma_f32_16x16x32_bf16 v[84:87], v[144:147], v[196:199], v[84:87]
	v_mfma_f32_16x16x32_bf16 v[80:83], v[148:151], v[196:199], v[80:83]
	v_mfma_f32_16x16x32_bf16 v[68:71], v[144:147], v[200:203], v[68:71]
	v_mfma_f32_16x16x32_bf16 v[64:67], v[148:151], v[200:203], v[64:67]
	v_mfma_f32_16x16x32_bf16 v[116:119], v[152:155], v[178:181], v[116:119]
	v_mfma_f32_16x16x32_bf16 v[112:115], v[156:159], v[178:181], v[112:115]
	v_mfma_f32_16x16x32_bf16 v[100:103], v[152:155], v[192:195], v[100:103]
	v_mfma_f32_16x16x32_bf16 v[96:99], v[156:159], v[192:195], v[96:99]
	v_mfma_f32_16x16x32_bf16 v[84:87], v[152:155], v[204:207], v[84:87]
	v_mfma_f32_16x16x32_bf16 v[80:83], v[156:159], v[204:207], v[80:83]
	v_mfma_f32_16x16x32_bf16 v[68:71], v[152:155], v[208:211], v[68:71]
	v_mfma_f32_16x16x32_bf16 v[64:67], v[156:159], v[208:211], v[64:67]
	s_setprio 0
	s_barrier
; #define PG8_STAGE(bufoff, gbase, voff) do { _Pragma("unroll") for (int _i = 0; _i < 2; ++_i) \
;         dma16((const char*)(gbase), (voff)[_i], ldsb + (bufoff) + ldsw + _i * 8192); } while (0)
; #define PG8_LDA(dst, b, h) do { const int a1_ = opqv(aoff0) ^ 64; _Pragma("unroll") for (int m = 0; m < 4; ++m) { dst[m][0] = *(const LAS bf16x8*)(lds + PG8_SA(b, h) + aoff0 + m * 2048); dst[m][1] = *(const LAS bf16x8*)(lds + PG8_SA(b, h) + a1_ + m * 2048); } } while (0)
; #define PG8_LDB(dst, b, h) do { const int b1_ = opqv(boff0) ^ 64; _Pragma("unroll") for (int n = 0; n < 2; ++n) { dst[n][0] = *(const LAS bf16x8*)(lds + PG8_SB(b, h) + boff0 + n * 2048); dst[n][1] = *(const LAS bf16x8*)(lds + PG8_SB(b, h) + b1_ + n * 2048); } } while (0)
; #define PG8_WAIT_V(n) asm volatile("s_waitcnt vmcnt(" #n ")" ::: "memory")
; template <class Epi>
; __device__ __forceinline__ void gemm_phase(LAS unsigned char* lds, const Gemm g, const StaticOrder& S, const Epi& E, int wave_) {
;     ...
;         for (int t = 0; t < nt; t += 2) {
;             const bool last = (t == nt - 2);
;             const char* a1 = cA + (size_t)(t + 1) * kstep;
;             const char* a2 = last ? nA : cA + (size_t)(t + 2) * kstep; const char* b2 = last ? nB : cB + (size_t)(t + 2) * kstep;
;             const char* a3 = a2 + kstep; const char* b3 = b2 + kstep;
;             PG8_STAGE(PG8_SA(1, 1), a1 + hstepA, voffA); PG8_LDB(B0, 0, 0); PG8_LDB(B1, 0, 1); PG8_SCHED; PG8_LDA(At, 0, 0);
;             PG8_WAIT_V(8); PG8_WAIT_L(0); PG8_BAR; PG8_MMA(0, 0, At, B0); PG8_MMA(0, 1, At, B1); PG8_BAR; PG8_SCHED;
;             PG8_STAGE(PG8_SB(0, 0), b2, voffB); PG8_STAGE(PG8_SB(0, 1), b2 + hstepB, voffB); PG8_STAGE(PG8_SA(0, 0), a2, voffA); PG8_LDA(At, 0, 1);
;             PG8_WAIT_V(8); PG8_WAIT_L(0); PG8_BAR; PG8_MMA(1, 0, At, B0); PG8_MMA(1, 1, At, B1); PG8_BAR; PG8_SCHED;
;             PG8_STAGE(PG8_SA(0, 1), a2 + hstepA, voffA); PG8_LDB(B0, 1, 0); PG8_LDB(B1, 1, 1); PG8_SCHED; PG8_LDA(At, 1, 0);
;             PG8_WAIT_V(8); PG8_WAIT_L(0); PG8_BAR; PG8_MMA(0, 0, At, B0); PG8_MMA(0, 1, At, B1); PG8_BAR; PG8_SCHED;
;             PG8_STAGE(PG8_SB(1, 0), b3, voffB); PG8_STAGE(PG8_SB(1, 1), b3 + hstepB, voffB); PG8_STAGE(PG8_SA(1, 0), a3, voffA); PG8_LDA(At, 1, 1);
;             PG8_WAIT_V(8); PG8_WAIT_L(0); PG8_BAR; PG8_MMA(1, 0, At, B0); PG8_MMA(1, 1, At, B1); PG8_BAR; PG8_SCHED;
	s_add_u32 s36, s36, 0x80080
	s_addc_u32 s37, s37, 0
	v_mov_b32_e32 v160, v171
	s_nop 0
	s_nop 0
	v_xad_u32 v182, v160, 64, 0
	ds_read_b128 v[160:163], v183 offset:49152
	ds_read_b128 v[174:177], v183 offset:51200
	ds_read_b128 v[178:181], v182 offset:49152
	ds_read_b128 v[192:195], v182 offset:51200
	ds_read_b128 v[196:199], v183 offset:53248
	ds_read_b128 v[200:203], v183 offset:55296
	ds_read_b128 v[204:207], v182 offset:53248
	ds_read_b128 v[208:211], v182 offset:55296
	s_mov_b32 m0, s35
	s_nop 0
	global_load_lds_dwordx4 v167, s[40:41]
	s_mov_b32 m0, s33
	s_nop 0
	global_load_lds_dwordx4 v169, s[40:41]
	s_mov_b32 m0, s77
	s_nop 0
	global_load_lds_dwordx4 v167, s[36:37]
	s_mov_b32 m0, s3
	s_nop 0
	global_load_lds_dwordx4 v169, s[36:37]
	s_mov_b32 m0, s22
	s_nop 0
	global_load_lds_dwordx4 v166, s[30:31]
	s_mov_b32 m0, s2
	s_nop 0
	global_load_lds_dwordx4 v168, s[30:31]
	s_waitcnt vmcnt(8)
	s_waitcnt lgkmcnt(0)
	s_setprio 1
	s_barrier
	v_mfma_f32_16x16x32_bf16 v[60:63], v[128:131], v[160:163], v[60:63]
	v_mfma_f32_16x16x32_bf16 v[56:59], v[132:135], v[160:163], v[56:59]
	v_mfma_f32_16x16x32_bf16 v[44:47], v[128:131], v[174:177], v[44:47]
	v_mfma_f32_16x16x32_bf16 v[40:43], v[132:135], v[174:177], v[40:43]
	v_mfma_f32_16x16x32_bf16 v[28:31], v[128:131], v[196:199], v[28:31]
	v_mfma_f32_16x16x32_bf16 v[24:27], v[132:135], v[196:199], v[24:27]
	v_mfma_f32_16x16x32_bf16 v[12:15], v[128:131], v[200:203], v[12:15]
	v_mfma_f32_16x16x32_bf16 v[8:11], v[132:135], v[200:203], v[8:11]
	v_mfma_f32_16x16x32_bf16 v[60:63], v[136:139], v[178:181], v[60:63]
	v_mfma_f32_16x16x32_bf16 v[56:59], v[140:143], v[178:181], v[56:59]
	v_mfma_f32_16x16x32_bf16 v[44:47], v[136:139], v[192:195], v[44:47]
	v_mfma_f32_16x16x32_bf16 v[40:43], v[140:143], v[192:195], v[40:43]
	v_mfma_f32_16x16x32_bf16 v[28:31], v[136:139], v[204:207], v[28:31]
	v_mfma_f32_16x16x32_bf16 v[24:27], v[140:143], v[204:207], v[24:27]
	v_mfma_f32_16x16x32_bf16 v[12:15], v[136:139], v[208:211], v[12:15]
	v_mfma_f32_16x16x32_bf16 v[8:11], v[140:143], v[208:211], v[8:11]
	s_setprio 0
	s_setprio 1
	v_mfma_f32_16x16x32_bf16 v[52:55], v[144:147], v[160:163], v[52:55]
	v_mfma_f32_16x16x32_bf16 v[48:51], v[148:151], v[160:163], v[48:51]
	v_mfma_f32_16x16x32_bf16 v[36:39], v[144:147], v[174:177], v[36:39]
	v_mfma_f32_16x16x32_bf16 v[32:35], v[148:151], v[174:177], v[32:35]
	v_mfma_f32_16x16x32_bf16 v[20:23], v[144:147], v[196:199], v[20:23]
	v_mfma_f32_16x16x32_bf16 v[16:19], v[148:151], v[196:199], v[16:19]
	v_mfma_f32_16x16x32_bf16 v[4:7], v[144:147], v[200:203], v[4:7]
	v_mfma_f32_16x16x32_bf16 v[0:3], v[148:151], v[200:203], v[0:3]
	v_mfma_f32_16x16x32_bf16 v[52:55], v[152:155], v[178:181], v[52:55]
	v_mfma_f32_16x16x32_bf16 v[48:51], v[156:159], v[178:181], v[48:51]
	v_mfma_f32_16x16x32_bf16 v[36:39], v[152:155], v[192:195], v[36:39]
	v_mfma_f32_16x16x32_bf16 v[32:35], v[156:159], v[192:195], v[32:35]
	v_mfma_f32_16x16x32_bf16 v[20:23], v[152:155], v[204:207], v[20:23]
	v_mfma_f32_16x16x32_bf16 v[16:19], v[156:159], v[204:207], v[16:19]
	v_mfma_f32_16x16x32_bf16 v[4:7], v[152:155], v[208:211], v[4:7]
	v_mfma_f32_16x16x32_bf16 v[0:3], v[156:159], v[208:211], v[0:3]
	s_setprio 0
	s_barrier
	s_add_i32 s57, s57, 2
	s_add_u32 s55, s55, 0x100
	s_addc_u32 s56, s56, 0
	s_add_u32 s12, s12, 0x100
	s_addc_u32 s13, s13, 0
	s_cmp_gt_u32 s57, 29
	s_cbranch_scc0 .LBB0_1104
	s_branch .Lpeel_exit_4
.LBB0_1104:
	s_add_u32 s30, s12, 0xfff80080
	s_addc_u32 s31, s13, -1
	s_cmp_eq_u32 s57, 28
	s_cselect_b32 s40, s17, s30
	s_cselect_b32 s41, s16, s31
	s_cselect_b32 s36, s19, s55
	s_cselect_b32 s37, s11, s56
	s_add_u32 s30, s40, 0x80
	v_mov_b32_e32 v128, v172
	s_addc_u32 s31, s41, 0
	v_add_u32_e32 v132, s23, v172
	v_xad_u32 v140, v128, 64, s23
	v_mov_b32_e32 v144, v172
	s_add_i32 s60, 0, 0x14000
	ds_read_b128 v[128:131], v132
	ds_read_b128 v[132:135], v132 offset:2048
	ds_read_b128 v[136:139], v140
	ds_read_b128 v[140:143], v140 offset:2048
	v_add_u32_e32 v148, s60, v172
	v_xad_u32 v156, v144, 64, s60
	ds_read_b128 v[144:147], v148
	ds_read_b128 v[148:151], v148 offset:2048
	ds_read_b128 v[152:155], v156
	ds_read_b128 v[156:159], v156 offset:2048
	v_mov_b32_e32 v160, v171
	v_add_u32_e32 v183, 0, v171
	v_xad_u32 v182, v160, 64, 0
	ds_read_b128 v[160:163], v183
	ds_read_b128 v[174:177], v183 offset:2048
	ds_read_b128 v[178:181], v182
	ds_read_b128 v[192:195], v182 offset:2048
	ds_read_b128 v[196:199], v183 offset:4096
	ds_read_b128 v[200:203], v183 offset:6144
	ds_read_b128 v[204:207], v182 offset:4096
	ds_read_b128 v[208:211], v182 offset:6144
	s_mov_b32 m0, s14
	s_nop 0
	global_load_lds_dwordx4 v166, s[12:13]
	s_mov_b32 m0, s15
	s_nop 0
	global_load_lds_dwordx4 v168, s[12:13]
	s_waitcnt vmcnt(8)
	s_waitcnt lgkmcnt(0)
	s_setprio 1
	s_barrier
; #define PG8_STAGE(bufoff, gbase, voff) do { _Pragma("unroll") for (int _i = 0; _i < 2; ++_i) \
;         dma16((const char*)(gbase), (voff)[_i], ldsb + (bufoff) + ldsw + _i * 8192); } while (0)
; #define PG8_LDA(dst, b, h) do { const int a1_ = opqv(aoff0) ^ 64; _Pragma("unroll") for (int m = 0; m < 4; ++m) { dst[m][0] = *(const LAS bf16x8*)(lds + PG8_SA(b, h) + aoff0 + m * 2048); dst[m][1] = *(const LAS bf16x8*)(lds + PG8_SA(b, h) + a1_ + m * 2048); } } while (0)
; #define PG8_MMA(ai, bj, At, Bt) do { __builtin_amdgcn_s_setprio(1); _Pragma("unroll") for (int m = 0; m < 4; ++m) _Pragma("unroll") for (int n = 0; n < 2; ++n) _Pragma("unroll") for (int k = 0; k < 2; ++k) \
;         acc[ai][bj][m][n] = __builtin_amdgcn_mfma_f32_16x16x32_bf16(Bt[n][k], At[m][k], acc[ai][bj][m][n], 0, 0, 0); __builtin_amdgcn_s_setprio(0); } while (0)
; #define PG8_WAIT_V(n) asm volatile("s_waitcnt vmcnt(" #n ")" ::: "memory")
; #define PG8_WAIT_L(n) asm volatile("s_waitcnt lgkmcnt(" #n ")" ::: "memory")
; #define PG8_BAR __builtin_amdgcn_s_barrier()
; #define PG8_SCHED __builtin_amdgcn_sched_barrier(0)
; template <class Epi>
; __device__ __forceinline__ void gemm_phase(LAS unsigned char* lds, const Gemm g, const StaticOrder& S, const Epi& E, int wave_) {
;     ...
;             PG8_WAIT_V(8); PG8_WAIT_L(0); PG8_BAR; PG8_MMA(0, 0, At, B0); PG8_MMA(0, 1, At, B1); PG8_BAR; PG8_SCHED;
;             PG8_STAGE(PG8_SB(0, 0), b2, voffB); PG8_STAGE(PG8_SB(0, 1), b2 + hstepB, voffB); PG8_STAGE(PG8_SA(0, 0), a2, voffA); PG8_LDA(At, 0, 1);
;             PG8_WAIT_V(8); PG8_WAIT_L(0); PG8_BAR; PG8_MMA(1, 0, At, B0); PG8_MMA(1, 1, At, B1); PG8_BAR; PG8_SCHED;
	v_mfma_f32_16x16x32_bf16 v[124:127], v[128:131], v[160:163], v[124:127]
	v_mfma_f32_16x16x32_bf16 v[120:123], v[132:135], v[160:163], v[120:123]
	v_mfma_f32_16x16x32_bf16 v[108:111], v[128:131], v[174:177], v[108:111]
	v_mfma_f32_16x16x32_bf16 v[104:107], v[132:135], v[174:177], v[104:107]
	v_mfma_f32_16x16x32_bf16 v[92:95], v[128:131], v[196:199], v[92:95]
	v_mfma_f32_16x16x32_bf16 v[88:91], v[132:135], v[196:199], v[88:91]
	v_mfma_f32_16x16x32_bf16 v[76:79], v[128:131], v[200:203], v[76:79]
	v_mfma_f32_16x16x32_bf16 v[72:75], v[132:135], v[200:203], v[72:75]
	v_mfma_f32_16x16x32_bf16 v[124:127], v[136:139], v[178:181], v[124:127]
	v_mfma_f32_16x16x32_bf16 v[120:123], v[140:143], v[178:181], v[120:123]
	v_mfma_f32_16x16x32_bf16 v[108:111], v[136:139], v[192:195], v[108:111]
	v_mfma_f32_16x16x32_bf16 v[104:107], v[140:143], v[192:195], v[104:107]
	v_mfma_f32_16x16x32_bf16 v[92:95], v[136:139], v[204:207], v[92:95]
	v_mfma_f32_16x16x32_bf16 v[88:91], v[140:143], v[204:207], v[88:91]
	v_mfma_f32_16x16x32_bf16 v[76:79], v[136:139], v[208:211], v[76:79]
	v_mfma_f32_16x16x32_bf16 v[72:75], v[140:143], v[208:211], v[72:75]
	s_setprio 0
	s_setprio 1
	v_mfma_f32_16x16x32_bf16 v[116:119], v[144:147], v[160:163], v[116:119]
	v_mfma_f32_16x16x32_bf16 v[112:115], v[148:151], v[160:163], v[112:115]
	v_mfma_f32_16x16x32_bf16 v[100:103], v[144:147], v[174:177], v[100:103]
	v_mfma_f32_16x16x32_bf16 v[96:99], v[148:151], v[174:177], v[96:99]
	v_mfma_f32_16x16x32_bf16 v[84:87], v[144:147], v[196:199], v[84:87]
	v_mfma_f32_16x16x32_bf16 v[80:83], v[148:151], v[196:199], v[80:83]
	v_mfma_f32_16x16x32_bf16 v[68:71], v[144:147], v[200:203], v[68:71]
	v_mfma_f32_16x16x32_bf16 v[64:67], v[148:151], v[200:203], v[64:67]
	v_mfma_f32_16x16x32_bf16 v[116:119], v[152:155], v[178:181], v[116:119]
	v_mfma_f32_16x16x32_bf16 v[112:115], v[156:159], v[178:181], v[112:115]
	v_mfma_f32_16x16x32_bf16 v[100:103], v[152:155], v[192:195], v[100:103]
	v_mfma_f32_16x16x32_bf16 v[96:99], v[156:159], v[192:195], v[96:99]
	v_mfma_f32_16x16x32_bf16 v[84:87], v[152:155], v[204:207], v[84:87]
	v_mfma_f32_16x16x32_bf16 v[80:83], v[156:159], v[204:207], v[80:83]
	v_mfma_f32_16x16x32_bf16 v[68:71], v[152:155], v[208:211], v[68:71]
	v_mfma_f32_16x16x32_bf16 v[64:67], v[156:159], v[208:211], v[64:67]
	s_setprio 0
	s_barrier
	v_mov_b32_e32 v160, v171
	s_add_u32 s60, s36, 0x80000
	s_addc_u32 s61, s37, 0
	s_nop 0
	s_nop 0
	s_nop 0
	v_xad_u32 v182, v160, 64, 0
	ds_read_b128 v[160:163], v183 offset:16384
	ds_read_b128 v[174:177], v183 offset:18432
	ds_read_b128 v[178:181], v182 offset:16384
	ds_read_b128 v[192:195], v182 offset:18432
	ds_read_b128 v[196:199], v183 offset:20480
	ds_read_b128 v[200:203], v183 offset:22528
	ds_read_b128 v[204:207], v182 offset:20480
	ds_read_b128 v[208:211], v182 offset:22528
	s_mov_b32 m0, s80
	s_nop 0
	global_load_lds_dwordx4 v167, s[36:37]
	s_mov_b32 m0, s81
	s_nop 0
	global_load_lds_dwordx4 v169, s[36:37]
	s_mov_b32 m0, s29
	s_nop 0
	global_load_lds_dwordx4 v167, s[60:61]
	s_mov_b32 m0, s88
	s_nop 0
	global_load_lds_dwordx4 v169, s[60:61]
	s_mov_b32 m0, s76
	s_nop 0
	global_load_lds_dwordx4 v166, s[40:41]
	s_mov_b32 m0, s89
	s_nop 0
	global_load_lds_dwordx4 v168, s[40:41]
	s_waitcnt vmcnt(8)
	s_waitcnt lgkmcnt(0)
	s_setprio 1
	s_barrier
	v_mfma_f32_16x16x32_bf16 v[60:63], v[128:131], v[160:163], v[60:63]
	v_mfma_f32_16x16x32_bf16 v[56:59], v[132:135], v[160:163], v[56:59]
	v_mfma_f32_16x16x32_bf16 v[44:47], v[128:131], v[174:177], v[44:47]
	v_mfma_f32_16x16x32_bf16 v[40:43], v[132:135], v[174:177], v[40:43]
	v_mfma_f32_16x16x32_bf16 v[28:31], v[128:131], v[196:199], v[28:31]
	v_mfma_f32_16x16x32_bf16 v[24:27], v[132:135], v[196:199], v[24:27]
	v_mfma_f32_16x16x32_bf16 v[12:15], v[128:131], v[200:203], v[12:15]
	v_mfma_f32_16x16x32_bf16 v[8:11], v[132:135], v[200:203], v[8:11]
	v_mfma_f32_16x16x32_bf16 v[60:63], v[136:139], v[178:181], v[60:63]
	v_mfma_f32_16x16x32_bf16 v[56:59], v[140:143], v[178:181], v[56:59]
	v_mfma_f32_16x16x32_bf16 v[44:47], v[136:139], v[192:195], v[44:47]
	v_mfma_f32_16x16x32_bf16 v[40:43], v[140:143], v[192:195], v[40:43]
	v_mfma_f32_16x16x32_bf16 v[28:31], v[136:139], v[204:207], v[28:31]
	v_mfma_f32_16x16x32_bf16 v[24:27], v[140:143], v[204:207], v[24:27]
	v_mfma_f32_16x16x32_bf16 v[12:15], v[136:139], v[208:211], v[12:15]
	v_mfma_f32_16x16x32_bf16 v[8:11], v[140:143], v[208:211], v[8:11]
	s_setprio 0
	s_setprio 1
	v_mfma_f32_16x16x32_bf16 v[52:55], v[144:147], v[160:163], v[52:55]
	v_mfma_f32_16x16x32_bf16 v[48:51], v[148:151], v[160:163], v[48:51]
	v_mfma_f32_16x16x32_bf16 v[36:39], v[144:147], v[174:177], v[36:39]
	v_mfma_f32_16x16x32_bf16 v[32:35], v[148:151], v[174:177], v[32:35]
	v_mfma_f32_16x16x32_bf16 v[20:23], v[144:147], v[196:199], v[20:23]
	v_mfma_f32_16x16x32_bf16 v[16:19], v[148:151], v[196:199], v[16:19]
	v_mfma_f32_16x16x32_bf16 v[4:7], v[144:147], v[200:203], v[4:7]
	v_mfma_f32_16x16x32_bf16 v[0:3], v[148:151], v[200:203], v[0:3]
	v_mfma_f32_16x16x32_bf16 v[52:55], v[152:155], v[178:181], v[52:55]
	v_mfma_f32_16x16x32_bf16 v[48:51], v[156:159], v[178:181], v[48:51]
	v_mfma_f32_16x16x32_bf16 v[36:39], v[152:155], v[192:195], v[36:39]
	v_mfma_f32_16x16x32_bf16 v[32:35], v[156:159], v[192:195], v[32:35]
	v_mfma_f32_16x16x32_bf16 v[20:23], v[152:155], v[204:207], v[20:23]
	v_mfma_f32_16x16x32_bf16 v[16:19], v[156:159], v[204:207], v[16:19]
	v_mfma_f32_16x16x32_bf16 v[4:7], v[152:155], v[208:211], v[4:7]
	v_mfma_f32_16x16x32_bf16 v[0:3], v[156:159], v[208:211], v[0:3]
	s_setprio 0
	s_barrier
; #define PG8_STAGE(bufoff, gbase, voff) do { _Pragma("unroll") for (int _i = 0; _i < 2; ++_i) \
;         dma16((const char*)(gbase), (voff)[_i], ldsb + (bufoff) + ldsw + _i * 8192); } while (0)
; #define PG8_LDA(dst, b, h) do { const int a1_ = opqv(aoff0) ^ 64; _Pragma("unroll") for (int m = 0; m < 4; ++m) { dst[m][0] = *(const LAS bf16x8*)(lds + PG8_SA(b, h) + aoff0 + m * 2048); dst[m][1] = *(const LAS bf16x8*)(lds + PG8_SA(b, h) + a1_ + m * 2048); } } while (0)
; #define PG8_LDB(dst, b, h) do { const int b1_ = opqv(boff0) ^ 64; _Pragma("unroll") for (int n = 0; n < 2; ++n) { dst[n][0] = *(const LAS bf16x8*)(lds + PG8_SB(b, h) + boff0 + n * 2048); dst[n][1] = *(const LAS bf16x8*)(lds + PG8_SB(b, h) + b1_ + n * 2048); } } while (0)
; #define PG8_MMA(ai, bj, At, Bt) do { __builtin_amdgcn_s_setprio(1); _Pragma("unroll") for (int m = 0; m < 4; ++m) _Pragma("unroll") for (int n = 0; n < 2; ++n) _Pragma("unroll") for (int k = 0; k < 2; ++k) \
;         acc[ai][bj][m][n] = __builtin_amdgcn_mfma_f32_16x16x32_bf16(Bt[n][k], At[m][k], acc[ai][bj][m][n], 0, 0, 0); __builtin_amdgcn_s_setprio(0); } while (0)
; #define PG8_WAIT_V(n) asm volatile("s_waitcnt vmcnt(" #n ")" ::: "memory")
; #define PG8_WAIT_L(n) asm volatile("s_waitcnt lgkmcnt(" #n ")" ::: "memory")
; #define PG8_BAR __builtin_amdgcn_s_barrier()
; #define PG8_SCHED __builtin_amdgcn_sched_barrier(0)
; template <class Epi>
; __device__ __forceinline__ void gemm_phase(LAS unsigned char* lds, const Gemm g, const StaticOrder& S, const Epi& E, int wave_) {
;     ...
;             PG8_STAGE(PG8_SA(0, 1), a2 + hstepA, voffA); PG8_LDB(B0, 1, 0); PG8_LDB(B1, 1, 1); PG8_SCHED; PG8_LDA(At, 1, 0);
;             PG8_WAIT_V(8); PG8_WAIT_L(0); PG8_BAR; PG8_MMA(0, 0, At, B0); PG8_MMA(0, 1, At, B1); PG8_BAR; PG8_SCHED;
;             PG8_STAGE(PG8_SB(1, 0), b3, voffB); PG8_STAGE(PG8_SB(1, 1), b3 + hstepB, voffB); PG8_STAGE(PG8_SA(1, 0), a3, voffA); PG8_LDA(At, 1, 1);
;             PG8_WAIT_V(8); PG8_WAIT_L(0); PG8_BAR; PG8_MMA(1, 0, At, B0); PG8_MMA(1, 1, At, B1); PG8_BAR; PG8_SCHED;
;         }
	s_add_u32 s40, s40, 0x80000
	s_addc_u32 s41, s41, 0
	s_mov_b32 m0, s1
	s_nop 0
	global_load_lds_dwordx4 v166, s[40:41]
	v_mov_b32_e32 v128, v172
	s_mov_b32 m0, s69
	s_nop 0
	global_load_lds_dwordx4 v168, s[40:41]
	v_add_u32_e32 v132, s34, v172
	v_xad_u32 v140, v128, 64, s34
	v_mov_b32_e32 v144, v172
	s_add_i32 s40, 0, 0x1c000
	ds_read_b128 v[128:131], v132
	ds_read_b128 v[132:135], v132 offset:2048
	ds_read_b128 v[136:139], v140
	ds_read_b128 v[140:143], v140 offset:2048
	v_add_u32_e32 v148, s40, v172
	v_xad_u32 v156, v144, 64, s40
	ds_read_b128 v[144:147], v148
	ds_read_b128 v[148:151], v148 offset:2048
	ds_read_b128 v[152:155], v156
	ds_read_b128 v[156:159], v156 offset:2048
	v_mov_b32_e32 v160, v171
	s_nop 0
	v_xad_u32 v182, v160, 64, 0
	ds_read_b128 v[160:163], v183 offset:32768
	ds_read_b128 v[174:177], v183 offset:34816
	ds_read_b128 v[178:181], v182 offset:32768
	ds_read_b128 v[192:195], v182 offset:34816
	ds_read_b128 v[196:199], v183 offset:36864
	ds_read_b128 v[200:203], v183 offset:38912
	ds_read_b128 v[204:207], v182 offset:36864
	ds_read_b128 v[208:211], v182 offset:38912
	s_waitcnt vmcnt(8)
	s_waitcnt lgkmcnt(0)
	s_setprio 1
	s_barrier
	v_mfma_f32_16x16x32_bf16 v[124:127], v[128:131], v[160:163], v[124:127]
	v_mfma_f32_16x16x32_bf16 v[120:123], v[132:135], v[160:163], v[120:123]
	v_mfma_f32_16x16x32_bf16 v[108:111], v[128:131], v[174:177], v[108:111]
	v_mfma_f32_16x16x32_bf16 v[104:107], v[132:135], v[174:177], v[104:107]
	v_mfma_f32_16x16x32_bf16 v[92:95], v[128:131], v[196:199], v[92:95]
	v_mfma_f32_16x16x32_bf16 v[88:91], v[132:135], v[196:199], v[88:91]
	v_mfma_f32_16x16x32_bf16 v[76:79], v[128:131], v[200:203], v[76:79]
	v_mfma_f32_16x16x32_bf16 v[72:75], v[132:135], v[200:203], v[72:75]
	v_mfma_f32_16x16x32_bf16 v[124:127], v[136:139], v[178:181], v[124:127]
	v_mfma_f32_16x16x32_bf16 v[120:123], v[140:143], v[178:181], v[120:123]
	v_mfma_f32_16x16x32_bf16 v[108:111], v[136:139], v[192:195], v[108:111]
	v_mfma_f32_16x16x32_bf16 v[104:107], v[140:143], v[192:195], v[104:107]
	v_mfma_f32_16x16x32_bf16 v[92:95], v[136:139], v[204:207], v[92:95]
	v_mfma_f32_16x16x32_bf16 v[88:91], v[140:143], v[204:207], v[88:91]
	v_mfma_f32_16x16x32_bf16 v[76:79], v[136:139], v[208:211], v[76:79]
	v_mfma_f32_16x16x32_bf16 v[72:75], v[140:143], v[208:211], v[72:75]
	s_setprio 0
	s_setprio 1
	v_mfma_f32_16x16x32_bf16 v[116:119], v[144:147], v[160:163], v[116:119]
	s_add_u32 s40, s36, 0x80
	s_addc_u32 s41, s37, 0
	v_mfma_f32_16x16x32_bf16 v[112:115], v[148:151], v[160:163], v[112:115]
	v_mfma_f32_16x16x32_bf16 v[100:103], v[144:147], v[174:177], v[100:103]
	v_mfma_f32_16x16x32_bf16 v[96:99], v[148:151], v[174:177], v[96:99]
	v_mfma_f32_16x16x32_bf16 v[84:87], v[144:147], v[196:199], v[84:87]
	v_mfma_f32_16x16x32_bf16 v[80:83], v[148:151], v[196:199], v[80:83]
	v_mfma_f32_16x16x32_bf16 v[68:71], v[144:147], v[200:203], v[68:71]
	v_mfma_f32_16x16x32_bf16 v[64:67], v[148:151], v[200:203], v[64:67]
	v_mfma_f32_16x16x32_bf16 v[116:119], v[152:155], v[178:181], v[116:119]
	v_mfma_f32_16x16x32_bf16 v[112:115], v[156:159], v[178:181], v[112:115]
	v_mfma_f32_16x16x32_bf16 v[100:103], v[152:155], v[192:195], v[100:103]
	v_mfma_f32_16x16x32_bf16 v[96:99], v[156:159], v[192:195], v[96:99]
	v_mfma_f32_16x16x32_bf16 v[84:87], v[152:155], v[204:207], v[84:87]
	v_mfma_f32_16x16x32_bf16 v[80:83], v[156:159], v[204:207], v[80:83]
	v_mfma_f32_16x16x32_bf16 v[68:71], v[152:155], v[208:211], v[68:71]
	v_mfma_f32_16x16x32_bf16 v[64:67], v[156:159], v[208:211], v[64:67]
	s_setprio 0
	s_barrier
	s_add_u32 s36, s36, 0x80080
	s_addc_u32 s37, s37, 0
	v_mov_b32_e32 v160, v171
	s_nop 0
	s_nop 0
	v_xad_u32 v182, v160, 64, 0
	ds_read_b128 v[160:163], v183 offset:49152
	ds_read_b128 v[174:177], v183 offset:51200
	ds_read_b128 v[178:181], v182 offset:49152
	ds_read_b128 v[192:195], v182 offset:51200
	ds_read_b128 v[196:199], v183 offset:53248
	ds_read_b128 v[200:203], v183 offset:55296
	ds_read_b128 v[204:207], v182 offset:53248
	ds_read_b128 v[208:211], v182 offset:55296
	s_mov_b32 m0, s35
	s_nop 0
	global_load_lds_dwordx4 v167, s[40:41]
	s_mov_b32 m0, s33
	s_nop 0
	global_load_lds_dwordx4 v169, s[40:41]
	s_mov_b32 m0, s77
	s_nop 0
	global_load_lds_dwordx4 v167, s[36:37]
	s_mov_b32 m0, s3
	s_nop 0
	global_load_lds_dwordx4 v169, s[36:37]
	s_mov_b32 m0, s22
	s_nop 0
	global_load_lds_dwordx4 v166, s[30:31]
	s_mov_b32 m0, s2
	s_nop 0
	global_load_lds_dwordx4 v168, s[30:31]
	s_waitcnt vmcnt(8)
	s_waitcnt lgkmcnt(0)
	s_setprio 1
	s_barrier
	v_mfma_f32_16x16x32_bf16 v[60:63], v[128:131], v[160:163], v[60:63]
	v_mfma_f32_16x16x32_bf16 v[56:59], v[132:135], v[160:163], v[56:59]
	v_mfma_f32_16x16x32_bf16 v[44:47], v[128:131], v[174:177], v[44:47]
	v_mfma_f32_16x16x32_bf16 v[40:43], v[132:135], v[174:177], v[40:43]
	v_mfma_f32_16x16x32_bf16 v[28:31], v[128:131], v[196:199], v[28:31]
	v_mfma_f32_16x16x32_bf16 v[24:27], v[132:135], v[196:199], v[24:27]
	v_mfma_f32_16x16x32_bf16 v[12:15], v[128:131], v[200:203], v[12:15]
	v_mfma_f32_16x16x32_bf16 v[8:11], v[132:135], v[200:203], v[8:11]
	v_mfma_f32_16x16x32_bf16 v[60:63], v[136:139], v[178:181], v[60:63]
	v_mfma_f32_16x16x32_bf16 v[56:59], v[140:143], v[178:181], v[56:59]
	v_mfma_f32_16x16x32_bf16 v[44:47], v[136:139], v[192:195], v[44:47]
	v_mfma_f32_16x16x32_bf16 v[40:43], v[140:143], v[192:195], v[40:43]
	v_mfma_f32_16x16x32_bf16 v[28:31], v[136:139], v[204:207], v[28:31]
	v_mfma_f32_16x16x32_bf16 v[24:27], v[140:143], v[204:207], v[24:27]
	v_mfma_f32_16x16x32_bf16 v[12:15], v[136:139], v[208:211], v[12:15]
	v_mfma_f32_16x16x32_bf16 v[8:11], v[140:143], v[208:211], v[8:11]
	s_setprio 0
	s_setprio 1
	v_mfma_f32_16x16x32_bf16 v[52:55], v[144:147], v[160:163], v[52:55]
	v_mfma_f32_16x16x32_bf16 v[48:51], v[148:151], v[160:163], v[48:51]
	v_mfma_f32_16x16x32_bf16 v[36:39], v[144:147], v[174:177], v[36:39]
	v_mfma_f32_16x16x32_bf16 v[32:35], v[148:151], v[174:177], v[32:35]
	v_mfma_f32_16x16x32_bf16 v[20:23], v[144:147], v[196:199], v[20:23]
	v_mfma_f32_16x16x32_bf16 v[16:19], v[148:151], v[196:199], v[16:19]
	v_mfma_f32_16x16x32_bf16 v[4:7], v[144:147], v[200:203], v[4:7]
	v_mfma_f32_16x16x32_bf16 v[0:3], v[148:151], v[200:203], v[0:3]
	v_mfma_f32_16x16x32_bf16 v[52:55], v[152:155], v[178:181], v[52:55]
	v_mfma_f32_16x16x32_bf16 v[48:51], v[156:159], v[178:181], v[48:51]
	v_mfma_f32_16x16x32_bf16 v[36:39], v[152:155], v[192:195], v[36:39]
	v_mfma_f32_16x16x32_bf16 v[32:35], v[156:159], v[192:195], v[32:35]
	v_mfma_f32_16x16x32_bf16 v[20:23], v[152:155], v[204:207], v[20:23]
	v_mfma_f32_16x16x32_bf16 v[16:19], v[156:159], v[204:207], v[16:19]
	v_mfma_f32_16x16x32_bf16 v[4:7], v[152:155], v[208:211], v[4:7]
	v_mfma_f32_16x16x32_bf16 v[0:3], v[156:159], v[208:211], v[0:3]
	s_setprio 0
	s_barrier
	s_add_i32 s57, s57, 2
	s_add_u32 s55, s55, 0x100
	s_addc_u32 s56, s56, 0
	s_add_u32 s12, s12, 0x100
	s_addc_u32 s13, s13, 0
	s_cmp_gt_u32 s57, 29
	s_cbranch_scc0 .LBB0_1104

; #define PG8_STAGE(bufoff, gbase, voff) do { _Pragma("unroll") for (int _i = 0; _i < 2; ++_i) \
;         dma16((const char*)(gbase), (voff)[_i], ldsb + (bufoff) + ldsw + _i * 8192); } while (0)
; #define PG8_LDA(dst, b, h) do { const int a1_ = opqv(aoff0) ^ 64; _Pragma("unroll") for (int m = 0; m < 4; ++m) { dst[m][0] = *(const LAS bf16x8*)(lds + PG8_SA(b, h) + aoff0 + m * 2048); dst[m][1] = *(const LAS bf16x8*)(lds + PG8_SA(b, h) + a1_ + m * 2048); } } while (0)
; #define PG8_LDB(dst, b, h) do { const int b1_ = opqv(boff0) ^ 64; _Pragma("unroll") for (int n = 0; n < 2; ++n) { dst[n][0] = *(const LAS bf16x8*)(lds + PG8_SB(b, h) + boff0 + n * 2048); dst[n][1] = *(const LAS bf16x8*)(lds + PG8_SB(b, h) + b1_ + n * 2048); } } while (0)
; #define PG8_MMA(ai, bj, At, Bt) do { __builtin_amdgcn_s_setprio(1); _Pragma("unroll") for (int m = 0; m < 4; ++m) _Pragma("unroll") for (int n = 0; n < 2; ++n) _Pragma("unroll") for (int k = 0; k < 2; ++k) \
;         acc[ai][bj][m][n] = __builtin_amdgcn_mfma_f32_16x16x32_bf16(Bt[n][k], At[m][k], acc[ai][bj][m][n], 0, 0, 0); __builtin_amdgcn_s_setprio(0); } while (0)
; #define PG8_WAIT_V(n) asm volatile("s_waitcnt vmcnt(" #n ")" ::: "memory")
; #define PG8_BAR __builtin_amdgcn_s_barrier()
; template <class Epi>
; __device__ __forceinline__ void gemm_phase(LAS unsigned char* lds, const Gemm g, const StaticOrder& S, const Epi& E, int wave_) {
;     ...
;         const bool has_next = S.next(ui + 1, nxt);
;         const char* nA = has_next ? (const char*)g.A + (size_t)nxt.pm * tstepA : cA; const char* nB = has_next ? (const char*)g.Bt + (size_t)nxt.pn * tstepB : cB;
; #pragma unroll 1
;         for (int t = 0; t < nt; t += 2) {
;             const bool last = (t == nt - 2);
;             const char* a1 = cA + (size_t)(t + 1) * kstep;
;             const char* a2 = last ? nA : cA + (size_t)(t + 2) * kstep; const char* b2 = last ? nB : cB + (size_t)(t + 2) * kstep;
;             const char* a3 = a2 + kstep; const char* b3 = b2 + kstep;
;             PG8_STAGE(PG8_SA(1, 1), a1 + hstepA, voffA); PG8_LDB(B0, 0, 0); PG8_LDB(B1, 0, 1); PG8_SCHED; PG8_LDA(At, 0, 0);
;             PG8_WAIT_V(8); PG8_WAIT_L(0); PG8_BAR; PG8_MMA(0, 0, At, B0); PG8_MMA(0, 1, At, B1); PG8_BAR; PG8_SCHED;
;             PG8_STAGE(PG8_SB(0, 0), b2, voffB); PG8_STAGE(PG8_SB(0, 1), b2 + hstepB, voffB); PG8_STAGE(PG8_SA(0, 0), a2, voffA); PG8_LDA(At, 0, 1);
.LBB0_1321:
	s_ashr_i32 s25, s24, 31
	s_lshl_b64 s[16:17], s[24:25], 20
	s_add_u32 s26, s21, s16
	s_addc_u32 s27, s46, s17
	s_and_b64 s[16:17], s[42:43], exec
	s_cselect_b32 s16, s27, s37
	s_cselect_b32 s17, s26, s36
	s_ashr_i32 s19, s18, 31
	s_lshl_b64 s[30:31], s[18:19], 20
	s_add_u32 s30, s47, s30
	s_addc_u32 s31, s48, s31
	s_and_b64 s[40:41], s[42:43], exec
	s_cselect_b32 s19, s31, s13
	s_cselect_b32 s25, s30, s12
	s_add_u32 s55, s12, 0x100
	s_addc_u32 s56, s13, 0
	s_add_u32 s12, s36, 0x80080
	s_addc_u32 s13, s37, 0
	s_mov_b32 s57, -2
	s_add_u32 s36, s12, 0xfff80080
	s_addc_u32 s37, s13, -1
	s_cmp_eq_u32 s57, 28
	s_cselect_b32 s44, s17, s36
	s_cselect_b32 s45, s16, s37
	s_cselect_b32 s40, s25, s55
	s_cselect_b32 s41, s19, s56
	s_add_u32 s36, s44, 0x80
	v_mov_b32_e32 v128, v178
	s_addc_u32 s37, s45, 0
	v_add_u32_e32 v132, s23, v178
	v_xad_u32 v140, v128, 64, s23
	v_mov_b32_e32 v144, v178
	s_add_i32 s60, 0, 0x14000
	ds_read_b128 v[128:131], v132
	ds_read_b128 v[132:135], v132 offset:2048
	ds_read_b128 v[136:139], v140
	ds_read_b128 v[140:143], v140 offset:2048
	v_add_u32_e32 v148, s60, v178
	v_xad_u32 v156, v144, 64, s60
	ds_read_b128 v[144:147], v148
	ds_read_b128 v[148:151], v148 offset:2048
	ds_read_b128 v[152:155], v156
	ds_read_b128 v[156:159], v156 offset:2048
	v_mov_b32_e32 v160, v177
	v_add_u32_e32 v169, 0, v177
	v_xad_u32 v168, v160, 64, 0
	ds_read_b128 v[160:163], v169
	ds_read_b128 v[164:167], v169 offset:2048
	ds_read_b128 v[180:183], v168
	ds_read_b128 v[192:195], v168 offset:2048
	ds_read_b128 v[196:199], v169 offset:4096
	ds_read_b128 v[200:203], v169 offset:6144
	ds_read_b128 v[204:207], v168 offset:4096
	ds_read_b128 v[208:211], v168 offset:6144
	s_mov_b32 m0, s14
	s_nop 0
	global_load_lds_dwordx4 v172, s[12:13]
	s_mov_b32 m0, s15
	s_nop 0
	global_load_lds_dwordx4 v174, s[12:13]
	s_waitcnt vmcnt(8)
	s_waitcnt lgkmcnt(0)
	s_setprio 1
	s_barrier
	v_mfma_f32_16x16x32_bf16 v[124:127], v[128:131], v[160:163], 0
	v_mfma_f32_16x16x32_bf16 v[120:123], v[132:135], v[160:163], 0
	v_mfma_f32_16x16x32_bf16 v[108:111], v[128:131], v[164:167], 0
	v_mfma_f32_16x16x32_bf16 v[104:107], v[132:135], v[164:167], 0
	v_mfma_f32_16x16x32_bf16 v[92:95], v[128:131], v[196:199], 0
	v_mfma_f32_16x16x32_bf16 v[88:91], v[132:135], v[196:199], 0
	v_mfma_f32_16x16x32_bf16 v[76:79], v[128:131], v[200:203], 0
	v_mfma_f32_16x16x32_bf16 v[72:75], v[132:135], v[200:203], 0
	v_mfma_f32_16x16x32_bf16 v[124:127], v[136:139], v[180:183], v[124:127]
	v_mfma_f32_16x16x32_bf16 v[120:123], v[140:143], v[180:183], v[120:123]
	v_mfma_f32_16x16x32_bf16 v[108:111], v[136:139], v[192:195], v[108:111]
	v_mfma_f32_16x16x32_bf16 v[104:107], v[140:143], v[192:195], v[104:107]
	v_mfma_f32_16x16x32_bf16 v[92:95], v[136:139], v[204:207], v[92:95]
	v_mfma_f32_16x16x32_bf16 v[88:91], v[140:143], v[204:207], v[88:91]
	v_mfma_f32_16x16x32_bf16 v[76:79], v[136:139], v[208:211], v[76:79]
	v_mfma_f32_16x16x32_bf16 v[72:75], v[140:143], v[208:211], v[72:75]
	s_setprio 0
	s_setprio 1
	v_mfma_f32_16x16x32_bf16 v[116:119], v[144:147], v[160:163], 0
	v_mfma_f32_16x16x32_bf16 v[112:115], v[148:151], v[160:163], 0
	v_mfma_f32_16x16x32_bf16 v[100:103], v[144:147], v[164:167], 0
	v_mfma_f32_16x16x32_bf16 v[96:99], v[148:151], v[164:167], 0
	v_mfma_f32_16x16x32_bf16 v[84:87], v[144:147], v[196:199], 0
	v_mfma_f32_16x16x32_bf16 v[80:83], v[148:151], v[196:199], 0
	v_mfma_f32_16x16x32_bf16 v[68:71], v[144:147], v[200:203], 0
	v_mfma_f32_16x16x32_bf16 v[64:67], v[148:151], v[200:203], 0
	v_mfma_f32_16x16x32_bf16 v[116:119], v[152:155], v[180:183], v[116:119]
	v_mfma_f32_16x16x32_bf16 v[112:115], v[156:159], v[180:183], v[112:115]
	v_mfma_f32_16x16x32_bf16 v[100:103], v[152:155], v[192:195], v[100:103]
	v_mfma_f32_16x16x32_bf16 v[96:99], v[156:159], v[192:195], v[96:99]
	v_mfma_f32_16x16x32_bf16 v[84:87], v[152:155], v[204:207], v[84:87]
	v_mfma_f32_16x16x32_bf16 v[80:83], v[156:159], v[204:207], v[80:83]
	v_mfma_f32_16x16x32_bf16 v[68:71], v[152:155], v[208:211], v[68:71]
	v_mfma_f32_16x16x32_bf16 v[64:67], v[156:159], v[208:211], v[64:67]
	s_setprio 0
	s_barrier
	v_mov_b32_e32 v160, v177
	s_add_u32 s60, s40, 0x80000
	s_addc_u32 s61, s41, 0
	s_nop 0
	s_nop 0
	s_nop 0
	v_xad_u32 v168, v160, 64, 0
	ds_read_b128 v[160:163], v169 offset:16384
	ds_read_b128 v[164:167], v169 offset:18432
	ds_read_b128 v[180:183], v168 offset:16384
	ds_read_b128 v[192:195], v168 offset:18432
	ds_read_b128 v[196:199], v169 offset:20480
	ds_read_b128 v[200:203], v169 offset:22528
	ds_read_b128 v[204:207], v168 offset:20480
	ds_read_b128 v[208:211], v168 offset:22528
	s_mov_b32 m0, s80
	s_nop 0
	global_load_lds_dwordx4 v173, s[40:41]
	s_mov_b32 m0, s81
	s_nop 0
	global_load_lds_dwordx4 v175, s[40:41]
	s_mov_b32 m0, s29
	s_nop 0
	global_load_lds_dwordx4 v173, s[60:61]
	s_mov_b32 m0, s88
	s_nop 0
	global_load_lds_dwordx4 v175, s[60:61]
	s_mov_b32 m0, s76
	s_nop 0
	global_load_lds_dwordx4 v172, s[44:45]
	s_mov_b32 m0, s89
	s_nop 0
	global_load_lds_dwordx4 v174, s[44:45]
	s_waitcnt vmcnt(8)
	s_waitcnt lgkmcnt(0)
	s_setprio 1
	s_barrier
; #define PG8_STAGE(bufoff, gbase, voff) do { _Pragma("unroll") for (int _i = 0; _i < 2; ++_i) \
;         dma16((const char*)(gbase), (voff)[_i], ldsb + (bufoff) + ldsw + _i * 8192); } while (0)
; #define PG8_LDA(dst, b, h) do { const int a1_ = opqv(aoff0) ^ 64; _Pragma("unroll") for (int m = 0; m < 4; ++m) { dst[m][0] = *(const LAS bf16x8*)(lds + PG8_SA(b, h) + aoff0 + m * 2048); dst[m][1] = *(const LAS bf16x8*)(lds + PG8_SA(b, h) + a1_ + m * 2048); } } while (0)
; #define PG8_LDB(dst, b, h) do { const int b1_ = opqv(boff0) ^ 64; _Pragma("unroll") for (int n = 0; n < 2; ++n) { dst[n][0] = *(const LAS bf16x8*)(lds + PG8_SB(b, h) + boff0 + n * 2048); dst[n][1] = *(const LAS bf16x8*)(lds + PG8_SB(b, h) + b1_ + n * 2048); } } while (0)
; #define PG8_MMA(ai, bj, At, Bt) do { __builtin_amdgcn_s_setprio(1); _Pragma("unroll") for (int m = 0; m < 4; ++m) _Pragma("unroll") for (int n = 0; n < 2; ++n) _Pragma("unroll") for (int k = 0; k < 2; ++k) \
;         acc[ai][bj][m][n] = __builtin_amdgcn_mfma_f32_16x16x32_bf16(Bt[n][k], At[m][k], acc[ai][bj][m][n], 0, 0, 0); __builtin_amdgcn_s_setprio(0); } while (0)
; #define PG8_WAIT_V(n) asm volatile("s_waitcnt vmcnt(" #n ")" ::: "memory")
; #define PG8_WAIT_L(n) asm volatile("s_waitcnt lgkmcnt(" #n ")" ::: "memory")
; #define PG8_BAR __builtin_amdgcn_s_barrier()
; #define PG8_SCHED __builtin_amdgcn_sched_barrier(0)
; template <class Epi>
; __device__ __forceinline__ void gemm_phase(LAS unsigned char* lds, const Gemm g, const StaticOrder& S, const Epi& E, int wave_) {
;     ...
;             PG8_WAIT_V(8); PG8_WAIT_L(0); PG8_BAR; PG8_MMA(1, 0, At, B0); PG8_MMA(1, 1, At, B1); PG8_BAR; PG8_SCHED;
;             PG8_STAGE(PG8_SA(0, 1), a2 + hstepA, voffA); PG8_LDB(B0, 1, 0); PG8_LDB(B1, 1, 1); PG8_SCHED; PG8_LDA(At, 1, 0);
;             PG8_WAIT_V(8); PG8_WAIT_L(0); PG8_BAR; PG8_MMA(0, 0, At, B0); PG8_MMA(0, 1, At, B1); PG8_BAR; PG8_SCHED;
	v_mfma_f32_16x16x32_bf16 v[60:63], v[128:131], v[160:163], 0
	v_mfma_f32_16x16x32_bf16 v[56:59], v[132:135], v[160:163], 0
	v_mfma_f32_16x16x32_bf16 v[44:47], v[128:131], v[164:167], 0
	v_mfma_f32_16x16x32_bf16 v[40:43], v[132:135], v[164:167], 0
	v_mfma_f32_16x16x32_bf16 v[28:31], v[128:131], v[196:199], 0
	v_mfma_f32_16x16x32_bf16 v[24:27], v[132:135], v[196:199], 0
	v_mfma_f32_16x16x32_bf16 v[12:15], v[128:131], v[200:203], 0
	v_mfma_f32_16x16x32_bf16 v[8:11], v[132:135], v[200:203], 0
	v_mfma_f32_16x16x32_bf16 v[60:63], v[136:139], v[180:183], v[60:63]
	v_mfma_f32_16x16x32_bf16 v[56:59], v[140:143], v[180:183], v[56:59]
	v_mfma_f32_16x16x32_bf16 v[44:47], v[136:139], v[192:195], v[44:47]
	v_mfma_f32_16x16x32_bf16 v[40:43], v[140:143], v[192:195], v[40:43]
	v_mfma_f32_16x16x32_bf16 v[28:31], v[136:139], v[204:207], v[28:31]
	v_mfma_f32_16x16x32_bf16 v[24:27], v[140:143], v[204:207], v[24:27]
	v_mfma_f32_16x16x32_bf16 v[12:15], v[136:139], v[208:211], v[12:15]
	v_mfma_f32_16x16x32_bf16 v[8:11], v[140:143], v[208:211], v[8:11]
	s_setprio 0
	s_setprio 1
	v_mfma_f32_16x16x32_bf16 v[52:55], v[144:147], v[160:163], 0
	v_mfma_f32_16x16x32_bf16 v[48:51], v[148:151], v[160:163], 0
	v_mfma_f32_16x16x32_bf16 v[36:39], v[144:147], v[164:167], 0
	v_mfma_f32_16x16x32_bf16 v[32:35], v[148:151], v[164:167], 0
	v_mfma_f32_16x16x32_bf16 v[20:23], v[144:147], v[196:199], 0
	v_mfma_f32_16x16x32_bf16 v[16:19], v[148:151], v[196:199], 0
	v_mfma_f32_16x16x32_bf16 v[4:7], v[144:147], v[200:203], 0
	v_mfma_f32_16x16x32_bf16 v[0:3], v[148:151], v[200:203], 0
	v_mfma_f32_16x16x32_bf16 v[52:55], v[152:155], v[180:183], v[52:55]
	v_mfma_f32_16x16x32_bf16 v[48:51], v[156:159], v[180:183], v[48:51]
	v_mfma_f32_16x16x32_bf16 v[36:39], v[152:155], v[192:195], v[36:39]
	v_mfma_f32_16x16x32_bf16 v[32:35], v[156:159], v[192:195], v[32:35]
	v_mfma_f32_16x16x32_bf16 v[20:23], v[152:155], v[204:207], v[20:23]
	v_mfma_f32_16x16x32_bf16 v[16:19], v[156:159], v[204:207], v[16:19]
	v_mfma_f32_16x16x32_bf16 v[4:7], v[152:155], v[208:211], v[4:7]
	v_mfma_f32_16x16x32_bf16 v[0:3], v[156:159], v[208:211], v[0:3]
	s_setprio 0
	s_barrier
	s_add_u32 s44, s44, 0x80000
	s_addc_u32 s45, s45, 0
	s_mov_b32 m0, s1
	s_nop 0
	global_load_lds_dwordx4 v172, s[44:45]
	v_mov_b32_e32 v128, v178
	s_mov_b32 m0, s69
	s_nop 0
	global_load_lds_dwordx4 v174, s[44:45]
	v_add_u32_e32 v132, s34, v178
	v_xad_u32 v140, v128, 64, s34
	v_mov_b32_e32 v144, v178
	s_add_i32 s44, 0, 0x1c000
	ds_read_b128 v[128:131], v132
	ds_read_b128 v[132:135], v132 offset:2048
	ds_read_b128 v[136:139], v140
	ds_read_b128 v[140:143], v140 offset:2048
	v_add_u32_e32 v148, s44, v178
	v_xad_u32 v156, v144, 64, s44
	ds_read_b128 v[144:147], v148
	ds_read_b128 v[148:151], v148 offset:2048
	ds_read_b128 v[152:155], v156
	ds_read_b128 v[156:159], v156 offset:2048
	v_mov_b32_e32 v160, v177
	s_nop 0
	v_xad_u32 v168, v160, 64, 0
	ds_read_b128 v[160:163], v169 offset:32768
	ds_read_b128 v[164:167], v169 offset:34816
	ds_read_b128 v[180:183], v168 offset:32768
	ds_read_b128 v[192:195], v168 offset:34816
	ds_read_b128 v[196:199], v169 offset:36864
	ds_read_b128 v[200:203], v169 offset:38912
	ds_read_b128 v[204:207], v168 offset:36864
	ds_read_b128 v[208:211], v168 offset:38912
	s_waitcnt vmcnt(8)
	s_waitcnt lgkmcnt(0)
	s_setprio 1
	s_barrier
	v_mfma_f32_16x16x32_bf16 v[124:127], v[128:131], v[160:163], v[124:127]
	v_mfma_f32_16x16x32_bf16 v[120:123], v[132:135], v[160:163], v[120:123]
	v_mfma_f32_16x16x32_bf16 v[108:111], v[128:131], v[164:167], v[108:111]
	v_mfma_f32_16x16x32_bf16 v[104:107], v[132:135], v[164:167], v[104:107]
	v_mfma_f32_16x16x32_bf16 v[92:95], v[128:131], v[196:199], v[92:95]
	v_mfma_f32_16x16x32_bf16 v[88:91], v[132:135], v[196:199], v[88:91]
	v_mfma_f32_16x16x32_bf16 v[76:79], v[128:131], v[200:203], v[76:79]
	v_mfma_f32_16x16x32_bf16 v[72:75], v[132:135], v[200:203], v[72:75]
	v_mfma_f32_16x16x32_bf16 v[124:127], v[136:139], v[180:183], v[124:127]
	v_mfma_f32_16x16x32_bf16 v[120:123], v[140:143], v[180:183], v[120:123]
	v_mfma_f32_16x16x32_bf16 v[108:111], v[136:139], v[192:195], v[108:111]
	v_mfma_f32_16x16x32_bf16 v[104:107], v[140:143], v[192:195], v[104:107]
	v_mfma_f32_16x16x32_bf16 v[92:95], v[136:139], v[204:207], v[92:95]
	v_mfma_f32_16x16x32_bf16 v[88:91], v[140:143], v[204:207], v[88:91]
	v_mfma_f32_16x16x32_bf16 v[76:79], v[136:139], v[208:211], v[76:79]
	v_mfma_f32_16x16x32_bf16 v[72:75], v[140:143], v[208:211], v[72:75]
	s_setprio 0
	s_setprio 1
	v_mfma_f32_16x16x32_bf16 v[116:119], v[144:147], v[160:163], v[116:119]
	s_add_u32 s44, s40, 0x80
	s_addc_u32 s45, s41, 0
	v_mfma_f32_16x16x32_bf16 v[112:115], v[148:151], v[160:163], v[112:115]
	v_mfma_f32_16x16x32_bf16 v[100:103], v[144:147], v[164:167], v[100:103]
	v_mfma_f32_16x16x32_bf16 v[96:99], v[148:151], v[164:167], v[96:99]
	v_mfma_f32_16x16x32_bf16 v[84:87], v[144:147], v[196:199], v[84:87]
	v_mfma_f32_16x16x32_bf16 v[80:83], v[148:151], v[196:199], v[80:83]
	v_mfma_f32_16x16x32_bf16 v[68:71], v[144:147], v[200:203], v[68:71]
	v_mfma_f32_16x16x32_bf16 v[64:67], v[148:151], v[200:203], v[64:67]
	v_mfma_f32_16x16x32_bf16 v[116:119], v[152:155], v[180:183], v[116:119]
	v_mfma_f32_16x16x32_bf16 v[112:115], v[156:159], v[180:183], v[112:115]
	v_mfma_f32_16x16x32_bf16 v[100:103], v[152:155], v[192:195], v[100:103]
	v_mfma_f32_16x16x32_bf16 v[96:99], v[156:159], v[192:195], v[96:99]
	v_mfma_f32_16x16x32_bf16 v[84:87], v[152:155], v[204:207], v[84:87]
	v_mfma_f32_16x16x32_bf16 v[80:83], v[156:159], v[204:207], v[80:83]
	v_mfma_f32_16x16x32_bf16 v[68:71], v[152:155], v[208:211], v[68:71]
	v_mfma_f32_16x16x32_bf16 v[64:67], v[156:159], v[208:211], v[64:67]
	s_setprio 0
	s_barrier
; #define PG8_STAGE(bufoff, gbase, voff) do { _Pragma("unroll") for (int _i = 0; _i < 2; ++_i) \
;         dma16((const char*)(gbase), (voff)[_i], ldsb + (bufoff) + ldsw + _i * 8192); } while (0)
; #define PG8_LDA(dst, b, h) do { const int a1_ = opqv(aoff0) ^ 64; _Pragma("unroll") for (int m = 0; m < 4; ++m) { dst[m][0] = *(const LAS bf16x8*)(lds + PG8_SA(b, h) + aoff0 + m * 2048); dst[m][1] = *(const LAS bf16x8*)(lds + PG8_SA(b, h) + a1_ + m * 2048); } } while (0)
; #define PG8_LDB(dst, b, h) do { const int b1_ = opqv(boff0) ^ 64; _Pragma("unroll") for (int n = 0; n < 2; ++n) { dst[n][0] = *(const LAS bf16x8*)(lds + PG8_SB(b, h) + boff0 + n * 2048); dst[n][1] = *(const LAS bf16x8*)(lds + PG8_SB(b, h) + b1_ + n * 2048); } } while (0)
; #define PG8_WAIT_V(n) asm volatile("s_waitcnt vmcnt(" #n ")" ::: "memory")
; template <class Epi>
; __device__ __forceinline__ void gemm_phase(LAS unsigned char* lds, const Gemm g, const StaticOrder& S, const Epi& E, int wave_) {
;     ...
;         for (int t = 0; t < nt; t += 2) {
;             const bool last = (t == nt - 2);
;             const char* a1 = cA + (size_t)(t + 1) * kstep;
;             const char* a2 = last ? nA : cA + (size_t)(t + 2) * kstep; const char* b2 = last ? nB : cB + (size_t)(t + 2) * kstep;
;             const char* a3 = a2 + kstep; const char* b3 = b2 + kstep;
;             PG8_STAGE(PG8_SA(1, 1), a1 + hstepA, voffA); PG8_LDB(B0, 0, 0); PG8_LDB(B1, 0, 1); PG8_SCHED; PG8_LDA(At, 0, 0);
;             PG8_WAIT_V(8); PG8_WAIT_L(0); PG8_BAR; PG8_MMA(0, 0, At, B0); PG8_MMA(0, 1, At, B1); PG8_BAR; PG8_SCHED;
;             PG8_STAGE(PG8_SB(0, 0), b2, voffB); PG8_STAGE(PG8_SB(0, 1), b2 + hstepB, voffB); PG8_STAGE(PG8_SA(0, 0), a2, voffA); PG8_LDA(At, 0, 1);
;             PG8_WAIT_V(8); PG8_WAIT_L(0); PG8_BAR; PG8_MMA(1, 0, At, B0); PG8_MMA(1, 1, At, B1); PG8_BAR; PG8_SCHED;
;             PG8_STAGE(PG8_SA(0, 1), a2 + hstepA, voffA); PG8_LDB(B0, 1, 0); PG8_LDB(B1, 1, 1); PG8_SCHED; PG8_LDA(At, 1, 0);
;             PG8_WAIT_V(8); PG8_WAIT_L(0); PG8_BAR; PG8_MMA(0, 0, At, B0); PG8_MMA(0, 1, At, B1); PG8_BAR; PG8_SCHED;
;             PG8_STAGE(PG8_SB(1, 0), b3, voffB); PG8_STAGE(PG8_SB(1, 1), b3 + hstepB, voffB); PG8_STAGE(PG8_SA(1, 0), a3, voffA); PG8_LDA(At, 1, 1);
;             PG8_WAIT_V(8); PG8_WAIT_L(0); PG8_BAR; PG8_MMA(1, 0, At, B0); PG8_MMA(1, 1, At, B1); PG8_BAR; PG8_SCHED;
	s_add_u32 s40, s40, 0x80080
	s_addc_u32 s41, s41, 0
	v_mov_b32_e32 v160, v177
	s_nop 0
	s_nop 0
	v_xad_u32 v168, v160, 64, 0
	ds_read_b128 v[160:163], v169 offset:49152
	ds_read_b128 v[164:167], v169 offset:51200
	ds_read_b128 v[180:183], v168 offset:49152
	ds_read_b128 v[192:195], v168 offset:51200
	ds_read_b128 v[196:199], v169 offset:53248
	ds_read_b128 v[200:203], v169 offset:55296
	ds_read_b128 v[204:207], v168 offset:53248
	ds_read_b128 v[208:211], v168 offset:55296
	s_mov_b32 m0, s35
	s_nop 0
	global_load_lds_dwordx4 v173, s[44:45]
	s_mov_b32 m0, s33
	s_nop 0
	global_load_lds_dwordx4 v175, s[44:45]
	s_mov_b32 m0, s77
	s_nop 0
	global_load_lds_dwordx4 v173, s[40:41]
	s_mov_b32 m0, s3
	s_nop 0
	global_load_lds_dwordx4 v175, s[40:41]
	s_mov_b32 m0, s22
	s_nop 0
	global_load_lds_dwordx4 v172, s[36:37]
	s_mov_b32 m0, s2
	s_nop 0
	global_load_lds_dwordx4 v174, s[36:37]
	s_waitcnt vmcnt(8)
	s_waitcnt lgkmcnt(0)
	s_setprio 1
	s_barrier
	v_mfma_f32_16x16x32_bf16 v[60:63], v[128:131], v[160:163], v[60:63]
	v_mfma_f32_16x16x32_bf16 v[56:59], v[132:135], v[160:163], v[56:59]
	v_mfma_f32_16x16x32_bf16 v[44:47], v[128:131], v[164:167], v[44:47]
	v_mfma_f32_16x16x32_bf16 v[40:43], v[132:135], v[164:167], v[40:43]
	v_mfma_f32_16x16x32_bf16 v[28:31], v[128:131], v[196:199], v[28:31]
	v_mfma_f32_16x16x32_bf16 v[24:27], v[132:135], v[196:199], v[24:27]
	v_mfma_f32_16x16x32_bf16 v[12:15], v[128:131], v[200:203], v[12:15]
	v_mfma_f32_16x16x32_bf16 v[8:11], v[132:135], v[200:203], v[8:11]
	v_mfma_f32_16x16x32_bf16 v[60:63], v[136:139], v[180:183], v[60:63]
	v_mfma_f32_16x16x32_bf16 v[56:59], v[140:143], v[180:183], v[56:59]
	v_mfma_f32_16x16x32_bf16 v[44:47], v[136:139], v[192:195], v[44:47]
	v_mfma_f32_16x16x32_bf16 v[40:43], v[140:143], v[192:195], v[40:43]
	v_mfma_f32_16x16x32_bf16 v[28:31], v[136:139], v[204:207], v[28:31]
	v_mfma_f32_16x16x32_bf16 v[24:27], v[140:143], v[204:207], v[24:27]
	v_mfma_f32_16x16x32_bf16 v[12:15], v[136:139], v[208:211], v[12:15]
	v_mfma_f32_16x16x32_bf16 v[8:11], v[140:143], v[208:211], v[8:11]
	s_setprio 0
	s_setprio 1
	v_mfma_f32_16x16x32_bf16 v[52:55], v[144:147], v[160:163], v[52:55]
	v_mfma_f32_16x16x32_bf16 v[48:51], v[148:151], v[160:163], v[48:51]
	v_mfma_f32_16x16x32_bf16 v[36:39], v[144:147], v[164:167], v[36:39]
	v_mfma_f32_16x16x32_bf16 v[32:35], v[148:151], v[164:167], v[32:35]
	v_mfma_f32_16x16x32_bf16 v[20:23], v[144:147], v[196:199], v[20:23]
	v_mfma_f32_16x16x32_bf16 v[16:19], v[148:151], v[196:199], v[16:19]
	v_mfma_f32_16x16x32_bf16 v[4:7], v[144:147], v[200:203], v[4:7]
	v_mfma_f32_16x16x32_bf16 v[0:3], v[148:151], v[200:203], v[0:3]
	v_mfma_f32_16x16x32_bf16 v[52:55], v[152:155], v[180:183], v[52:55]
	v_mfma_f32_16x16x32_bf16 v[48:51], v[156:159], v[180:183], v[48:51]
	v_mfma_f32_16x16x32_bf16 v[36:39], v[152:155], v[192:195], v[36:39]
	v_mfma_f32_16x16x32_bf16 v[32:35], v[156:159], v[192:195], v[32:35]
	v_mfma_f32_16x16x32_bf16 v[20:23], v[152:155], v[204:207], v[20:23]
	v_mfma_f32_16x16x32_bf16 v[16:19], v[156:159], v[204:207], v[16:19]
	v_mfma_f32_16x16x32_bf16 v[4:7], v[152:155], v[208:211], v[4:7]
	v_mfma_f32_16x16x32_bf16 v[0:3], v[156:159], v[208:211], v[0:3]
	s_setprio 0
	s_barrier
	s_add_i32 s57, s57, 2
	s_add_u32 s55, s55, 0x100
	s_addc_u32 s56, s56, 0
	s_add_u32 s12, s12, 0x100
	s_addc_u32 s13, s13, 0
	s_cmp_gt_u32 s57, 29
	s_cbranch_scc0 .LBB0_1322
	s_branch .Lpeel_exit_3
.LBB0_1322:
	s_add_u32 s36, s12, 0xfff80080
	s_addc_u32 s37, s13, -1
	s_cmp_eq_u32 s57, 28
	s_cselect_b32 s44, s17, s36
	s_cselect_b32 s45, s16, s37
	s_cselect_b32 s40, s25, s55
	s_cselect_b32 s41, s19, s56
	s_add_u32 s36, s44, 0x80
	v_mov_b32_e32 v128, v178
	s_addc_u32 s37, s45, 0
	v_add_u32_e32 v132, s23, v178
	v_xad_u32 v140, v128, 64, s23
	v_mov_b32_e32 v144, v178
	s_add_i32 s60, 0, 0x14000
	ds_read_b128 v[128:131], v132
	ds_read_b128 v[132:135], v132 offset:2048
	ds_read_b128 v[136:139], v140
	ds_read_b128 v[140:143], v140 offset:2048
	v_add_u32_e32 v148, s60, v178
	v_xad_u32 v156, v144, 64, s60
	ds_read_b128 v[144:147], v148
	ds_read_b128 v[148:151], v148 offset:2048
	ds_read_b128 v[152:155], v156
	ds_read_b128 v[156:159], v156 offset:2048
	v_mov_b32_e32 v160, v177
	v_add_u32_e32 v169, 0, v177
	v_xad_u32 v168, v160, 64, 0
	ds_read_b128 v[160:163], v169
	ds_read_b128 v[164:167], v169 offset:2048
	ds_read_b128 v[180:183], v168
	ds_read_b128 v[192:195], v168 offset:2048
	ds_read_b128 v[196:199], v169 offset:4096
	ds_read_b128 v[200:203], v169 offset:6144
	ds_read_b128 v[204:207], v168 offset:4096
	ds_read_b128 v[208:211], v168 offset:6144
	s_mov_b32 m0, s14
	s_nop 0
	global_load_lds_dwordx4 v172, s[12:13]
	s_mov_b32 m0, s15
	s_nop 0
	global_load_lds_dwordx4 v174, s[12:13]
	s_waitcnt vmcnt(8)
	s_waitcnt lgkmcnt(0)
	s_setprio 1
	s_barrier
; #define PG8_STAGE(bufoff, gbase, voff) do { _Pragma("unroll") for (int _i = 0; _i < 2; ++_i) \
;         dma16((const char*)(gbase), (voff)[_i], ldsb + (bufoff) + ldsw + _i * 8192); } while (0)
; #define PG8_LDA(dst, b, h) do { const int a1_ = opqv(aoff0) ^ 64; _Pragma("unroll") for (int m = 0; m < 4; ++m) { dst[m][0] = *(const LAS bf16x8*)(lds + PG8_SA(b, h) + aoff0 + m * 2048); dst[m][1] = *(const LAS bf16x8*)(lds + PG8_SA(b, h) + a1_ + m * 2048); } } while (0)
; #define PG8_MMA(ai, bj, At, Bt) do { __builtin_amdgcn_s_setprio(1); _Pragma("unroll") for (int m = 0; m < 4; ++m) _Pragma("unroll") for (int n = 0; n < 2; ++n) _Pragma("unroll") for (int k = 0; k < 2; ++k) \
;         acc[ai][bj][m][n] = __builtin_amdgcn_mfma_f32_16x16x32_bf16(Bt[n][k], At[m][k], acc[ai][bj][m][n], 0, 0, 0); __builtin_amdgcn_s_setprio(0); } while (0)
; #define PG8_WAIT_V(n) asm volatile("s_waitcnt vmcnt(" #n ")" ::: "memory")
; #define PG8_WAIT_L(n) asm volatile("s_waitcnt lgkmcnt(" #n ")" ::: "memory")
; #define PG8_BAR __builtin_amdgcn_s_barrier()
; #define PG8_SCHED __builtin_amdgcn_sched_barrier(0)
; template <class Epi>
; __device__ __forceinline__ void gemm_phase(LAS unsigned char* lds, const Gemm g, const StaticOrder& S, const Epi& E, int wave_) {
;     ...
;             PG8_WAIT_V(8); PG8_WAIT_L(0); PG8_BAR; PG8_MMA(0, 0, At, B0); PG8_MMA(0, 1, At, B1); PG8_BAR; PG8_SCHED;
;             PG8_STAGE(PG8_SB(0, 0), b2, voffB); PG8_STAGE(PG8_SB(0, 1), b2 + hstepB, voffB); PG8_STAGE(PG8_SA(0, 0), a2, voffA); PG8_LDA(At, 0, 1);
;             PG8_WAIT_V(8); PG8_WAIT_L(0); PG8_BAR; PG8_MMA(1, 0, At, B0); PG8_MMA(1, 1, At, B1); PG8_BAR; PG8_SCHED;
	v_mfma_f32_16x16x32_bf16 v[124:127], v[128:131], v[160:163], v[124:127]
	v_mfma_f32_16x16x32_bf16 v[120:123], v[132:135], v[160:163], v[120:123]
	v_mfma_f32_16x16x32_bf16 v[108:111], v[128:131], v[164:167], v[108:111]
	v_mfma_f32_16x16x32_bf16 v[104:107], v[132:135], v[164:167], v[104:107]
	v_mfma_f32_16x16x32_bf16 v[92:95], v[128:131], v[196:199], v[92:95]
	v_mfma_f32_16x16x32_bf16 v[88:91], v[132:135], v[196:199], v[88:91]
	v_mfma_f32_16x16x32_bf16 v[76:79], v[128:131], v[200:203], v[76:79]
	v_mfma_f32_16x16x32_bf16 v[72:75], v[132:135], v[200:203], v[72:75]
	v_mfma_f32_16x16x32_bf16 v[124:127], v[136:139], v[180:183], v[124:127]
	v_mfma_f32_16x16x32_bf16 v[120:123], v[140:143], v[180:183], v[120:123]
	v_mfma_f32_16x16x32_bf16 v[108:111], v[136:139], v[192:195], v[108:111]
	v_mfma_f32_16x16x32_bf16 v[104:107], v[140:143], v[192:195], v[104:107]
	v_mfma_f32_16x16x32_bf16 v[92:95], v[136:139], v[204:207], v[92:95]
	v_mfma_f32_16x16x32_bf16 v[88:91], v[140:143], v[204:207], v[88:91]
	v_mfma_f32_16x16x32_bf16 v[76:79], v[136:139], v[208:211], v[76:79]
	v_mfma_f32_16x16x32_bf16 v[72:75], v[140:143], v[208:211], v[72:75]
	s_setprio 0
	s_setprio 1
	v_mfma_f32_16x16x32_bf16 v[116:119], v[144:147], v[160:163], v[116:119]
	v_mfma_f32_16x16x32_bf16 v[112:115], v[148:151], v[160:163], v[112:115]
	v_mfma_f32_16x16x32_bf16 v[100:103], v[144:147], v[164:167], v[100:103]
	v_mfma_f32_16x16x32_bf16 v[96:99], v[148:151], v[164:167], v[96:99]
	v_mfma_f32_16x16x32_bf16 v[84:87], v[144:147], v[196:199], v[84:87]
	v_mfma_f32_16x16x32_bf16 v[80:83], v[148:151], v[196:199], v[80:83]
	v_mfma_f32_16x16x32_bf16 v[68:71], v[144:147], v[200:203], v[68:71]
	v_mfma_f32_16x16x32_bf16 v[64:67], v[148:151], v[200:203], v[64:67]
	v_mfma_f32_16x16x32_bf16 v[116:119], v[152:155], v[180:183], v[116:119]
	v_mfma_f32_16x16x32_bf16 v[112:115], v[156:159], v[180:183], v[112:115]
	v_mfma_f32_16x16x32_bf16 v[100:103], v[152:155], v[192:195], v[100:103]
	v_mfma_f32_16x16x32_bf16 v[96:99], v[156:159], v[192:195], v[96:99]
	v_mfma_f32_16x16x32_bf16 v[84:87], v[152:155], v[204:207], v[84:87]
	v_mfma_f32_16x16x32_bf16 v[80:83], v[156:159], v[204:207], v[80:83]
	v_mfma_f32_16x16x32_bf16 v[68:71], v[152:155], v[208:211], v[68:71]
	v_mfma_f32_16x16x32_bf16 v[64:67], v[156:159], v[208:211], v[64:67]
	s_setprio 0
	s_barrier
	v_mov_b32_e32 v160, v177
	s_add_u32 s60, s40, 0x80000
	s_addc_u32 s61, s41, 0
	s_nop 0
	s_nop 0
	s_nop 0
	v_xad_u32 v168, v160, 64, 0
	ds_read_b128 v[160:163], v169 offset:16384
	ds_read_b128 v[164:167], v169 offset:18432
	ds_read_b128 v[180:183], v168 offset:16384
	ds_read_b128 v[192:195], v168 offset:18432
	ds_read_b128 v[196:199], v169 offset:20480
	ds_read_b128 v[200:203], v169 offset:22528
	ds_read_b128 v[204:207], v168 offset:20480
	ds_read_b128 v[208:211], v168 offset:22528
	s_mov_b32 m0, s80
	s_nop 0
	global_load_lds_dwordx4 v173, s[40:41]
	s_mov_b32 m0, s81
	s_nop 0
	global_load_lds_dwordx4 v175, s[40:41]
	s_mov_b32 m0, s29
	s_nop 0
	global_load_lds_dwordx4 v173, s[60:61]
	s_mov_b32 m0, s88
	s_nop 0
	global_load_lds_dwordx4 v175, s[60:61]
	s_mov_b32 m0, s76
	s_nop 0
	global_load_lds_dwordx4 v172, s[44:45]
	s_mov_b32 m0, s89
	s_nop 0
	global_load_lds_dwordx4 v174, s[44:45]
	s_waitcnt vmcnt(8)
	s_waitcnt lgkmcnt(0)
	s_setprio 1
	s_barrier
	v_mfma_f32_16x16x32_bf16 v[60:63], v[128:131], v[160:163], v[60:63]
	v_mfma_f32_16x16x32_bf16 v[56:59], v[132:135], v[160:163], v[56:59]
	v_mfma_f32_16x16x32_bf16 v[44:47], v[128:131], v[164:167], v[44:47]
	v_mfma_f32_16x16x32_bf16 v[40:43], v[132:135], v[164:167], v[40:43]
	v_mfma_f32_16x16x32_bf16 v[28:31], v[128:131], v[196:199], v[28:31]
	v_mfma_f32_16x16x32_bf16 v[24:27], v[132:135], v[196:199], v[24:27]
	v_mfma_f32_16x16x32_bf16 v[12:15], v[128:131], v[200:203], v[12:15]
	v_mfma_f32_16x16x32_bf16 v[8:11], v[132:135], v[200:203], v[8:11]
	v_mfma_f32_16x16x32_bf16 v[60:63], v[136:139], v[180:183], v[60:63]
	v_mfma_f32_16x16x32_bf16 v[56:59], v[140:143], v[180:183], v[56:59]
	v_mfma_f32_16x16x32_bf16 v[44:47], v[136:139], v[192:195], v[44:47]
	v_mfma_f32_16x16x32_bf16 v[40:43], v[140:143], v[192:195], v[40:43]
	v_mfma_f32_16x16x32_bf16 v[28:31], v[136:139], v[204:207], v[28:31]
	v_mfma_f32_16x16x32_bf16 v[24:27], v[140:143], v[204:207], v[24:27]
	v_mfma_f32_16x16x32_bf16 v[12:15], v[136:139], v[208:211], v[12:15]
	v_mfma_f32_16x16x32_bf16 v[8:11], v[140:143], v[208:211], v[8:11]
	s_setprio 0
	s_setprio 1
	v_mfma_f32_16x16x32_bf16 v[52:55], v[144:147], v[160:163], v[52:55]
	v_mfma_f32_16x16x32_bf16 v[48:51], v[148:151], v[160:163], v[48:51]
	v_mfma_f32_16x16x32_bf16 v[36:39], v[144:147], v[164:167], v[36:39]
	v_mfma_f32_16x16x32_bf16 v[32:35], v[148:151], v[164:167], v[32:35]
	v_mfma_f32_16x16x32_bf16 v[20:23], v[144:147], v[196:199], v[20:23]
	v_mfma_f32_16x16x32_bf16 v[16:19], v[148:151], v[196:199], v[16:19]
	v_mfma_f32_16x16x32_bf16 v[4:7], v[144:147], v[200:203], v[4:7]
	v_mfma_f32_16x16x32_bf16 v[0:3], v[148:151], v[200:203], v[0:3]
	v_mfma_f32_16x16x32_bf16 v[52:55], v[152:155], v[180:183], v[52:55]
	v_mfma_f32_16x16x32_bf16 v[48:51], v[156:159], v[180:183], v[48:51]
	v_mfma_f32_16x16x32_bf16 v[36:39], v[152:155], v[192:195], v[36:39]
	v_mfma_f32_16x16x32_bf16 v[32:35], v[156:159], v[192:195], v[32:35]
	v_mfma_f32_16x16x32_bf16 v[20:23], v[152:155], v[204:207], v[20:23]
	v_mfma_f32_16x16x32_bf16 v[16:19], v[156:159], v[204:207], v[16:19]
	v_mfma_f32_16x16x32_bf16 v[4:7], v[152:155], v[208:211], v[4:7]
	v_mfma_f32_16x16x32_bf16 v[0:3], v[156:159], v[208:211], v[0:3]
	s_setprio 0
	s_barrier
; #define PG8_STAGE(bufoff, gbase, voff) do { _Pragma("unroll") for (int _i = 0; _i < 2; ++_i) \
;         dma16((const char*)(gbase), (voff)[_i], ldsb + (bufoff) + ldsw + _i * 8192); } while (0)
; #define PG8_LDA(dst, b, h) do { const int a1_ = opqv(aoff0) ^ 64; _Pragma("unroll") for (int m = 0; m < 4; ++m) { dst[m][0] = *(const LAS bf16x8*)(lds + PG8_SA(b, h) + aoff0 + m * 2048); dst[m][1] = *(const LAS bf16x8*)(lds + PG8_SA(b, h) + a1_ + m * 2048); } } while (0)
; #define PG8_LDB(dst, b, h) do { const int b1_ = opqv(boff0) ^ 64; _Pragma("unroll") for (int n = 0; n < 2; ++n) { dst[n][0] = *(const LAS bf16x8*)(lds + PG8_SB(b, h) + boff0 + n * 2048); dst[n][1] = *(const LAS bf16x8*)(lds + PG8_SB(b, h) + b1_ + n * 2048); } } while (0)
; #define PG8_MMA(ai, bj, At, Bt) do { __builtin_amdgcn_s_setprio(1); _Pragma("unroll") for (int m = 0; m < 4; ++m) _Pragma("unroll") for (int n = 0; n < 2; ++n) _Pragma("unroll") for (int k = 0; k < 2; ++k) \
;         acc[ai][bj][m][n] = __builtin_amdgcn_mfma_f32_16x16x32_bf16(Bt[n][k], At[m][k], acc[ai][bj][m][n], 0, 0, 0); __builtin_amdgcn_s_setprio(0); } while (0)
; #define PG8_WAIT_V(n) asm volatile("s_waitcnt vmcnt(" #n ")" ::: "memory")
; #define PG8_WAIT_L(n) asm volatile("s_waitcnt lgkmcnt(" #n ")" ::: "memory")
; #define PG8_BAR __builtin_amdgcn_s_barrier()
; #define PG8_SCHED __builtin_amdgcn_sched_barrier(0)
; template <class Epi>
; __device__ __forceinline__ void gemm_phase(LAS unsigned char* lds, const Gemm g, const StaticOrder& S, const Epi& E, int wave_) {
;     ...
;             PG8_STAGE(PG8_SA(0, 1), a2 + hstepA, voffA); PG8_LDB(B0, 1, 0); PG8_LDB(B1, 1, 1); PG8_SCHED; PG8_LDA(At, 1, 0);
;             PG8_WAIT_V(8); PG8_WAIT_L(0); PG8_BAR; PG8_MMA(0, 0, At, B0); PG8_MMA(0, 1, At, B1); PG8_BAR; PG8_SCHED;
;             PG8_STAGE(PG8_SB(1, 0), b3, voffB); PG8_STAGE(PG8_SB(1, 1), b3 + hstepB, voffB); PG8_STAGE(PG8_SA(1, 0), a3, voffA); PG8_LDA(At, 1, 1);
;             PG8_WAIT_V(8); PG8_WAIT_L(0); PG8_BAR; PG8_MMA(1, 0, At, B0); PG8_MMA(1, 1, At, B1); PG8_BAR; PG8_SCHED;
;         }
	s_add_u32 s44, s44, 0x80000
	s_addc_u32 s45, s45, 0
	s_mov_b32 m0, s1
	s_nop 0
	global_load_lds_dwordx4 v172, s[44:45]
	v_mov_b32_e32 v128, v178
	s_mov_b32 m0, s69
	s_nop 0
	global_load_lds_dwordx4 v174, s[44:45]
	v_add_u32_e32 v132, s34, v178
	v_xad_u32 v140, v128, 64, s34
	v_mov_b32_e32 v144, v178
	s_add_i32 s44, 0, 0x1c000
	ds_read_b128 v[128:131], v132
	ds_read_b128 v[132:135], v132 offset:2048
	ds_read_b128 v[136:139], v140
	ds_read_b128 v[140:143], v140 offset:2048
	v_add_u32_e32 v148, s44, v178
	v_xad_u32 v156, v144, 64, s44
	ds_read_b128 v[144:147], v148
	ds_read_b128 v[148:151], v148 offset:2048
	ds_read_b128 v[152:155], v156
	ds_read_b128 v[156:159], v156 offset:2048
	v_mov_b32_e32 v160, v177
	s_nop 0
	v_xad_u32 v168, v160, 64, 0
	ds_read_b128 v[160:163], v169 offset:32768
	ds_read_b128 v[164:167], v169 offset:34816
	ds_read_b128 v[180:183], v168 offset:32768
	ds_read_b128 v[192:195], v168 offset:34816
	ds_read_b128 v[196:199], v169 offset:36864
	ds_read_b128 v[200:203], v169 offset:38912
	ds_read_b128 v[204:207], v168 offset:36864
	ds_read_b128 v[208:211], v168 offset:38912
	s_waitcnt vmcnt(8)
	s_waitcnt lgkmcnt(0)
	s_setprio 1
	s_barrier
	v_mfma_f32_16x16x32_bf16 v[124:127], v[128:131], v[160:163], v[124:127]
	v_mfma_f32_16x16x32_bf16 v[120:123], v[132:135], v[160:163], v[120:123]
	v_mfma_f32_16x16x32_bf16 v[108:111], v[128:131], v[164:167], v[108:111]
	v_mfma_f32_16x16x32_bf16 v[104:107], v[132:135], v[164:167], v[104:107]
	v_mfma_f32_16x16x32_bf16 v[92:95], v[128:131], v[196:199], v[92:95]
	v_mfma_f32_16x16x32_bf16 v[88:91], v[132:135], v[196:199], v[88:91]
	v_mfma_f32_16x16x32_bf16 v[76:79], v[128:131], v[200:203], v[76:79]
	v_mfma_f32_16x16x32_bf16 v[72:75], v[132:135], v[200:203], v[72:75]
	v_mfma_f32_16x16x32_bf16 v[124:127], v[136:139], v[180:183], v[124:127]
	v_mfma_f32_16x16x32_bf16 v[120:123], v[140:143], v[180:183], v[120:123]
	v_mfma_f32_16x16x32_bf16 v[108:111], v[136:139], v[192:195], v[108:111]
	v_mfma_f32_16x16x32_bf16 v[104:107], v[140:143], v[192:195], v[104:107]
	v_mfma_f32_16x16x32_bf16 v[92:95], v[136:139], v[204:207], v[92:95]
	v_mfma_f32_16x16x32_bf16 v[88:91], v[140:143], v[204:207], v[88:91]
	v_mfma_f32_16x16x32_bf16 v[76:79], v[136:139], v[208:211], v[76:79]
	v_mfma_f32_16x16x32_bf16 v[72:75], v[140:143], v[208:211], v[72:75]
	s_setprio 0
	s_setprio 1
	v_mfma_f32_16x16x32_bf16 v[116:119], v[144:147], v[160:163], v[116:119]
	s_add_u32 s44, s40, 0x80
	s_addc_u32 s45, s41, 0
	v_mfma_f32_16x16x32_bf16 v[112:115], v[148:151], v[160:163], v[112:115]
	v_mfma_f32_16x16x32_bf16 v[100:103], v[144:147], v[164:167], v[100:103]
	v_mfma_f32_16x16x32_bf16 v[96:99], v[148:151], v[164:167], v[96:99]
	v_mfma_f32_16x16x32_bf16 v[84:87], v[144:147], v[196:199], v[84:87]
	v_mfma_f32_16x16x32_bf16 v[80:83], v[148:151], v[196:199], v[80:83]
	v_mfma_f32_16x16x32_bf16 v[68:71], v[144:147], v[200:203], v[68:71]
	v_mfma_f32_16x16x32_bf16 v[64:67], v[148:151], v[200:203], v[64:67]
	v_mfma_f32_16x16x32_bf16 v[116:119], v[152:155], v[180:183], v[116:119]
	v_mfma_f32_16x16x32_bf16 v[112:115], v[156:159], v[180:183], v[112:115]
	v_mfma_f32_16x16x32_bf16 v[100:103], v[152:155], v[192:195], v[100:103]
	v_mfma_f32_16x16x32_bf16 v[96:99], v[156:159], v[192:195], v[96:99]
	v_mfma_f32_16x16x32_bf16 v[84:87], v[152:155], v[204:207], v[84:87]
	v_mfma_f32_16x16x32_bf16 v[80:83], v[156:159], v[204:207], v[80:83]
	v_mfma_f32_16x16x32_bf16 v[68:71], v[152:155], v[208:211], v[68:71]
	v_mfma_f32_16x16x32_bf16 v[64:67], v[156:159], v[208:211], v[64:67]
	s_setprio 0
	s_barrier
	s_add_u32 s40, s40, 0x80080
	s_addc_u32 s41, s41, 0
	v_mov_b32_e32 v160, v177
	s_nop 0
	s_nop 0
	v_xad_u32 v168, v160, 64, 0
	ds_read_b128 v[160:163], v169 offset:49152
	ds_read_b128 v[164:167], v169 offset:51200
	ds_read_b128 v[180:183], v168 offset:49152
	ds_read_b128 v[192:195], v168 offset:51200
	ds_read_b128 v[196:199], v169 offset:53248
	ds_read_b128 v[200:203], v169 offset:55296
	ds_read_b128 v[204:207], v168 offset:53248
	ds_read_b128 v[208:211], v168 offset:55296
	s_mov_b32 m0, s35
	s_nop 0
	global_load_lds_dwordx4 v173, s[44:45]
	s_mov_b32 m0, s33
	s_nop 0
	global_load_lds_dwordx4 v175, s[44:45]
	s_mov_b32 m0, s77
	s_nop 0
	global_load_lds_dwordx4 v173, s[40:41]
	s_mov_b32 m0, s3
	s_nop 0
	global_load_lds_dwordx4 v175, s[40:41]
	s_mov_b32 m0, s22
	s_nop 0
	global_load_lds_dwordx4 v172, s[36:37]
	s_mov_b32 m0, s2
	s_nop 0
	global_load_lds_dwordx4 v174, s[36:37]
	s_waitcnt vmcnt(8)
	s_waitcnt lgkmcnt(0)
	s_setprio 1
	s_barrier
	v_mfma_f32_16x16x32_bf16 v[60:63], v[128:131], v[160:163], v[60:63]
	v_mfma_f32_16x16x32_bf16 v[56:59], v[132:135], v[160:163], v[56:59]
	v_mfma_f32_16x16x32_bf16 v[44:47], v[128:131], v[164:167], v[44:47]
	v_mfma_f32_16x16x32_bf16 v[40:43], v[132:135], v[164:167], v[40:43]
	v_mfma_f32_16x16x32_bf16 v[28:31], v[128:131], v[196:199], v[28:31]
	v_mfma_f32_16x16x32_bf16 v[24:27], v[132:135], v[196:199], v[24:27]
	v_mfma_f32_16x16x32_bf16 v[12:15], v[128:131], v[200:203], v[12:15]
	v_mfma_f32_16x16x32_bf16 v[8:11], v[132:135], v[200:203], v[8:11]
	v_mfma_f32_16x16x32_bf16 v[60:63], v[136:139], v[180:183], v[60:63]
	v_mfma_f32_16x16x32_bf16 v[56:59], v[140:143], v[180:183], v[56:59]
	v_mfma_f32_16x16x32_bf16 v[44:47], v[136:139], v[192:195], v[44:47]
	v_mfma_f32_16x16x32_bf16 v[40:43], v[140:143], v[192:195], v[40:43]
	v_mfma_f32_16x16x32_bf16 v[28:31], v[136:139], v[204:207], v[28:31]
	v_mfma_f32_16x16x32_bf16 v[24:27], v[140:143], v[204:207], v[24:27]
	v_mfma_f32_16x16x32_bf16 v[12:15], v[136:139], v[208:211], v[12:15]
	v_mfma_f32_16x16x32_bf16 v[8:11], v[140:143], v[208:211], v[8:11]
	s_setprio 0
	s_setprio 1
	v_mfma_f32_16x16x32_bf16 v[52:55], v[144:147], v[160:163], v[52:55]
	v_mfma_f32_16x16x32_bf16 v[48:51], v[148:151], v[160:163], v[48:51]
	v_mfma_f32_16x16x32_bf16 v[36:39], v[144:147], v[164:167], v[36:39]
	v_mfma_f32_16x16x32_bf16 v[32:35], v[148:151], v[164:167], v[32:35]
	v_mfma_f32_16x16x32_bf16 v[20:23], v[144:147], v[196:199], v[20:23]
	v_mfma_f32_16x16x32_bf16 v[16:19], v[148:151], v[196:199], v[16:19]
	v_mfma_f32_16x16x32_bf16 v[4:7], v[144:147], v[200:203], v[4:7]
	v_mfma_f32_16x16x32_bf16 v[0:3], v[148:151], v[200:203], v[0:3]
	v_mfma_f32_16x16x32_bf16 v[52:55], v[152:155], v[180:183], v[52:55]
	v_mfma_f32_16x16x32_bf16 v[48:51], v[156:159], v[180:183], v[48:51]
	v_mfma_f32_16x16x32_bf16 v[36:39], v[152:155], v[192:195], v[36:39]
	v_mfma_f32_16x16x32_bf16 v[32:35], v[156:159], v[192:195], v[32:35]
	v_mfma_f32_16x16x32_bf16 v[20:23], v[152:155], v[204:207], v[20:23]
	v_mfma_f32_16x16x32_bf16 v[16:19], v[156:159], v[204:207], v[16:19]
	v_mfma_f32_16x16x32_bf16 v[4:7], v[152:155], v[208:211], v[4:7]
	v_mfma_f32_16x16x32_bf16 v[0:3], v[156:159], v[208:211], v[0:3]
	s_setprio 0
	s_barrier
	s_add_i32 s57, s57, 2
	s_add_u32 s55, s55, 0x100
	s_addc_u32 s56, s56, 0
	s_add_u32 s12, s12, 0x100
	s_addc_u32 s13, s13, 0
	s_cmp_gt_u32 s57, 29
	s_cbranch_scc0 .LBB0_1322

; #define PG8_STAGE(bufoff, gbase, voff) do { _Pragma("unroll") for (int _i = 0; _i < 2; ++_i) \
;         dma16((const char*)(gbase), (voff)[_i], ldsb + (bufoff) + ldsw + _i * 8192); } while (0)
; #define PG8_LDA(dst, b, h) do { const int a1_ = opqv(aoff0) ^ 64; _Pragma("unroll") for (int m = 0; m < 4; ++m) { dst[m][0] = *(const LAS bf16x8*)(lds + PG8_SA(b, h) + aoff0 + m * 2048); dst[m][1] = *(const LAS bf16x8*)(lds + PG8_SA(b, h) + a1_ + m * 2048); } } while (0)
; #define PG8_LDB(dst, b, h) do { const int b1_ = opqv(boff0) ^ 64; _Pragma("unroll") for (int n = 0; n < 2; ++n) { dst[n][0] = *(const LAS bf16x8*)(lds + PG8_SB(b, h) + boff0 + n * 2048); dst[n][1] = *(const LAS bf16x8*)(lds + PG8_SB(b, h) + b1_ + n * 2048); } } while (0)
; #define PG8_MMA(ai, bj, At, Bt) do { __builtin_amdgcn_s_setprio(1); _Pragma("unroll") for (int m = 0; m < 4; ++m) _Pragma("unroll") for (int n = 0; n < 2; ++n) _Pragma("unroll") for (int k = 0; k < 2; ++k) \
;         acc[ai][bj][m][n] = __builtin_amdgcn_mfma_f32_16x16x32_bf16(Bt[n][k], At[m][k], acc[ai][bj][m][n], 0, 0, 0); __builtin_amdgcn_s_setprio(0); } while (0)
; template <class Epi>
; __device__ __forceinline__ void gemm_phase(LAS unsigned char* lds, const Gemm g, const StaticOrder& S, const Epi& E, int wave_) {
;     ...
;         const bool has_next = S.next(ui + 1, nxt);
;         const char* nA = has_next ? (const char*)g.A + (size_t)nxt.pm * tstepA : cA; const char* nB = has_next ? (const char*)g.Bt + (size_t)nxt.pn * tstepB : cB;
; #pragma unroll 1
;         for (int t = 0; t < nt; t += 2) {
;             const bool last = (t == nt - 2);
;             const char* a1 = cA + (size_t)(t + 1) * kstep;
;             const char* a2 = last ? nA : cA + (size_t)(t + 2) * kstep; const char* b2 = last ? nB : cB + (size_t)(t + 2) * kstep;
;             const char* a3 = a2 + kstep; const char* b3 = b2 + kstep;
;             PG8_STAGE(PG8_SA(1, 1), a1 + hstepA, voffA); PG8_LDB(B0, 0, 0); PG8_LDB(B1, 0, 1); PG8_SCHED; PG8_LDA(At, 0, 0);
;             PG8_WAIT_V(8); PG8_WAIT_L(0); PG8_BAR; PG8_MMA(0, 0, At, B0); PG8_MMA(0, 1, At, B1); PG8_BAR; PG8_SCHED;
;             PG8_STAGE(PG8_SB(0, 0), b2, voffB); PG8_STAGE(PG8_SB(0, 1), b2 + hstepB, voffB); PG8_STAGE(PG8_SA(0, 0), a2, voffA); PG8_LDA(At, 0, 1);
;             PG8_WAIT_V(8); PG8_WAIT_L(0); PG8_BAR; PG8_MMA(1, 0, At, B0); PG8_MMA(1, 1, At, B1); PG8_BAR; PG8_SCHED;
.LBB0_1341:
	s_ashr_i32 s9, s8, 31
	s_lshl_b64 s[10:11], s[8:9], 17
	s_add_u32 s10, s16, s10
	s_addc_u32 s11, s17, s11
	s_and_b64 s[12:13], s[42:43], exec
	s_cselect_b32 s9, s11, s27
	s_cselect_b32 s61, s10, s26
	s_ashr_i32 s7, s6, 31
	s_lshl_b64 s[12:13], s[6:7], 17
	s_add_u32 s18, s21, s12
	s_addc_u32 s19, s52, s13
	s_and_b64 s[12:13], s[42:43], exec
	s_cselect_b32 s7, s19, s25
	s_cselect_b32 s62, s18, s24
	s_mov_b64 s[30:31], 0
	s_mov_b64 s[12:13], -1
	s_mov_b64 s[36:37], 0
	s_add_u32 s46, s26, s30
	s_addc_u32 s47, s27, s31
	s_add_u32 s44, s46, 0x100
	s_addc_u32 s45, s47, 0
	s_and_b64 s[40:41], s[36:37], exec
	s_cselect_b32 s45, s9, s45
	s_cselect_b32 s44, s61, s44
	s_add_u32 s30, s24, s30
	s_addc_u32 s31, s25, s31
	s_add_u32 s40, s30, 0x100
	s_addc_u32 s41, s31, 0
	s_add_u32 s30, s44, 0x80
	s_addc_u32 s31, s45, 0
	s_add_u32 s56, s46, 0x10080
	s_addc_u32 s57, s47, 0
	s_mov_b32 m0, s14
	s_nop 0
	global_load_lds_dwordx4 v130, s[56:57]
	v_mov_b32_e32 v128, v136
	s_mov_b32 m0, s15
	s_nop 0
	global_load_lds_dwordx4 v132, s[56:57]
	s_and_b64 s[36:37], s[36:37], exec
	v_xad_u32 v128, v128, 64, s23
	v_add_u32_e32 v129, s23, v136
	s_cselect_b32 s49, s7, s41
	s_cselect_b32 s48, s62, s40
	s_add_i32 s37, 0, 0x14000
	ds_read_b128 v[138:141], v129
	ds_read_b128 v[142:145], v129 offset:2048
	ds_read_b128 v[146:149], v128
	ds_read_b128 v[150:153], v128 offset:2048
	v_mov_b32_e32 v128, v136
	v_add_u32_e32 v129, s37, v136
	s_add_u32 s46, s48, 0x10000
	v_xad_u32 v128, v128, 64, s37
	ds_read_b128 v[154:157], v129
	ds_read_b128 v[158:161], v129 offset:2048
	ds_read_b128 v[162:165], v128
	ds_read_b128 v[166:169], v128 offset:2048
	s_addc_u32 s47, s49, 0
	s_add_u32 s40, s44, 0x10000
	s_addc_u32 s41, s45, 0
	s_add_i32 s63, 0, 0x1c000
	s_add_u32 s36, s48, 0x80
	s_addc_u32 s37, s49, 0
	s_add_u32 s56, s48, 0x10080
	s_addc_u32 s57, s49, 0
	v_mov_b32_e32 v128, v135
	v_add_u32_e32 v129, 0, v135
	v_xad_u32 v128, v128, 64, 0
	ds_read_b128 v[172:175], v129
	ds_read_b128 v[176:179], v129 offset:2048
	ds_read_b128 v[180:183], v128
	ds_read_b128 v[192:195], v128 offset:2048
	ds_read_b128 v[196:199], v129 offset:4096
	ds_read_b128 v[200:203], v129 offset:6144
	ds_read_b128 v[204:207], v128 offset:4096
	ds_read_b128 v[208:211], v128 offset:6144
	s_waitcnt vmcnt(8)
	s_waitcnt lgkmcnt(0)
	s_setprio 1
	s_barrier
	v_mfma_f32_16x16x32_bf16 v[124:127], v[138:141], v[172:175], 0
	v_mfma_f32_16x16x32_bf16 v[120:123], v[142:145], v[172:175], 0
	v_mfma_f32_16x16x32_bf16 v[116:119], v[138:141], v[176:179], 0
	v_mfma_f32_16x16x32_bf16 v[108:111], v[142:145], v[176:179], 0
	v_mfma_f32_16x16x32_bf16 v[100:103], v[138:141], v[196:199], 0
	v_mfma_f32_16x16x32_bf16 v[92:95], v[142:145], v[196:199], 0
	v_mfma_f32_16x16x32_bf16 v[84:87], v[138:141], v[200:203], 0
	v_mfma_f32_16x16x32_bf16 v[76:79], v[142:145], v[200:203], 0
	v_mfma_f32_16x16x32_bf16 v[124:127], v[146:149], v[180:183], v[124:127]
	v_mfma_f32_16x16x32_bf16 v[120:123], v[150:153], v[180:183], v[120:123]
	v_mfma_f32_16x16x32_bf16 v[116:119], v[146:149], v[192:195], v[116:119]
	v_mfma_f32_16x16x32_bf16 v[108:111], v[150:153], v[192:195], v[108:111]
	v_mfma_f32_16x16x32_bf16 v[100:103], v[146:149], v[204:207], v[100:103]
	v_mfma_f32_16x16x32_bf16 v[92:95], v[150:153], v[204:207], v[92:95]
	v_mfma_f32_16x16x32_bf16 v[84:87], v[146:149], v[208:211], v[84:87]
	v_mfma_f32_16x16x32_bf16 v[76:79], v[150:153], v[208:211], v[76:79]
	s_setprio 0
	s_setprio 1
	v_mfma_f32_16x16x32_bf16 v[112:115], v[154:157], v[172:175], 0
	v_mfma_f32_16x16x32_bf16 v[104:107], v[158:161], v[172:175], 0
	v_mfma_f32_16x16x32_bf16 v[96:99], v[154:157], v[176:179], 0
	v_mfma_f32_16x16x32_bf16 v[88:91], v[158:161], v[176:179], 0
	v_mfma_f32_16x16x32_bf16 v[80:83], v[154:157], v[196:199], 0
	v_mfma_f32_16x16x32_bf16 v[72:75], v[158:161], v[196:199], 0
	v_mfma_f32_16x16x32_bf16 v[68:71], v[154:157], v[200:203], 0
	v_mfma_f32_16x16x32_bf16 v[64:67], v[158:161], v[200:203], 0
	v_mfma_f32_16x16x32_bf16 v[112:115], v[162:165], v[180:183], v[112:115]
	v_mfma_f32_16x16x32_bf16 v[104:107], v[166:169], v[180:183], v[104:107]
	v_mfma_f32_16x16x32_bf16 v[96:99], v[162:165], v[192:195], v[96:99]
	v_mfma_f32_16x16x32_bf16 v[88:91], v[166:169], v[192:195], v[88:91]
	v_mfma_f32_16x16x32_bf16 v[80:83], v[162:165], v[204:207], v[80:83]
	v_mfma_f32_16x16x32_bf16 v[72:75], v[166:169], v[204:207], v[72:75]
	v_mfma_f32_16x16x32_bf16 v[68:71], v[162:165], v[208:211], v[68:71]
	v_mfma_f32_16x16x32_bf16 v[64:67], v[166:169], v[208:211], v[64:67]
	s_setprio 0
	s_barrier
	v_mov_b32_e32 v128, v135
	s_nop 0
	s_nop 0
	s_nop 0
	v_xad_u32 v128, v128, 64, 0
	ds_read_b128 v[172:175], v129 offset:16384
	ds_read_b128 v[176:179], v129 offset:18432
	ds_read_b128 v[180:183], v128 offset:16384
	ds_read_b128 v[192:195], v128 offset:18432
	ds_read_b128 v[196:199], v129 offset:20480
	ds_read_b128 v[200:203], v129 offset:22528
	ds_read_b128 v[204:207], v128 offset:20480
	ds_read_b128 v[208:211], v128 offset:22528
	s_mov_b32 m0, s80
	s_nop 0
	global_load_lds_dwordx4 v131, s[48:49]
	s_mov_b32 m0, s81
	s_nop 0
	global_load_lds_dwordx4 v133, s[48:49]
	s_mov_b32 m0, s29
	s_nop 0
	global_load_lds_dwordx4 v131, s[46:47]
	s_mov_b32 m0, s88
	s_nop 0
	global_load_lds_dwordx4 v133, s[46:47]
	s_mov_b32 m0, s76
	s_nop 0
	global_load_lds_dwordx4 v130, s[44:45]
	s_mov_b32 m0, s89
	s_nop 0
	global_load_lds_dwordx4 v132, s[44:45]
	s_waitcnt vmcnt(8)
	s_waitcnt lgkmcnt(0)
	s_setprio 1
	s_barrier
; #define PG8_STAGE(bufoff, gbase, voff) do { _Pragma("unroll") for (int _i = 0; _i < 2; ++_i) \
;         dma16((const char*)(gbase), (voff)[_i], ldsb + (bufoff) + ldsw + _i * 8192); } while (0)
; #define PG8_LDA(dst, b, h) do { const int a1_ = opqv(aoff0) ^ 64; _Pragma("unroll") for (int m = 0; m < 4; ++m) { dst[m][0] = *(const LAS bf16x8*)(lds + PG8_SA(b, h) + aoff0 + m * 2048); dst[m][1] = *(const LAS bf16x8*)(lds + PG8_SA(b, h) + a1_ + m * 2048); } } while (0)
; #define PG8_LDB(dst, b, h) do { const int b1_ = opqv(boff0) ^ 64; _Pragma("unroll") for (int n = 0; n < 2; ++n) { dst[n][0] = *(const LAS bf16x8*)(lds + PG8_SB(b, h) + boff0 + n * 2048); dst[n][1] = *(const LAS bf16x8*)(lds + PG8_SB(b, h) + b1_ + n * 2048); } } while (0)
; #define PG8_MMA(ai, bj, At, Bt) do { __builtin_amdgcn_s_setprio(1); _Pragma("unroll") for (int m = 0; m < 4; ++m) _Pragma("unroll") for (int n = 0; n < 2; ++n) _Pragma("unroll") for (int k = 0; k < 2; ++k) \
;         acc[ai][bj][m][n] = __builtin_amdgcn_mfma_f32_16x16x32_bf16(Bt[n][k], At[m][k], acc[ai][bj][m][n], 0, 0, 0); __builtin_amdgcn_s_setprio(0); } while (0)
; #define PG8_WAIT_V(n) asm volatile("s_waitcnt vmcnt(" #n ")" ::: "memory")
; #define PG8_WAIT_L(n) asm volatile("s_waitcnt lgkmcnt(" #n ")" ::: "memory")
; #define PG8_BAR __builtin_amdgcn_s_barrier()
; #define PG8_SCHED __builtin_amdgcn_sched_barrier(0)
; template <class Epi>
; __device__ __forceinline__ void gemm_phase(LAS unsigned char* lds, const Gemm g, const StaticOrder& S, const Epi& E, int wave_) {
;     ...
;             PG8_WAIT_V(8); PG8_WAIT_L(0); PG8_BAR; PG8_MMA(1, 0, At, B0); PG8_MMA(1, 1, At, B1); PG8_BAR; PG8_SCHED;
;             PG8_STAGE(PG8_SA(0, 1), a2 + hstepA, voffA); PG8_LDB(B0, 1, 0); PG8_LDB(B1, 1, 1); PG8_SCHED; PG8_LDA(At, 1, 0);
;             PG8_WAIT_V(8); PG8_WAIT_L(0); PG8_BAR; PG8_MMA(0, 0, At, B0); PG8_MMA(0, 1, At, B1); PG8_BAR; PG8_SCHED;
	v_mfma_f32_16x16x32_bf16 v[60:63], v[138:141], v[172:175], 0
	v_mfma_f32_16x16x32_bf16 v[56:59], v[142:145], v[172:175], 0
	v_mfma_f32_16x16x32_bf16 v[52:55], v[138:141], v[176:179], 0
	v_mfma_f32_16x16x32_bf16 v[44:47], v[142:145], v[176:179], 0
	v_mfma_f32_16x16x32_bf16 v[36:39], v[138:141], v[196:199], 0
	v_mfma_f32_16x16x32_bf16 v[28:31], v[142:145], v[196:199], 0
	v_mfma_f32_16x16x32_bf16 v[20:23], v[138:141], v[200:203], 0
	v_mfma_f32_16x16x32_bf16 v[12:15], v[142:145], v[200:203], 0
	v_mfma_f32_16x16x32_bf16 v[60:63], v[146:149], v[180:183], v[60:63]
	v_mfma_f32_16x16x32_bf16 v[56:59], v[150:153], v[180:183], v[56:59]
	v_mfma_f32_16x16x32_bf16 v[52:55], v[146:149], v[192:195], v[52:55]
	v_mfma_f32_16x16x32_bf16 v[44:47], v[150:153], v[192:195], v[44:47]
	v_mfma_f32_16x16x32_bf16 v[36:39], v[146:149], v[204:207], v[36:39]
	v_mfma_f32_16x16x32_bf16 v[28:31], v[150:153], v[204:207], v[28:31]
	v_mfma_f32_16x16x32_bf16 v[20:23], v[146:149], v[208:211], v[20:23]
	v_mfma_f32_16x16x32_bf16 v[12:15], v[150:153], v[208:211], v[12:15]
	s_setprio 0
	s_setprio 1
	v_mfma_f32_16x16x32_bf16 v[48:51], v[154:157], v[172:175], 0
	v_mfma_f32_16x16x32_bf16 v[40:43], v[158:161], v[172:175], 0
	v_mfma_f32_16x16x32_bf16 v[32:35], v[154:157], v[176:179], 0
	v_mfma_f32_16x16x32_bf16 v[24:27], v[158:161], v[176:179], 0
	v_mfma_f32_16x16x32_bf16 v[16:19], v[154:157], v[196:199], 0
	v_mfma_f32_16x16x32_bf16 v[8:11], v[158:161], v[196:199], 0
	v_mfma_f32_16x16x32_bf16 v[4:7], v[154:157], v[200:203], 0
	v_mfma_f32_16x16x32_bf16 v[0:3], v[158:161], v[200:203], 0
	v_mfma_f32_16x16x32_bf16 v[48:51], v[162:165], v[180:183], v[48:51]
	v_mfma_f32_16x16x32_bf16 v[40:43], v[166:169], v[180:183], v[40:43]
	v_mfma_f32_16x16x32_bf16 v[32:35], v[162:165], v[192:195], v[32:35]
	v_mfma_f32_16x16x32_bf16 v[24:27], v[166:169], v[192:195], v[24:27]
	v_mfma_f32_16x16x32_bf16 v[16:19], v[162:165], v[204:207], v[16:19]
	v_mfma_f32_16x16x32_bf16 v[8:11], v[166:169], v[204:207], v[8:11]
	v_mfma_f32_16x16x32_bf16 v[4:7], v[162:165], v[208:211], v[4:7]
	v_mfma_f32_16x16x32_bf16 v[0:3], v[166:169], v[208:211], v[0:3]
	s_setprio 0
	s_barrier
	v_mov_b32_e32 v128, v136
	v_add_u32_e32 v142, s34, v136
	v_xad_u32 v128, v128, 64, s34
	ds_read_b128 v[138:141], v142
	ds_read_b128 v[142:145], v142 offset:2048
	ds_read_b128 v[146:149], v128
	ds_read_b128 v[150:153], v128 offset:2048
	v_mov_b32_e32 v128, v136
	v_add_u32_e32 v158, s63, v136
	v_xad_u32 v128, v128, 64, s63
	ds_read_b128 v[154:157], v158
	ds_read_b128 v[158:161], v158 offset:2048
	ds_read_b128 v[162:165], v128
	ds_read_b128 v[166:169], v128 offset:2048
	v_mov_b32_e32 v128, v135
	s_nop 0
	v_xad_u32 v128, v128, 64, 0
	ds_read_b128 v[172:175], v129 offset:32768
	ds_read_b128 v[176:179], v129 offset:34816
	ds_read_b128 v[180:183], v128 offset:32768
	ds_read_b128 v[192:195], v128 offset:34816
	ds_read_b128 v[196:199], v129 offset:36864
	ds_read_b128 v[200:203], v129 offset:38912
	ds_read_b128 v[204:207], v128 offset:36864
	ds_read_b128 v[208:211], v128 offset:38912
	s_mov_b32 m0, s1
	s_nop 0
	global_load_lds_dwordx4 v130, s[40:41]
	s_mov_b32 m0, s69
	s_nop 0
	global_load_lds_dwordx4 v132, s[40:41]
	s_waitcnt vmcnt(8)
	s_waitcnt lgkmcnt(0)
	s_setprio 1
	s_barrier
	v_mfma_f32_16x16x32_bf16 v[124:127], v[138:141], v[172:175], v[124:127]
	v_mfma_f32_16x16x32_bf16 v[120:123], v[142:145], v[172:175], v[120:123]
	v_mfma_f32_16x16x32_bf16 v[116:119], v[138:141], v[176:179], v[116:119]
	v_mfma_f32_16x16x32_bf16 v[108:111], v[142:145], v[176:179], v[108:111]
	v_mfma_f32_16x16x32_bf16 v[100:103], v[138:141], v[196:199], v[100:103]
	v_mfma_f32_16x16x32_bf16 v[92:95], v[142:145], v[196:199], v[92:95]
	v_mfma_f32_16x16x32_bf16 v[84:87], v[138:141], v[200:203], v[84:87]
	v_mfma_f32_16x16x32_bf16 v[76:79], v[142:145], v[200:203], v[76:79]
	v_mfma_f32_16x16x32_bf16 v[124:127], v[146:149], v[180:183], v[124:127]
	v_mfma_f32_16x16x32_bf16 v[120:123], v[150:153], v[180:183], v[120:123]
	v_mfma_f32_16x16x32_bf16 v[116:119], v[146:149], v[192:195], v[116:119]
	v_mfma_f32_16x16x32_bf16 v[108:111], v[150:153], v[192:195], v[108:111]
	v_mfma_f32_16x16x32_bf16 v[100:103], v[146:149], v[204:207], v[100:103]
	v_mfma_f32_16x16x32_bf16 v[92:95], v[150:153], v[204:207], v[92:95]
	v_mfma_f32_16x16x32_bf16 v[84:87], v[146:149], v[208:211], v[84:87]
	v_mfma_f32_16x16x32_bf16 v[76:79], v[150:153], v[208:211], v[76:79]
	s_setprio 0
	s_setprio 1
	v_mfma_f32_16x16x32_bf16 v[112:115], v[154:157], v[172:175], v[112:115]
	v_mfma_f32_16x16x32_bf16 v[104:107], v[158:161], v[172:175], v[104:107]
	v_mfma_f32_16x16x32_bf16 v[96:99], v[154:157], v[176:179], v[96:99]
	v_mfma_f32_16x16x32_bf16 v[88:91], v[158:161], v[176:179], v[88:91]
	v_mfma_f32_16x16x32_bf16 v[80:83], v[154:157], v[196:199], v[80:83]
	v_mfma_f32_16x16x32_bf16 v[72:75], v[158:161], v[196:199], v[72:75]
	v_mfma_f32_16x16x32_bf16 v[68:71], v[154:157], v[200:203], v[68:71]
	v_mfma_f32_16x16x32_bf16 v[64:67], v[158:161], v[200:203], v[64:67]
	v_mfma_f32_16x16x32_bf16 v[112:115], v[162:165], v[180:183], v[112:115]
	v_mfma_f32_16x16x32_bf16 v[104:107], v[166:169], v[180:183], v[104:107]
	v_mfma_f32_16x16x32_bf16 v[96:99], v[162:165], v[192:195], v[96:99]
	v_mfma_f32_16x16x32_bf16 v[88:91], v[166:169], v[192:195], v[88:91]
	v_mfma_f32_16x16x32_bf16 v[80:83], v[162:165], v[204:207], v[80:83]
	v_mfma_f32_16x16x32_bf16 v[72:75], v[166:169], v[204:207], v[72:75]
	v_mfma_f32_16x16x32_bf16 v[68:71], v[162:165], v[208:211], v[68:71]
	v_mfma_f32_16x16x32_bf16 v[64:67], v[166:169], v[208:211], v[64:67]
	s_setprio 0
	s_barrier
; #define PG8_STAGE(bufoff, gbase, voff) do { _Pragma("unroll") for (int _i = 0; _i < 2; ++_i) \
;         dma16((const char*)(gbase), (voff)[_i], ldsb + (bufoff) + ldsw + _i * 8192); } while (0)
; #define PG8_LDA(dst, b, h) do { const int a1_ = opqv(aoff0) ^ 64; _Pragma("unroll") for (int m = 0; m < 4; ++m) { dst[m][0] = *(const LAS bf16x8*)(lds + PG8_SA(b, h) + aoff0 + m * 2048); dst[m][1] = *(const LAS bf16x8*)(lds + PG8_SA(b, h) + a1_ + m * 2048); } } while (0)
; #define PG8_WAIT_V(n) asm volatile("s_waitcnt vmcnt(" #n ")" ::: "memory")
; #define PG8_BAR __builtin_amdgcn_s_barrier()
; template <class Epi>
; __device__ __forceinline__ void gemm_phase(LAS unsigned char* lds, const Gemm g, const StaticOrder& S, const Epi& E, int wave_) {
;     ...
;         const bool has_next = S.next(ui + 1, nxt);
;         const char* nA = has_next ? (const char*)g.A + (size_t)nxt.pm * tstepA : cA; const char* nB = has_next ? (const char*)g.Bt + (size_t)nxt.pn * tstepB : cB;
; #pragma unroll 1
;         for (int t = 0; t < nt; t += 2) {
;             const bool last = (t == nt - 2);
;             const char* a1 = cA + (size_t)(t + 1) * kstep;
;             const char* a2 = last ? nA : cA + (size_t)(t + 2) * kstep; const char* b2 = last ? nB : cB + (size_t)(t + 2) * kstep;
;             const char* a3 = a2 + kstep; const char* b3 = b2 + kstep;
;             PG8_STAGE(PG8_SA(1, 1), a1 + hstepA, voffA); PG8_LDB(B0, 0, 0); PG8_LDB(B1, 0, 1); PG8_SCHED; PG8_LDA(At, 0, 0);
;             PG8_WAIT_V(8); PG8_WAIT_L(0); PG8_BAR; PG8_MMA(0, 0, At, B0); PG8_MMA(0, 1, At, B1); PG8_BAR; PG8_SCHED;
;             PG8_STAGE(PG8_SB(0, 0), b2, voffB); PG8_STAGE(PG8_SB(0, 1), b2 + hstepB, voffB); PG8_STAGE(PG8_SA(0, 0), a2, voffA); PG8_LDA(At, 0, 1);
;             PG8_WAIT_V(8); PG8_WAIT_L(0); PG8_BAR; PG8_MMA(1, 0, At, B0); PG8_MMA(1, 1, At, B1); PG8_BAR; PG8_SCHED;
;             PG8_STAGE(PG8_SA(0, 1), a2 + hstepA, voffA); PG8_LDB(B0, 1, 0); PG8_LDB(B1, 1, 1); PG8_SCHED; PG8_LDA(At, 1, 0);
;             PG8_WAIT_V(8); PG8_WAIT_L(0); PG8_BAR; PG8_MMA(0, 0, At, B0); PG8_MMA(0, 1, At, B1); PG8_BAR; PG8_SCHED;
;             PG8_STAGE(PG8_SB(1, 0), b3, voffB); PG8_STAGE(PG8_SB(1, 1), b3 + hstepB, voffB); PG8_STAGE(PG8_SA(1, 0), a3, voffA); PG8_LDA(At, 1, 1);
;             PG8_WAIT_V(8); PG8_WAIT_L(0); PG8_BAR; PG8_MMA(1, 0, At, B0); PG8_MMA(1, 1, At, B1); PG8_BAR; PG8_SCHED;
	v_mov_b32_e32 v128, v135
	s_nop 0
	s_nop 0
	s_nop 0
	s_nop 0
	v_xad_u32 v128, v128, 64, 0
	ds_read_b128 v[172:175], v129 offset:49152
	ds_read_b128 v[176:179], v129 offset:51200
	ds_read_b128 v[180:183], v128 offset:49152
	ds_read_b128 v[192:195], v128 offset:51200
	ds_read_b128 v[196:199], v129 offset:53248
	ds_read_b128 v[200:203], v129 offset:55296
	ds_read_b128 v[204:207], v128 offset:53248
	ds_read_b128 v[208:211], v128 offset:55296
	s_mov_b32 m0, s35
	s_nop 0
	global_load_lds_dwordx4 v131, s[36:37]
	s_mov_b32 m0, s33
	s_nop 0
	global_load_lds_dwordx4 v133, s[36:37]
	s_mov_b32 m0, s77
	s_nop 0
	global_load_lds_dwordx4 v131, s[56:57]
	s_mov_b32 m0, s3
	s_nop 0
	global_load_lds_dwordx4 v133, s[56:57]
	s_mov_b32 m0, s22
	s_nop 0
	global_load_lds_dwordx4 v130, s[30:31]
	s_mov_b32 m0, s2
	s_nop 0
	global_load_lds_dwordx4 v132, s[30:31]
	s_waitcnt vmcnt(8)
	s_waitcnt lgkmcnt(0)
	s_setprio 1
	s_barrier
	v_mfma_f32_16x16x32_bf16 v[60:63], v[138:141], v[172:175], v[60:63]
	v_mfma_f32_16x16x32_bf16 v[56:59], v[142:145], v[172:175], v[56:59]
	v_mfma_f32_16x16x32_bf16 v[52:55], v[138:141], v[176:179], v[52:55]
	v_mfma_f32_16x16x32_bf16 v[44:47], v[142:145], v[176:179], v[44:47]
	v_mfma_f32_16x16x32_bf16 v[36:39], v[138:141], v[196:199], v[36:39]
	v_mfma_f32_16x16x32_bf16 v[28:31], v[142:145], v[196:199], v[28:31]
	v_mfma_f32_16x16x32_bf16 v[20:23], v[138:141], v[200:203], v[20:23]
	v_mfma_f32_16x16x32_bf16 v[12:15], v[142:145], v[200:203], v[12:15]
	v_mfma_f32_16x16x32_bf16 v[60:63], v[146:149], v[180:183], v[60:63]
	v_mfma_f32_16x16x32_bf16 v[56:59], v[150:153], v[180:183], v[56:59]
	v_mfma_f32_16x16x32_bf16 v[52:55], v[146:149], v[192:195], v[52:55]
	v_mfma_f32_16x16x32_bf16 v[44:47], v[150:153], v[192:195], v[44:47]
	v_mfma_f32_16x16x32_bf16 v[36:39], v[146:149], v[204:207], v[36:39]
	v_mfma_f32_16x16x32_bf16 v[28:31], v[150:153], v[204:207], v[28:31]
	v_mfma_f32_16x16x32_bf16 v[20:23], v[146:149], v[208:211], v[20:23]
	v_mfma_f32_16x16x32_bf16 v[12:15], v[150:153], v[208:211], v[12:15]
	s_setprio 0
	s_setprio 1
	v_mfma_f32_16x16x32_bf16 v[48:51], v[154:157], v[172:175], v[48:51]
	v_mfma_f32_16x16x32_bf16 v[40:43], v[158:161], v[172:175], v[40:43]
	v_mfma_f32_16x16x32_bf16 v[32:35], v[154:157], v[176:179], v[32:35]
	v_mfma_f32_16x16x32_bf16 v[24:27], v[158:161], v[176:179], v[24:27]
	v_mfma_f32_16x16x32_bf16 v[16:19], v[154:157], v[196:199], v[16:19]
	v_mfma_f32_16x16x32_bf16 v[8:11], v[158:161], v[196:199], v[8:11]
	v_mfma_f32_16x16x32_bf16 v[4:7], v[154:157], v[200:203], v[4:7]
	v_mfma_f32_16x16x32_bf16 v[0:3], v[158:161], v[200:203], v[0:3]
	v_mfma_f32_16x16x32_bf16 v[48:51], v[162:165], v[180:183], v[48:51]
	v_mfma_f32_16x16x32_bf16 v[40:43], v[166:169], v[180:183], v[40:43]
	v_mfma_f32_16x16x32_bf16 v[32:35], v[162:165], v[192:195], v[32:35]
	v_mfma_f32_16x16x32_bf16 v[24:27], v[166:169], v[192:195], v[24:27]
	v_mfma_f32_16x16x32_bf16 v[16:19], v[162:165], v[204:207], v[16:19]
	v_mfma_f32_16x16x32_bf16 v[8:11], v[166:169], v[204:207], v[8:11]
	v_mfma_f32_16x16x32_bf16 v[4:7], v[162:165], v[208:211], v[4:7]
	v_mfma_f32_16x16x32_bf16 v[0:3], v[166:169], v[208:211], v[0:3]
	s_setprio 0
	s_barrier
	s_andn2_b64 vcc, exec, s[12:13]
	s_mov_b64 s[36:37], -1
	s_mov_b64 s[12:13], 0
	s_mov_b64 s[30:31], 0x100
	s_cbranch_vccz .LBB0_1342
	s_branch .Lpeel_exit_2
.LBB0_1342:
	s_add_u32 s46, s26, s30
	s_addc_u32 s47, s27, s31
	s_add_u32 s44, s46, 0x100
	s_addc_u32 s45, s47, 0
	s_and_b64 s[40:41], s[36:37], exec
	s_cselect_b32 s45, s9, s45
	s_cselect_b32 s44, s61, s44
	s_add_u32 s30, s24, s30
	s_addc_u32 s31, s25, s31
	s_add_u32 s40, s30, 0x100
	s_addc_u32 s41, s31, 0
	s_add_u32 s30, s44, 0x80
	s_addc_u32 s31, s45, 0
	s_add_u32 s56, s46, 0x10080
	s_addc_u32 s57, s47, 0
	s_mov_b32 m0, s14
	s_nop 0
	global_load_lds_dwordx4 v130, s[56:57]
	v_mov_b32_e32 v128, v136
	s_mov_b32 m0, s15
	s_nop 0
	global_load_lds_dwordx4 v132, s[56:57]
	s_and_b64 s[36:37], s[36:37], exec
	v_xad_u32 v128, v128, 64, s23
	v_add_u32_e32 v129, s23, v136
	s_cselect_b32 s49, s7, s41
	s_cselect_b32 s48, s62, s40
	s_add_i32 s37, 0, 0x14000
	ds_read_b128 v[138:141], v129
	ds_read_b128 v[142:145], v129 offset:2048
	ds_read_b128 v[146:149], v128
	ds_read_b128 v[150:153], v128 offset:2048
	v_mov_b32_e32 v128, v136
	v_add_u32_e32 v129, s37, v136
	s_add_u32 s46, s48, 0x10000
	v_xad_u32 v128, v128, 64, s37
	ds_read_b128 v[154:157], v129
	ds_read_b128 v[158:161], v129 offset:2048
	ds_read_b128 v[162:165], v128
	ds_read_b128 v[166:169], v128 offset:2048
	s_addc_u32 s47, s49, 0
	s_add_u32 s40, s44, 0x10000
	s_addc_u32 s41, s45, 0
	s_add_i32 s63, 0, 0x1c000
	s_add_u32 s36, s48, 0x80
	s_addc_u32 s37, s49, 0
	s_add_u32 s56, s48, 0x10080
	s_addc_u32 s57, s49, 0
	v_mov_b32_e32 v128, v135
	v_add_u32_e32 v129, 0, v135
	v_xad_u32 v128, v128, 64, 0
	ds_read_b128 v[172:175], v129
	ds_read_b128 v[176:179], v129 offset:2048
	ds_read_b128 v[180:183], v128
	ds_read_b128 v[192:195], v128 offset:2048
	ds_read_b128 v[196:199], v129 offset:4096
	ds_read_b128 v[200:203], v129 offset:6144
	ds_read_b128 v[204:207], v128 offset:4096
	ds_read_b128 v[208:211], v128 offset:6144
	s_waitcnt vmcnt(8)
	s_waitcnt lgkmcnt(0)
	s_setprio 1
	s_barrier
; #define PG8_STAGE(bufoff, gbase, voff) do { _Pragma("unroll") for (int _i = 0; _i < 2; ++_i) \
;         dma16((const char*)(gbase), (voff)[_i], ldsb + (bufoff) + ldsw + _i * 8192); } while (0)
; #define PG8_LDA(dst, b, h) do { const int a1_ = opqv(aoff0) ^ 64; _Pragma("unroll") for (int m = 0; m < 4; ++m) { dst[m][0] = *(const LAS bf16x8*)(lds + PG8_SA(b, h) + aoff0 + m * 2048); dst[m][1] = *(const LAS bf16x8*)(lds + PG8_SA(b, h) + a1_ + m * 2048); } } while (0)
; #define PG8_LDB(dst, b, h) do { const int b1_ = opqv(boff0) ^ 64; _Pragma("unroll") for (int n = 0; n < 2; ++n) { dst[n][0] = *(const LAS bf16x8*)(lds + PG8_SB(b, h) + boff0 + n * 2048); dst[n][1] = *(const LAS bf16x8*)(lds + PG8_SB(b, h) + b1_ + n * 2048); } } while (0)
; #define PG8_MMA(ai, bj, At, Bt) do { __builtin_amdgcn_s_setprio(1); _Pragma("unroll") for (int m = 0; m < 4; ++m) _Pragma("unroll") for (int n = 0; n < 2; ++n) _Pragma("unroll") for (int k = 0; k < 2; ++k) \
;         acc[ai][bj][m][n] = __builtin_amdgcn_mfma_f32_16x16x32_bf16(Bt[n][k], At[m][k], acc[ai][bj][m][n], 0, 0, 0); __builtin_amdgcn_s_setprio(0); } while (0)
; #define PG8_WAIT_V(n) asm volatile("s_waitcnt vmcnt(" #n ")" ::: "memory")
; #define PG8_WAIT_L(n) asm volatile("s_waitcnt lgkmcnt(" #n ")" ::: "memory")
; #define PG8_BAR __builtin_amdgcn_s_barrier()
; #define PG8_SCHED __builtin_amdgcn_sched_barrier(0)
; template <class Epi>
; __device__ __forceinline__ void gemm_phase(LAS unsigned char* lds, const Gemm g, const StaticOrder& S, const Epi& E, int wave_) {
;     ...
;             PG8_WAIT_V(8); PG8_WAIT_L(0); PG8_BAR; PG8_MMA(0, 0, At, B0); PG8_MMA(0, 1, At, B1); PG8_BAR; PG8_SCHED;
;             PG8_STAGE(PG8_SB(0, 0), b2, voffB); PG8_STAGE(PG8_SB(0, 1), b2 + hstepB, voffB); PG8_STAGE(PG8_SA(0, 0), a2, voffA); PG8_LDA(At, 0, 1);
;             PG8_WAIT_V(8); PG8_WAIT_L(0); PG8_BAR; PG8_MMA(1, 0, At, B0); PG8_MMA(1, 1, At, B1); PG8_BAR; PG8_SCHED;
;             PG8_STAGE(PG8_SA(0, 1), a2 + hstepA, voffA); PG8_LDB(B0, 1, 0); PG8_LDB(B1, 1, 1); PG8_SCHED; PG8_LDA(At, 1, 0);
;             PG8_WAIT_V(8); PG8_WAIT_L(0); PG8_BAR; PG8_MMA(0, 0, At, B0); PG8_MMA(0, 1, At, B1); PG8_BAR; PG8_SCHED;
	v_mfma_f32_16x16x32_bf16 v[124:127], v[138:141], v[172:175], v[124:127]
	v_mfma_f32_16x16x32_bf16 v[120:123], v[142:145], v[172:175], v[120:123]
	v_mfma_f32_16x16x32_bf16 v[116:119], v[138:141], v[176:179], v[116:119]
	v_mfma_f32_16x16x32_bf16 v[108:111], v[142:145], v[176:179], v[108:111]
	v_mfma_f32_16x16x32_bf16 v[100:103], v[138:141], v[196:199], v[100:103]
	v_mfma_f32_16x16x32_bf16 v[92:95], v[142:145], v[196:199], v[92:95]
	v_mfma_f32_16x16x32_bf16 v[84:87], v[138:141], v[200:203], v[84:87]
	v_mfma_f32_16x16x32_bf16 v[76:79], v[142:145], v[200:203], v[76:79]
	v_mfma_f32_16x16x32_bf16 v[124:127], v[146:149], v[180:183], v[124:127]
	v_mfma_f32_16x16x32_bf16 v[120:123], v[150:153], v[180:183], v[120:123]
	v_mfma_f32_16x16x32_bf16 v[116:119], v[146:149], v[192:195], v[116:119]
	v_mfma_f32_16x16x32_bf16 v[108:111], v[150:153], v[192:195], v[108:111]
	v_mfma_f32_16x16x32_bf16 v[100:103], v[146:149], v[204:207], v[100:103]
	v_mfma_f32_16x16x32_bf16 v[92:95], v[150:153], v[204:207], v[92:95]
	v_mfma_f32_16x16x32_bf16 v[84:87], v[146:149], v[208:211], v[84:87]
	v_mfma_f32_16x16x32_bf16 v[76:79], v[150:153], v[208:211], v[76:79]
	s_setprio 0
	s_setprio 1
	v_mfma_f32_16x16x32_bf16 v[112:115], v[154:157], v[172:175], v[112:115]
	v_mfma_f32_16x16x32_bf16 v[104:107], v[158:161], v[172:175], v[104:107]
	v_mfma_f32_16x16x32_bf16 v[96:99], v[154:157], v[176:179], v[96:99]
	v_mfma_f32_16x16x32_bf16 v[88:91], v[158:161], v[176:179], v[88:91]
	v_mfma_f32_16x16x32_bf16 v[80:83], v[154:157], v[196:199], v[80:83]
	v_mfma_f32_16x16x32_bf16 v[72:75], v[158:161], v[196:199], v[72:75]
	v_mfma_f32_16x16x32_bf16 v[68:71], v[154:157], v[200:203], v[68:71]
	v_mfma_f32_16x16x32_bf16 v[64:67], v[158:161], v[200:203], v[64:67]
	v_mfma_f32_16x16x32_bf16 v[112:115], v[162:165], v[180:183], v[112:115]
	v_mfma_f32_16x16x32_bf16 v[104:107], v[166:169], v[180:183], v[104:107]
	v_mfma_f32_16x16x32_bf16 v[96:99], v[162:165], v[192:195], v[96:99]
	v_mfma_f32_16x16x32_bf16 v[88:91], v[166:169], v[192:195], v[88:91]
	v_mfma_f32_16x16x32_bf16 v[80:83], v[162:165], v[204:207], v[80:83]
	v_mfma_f32_16x16x32_bf16 v[72:75], v[166:169], v[204:207], v[72:75]
	v_mfma_f32_16x16x32_bf16 v[68:71], v[162:165], v[208:211], v[68:71]
	v_mfma_f32_16x16x32_bf16 v[64:67], v[166:169], v[208:211], v[64:67]
	s_setprio 0
	s_barrier
	v_mov_b32_e32 v128, v135
	s_nop 0
	s_nop 0
	s_nop 0
	v_xad_u32 v128, v128, 64, 0
	ds_read_b128 v[172:175], v129 offset:16384
	ds_read_b128 v[176:179], v129 offset:18432
	ds_read_b128 v[180:183], v128 offset:16384
	ds_read_b128 v[192:195], v128 offset:18432
	ds_read_b128 v[196:199], v129 offset:20480
	ds_read_b128 v[200:203], v129 offset:22528
	ds_read_b128 v[204:207], v128 offset:20480
	ds_read_b128 v[208:211], v128 offset:22528
	s_mov_b32 m0, s80
	s_nop 0
	global_load_lds_dwordx4 v131, s[48:49]
	s_mov_b32 m0, s81
	s_nop 0
	global_load_lds_dwordx4 v133, s[48:49]
	s_mov_b32 m0, s29
	s_nop 0
	global_load_lds_dwordx4 v131, s[46:47]
	s_mov_b32 m0, s88
	s_nop 0
	global_load_lds_dwordx4 v133, s[46:47]
	s_mov_b32 m0, s76
	s_nop 0
	global_load_lds_dwordx4 v130, s[44:45]
	s_mov_b32 m0, s89
	s_nop 0
	global_load_lds_dwordx4 v132, s[44:45]
	s_waitcnt vmcnt(8)
	s_waitcnt lgkmcnt(0)
	s_setprio 1
	s_barrier
	v_mfma_f32_16x16x32_bf16 v[60:63], v[138:141], v[172:175], v[60:63]
	v_mfma_f32_16x16x32_bf16 v[56:59], v[142:145], v[172:175], v[56:59]
	v_mfma_f32_16x16x32_bf16 v[52:55], v[138:141], v[176:179], v[52:55]
	v_mfma_f32_16x16x32_bf16 v[44:47], v[142:145], v[176:179], v[44:47]
	v_mfma_f32_16x16x32_bf16 v[36:39], v[138:141], v[196:199], v[36:39]
	v_mfma_f32_16x16x32_bf16 v[28:31], v[142:145], v[196:199], v[28:31]
	v_mfma_f32_16x16x32_bf16 v[20:23], v[138:141], v[200:203], v[20:23]
	v_mfma_f32_16x16x32_bf16 v[12:15], v[142:145], v[200:203], v[12:15]
	v_mfma_f32_16x16x32_bf16 v[60:63], v[146:149], v[180:183], v[60:63]
	v_mfma_f32_16x16x32_bf16 v[56:59], v[150:153], v[180:183], v[56:59]
	v_mfma_f32_16x16x32_bf16 v[52:55], v[146:149], v[192:195], v[52:55]
	v_mfma_f32_16x16x32_bf16 v[44:47], v[150:153], v[192:195], v[44:47]
	v_mfma_f32_16x16x32_bf16 v[36:39], v[146:149], v[204:207], v[36:39]
	v_mfma_f32_16x16x32_bf16 v[28:31], v[150:153], v[204:207], v[28:31]
	v_mfma_f32_16x16x32_bf16 v[20:23], v[146:149], v[208:211], v[20:23]
	v_mfma_f32_16x16x32_bf16 v[12:15], v[150:153], v[208:211], v[12:15]
	s_setprio 0
	s_setprio 1
	v_mfma_f32_16x16x32_bf16 v[48:51], v[154:157], v[172:175], v[48:51]
	v_mfma_f32_16x16x32_bf16 v[40:43], v[158:161], v[172:175], v[40:43]
	v_mfma_f32_16x16x32_bf16 v[32:35], v[154:157], v[176:179], v[32:35]
	v_mfma_f32_16x16x32_bf16 v[24:27], v[158:161], v[176:179], v[24:27]
	v_mfma_f32_16x16x32_bf16 v[16:19], v[154:157], v[196:199], v[16:19]
	v_mfma_f32_16x16x32_bf16 v[8:11], v[158:161], v[196:199], v[8:11]
	v_mfma_f32_16x16x32_bf16 v[4:7], v[154:157], v[200:203], v[4:7]
	v_mfma_f32_16x16x32_bf16 v[0:3], v[158:161], v[200:203], v[0:3]
	v_mfma_f32_16x16x32_bf16 v[48:51], v[162:165], v[180:183], v[48:51]
	v_mfma_f32_16x16x32_bf16 v[40:43], v[166:169], v[180:183], v[40:43]
	v_mfma_f32_16x16x32_bf16 v[32:35], v[162:165], v[192:195], v[32:35]
	v_mfma_f32_16x16x32_bf16 v[24:27], v[166:169], v[192:195], v[24:27]
	v_mfma_f32_16x16x32_bf16 v[16:19], v[162:165], v[204:207], v[16:19]
	v_mfma_f32_16x16x32_bf16 v[8:11], v[166:169], v[204:207], v[8:11]
	v_mfma_f32_16x16x32_bf16 v[4:7], v[162:165], v[208:211], v[4:7]
	v_mfma_f32_16x16x32_bf16 v[0:3], v[166:169], v[208:211], v[0:3]
	s_setprio 0
	s_barrier
; #define PG8_STAGE(bufoff, gbase, voff) do { _Pragma("unroll") for (int _i = 0; _i < 2; ++_i) \
;         dma16((const char*)(gbase), (voff)[_i], ldsb + (bufoff) + ldsw + _i * 8192); } while (0)
; #define PG8_LDA(dst, b, h) do { const int a1_ = opqv(aoff0) ^ 64; _Pragma("unroll") for (int m = 0; m < 4; ++m) { dst[m][0] = *(const LAS bf16x8*)(lds + PG8_SA(b, h) + aoff0 + m * 2048); dst[m][1] = *(const LAS bf16x8*)(lds + PG8_SA(b, h) + a1_ + m * 2048); } } while (0)
; #define PG8_LDB(dst, b, h) do { const int b1_ = opqv(boff0) ^ 64; _Pragma("unroll") for (int n = 0; n < 2; ++n) { dst[n][0] = *(const LAS bf16x8*)(lds + PG8_SB(b, h) + boff0 + n * 2048); dst[n][1] = *(const LAS bf16x8*)(lds + PG8_SB(b, h) + b1_ + n * 2048); } } while (0)
; #define PG8_MMA(ai, bj, At, Bt) do { __builtin_amdgcn_s_setprio(1); _Pragma("unroll") for (int m = 0; m < 4; ++m) _Pragma("unroll") for (int n = 0; n < 2; ++n) _Pragma("unroll") for (int k = 0; k < 2; ++k) \
;         acc[ai][bj][m][n] = __builtin_amdgcn_mfma_f32_16x16x32_bf16(Bt[n][k], At[m][k], acc[ai][bj][m][n], 0, 0, 0); __builtin_amdgcn_s_setprio(0); } while (0)
; #define PG8_WAIT_V(n) asm volatile("s_waitcnt vmcnt(" #n ")" ::: "memory")
; #define PG8_WAIT_L(n) asm volatile("s_waitcnt lgkmcnt(" #n ")" ::: "memory")
; #define PG8_BAR __builtin_amdgcn_s_barrier()
; #define PG8_SCHED __builtin_amdgcn_sched_barrier(0)
; template <class Epi>
; __device__ __forceinline__ void gemm_phase(LAS unsigned char* lds, const Gemm g, const StaticOrder& S, const Epi& E, int wave_) {
;     ...
;             PG8_STAGE(PG8_SA(0, 1), a2 + hstepA, voffA); PG8_LDB(B0, 1, 0); PG8_LDB(B1, 1, 1); PG8_SCHED; PG8_LDA(At, 1, 0);
;             PG8_WAIT_V(8); PG8_WAIT_L(0); PG8_BAR; PG8_MMA(0, 0, At, B0); PG8_MMA(0, 1, At, B1); PG8_BAR; PG8_SCHED;
;             PG8_STAGE(PG8_SB(1, 0), b3, voffB); PG8_STAGE(PG8_SB(1, 1), b3 + hstepB, voffB); PG8_STAGE(PG8_SA(1, 0), a3, voffA); PG8_LDA(At, 1, 1);
;             PG8_WAIT_V(8); PG8_WAIT_L(0); PG8_BAR; PG8_MMA(1, 0, At, B0); PG8_MMA(1, 1, At, B1); PG8_BAR; PG8_SCHED;
;         }
	v_mov_b32_e32 v128, v136
	v_add_u32_e32 v142, s34, v136
	v_xad_u32 v128, v128, 64, s34
	ds_read_b128 v[138:141], v142
	ds_read_b128 v[142:145], v142 offset:2048
	ds_read_b128 v[146:149], v128
	ds_read_b128 v[150:153], v128 offset:2048
	v_mov_b32_e32 v128, v136
	v_add_u32_e32 v158, s63, v136
	v_xad_u32 v128, v128, 64, s63
	ds_read_b128 v[154:157], v158
	ds_read_b128 v[158:161], v158 offset:2048
	ds_read_b128 v[162:165], v128
	ds_read_b128 v[166:169], v128 offset:2048
	v_mov_b32_e32 v128, v135
	s_nop 0
	v_xad_u32 v128, v128, 64, 0
	ds_read_b128 v[172:175], v129 offset:32768
	ds_read_b128 v[176:179], v129 offset:34816
	ds_read_b128 v[180:183], v128 offset:32768
	ds_read_b128 v[192:195], v128 offset:34816
	ds_read_b128 v[196:199], v129 offset:36864
	ds_read_b128 v[200:203], v129 offset:38912
	ds_read_b128 v[204:207], v128 offset:36864
	ds_read_b128 v[208:211], v128 offset:38912
	s_mov_b32 m0, s1
	s_nop 0
	global_load_lds_dwordx4 v130, s[40:41]
	s_mov_b32 m0, s69
	s_nop 0
	global_load_lds_dwordx4 v132, s[40:41]
	s_waitcnt vmcnt(8)
	s_waitcnt lgkmcnt(0)
	s_setprio 1
	s_barrier
	v_mfma_f32_16x16x32_bf16 v[124:127], v[138:141], v[172:175], v[124:127]
	v_mfma_f32_16x16x32_bf16 v[120:123], v[142:145], v[172:175], v[120:123]
	v_mfma_f32_16x16x32_bf16 v[116:119], v[138:141], v[176:179], v[116:119]
	v_mfma_f32_16x16x32_bf16 v[108:111], v[142:145], v[176:179], v[108:111]
	v_mfma_f32_16x16x32_bf16 v[100:103], v[138:141], v[196:199], v[100:103]
	v_mfma_f32_16x16x32_bf16 v[92:95], v[142:145], v[196:199], v[92:95]
	v_mfma_f32_16x16x32_bf16 v[84:87], v[138:141], v[200:203], v[84:87]
	v_mfma_f32_16x16x32_bf16 v[76:79], v[142:145], v[200:203], v[76:79]
	v_mfma_f32_16x16x32_bf16 v[124:127], v[146:149], v[180:183], v[124:127]
	v_mfma_f32_16x16x32_bf16 v[120:123], v[150:153], v[180:183], v[120:123]
	v_mfma_f32_16x16x32_bf16 v[116:119], v[146:149], v[192:195], v[116:119]
	v_mfma_f32_16x16x32_bf16 v[108:111], v[150:153], v[192:195], v[108:111]
	v_mfma_f32_16x16x32_bf16 v[100:103], v[146:149], v[204:207], v[100:103]
	v_mfma_f32_16x16x32_bf16 v[92:95], v[150:153], v[204:207], v[92:95]
	v_mfma_f32_16x16x32_bf16 v[84:87], v[146:149], v[208:211], v[84:87]
	v_mfma_f32_16x16x32_bf16 v[76:79], v[150:153], v[208:211], v[76:79]
	s_setprio 0
	s_setprio 1
	v_mfma_f32_16x16x32_bf16 v[112:115], v[154:157], v[172:175], v[112:115]
	v_mfma_f32_16x16x32_bf16 v[104:107], v[158:161], v[172:175], v[104:107]
	v_mfma_f32_16x16x32_bf16 v[96:99], v[154:157], v[176:179], v[96:99]
	v_mfma_f32_16x16x32_bf16 v[88:91], v[158:161], v[176:179], v[88:91]
	v_mfma_f32_16x16x32_bf16 v[80:83], v[154:157], v[196:199], v[80:83]
	v_mfma_f32_16x16x32_bf16 v[72:75], v[158:161], v[196:199], v[72:75]
	v_mfma_f32_16x16x32_bf16 v[68:71], v[154:157], v[200:203], v[68:71]
	v_mfma_f32_16x16x32_bf16 v[64:67], v[158:161], v[200:203], v[64:67]
	v_mfma_f32_16x16x32_bf16 v[112:115], v[162:165], v[180:183], v[112:115]
	v_mfma_f32_16x16x32_bf16 v[104:107], v[166:169], v[180:183], v[104:107]
	v_mfma_f32_16x16x32_bf16 v[96:99], v[162:165], v[192:195], v[96:99]
	v_mfma_f32_16x16x32_bf16 v[88:91], v[166:169], v[192:195], v[88:91]
	v_mfma_f32_16x16x32_bf16 v[80:83], v[162:165], v[204:207], v[80:83]
	v_mfma_f32_16x16x32_bf16 v[72:75], v[166:169], v[204:207], v[72:75]
	v_mfma_f32_16x16x32_bf16 v[68:71], v[162:165], v[208:211], v[68:71]
	v_mfma_f32_16x16x32_bf16 v[64:67], v[166:169], v[208:211], v[64:67]
	s_setprio 0
	s_barrier
	v_mov_b32_e32 v128, v135
	s_nop 0
	s_nop 0
	s_nop 0
	s_nop 0
	v_xad_u32 v128, v128, 64, 0
	ds_read_b128 v[172:175], v129 offset:49152
	ds_read_b128 v[176:179], v129 offset:51200
	ds_read_b128 v[180:183], v128 offset:49152
	ds_read_b128 v[192:195], v128 offset:51200
	ds_read_b128 v[196:199], v129 offset:53248
	ds_read_b128 v[200:203], v129 offset:55296
	ds_read_b128 v[204:207], v128 offset:53248
	ds_read_b128 v[208:211], v128 offset:55296
	s_mov_b32 m0, s35
	s_nop 0
	global_load_lds_dwordx4 v131, s[36:37]
	s_mov_b32 m0, s33
	s_nop 0
	global_load_lds_dwordx4 v133, s[36:37]
	s_mov_b32 m0, s77
	s_nop 0
	global_load_lds_dwordx4 v131, s[56:57]
	s_mov_b32 m0, s3
	s_nop 0
	global_load_lds_dwordx4 v133, s[56:57]
	s_mov_b32 m0, s22
	s_nop 0
	global_load_lds_dwordx4 v130, s[30:31]
	s_mov_b32 m0, s2
	s_nop 0
	global_load_lds_dwordx4 v132, s[30:31]
	s_waitcnt vmcnt(8)
	s_waitcnt lgkmcnt(0)
	s_setprio 1
	s_barrier
	v_mfma_f32_16x16x32_bf16 v[60:63], v[138:141], v[172:175], v[60:63]
	v_mfma_f32_16x16x32_bf16 v[56:59], v[142:145], v[172:175], v[56:59]
	v_mfma_f32_16x16x32_bf16 v[52:55], v[138:141], v[176:179], v[52:55]
	v_mfma_f32_16x16x32_bf16 v[44:47], v[142:145], v[176:179], v[44:47]
	v_mfma_f32_16x16x32_bf16 v[36:39], v[138:141], v[196:199], v[36:39]
	v_mfma_f32_16x16x32_bf16 v[28:31], v[142:145], v[196:199], v[28:31]
	v_mfma_f32_16x16x32_bf16 v[20:23], v[138:141], v[200:203], v[20:23]
	v_mfma_f32_16x16x32_bf16 v[12:15], v[142:145], v[200:203], v[12:15]
	v_mfma_f32_16x16x32_bf16 v[60:63], v[146:149], v[180:183], v[60:63]
	v_mfma_f32_16x16x32_bf16 v[56:59], v[150:153], v[180:183], v[56:59]
	v_mfma_f32_16x16x32_bf16 v[52:55], v[146:149], v[192:195], v[52:55]
	v_mfma_f32_16x16x32_bf16 v[44:47], v[150:153], v[192:195], v[44:47]
	v_mfma_f32_16x16x32_bf16 v[36:39], v[146:149], v[204:207], v[36:39]
	v_mfma_f32_16x16x32_bf16 v[28:31], v[150:153], v[204:207], v[28:31]
	v_mfma_f32_16x16x32_bf16 v[20:23], v[146:149], v[208:211], v[20:23]
	v_mfma_f32_16x16x32_bf16 v[12:15], v[150:153], v[208:211], v[12:15]
	s_setprio 0
	s_setprio 1
	v_mfma_f32_16x16x32_bf16 v[48:51], v[154:157], v[172:175], v[48:51]
	v_mfma_f32_16x16x32_bf16 v[40:43], v[158:161], v[172:175], v[40:43]
	v_mfma_f32_16x16x32_bf16 v[32:35], v[154:157], v[176:179], v[32:35]
	v_mfma_f32_16x16x32_bf16 v[24:27], v[158:161], v[176:179], v[24:27]
	v_mfma_f32_16x16x32_bf16 v[16:19], v[154:157], v[196:199], v[16:19]
	v_mfma_f32_16x16x32_bf16 v[8:11], v[158:161], v[196:199], v[8:11]
	v_mfma_f32_16x16x32_bf16 v[4:7], v[154:157], v[200:203], v[4:7]
	v_mfma_f32_16x16x32_bf16 v[0:3], v[158:161], v[200:203], v[0:3]
	v_mfma_f32_16x16x32_bf16 v[48:51], v[162:165], v[180:183], v[48:51]
	v_mfma_f32_16x16x32_bf16 v[40:43], v[166:169], v[180:183], v[40:43]
	v_mfma_f32_16x16x32_bf16 v[32:35], v[162:165], v[192:195], v[32:35]
	v_mfma_f32_16x16x32_bf16 v[24:27], v[166:169], v[192:195], v[24:27]
	v_mfma_f32_16x16x32_bf16 v[16:19], v[162:165], v[204:207], v[16:19]
	v_mfma_f32_16x16x32_bf16 v[8:11], v[166:169], v[204:207], v[8:11]
	v_mfma_f32_16x16x32_bf16 v[4:7], v[162:165], v[208:211], v[4:7]
	v_mfma_f32_16x16x32_bf16 v[0:3], v[166:169], v[208:211], v[0:3]
	s_setprio 0
	s_barrier
	s_andn2_b64 vcc, exec, s[12:13]
	s_mov_b64 s[36:37], -1
	s_mov_b64 s[12:13], 0
	s_mov_b64 s[30:31], 0x100
	s_cbranch_vccz .LBB0_1342

; #define PG8_STAGE(bufoff, gbase, voff) do { _Pragma("unroll") for (int _i = 0; _i < 2; ++_i) \
;         dma16((const char*)(gbase), (voff)[_i], ldsb + (bufoff) + ldsw + _i * 8192); } while (0)
; #define PG8_LDA(dst, b, h) do { const int a1_ = opqv(aoff0) ^ 64; _Pragma("unroll") for (int m = 0; m < 4; ++m) { dst[m][0] = *(const LAS bf16x8*)(lds + PG8_SA(b, h) + aoff0 + m * 2048); dst[m][1] = *(const LAS bf16x8*)(lds + PG8_SA(b, h) + a1_ + m * 2048); } } while (0)
; #define PG8_LDB(dst, b, h) do { const int b1_ = opqv(boff0) ^ 64; _Pragma("unroll") for (int n = 0; n < 2; ++n) { dst[n][0] = *(const LAS bf16x8*)(lds + PG8_SB(b, h) + boff0 + n * 2048); dst[n][1] = *(const LAS bf16x8*)(lds + PG8_SB(b, h) + b1_ + n * 2048); } } while (0)
; #define PG8_MMA(ai, bj, At, Bt) do { __builtin_amdgcn_s_setprio(1); _Pragma("unroll") for (int m = 0; m < 4; ++m) _Pragma("unroll") for (int n = 0; n < 2; ++n) _Pragma("unroll") for (int k = 0; k < 2; ++k) \
;         acc[ai][bj][m][n] = __builtin_amdgcn_mfma_f32_16x16x32_bf16(Bt[n][k], At[m][k], acc[ai][bj][m][n], 0, 0, 0); __builtin_amdgcn_s_setprio(0); } while (0)
; template <class Epi>
; __device__ __forceinline__ void gemm_phase(LAS unsigned char* lds, const Gemm g, const StaticOrder& S, const Epi& E, int wave_) {
;     ...
;         const bool has_next = S.next(ui + 1, nxt);
;         const char* nA = has_next ? (const char*)g.A + (size_t)nxt.pm * tstepA : cA; const char* nB = has_next ? (const char*)g.Bt + (size_t)nxt.pn * tstepB : cB;
; #pragma unroll 1
;         for (int t = 0; t < nt; t += 2) {
;             const bool last = (t == nt - 2);
;             const char* a1 = cA + (size_t)(t + 1) * kstep;
;             const char* a2 = last ? nA : cA + (size_t)(t + 2) * kstep; const char* b2 = last ? nB : cB + (size_t)(t + 2) * kstep;
;             const char* a3 = a2 + kstep; const char* b3 = b2 + kstep;
;             PG8_STAGE(PG8_SA(1, 1), a1 + hstepA, voffA); PG8_LDB(B0, 0, 0); PG8_LDB(B1, 0, 1); PG8_SCHED; PG8_LDA(At, 0, 0);
;             PG8_WAIT_V(8); PG8_WAIT_L(0); PG8_BAR; PG8_MMA(0, 0, At, B0); PG8_MMA(0, 1, At, B1); PG8_BAR; PG8_SCHED;
;             PG8_STAGE(PG8_SB(0, 0), b2, voffB); PG8_STAGE(PG8_SB(0, 1), b2 + hstepB, voffB); PG8_STAGE(PG8_SA(0, 0), a2, voffA); PG8_LDA(At, 0, 1);
;             PG8_WAIT_V(8); PG8_WAIT_L(0); PG8_BAR; PG8_MMA(1, 0, At, B0); PG8_MMA(1, 1, At, B1); PG8_BAR; PG8_SCHED;
.LBB0_1551:
	s_add_u32 s16, s12, 0x100
	s_addc_u32 s17, s13, 0
	s_add_u32 s12, s36, 0x160080
	s_addc_u32 s13, s37, 0
	s_mov_b32 s59, -2
	s_add_u32 s36, s12, 0xffea0080
	s_addc_u32 s37, s13, -1
	s_cmpk_eq_i32 s59, 0x54
	s_cselect_b32 s46, s26, s36
	s_cselect_b32 s47, s27, s37
	s_cselect_b32 s40, s30, s16
	s_cselect_b32 s41, s31, s17
	s_add_u32 s36, s46, 0x80
	v_mov_b32_e32 v64, v219
	s_addc_u32 s37, s47, 0
	v_add_u32_e32 v68, s23, v219
	v_xad_u32 v76, v64, 64, s23
	v_mov_b32_e32 v80, v219
	s_add_i32 s60, 0, 0x14000
	ds_read_b128 v[64:67], v68
	ds_read_b128 v[68:71], v68 offset:2048
	ds_read_b128 v[72:75], v76
	ds_read_b128 v[76:79], v76 offset:2048
	v_add_u32_e32 v84, s60, v219
	v_xad_u32 v92, v80, 64, s60
	ds_read_b128 v[80:83], v84
	ds_read_b128 v[84:87], v84 offset:2048
	ds_read_b128 v[88:91], v92
	ds_read_b128 v[92:95], v92 offset:2048
	v_mov_b32_e32 v160, v218
	v_add_u32_e32 v191, 0, v218
	v_xad_u32 v190, v160, 64, 0
	ds_read_b128 v[160:163], v191
	ds_read_b128 v[164:167], v191 offset:2048
	ds_read_b128 v[168:171], v190
	ds_read_b128 v[172:175], v190 offset:2048
	ds_read_b128 v[176:179], v191 offset:4096
	ds_read_b128 v[180:183], v191 offset:6144
	ds_read_b128 v[192:195], v190 offset:4096
	ds_read_b128 v[196:199], v190 offset:6144
	s_mov_b32 m0, s14
	s_nop 0
	global_load_lds_dwordx4 v184, s[12:13]
	s_mov_b32 m0, s15
	s_nop 0
	global_load_lds_dwordx4 v215, s[12:13]
	s_waitcnt vmcnt(8)
	s_waitcnt lgkmcnt(0)
	s_setprio 1
	s_barrier
	v_mfma_f32_16x16x32_bf16 v[156:159], v[64:67], v[160:163], 0
	v_mfma_f32_16x16x32_bf16 v[152:155], v[68:71], v[160:163], 0
	v_mfma_f32_16x16x32_bf16 v[140:143], v[64:67], v[164:167], 0
	v_mfma_f32_16x16x32_bf16 v[136:139], v[68:71], v[164:167], 0
	v_mfma_f32_16x16x32_bf16 v[124:127], v[64:67], v[176:179], 0
	v_mfma_f32_16x16x32_bf16 v[120:123], v[68:71], v[176:179], 0
	v_mfma_f32_16x16x32_bf16 v[108:111], v[64:67], v[180:183], 0
	v_mfma_f32_16x16x32_bf16 v[104:107], v[68:71], v[180:183], 0
	v_mfma_f32_16x16x32_bf16 v[156:159], v[72:75], v[168:171], v[156:159]
	v_mfma_f32_16x16x32_bf16 v[152:155], v[76:79], v[168:171], v[152:155]
	v_mfma_f32_16x16x32_bf16 v[140:143], v[72:75], v[172:175], v[140:143]
	v_mfma_f32_16x16x32_bf16 v[136:139], v[76:79], v[172:175], v[136:139]
	v_mfma_f32_16x16x32_bf16 v[124:127], v[72:75], v[192:195], v[124:127]
	v_mfma_f32_16x16x32_bf16 v[120:123], v[76:79], v[192:195], v[120:123]
	v_mfma_f32_16x16x32_bf16 v[108:111], v[72:75], v[196:199], v[108:111]
	v_mfma_f32_16x16x32_bf16 v[104:107], v[76:79], v[196:199], v[104:107]
	s_setprio 0
	s_setprio 1
	v_mfma_f32_16x16x32_bf16 v[148:151], v[80:83], v[160:163], 0
	v_mfma_f32_16x16x32_bf16 v[144:147], v[84:87], v[160:163], 0
	v_mfma_f32_16x16x32_bf16 v[132:135], v[80:83], v[164:167], 0
	v_mfma_f32_16x16x32_bf16 v[128:131], v[84:87], v[164:167], 0
	v_mfma_f32_16x16x32_bf16 v[116:119], v[80:83], v[176:179], 0
	v_mfma_f32_16x16x32_bf16 v[112:115], v[84:87], v[176:179], 0
	v_mfma_f32_16x16x32_bf16 v[100:103], v[80:83], v[180:183], 0
	v_mfma_f32_16x16x32_bf16 v[96:99], v[84:87], v[180:183], 0
	v_mfma_f32_16x16x32_bf16 v[148:151], v[88:91], v[168:171], v[148:151]
	v_mfma_f32_16x16x32_bf16 v[144:147], v[92:95], v[168:171], v[144:147]
	v_mfma_f32_16x16x32_bf16 v[132:135], v[88:91], v[172:175], v[132:135]
	v_mfma_f32_16x16x32_bf16 v[128:131], v[92:95], v[172:175], v[128:131]
	v_mfma_f32_16x16x32_bf16 v[116:119], v[88:91], v[192:195], v[116:119]
	v_mfma_f32_16x16x32_bf16 v[112:115], v[92:95], v[192:195], v[112:115]
	v_mfma_f32_16x16x32_bf16 v[100:103], v[88:91], v[196:199], v[100:103]
	v_mfma_f32_16x16x32_bf16 v[96:99], v[92:95], v[196:199], v[96:99]
	s_setprio 0
	s_barrier
	v_mov_b32_e32 v160, v218
	s_add_u32 s60, s40, 0x160000
	s_addc_u32 s61, s41, 0
	s_nop 0
	s_nop 0
	s_nop 0
	v_xad_u32 v190, v160, 64, 0
	ds_read_b128 v[160:163], v191 offset:16384
	ds_read_b128 v[164:167], v191 offset:18432
	ds_read_b128 v[168:171], v190 offset:16384
	ds_read_b128 v[172:175], v190 offset:18432
	ds_read_b128 v[176:179], v191 offset:20480
	ds_read_b128 v[180:183], v191 offset:22528
	ds_read_b128 v[192:195], v190 offset:20480
	ds_read_b128 v[196:199], v190 offset:22528
	s_mov_b32 m0, s80
	s_nop 0
	global_load_lds_dwordx4 v214, s[40:41]
	s_mov_b32 m0, s81
	s_nop 0
	global_load_lds_dwordx4 v216, s[40:41]
	s_mov_b32 m0, s29
	s_nop 0
	global_load_lds_dwordx4 v214, s[60:61]
	s_mov_b32 m0, s88
	s_nop 0
	global_load_lds_dwordx4 v216, s[60:61]
	s_mov_b32 m0, s76
	s_nop 0
	global_load_lds_dwordx4 v184, s[46:47]
	s_mov_b32 m0, s89
	s_nop 0
	global_load_lds_dwordx4 v215, s[46:47]
	s_waitcnt vmcnt(8)
	s_waitcnt lgkmcnt(0)
	s_setprio 1
	s_barrier
	v_mfma_f32_16x16x32_bf16 v[60:63], v[64:67], v[160:163], 0
	v_mfma_f32_16x16x32_bf16 v[56:59], v[68:71], v[160:163], 0
	v_mfma_f32_16x16x32_bf16 v[44:47], v[64:67], v[164:167], 0
	v_mfma_f32_16x16x32_bf16 v[40:43], v[68:71], v[164:167], 0
	v_mfma_f32_16x16x32_bf16 v[28:31], v[64:67], v[176:179], 0
	v_mfma_f32_16x16x32_bf16 v[24:27], v[68:71], v[176:179], 0
	v_mfma_f32_16x16x32_bf16 v[12:15], v[64:67], v[180:183], 0
	v_mfma_f32_16x16x32_bf16 v[8:11], v[68:71], v[180:183], 0
	v_mfma_f32_16x16x32_bf16 v[60:63], v[72:75], v[168:171], v[60:63]
	v_mfma_f32_16x16x32_bf16 v[56:59], v[76:79], v[168:171], v[56:59]
	v_mfma_f32_16x16x32_bf16 v[44:47], v[72:75], v[172:175], v[44:47]
	v_mfma_f32_16x16x32_bf16 v[40:43], v[76:79], v[172:175], v[40:43]
	v_mfma_f32_16x16x32_bf16 v[28:31], v[72:75], v[192:195], v[28:31]
	v_mfma_f32_16x16x32_bf16 v[24:27], v[76:79], v[192:195], v[24:27]
	v_mfma_f32_16x16x32_bf16 v[12:15], v[72:75], v[196:199], v[12:15]
	v_mfma_f32_16x16x32_bf16 v[8:11], v[76:79], v[196:199], v[8:11]
	s_setprio 0
	s_setprio 1
	v_mfma_f32_16x16x32_bf16 v[52:55], v[80:83], v[160:163], 0
	v_mfma_f32_16x16x32_bf16 v[48:51], v[84:87], v[160:163], 0
	v_mfma_f32_16x16x32_bf16 v[36:39], v[80:83], v[164:167], 0
	v_mfma_f32_16x16x32_bf16 v[32:35], v[84:87], v[164:167], 0
	v_mfma_f32_16x16x32_bf16 v[20:23], v[80:83], v[176:179], 0
	v_mfma_f32_16x16x32_bf16 v[16:19], v[84:87], v[176:179], 0
	v_mfma_f32_16x16x32_bf16 v[4:7], v[80:83], v[180:183], 0
	v_mfma_f32_16x16x32_bf16 v[0:3], v[84:87], v[180:183], 0
	v_mfma_f32_16x16x32_bf16 v[52:55], v[88:91], v[168:171], v[52:55]
	v_mfma_f32_16x16x32_bf16 v[48:51], v[92:95], v[168:171], v[48:51]
	v_mfma_f32_16x16x32_bf16 v[36:39], v[88:91], v[172:175], v[36:39]
	v_mfma_f32_16x16x32_bf16 v[32:35], v[92:95], v[172:175], v[32:35]
	v_mfma_f32_16x16x32_bf16 v[20:23], v[88:91], v[192:195], v[20:23]
	v_mfma_f32_16x16x32_bf16 v[16:19], v[92:95], v[192:195], v[16:19]
	v_mfma_f32_16x16x32_bf16 v[4:7], v[88:91], v[196:199], v[4:7]
	v_mfma_f32_16x16x32_bf16 v[0:3], v[92:95], v[196:199], v[0:3]
	s_setprio 0
	s_barrier
; #define PG8_STAGE(bufoff, gbase, voff) do { _Pragma("unroll") for (int _i = 0; _i < 2; ++_i) \
;         dma16((const char*)(gbase), (voff)[_i], ldsb + (bufoff) + ldsw + _i * 8192); } while (0)
; #define PG8_LDA(dst, b, h) do { const int a1_ = opqv(aoff0) ^ 64; _Pragma("unroll") for (int m = 0; m < 4; ++m) { dst[m][0] = *(const LAS bf16x8*)(lds + PG8_SA(b, h) + aoff0 + m * 2048); dst[m][1] = *(const LAS bf16x8*)(lds + PG8_SA(b, h) + a1_ + m * 2048); } } while (0)
; #define PG8_LDB(dst, b, h) do { const int b1_ = opqv(boff0) ^ 64; _Pragma("unroll") for (int n = 0; n < 2; ++n) { dst[n][0] = *(const LAS bf16x8*)(lds + PG8_SB(b, h) + boff0 + n * 2048); dst[n][1] = *(const LAS bf16x8*)(lds + PG8_SB(b, h) + b1_ + n * 2048); } } while (0)
; #define PG8_MMA(ai, bj, At, Bt) do { __builtin_amdgcn_s_setprio(1); _Pragma("unroll") for (int m = 0; m < 4; ++m) _Pragma("unroll") for (int n = 0; n < 2; ++n) _Pragma("unroll") for (int k = 0; k < 2; ++k) \
;         acc[ai][bj][m][n] = __builtin_amdgcn_mfma_f32_16x16x32_bf16(Bt[n][k], At[m][k], acc[ai][bj][m][n], 0, 0, 0); __builtin_amdgcn_s_setprio(0); } while (0)
; #define PG8_WAIT_V(n) asm volatile("s_waitcnt vmcnt(" #n ")" ::: "memory")
; #define PG8_WAIT_L(n) asm volatile("s_waitcnt lgkmcnt(" #n ")" ::: "memory")
; #define PG8_BAR __builtin_amdgcn_s_barrier()
; #define PG8_SCHED __builtin_amdgcn_sched_barrier(0)
; template <class Epi>
; __device__ __forceinline__ void gemm_phase(LAS unsigned char* lds, const Gemm g, const StaticOrder& S, const Epi& E, int wave_) {
;     ...
;             PG8_STAGE(PG8_SA(0, 1), a2 + hstepA, voffA); PG8_LDB(B0, 1, 0); PG8_LDB(B1, 1, 1); PG8_SCHED; PG8_LDA(At, 1, 0);
;             PG8_WAIT_V(8); PG8_WAIT_L(0); PG8_BAR; PG8_MMA(0, 0, At, B0); PG8_MMA(0, 1, At, B1); PG8_BAR; PG8_SCHED;
;             PG8_STAGE(PG8_SB(1, 0), b3, voffB); PG8_STAGE(PG8_SB(1, 1), b3 + hstepB, voffB); PG8_STAGE(PG8_SA(1, 0), a3, voffA); PG8_LDA(At, 1, 1);
;             PG8_WAIT_V(8); PG8_WAIT_L(0); PG8_BAR; PG8_MMA(1, 0, At, B0); PG8_MMA(1, 1, At, B1); PG8_BAR; PG8_SCHED;
;         }
	s_add_u32 s46, s46, 0x160000
	s_addc_u32 s47, s47, 0
	s_mov_b32 m0, s1
	s_nop 0
	global_load_lds_dwordx4 v184, s[46:47]
	v_mov_b32_e32 v64, v219
	s_mov_b32 m0, s69
	s_nop 0
	global_load_lds_dwordx4 v215, s[46:47]
	v_add_u32_e32 v68, s34, v219
	v_xad_u32 v76, v64, 64, s34
	v_mov_b32_e32 v80, v219
	s_add_i32 s46, 0, 0x1c000
	ds_read_b128 v[64:67], v68
	ds_read_b128 v[68:71], v68 offset:2048
	ds_read_b128 v[72:75], v76
	ds_read_b128 v[76:79], v76 offset:2048
	v_add_u32_e32 v84, s46, v219
	v_xad_u32 v92, v80, 64, s46
	ds_read_b128 v[80:83], v84
	ds_read_b128 v[84:87], v84 offset:2048
	ds_read_b128 v[88:91], v92
	ds_read_b128 v[92:95], v92 offset:2048
	v_mov_b32_e32 v160, v218
	s_nop 0
	v_xad_u32 v190, v160, 64, 0
	ds_read_b128 v[160:163], v191 offset:32768
	ds_read_b128 v[164:167], v191 offset:34816
	ds_read_b128 v[168:171], v190 offset:32768
	ds_read_b128 v[172:175], v190 offset:34816
	ds_read_b128 v[176:179], v191 offset:36864
	ds_read_b128 v[180:183], v191 offset:38912
	ds_read_b128 v[192:195], v190 offset:36864
	ds_read_b128 v[196:199], v190 offset:38912
	s_waitcnt vmcnt(8)
	s_waitcnt lgkmcnt(0)
	s_setprio 1
	s_barrier
	v_mfma_f32_16x16x32_bf16 v[156:159], v[64:67], v[160:163], v[156:159]
	v_mfma_f32_16x16x32_bf16 v[152:155], v[68:71], v[160:163], v[152:155]
	v_mfma_f32_16x16x32_bf16 v[140:143], v[64:67], v[164:167], v[140:143]
	v_mfma_f32_16x16x32_bf16 v[136:139], v[68:71], v[164:167], v[136:139]
	v_mfma_f32_16x16x32_bf16 v[124:127], v[64:67], v[176:179], v[124:127]
	v_mfma_f32_16x16x32_bf16 v[120:123], v[68:71], v[176:179], v[120:123]
	v_mfma_f32_16x16x32_bf16 v[108:111], v[64:67], v[180:183], v[108:111]
	v_mfma_f32_16x16x32_bf16 v[104:107], v[68:71], v[180:183], v[104:107]
	v_mfma_f32_16x16x32_bf16 v[156:159], v[72:75], v[168:171], v[156:159]
	v_mfma_f32_16x16x32_bf16 v[152:155], v[76:79], v[168:171], v[152:155]
	v_mfma_f32_16x16x32_bf16 v[140:143], v[72:75], v[172:175], v[140:143]
	v_mfma_f32_16x16x32_bf16 v[136:139], v[76:79], v[172:175], v[136:139]
	v_mfma_f32_16x16x32_bf16 v[124:127], v[72:75], v[192:195], v[124:127]
	v_mfma_f32_16x16x32_bf16 v[120:123], v[76:79], v[192:195], v[120:123]
	v_mfma_f32_16x16x32_bf16 v[108:111], v[72:75], v[196:199], v[108:111]
	v_mfma_f32_16x16x32_bf16 v[104:107], v[76:79], v[196:199], v[104:107]
	s_setprio 0
	s_setprio 1
	v_mfma_f32_16x16x32_bf16 v[148:151], v[80:83], v[160:163], v[148:151]
	s_add_u32 s46, s40, 0x80
	s_addc_u32 s47, s41, 0
	v_mfma_f32_16x16x32_bf16 v[144:147], v[84:87], v[160:163], v[144:147]
	v_mfma_f32_16x16x32_bf16 v[132:135], v[80:83], v[164:167], v[132:135]
	v_mfma_f32_16x16x32_bf16 v[128:131], v[84:87], v[164:167], v[128:131]
	v_mfma_f32_16x16x32_bf16 v[116:119], v[80:83], v[176:179], v[116:119]
	v_mfma_f32_16x16x32_bf16 v[112:115], v[84:87], v[176:179], v[112:115]
	v_mfma_f32_16x16x32_bf16 v[100:103], v[80:83], v[180:183], v[100:103]
	v_mfma_f32_16x16x32_bf16 v[96:99], v[84:87], v[180:183], v[96:99]
	v_mfma_f32_16x16x32_bf16 v[148:151], v[88:91], v[168:171], v[148:151]
	v_mfma_f32_16x16x32_bf16 v[144:147], v[92:95], v[168:171], v[144:147]
	v_mfma_f32_16x16x32_bf16 v[132:135], v[88:91], v[172:175], v[132:135]
	v_mfma_f32_16x16x32_bf16 v[128:131], v[92:95], v[172:175], v[128:131]
	v_mfma_f32_16x16x32_bf16 v[116:119], v[88:91], v[192:195], v[116:119]
	v_mfma_f32_16x16x32_bf16 v[112:115], v[92:95], v[192:195], v[112:115]
	v_mfma_f32_16x16x32_bf16 v[100:103], v[88:91], v[196:199], v[100:103]
	v_mfma_f32_16x16x32_bf16 v[96:99], v[92:95], v[196:199], v[96:99]
	s_setprio 0
	s_barrier
	s_add_u32 s40, s40, 0x160080
	s_addc_u32 s41, s41, 0
	v_mov_b32_e32 v160, v218
	s_nop 0
	s_nop 0
	v_xad_u32 v190, v160, 64, 0
	ds_read_b128 v[160:163], v191 offset:49152
	ds_read_b128 v[164:167], v191 offset:51200
	ds_read_b128 v[168:171], v190 offset:49152
	ds_read_b128 v[172:175], v190 offset:51200
	ds_read_b128 v[176:179], v191 offset:53248
	ds_read_b128 v[180:183], v191 offset:55296
	ds_read_b128 v[192:195], v190 offset:53248
	ds_read_b128 v[196:199], v190 offset:55296
	s_mov_b32 m0, s35
	s_nop 0
	global_load_lds_dwordx4 v214, s[46:47]
	s_mov_b32 m0, s33
	s_nop 0
	global_load_lds_dwordx4 v216, s[46:47]
	s_mov_b32 m0, s77
	s_nop 0
	global_load_lds_dwordx4 v214, s[40:41]
	s_mov_b32 m0, s3
	s_nop 0
	global_load_lds_dwordx4 v216, s[40:41]
	s_mov_b32 m0, s22
	s_nop 0
	global_load_lds_dwordx4 v184, s[36:37]
	s_mov_b32 m0, s2
	s_nop 0
	global_load_lds_dwordx4 v215, s[36:37]
	s_waitcnt vmcnt(8)
	s_waitcnt lgkmcnt(0)
	s_setprio 1
	s_barrier
	v_mfma_f32_16x16x32_bf16 v[60:63], v[64:67], v[160:163], v[60:63]
	v_mfma_f32_16x16x32_bf16 v[56:59], v[68:71], v[160:163], v[56:59]
	v_mfma_f32_16x16x32_bf16 v[44:47], v[64:67], v[164:167], v[44:47]
	v_mfma_f32_16x16x32_bf16 v[40:43], v[68:71], v[164:167], v[40:43]
	v_mfma_f32_16x16x32_bf16 v[28:31], v[64:67], v[176:179], v[28:31]
	v_mfma_f32_16x16x32_bf16 v[24:27], v[68:71], v[176:179], v[24:27]
	v_mfma_f32_16x16x32_bf16 v[12:15], v[64:67], v[180:183], v[12:15]
	v_mfma_f32_16x16x32_bf16 v[8:11], v[68:71], v[180:183], v[8:11]
	v_mfma_f32_16x16x32_bf16 v[60:63], v[72:75], v[168:171], v[60:63]
	v_mfma_f32_16x16x32_bf16 v[56:59], v[76:79], v[168:171], v[56:59]
	v_mfma_f32_16x16x32_bf16 v[44:47], v[72:75], v[172:175], v[44:47]
	v_mfma_f32_16x16x32_bf16 v[40:43], v[76:79], v[172:175], v[40:43]
	v_mfma_f32_16x16x32_bf16 v[28:31], v[72:75], v[192:195], v[28:31]
	v_mfma_f32_16x16x32_bf16 v[24:27], v[76:79], v[192:195], v[24:27]
	v_mfma_f32_16x16x32_bf16 v[12:15], v[72:75], v[196:199], v[12:15]
	v_mfma_f32_16x16x32_bf16 v[8:11], v[76:79], v[196:199], v[8:11]
	s_setprio 0
	s_setprio 1
	v_mfma_f32_16x16x32_bf16 v[52:55], v[80:83], v[160:163], v[52:55]
	v_mfma_f32_16x16x32_bf16 v[48:51], v[84:87], v[160:163], v[48:51]
	v_mfma_f32_16x16x32_bf16 v[36:39], v[80:83], v[164:167], v[36:39]
	v_mfma_f32_16x16x32_bf16 v[32:35], v[84:87], v[164:167], v[32:35]
	v_mfma_f32_16x16x32_bf16 v[20:23], v[80:83], v[176:179], v[20:23]
	v_mfma_f32_16x16x32_bf16 v[16:19], v[84:87], v[176:179], v[16:19]
	v_mfma_f32_16x16x32_bf16 v[4:7], v[80:83], v[180:183], v[4:7]
	v_mfma_f32_16x16x32_bf16 v[0:3], v[84:87], v[180:183], v[0:3]
	v_mfma_f32_16x16x32_bf16 v[52:55], v[88:91], v[168:171], v[52:55]
	v_mfma_f32_16x16x32_bf16 v[48:51], v[92:95], v[168:171], v[48:51]
	v_mfma_f32_16x16x32_bf16 v[36:39], v[88:91], v[172:175], v[36:39]
	v_mfma_f32_16x16x32_bf16 v[32:35], v[92:95], v[172:175], v[32:35]
	v_mfma_f32_16x16x32_bf16 v[20:23], v[88:91], v[192:195], v[20:23]
	v_mfma_f32_16x16x32_bf16 v[16:19], v[92:95], v[192:195], v[16:19]
	v_mfma_f32_16x16x32_bf16 v[4:7], v[88:91], v[196:199], v[4:7]
	v_mfma_f32_16x16x32_bf16 v[0:3], v[92:95], v[196:199], v[0:3]
	s_setprio 0
	s_barrier
	s_add_i32 s59, s59, 2
	s_add_u32 s16, s16, 0x100
	s_addc_u32 s17, s17, 0
	s_add_u32 s12, s12, 0x100
	s_addc_u32 s13, s13, 0
	s_cmpk_gt_u32 s59, 0x55
	s_cbranch_scc0 .LBB0_1552
	s_branch .Lpeel_exit_1
; #define PG8_STAGE(bufoff, gbase, voff) do { _Pragma("unroll") for (int _i = 0; _i < 2; ++_i) \
;         dma16((const char*)(gbase), (voff)[_i], ldsb + (bufoff) + ldsw + _i * 8192); } while (0)
; #define PG8_LDA(dst, b, h) do { const int a1_ = opqv(aoff0) ^ 64; _Pragma("unroll") for (int m = 0; m < 4; ++m) { dst[m][0] = *(const LAS bf16x8*)(lds + PG8_SA(b, h) + aoff0 + m * 2048); dst[m][1] = *(const LAS bf16x8*)(lds + PG8_SA(b, h) + a1_ + m * 2048); } } while (0)
; #define PG8_LDB(dst, b, h) do { const int b1_ = opqv(boff0) ^ 64; _Pragma("unroll") for (int n = 0; n < 2; ++n) { dst[n][0] = *(const LAS bf16x8*)(lds + PG8_SB(b, h) + boff0 + n * 2048); dst[n][1] = *(const LAS bf16x8*)(lds + PG8_SB(b, h) + b1_ + n * 2048); } } while (0)
; #define PG8_MMA(ai, bj, At, Bt) do { __builtin_amdgcn_s_setprio(1); _Pragma("unroll") for (int m = 0; m < 4; ++m) _Pragma("unroll") for (int n = 0; n < 2; ++n) _Pragma("unroll") for (int k = 0; k < 2; ++k) \
;         acc[ai][bj][m][n] = __builtin_amdgcn_mfma_f32_16x16x32_bf16(Bt[n][k], At[m][k], acc[ai][bj][m][n], 0, 0, 0); __builtin_amdgcn_s_setprio(0); } while (0)
; #define PG8_WAIT_V(n) asm volatile("s_waitcnt vmcnt(" #n ")" ::: "memory")
; #define PG8_WAIT_L(n) asm volatile("s_waitcnt lgkmcnt(" #n ")" ::: "memory")
; #define PG8_BAR __builtin_amdgcn_s_barrier()
; #define PG8_SCHED __builtin_amdgcn_sched_barrier(0)
; template <class Epi>
; __device__ __forceinline__ void gemm_phase(LAS unsigned char* lds, const Gemm g, const StaticOrder& S, const Epi& E, int wave_) {
;     ...
;         for (int t = 0; t < nt; t += 2) {
;             const bool last = (t == nt - 2);
;             const char* a1 = cA + (size_t)(t + 1) * kstep;
;             const char* a2 = last ? nA : cA + (size_t)(t + 2) * kstep; const char* b2 = last ? nB : cB + (size_t)(t + 2) * kstep;
;             const char* a3 = a2 + kstep; const char* b3 = b2 + kstep;
;             PG8_STAGE(PG8_SA(1, 1), a1 + hstepA, voffA); PG8_LDB(B0, 0, 0); PG8_LDB(B1, 0, 1); PG8_SCHED; PG8_LDA(At, 0, 0);
;             PG8_WAIT_V(8); PG8_WAIT_L(0); PG8_BAR; PG8_MMA(0, 0, At, B0); PG8_MMA(0, 1, At, B1); PG8_BAR; PG8_SCHED;
;             PG8_STAGE(PG8_SB(0, 0), b2, voffB); PG8_STAGE(PG8_SB(0, 1), b2 + hstepB, voffB); PG8_STAGE(PG8_SA(0, 0), a2, voffA); PG8_LDA(At, 0, 1);
;             PG8_WAIT_V(8); PG8_WAIT_L(0); PG8_BAR; PG8_MMA(1, 0, At, B0); PG8_MMA(1, 1, At, B1); PG8_BAR; PG8_SCHED;
.LBB0_1552:
	s_add_u32 s36, s12, 0xffea0080
	s_addc_u32 s37, s13, -1
	s_cmpk_eq_i32 s59, 0x54
	s_cselect_b32 s46, s26, s36
	s_cselect_b32 s47, s27, s37
	s_cselect_b32 s40, s30, s16
	s_cselect_b32 s41, s31, s17
	s_add_u32 s36, s46, 0x80
	v_mov_b32_e32 v64, v219
	s_addc_u32 s37, s47, 0
	v_add_u32_e32 v68, s23, v219
	v_xad_u32 v76, v64, 64, s23
	v_mov_b32_e32 v80, v219
	s_add_i32 s60, 0, 0x14000
	ds_read_b128 v[64:67], v68
	ds_read_b128 v[68:71], v68 offset:2048
	ds_read_b128 v[72:75], v76
	ds_read_b128 v[76:79], v76 offset:2048
	v_add_u32_e32 v84, s60, v219
	v_xad_u32 v92, v80, 64, s60
	ds_read_b128 v[80:83], v84
	ds_read_b128 v[84:87], v84 offset:2048
	ds_read_b128 v[88:91], v92
	ds_read_b128 v[92:95], v92 offset:2048
	v_mov_b32_e32 v160, v218
	v_add_u32_e32 v191, 0, v218
	v_xad_u32 v190, v160, 64, 0
	ds_read_b128 v[160:163], v191
	ds_read_b128 v[164:167], v191 offset:2048
	ds_read_b128 v[168:171], v190
	ds_read_b128 v[172:175], v190 offset:2048
	ds_read_b128 v[176:179], v191 offset:4096
	ds_read_b128 v[180:183], v191 offset:6144
	ds_read_b128 v[192:195], v190 offset:4096
	ds_read_b128 v[196:199], v190 offset:6144
	s_mov_b32 m0, s14
	s_nop 0
	global_load_lds_dwordx4 v184, s[12:13]
	s_mov_b32 m0, s15
	s_nop 0
	global_load_lds_dwordx4 v215, s[12:13]
	s_waitcnt vmcnt(8)
	s_waitcnt lgkmcnt(0)
	s_setprio 1
	s_barrier
	v_mfma_f32_16x16x32_bf16 v[156:159], v[64:67], v[160:163], v[156:159]
	v_mfma_f32_16x16x32_bf16 v[152:155], v[68:71], v[160:163], v[152:155]
	v_mfma_f32_16x16x32_bf16 v[140:143], v[64:67], v[164:167], v[140:143]
	v_mfma_f32_16x16x32_bf16 v[136:139], v[68:71], v[164:167], v[136:139]
	v_mfma_f32_16x16x32_bf16 v[124:127], v[64:67], v[176:179], v[124:127]
	v_mfma_f32_16x16x32_bf16 v[120:123], v[68:71], v[176:179], v[120:123]
	v_mfma_f32_16x16x32_bf16 v[108:111], v[64:67], v[180:183], v[108:111]
	v_mfma_f32_16x16x32_bf16 v[104:107], v[68:71], v[180:183], v[104:107]
	v_mfma_f32_16x16x32_bf16 v[156:159], v[72:75], v[168:171], v[156:159]
	v_mfma_f32_16x16x32_bf16 v[152:155], v[76:79], v[168:171], v[152:155]
	v_mfma_f32_16x16x32_bf16 v[140:143], v[72:75], v[172:175], v[140:143]
	v_mfma_f32_16x16x32_bf16 v[136:139], v[76:79], v[172:175], v[136:139]
	v_mfma_f32_16x16x32_bf16 v[124:127], v[72:75], v[192:195], v[124:127]
	v_mfma_f32_16x16x32_bf16 v[120:123], v[76:79], v[192:195], v[120:123]
	v_mfma_f32_16x16x32_bf16 v[108:111], v[72:75], v[196:199], v[108:111]
	v_mfma_f32_16x16x32_bf16 v[104:107], v[76:79], v[196:199], v[104:107]
	s_setprio 0
	s_setprio 1
	v_mfma_f32_16x16x32_bf16 v[148:151], v[80:83], v[160:163], v[148:151]
	v_mfma_f32_16x16x32_bf16 v[144:147], v[84:87], v[160:163], v[144:147]
	v_mfma_f32_16x16x32_bf16 v[132:135], v[80:83], v[164:167], v[132:135]
	v_mfma_f32_16x16x32_bf16 v[128:131], v[84:87], v[164:167], v[128:131]
	v_mfma_f32_16x16x32_bf16 v[116:119], v[80:83], v[176:179], v[116:119]
	v_mfma_f32_16x16x32_bf16 v[112:115], v[84:87], v[176:179], v[112:115]
	v_mfma_f32_16x16x32_bf16 v[100:103], v[80:83], v[180:183], v[100:103]
	v_mfma_f32_16x16x32_bf16 v[96:99], v[84:87], v[180:183], v[96:99]
	v_mfma_f32_16x16x32_bf16 v[148:151], v[88:91], v[168:171], v[148:151]
	v_mfma_f32_16x16x32_bf16 v[144:147], v[92:95], v[168:171], v[144:147]
	v_mfma_f32_16x16x32_bf16 v[132:135], v[88:91], v[172:175], v[132:135]
	v_mfma_f32_16x16x32_bf16 v[128:131], v[92:95], v[172:175], v[128:131]
	v_mfma_f32_16x16x32_bf16 v[116:119], v[88:91], v[192:195], v[116:119]
	v_mfma_f32_16x16x32_bf16 v[112:115], v[92:95], v[192:195], v[112:115]
	v_mfma_f32_16x16x32_bf16 v[100:103], v[88:91], v[196:199], v[100:103]
	v_mfma_f32_16x16x32_bf16 v[96:99], v[92:95], v[196:199], v[96:99]
	s_setprio 0
	s_barrier
	v_mov_b32_e32 v160, v218
	s_add_u32 s60, s40, 0x160000
	s_addc_u32 s61, s41, 0
	s_nop 0
	s_nop 0
	s_nop 0
	v_xad_u32 v190, v160, 64, 0
	ds_read_b128 v[160:163], v191 offset:16384
	ds_read_b128 v[164:167], v191 offset:18432
	ds_read_b128 v[168:171], v190 offset:16384
	ds_read_b128 v[172:175], v190 offset:18432
	ds_read_b128 v[176:179], v191 offset:20480
	ds_read_b128 v[180:183], v191 offset:22528
	ds_read_b128 v[192:195], v190 offset:20480
	ds_read_b128 v[196:199], v190 offset:22528
	s_mov_b32 m0, s80
	s_nop 0
	global_load_lds_dwordx4 v214, s[40:41]
	s_mov_b32 m0, s81
	s_nop 0
	global_load_lds_dwordx4 v216, s[40:41]
	s_mov_b32 m0, s29
	s_nop 0
	global_load_lds_dwordx4 v214, s[60:61]
	s_mov_b32 m0, s88
	s_nop 0
	global_load_lds_dwordx4 v216, s[60:61]
	s_mov_b32 m0, s76
	s_nop 0
	global_load_lds_dwordx4 v184, s[46:47]
	s_mov_b32 m0, s89
	s_nop 0
	global_load_lds_dwordx4 v215, s[46:47]
	s_waitcnt vmcnt(8)
	s_waitcnt lgkmcnt(0)
	s_setprio 1
	s_barrier
; #define PG8_STAGE(bufoff, gbase, voff) do { _Pragma("unroll") for (int _i = 0; _i < 2; ++_i) \
;         dma16((const char*)(gbase), (voff)[_i], ldsb + (bufoff) + ldsw + _i * 8192); } while (0)
; #define PG8_LDA(dst, b, h) do { const int a1_ = opqv(aoff0) ^ 64; _Pragma("unroll") for (int m = 0; m < 4; ++m) { dst[m][0] = *(const LAS bf16x8*)(lds + PG8_SA(b, h) + aoff0 + m * 2048); dst[m][1] = *(const LAS bf16x8*)(lds + PG8_SA(b, h) + a1_ + m * 2048); } } while (0)
; #define PG8_LDB(dst, b, h) do { const int b1_ = opqv(boff0) ^ 64; _Pragma("unroll") for (int n = 0; n < 2; ++n) { dst[n][0] = *(const LAS bf16x8*)(lds + PG8_SB(b, h) + boff0 + n * 2048); dst[n][1] = *(const LAS bf16x8*)(lds + PG8_SB(b, h) + b1_ + n * 2048); } } while (0)
; #define PG8_MMA(ai, bj, At, Bt) do { __builtin_amdgcn_s_setprio(1); _Pragma("unroll") for (int m = 0; m < 4; ++m) _Pragma("unroll") for (int n = 0; n < 2; ++n) _Pragma("unroll") for (int k = 0; k < 2; ++k) \
;         acc[ai][bj][m][n] = __builtin_amdgcn_mfma_f32_16x16x32_bf16(Bt[n][k], At[m][k], acc[ai][bj][m][n], 0, 0, 0); __builtin_amdgcn_s_setprio(0); } while (0)
; #define PG8_WAIT_V(n) asm volatile("s_waitcnt vmcnt(" #n ")" ::: "memory")
; #define PG8_WAIT_L(n) asm volatile("s_waitcnt lgkmcnt(" #n ")" ::: "memory")
; #define PG8_BAR __builtin_amdgcn_s_barrier()
; #define PG8_SCHED __builtin_amdgcn_sched_barrier(0)
; template <class Epi>
; __device__ __forceinline__ void gemm_phase(LAS unsigned char* lds, const Gemm g, const StaticOrder& S, const Epi& E, int wave_) {
;     ...
;             PG8_WAIT_V(8); PG8_WAIT_L(0); PG8_BAR; PG8_MMA(1, 0, At, B0); PG8_MMA(1, 1, At, B1); PG8_BAR; PG8_SCHED;
;             PG8_STAGE(PG8_SA(0, 1), a2 + hstepA, voffA); PG8_LDB(B0, 1, 0); PG8_LDB(B1, 1, 1); PG8_SCHED; PG8_LDA(At, 1, 0);
;             PG8_WAIT_V(8); PG8_WAIT_L(0); PG8_BAR; PG8_MMA(0, 0, At, B0); PG8_MMA(0, 1, At, B1); PG8_BAR; PG8_SCHED;
	v_mfma_f32_16x16x32_bf16 v[60:63], v[64:67], v[160:163], v[60:63]
	v_mfma_f32_16x16x32_bf16 v[56:59], v[68:71], v[160:163], v[56:59]
	v_mfma_f32_16x16x32_bf16 v[44:47], v[64:67], v[164:167], v[44:47]
	v_mfma_f32_16x16x32_bf16 v[40:43], v[68:71], v[164:167], v[40:43]
	v_mfma_f32_16x16x32_bf16 v[28:31], v[64:67], v[176:179], v[28:31]
	v_mfma_f32_16x16x32_bf16 v[24:27], v[68:71], v[176:179], v[24:27]
	v_mfma_f32_16x16x32_bf16 v[12:15], v[64:67], v[180:183], v[12:15]
	v_mfma_f32_16x16x32_bf16 v[8:11], v[68:71], v[180:183], v[8:11]
	v_mfma_f32_16x16x32_bf16 v[60:63], v[72:75], v[168:171], v[60:63]
	v_mfma_f32_16x16x32_bf16 v[56:59], v[76:79], v[168:171], v[56:59]
	v_mfma_f32_16x16x32_bf16 v[44:47], v[72:75], v[172:175], v[44:47]
	v_mfma_f32_16x16x32_bf16 v[40:43], v[76:79], v[172:175], v[40:43]
	v_mfma_f32_16x16x32_bf16 v[28:31], v[72:75], v[192:195], v[28:31]
	v_mfma_f32_16x16x32_bf16 v[24:27], v[76:79], v[192:195], v[24:27]
	v_mfma_f32_16x16x32_bf16 v[12:15], v[72:75], v[196:199], v[12:15]
	v_mfma_f32_16x16x32_bf16 v[8:11], v[76:79], v[196:199], v[8:11]
	s_setprio 0
	s_setprio 1
	v_mfma_f32_16x16x32_bf16 v[52:55], v[80:83], v[160:163], v[52:55]
	v_mfma_f32_16x16x32_bf16 v[48:51], v[84:87], v[160:163], v[48:51]
	v_mfma_f32_16x16x32_bf16 v[36:39], v[80:83], v[164:167], v[36:39]
	v_mfma_f32_16x16x32_bf16 v[32:35], v[84:87], v[164:167], v[32:35]
	v_mfma_f32_16x16x32_bf16 v[20:23], v[80:83], v[176:179], v[20:23]
	v_mfma_f32_16x16x32_bf16 v[16:19], v[84:87], v[176:179], v[16:19]
	v_mfma_f32_16x16x32_bf16 v[4:7], v[80:83], v[180:183], v[4:7]
	v_mfma_f32_16x16x32_bf16 v[0:3], v[84:87], v[180:183], v[0:3]
	v_mfma_f32_16x16x32_bf16 v[52:55], v[88:91], v[168:171], v[52:55]
	v_mfma_f32_16x16x32_bf16 v[48:51], v[92:95], v[168:171], v[48:51]
	v_mfma_f32_16x16x32_bf16 v[36:39], v[88:91], v[172:175], v[36:39]
	v_mfma_f32_16x16x32_bf16 v[32:35], v[92:95], v[172:175], v[32:35]
	v_mfma_f32_16x16x32_bf16 v[20:23], v[88:91], v[192:195], v[20:23]
	v_mfma_f32_16x16x32_bf16 v[16:19], v[92:95], v[192:195], v[16:19]
	v_mfma_f32_16x16x32_bf16 v[4:7], v[88:91], v[196:199], v[4:7]
	v_mfma_f32_16x16x32_bf16 v[0:3], v[92:95], v[196:199], v[0:3]
	s_setprio 0
	s_barrier
	s_add_u32 s46, s46, 0x160000
	s_addc_u32 s47, s47, 0
	s_mov_b32 m0, s1
	s_nop 0
	global_load_lds_dwordx4 v184, s[46:47]
	v_mov_b32_e32 v64, v219
	s_mov_b32 m0, s69
	s_nop 0
	global_load_lds_dwordx4 v215, s[46:47]
	v_add_u32_e32 v68, s34, v219
	v_xad_u32 v76, v64, 64, s34
	v_mov_b32_e32 v80, v219
	s_add_i32 s46, 0, 0x1c000
	ds_read_b128 v[64:67], v68
	ds_read_b128 v[68:71], v68 offset:2048
	ds_read_b128 v[72:75], v76
	ds_read_b128 v[76:79], v76 offset:2048
	v_add_u32_e32 v84, s46, v219
	v_xad_u32 v92, v80, 64, s46
	ds_read_b128 v[80:83], v84
	ds_read_b128 v[84:87], v84 offset:2048
	ds_read_b128 v[88:91], v92
	ds_read_b128 v[92:95], v92 offset:2048
	v_mov_b32_e32 v160, v218
	s_nop 0
	v_xad_u32 v190, v160, 64, 0
	ds_read_b128 v[160:163], v191 offset:32768
	ds_read_b128 v[164:167], v191 offset:34816
	ds_read_b128 v[168:171], v190 offset:32768
	ds_read_b128 v[172:175], v190 offset:34816
	ds_read_b128 v[176:179], v191 offset:36864
	ds_read_b128 v[180:183], v191 offset:38912
	ds_read_b128 v[192:195], v190 offset:36864
	ds_read_b128 v[196:199], v190 offset:38912
	s_waitcnt vmcnt(8)
	s_waitcnt lgkmcnt(0)
	s_setprio 1
	s_barrier
; #define PG8_STAGE(bufoff, gbase, voff) do { _Pragma("unroll") for (int _i = 0; _i < 2; ++_i) \
;         dma16((const char*)(gbase), (voff)[_i], ldsb + (bufoff) + ldsw + _i * 8192); } while (0)
; #define PG8_LDA(dst, b, h) do { const int a1_ = opqv(aoff0) ^ 64; _Pragma("unroll") for (int m = 0; m < 4; ++m) { dst[m][0] = *(const LAS bf16x8*)(lds + PG8_SA(b, h) + aoff0 + m * 2048); dst[m][1] = *(const LAS bf16x8*)(lds + PG8_SA(b, h) + a1_ + m * 2048); } } while (0)
; #define PG8_MMA(ai, bj, At, Bt) do { __builtin_amdgcn_s_setprio(1); _Pragma("unroll") for (int m = 0; m < 4; ++m) _Pragma("unroll") for (int n = 0; n < 2; ++n) _Pragma("unroll") for (int k = 0; k < 2; ++k) \
;         acc[ai][bj][m][n] = __builtin_amdgcn_mfma_f32_16x16x32_bf16(Bt[n][k], At[m][k], acc[ai][bj][m][n], 0, 0, 0); __builtin_amdgcn_s_setprio(0); } while (0)
; #define PG8_WAIT_V(n) asm volatile("s_waitcnt vmcnt(" #n ")" ::: "memory")
; #define PG8_WAIT_L(n) asm volatile("s_waitcnt lgkmcnt(" #n ")" ::: "memory")
; #define PG8_BAR __builtin_amdgcn_s_barrier()
; #define PG8_SCHED __builtin_amdgcn_sched_barrier(0)
; template <class Epi>
; __device__ __forceinline__ void gemm_phase(LAS unsigned char* lds, const Gemm g, const StaticOrder& S, const Epi& E, int wave_) {
;     ...
;             PG8_WAIT_V(8); PG8_WAIT_L(0); PG8_BAR; PG8_MMA(0, 0, At, B0); PG8_MMA(0, 1, At, B1); PG8_BAR; PG8_SCHED;
;             PG8_STAGE(PG8_SB(1, 0), b3, voffB); PG8_STAGE(PG8_SB(1, 1), b3 + hstepB, voffB); PG8_STAGE(PG8_SA(1, 0), a3, voffA); PG8_LDA(At, 1, 1);
;             PG8_WAIT_V(8); PG8_WAIT_L(0); PG8_BAR; PG8_MMA(1, 0, At, B0); PG8_MMA(1, 1, At, B1); PG8_BAR; PG8_SCHED;
;         }
	v_mfma_f32_16x16x32_bf16 v[156:159], v[64:67], v[160:163], v[156:159]
	v_mfma_f32_16x16x32_bf16 v[152:155], v[68:71], v[160:163], v[152:155]
	v_mfma_f32_16x16x32_bf16 v[140:143], v[64:67], v[164:167], v[140:143]
	v_mfma_f32_16x16x32_bf16 v[136:139], v[68:71], v[164:167], v[136:139]
	v_mfma_f32_16x16x32_bf16 v[124:127], v[64:67], v[176:179], v[124:127]
	v_mfma_f32_16x16x32_bf16 v[120:123], v[68:71], v[176:179], v[120:123]
	v_mfma_f32_16x16x32_bf16 v[108:111], v[64:67], v[180:183], v[108:111]
	v_mfma_f32_16x16x32_bf16 v[104:107], v[68:71], v[180:183], v[104:107]
	v_mfma_f32_16x16x32_bf16 v[156:159], v[72:75], v[168:171], v[156:159]
	v_mfma_f32_16x16x32_bf16 v[152:155], v[76:79], v[168:171], v[152:155]
	v_mfma_f32_16x16x32_bf16 v[140:143], v[72:75], v[172:175], v[140:143]
	v_mfma_f32_16x16x32_bf16 v[136:139], v[76:79], v[172:175], v[136:139]
	v_mfma_f32_16x16x32_bf16 v[124:127], v[72:75], v[192:195], v[124:127]
	v_mfma_f32_16x16x32_bf16 v[120:123], v[76:79], v[192:195], v[120:123]
	v_mfma_f32_16x16x32_bf16 v[108:111], v[72:75], v[196:199], v[108:111]
	v_mfma_f32_16x16x32_bf16 v[104:107], v[76:79], v[196:199], v[104:107]
	s_setprio 0
	s_setprio 1
	v_mfma_f32_16x16x32_bf16 v[148:151], v[80:83], v[160:163], v[148:151]
	s_add_u32 s46, s40, 0x80
	s_addc_u32 s47, s41, 0
	v_mfma_f32_16x16x32_bf16 v[144:147], v[84:87], v[160:163], v[144:147]
	v_mfma_f32_16x16x32_bf16 v[132:135], v[80:83], v[164:167], v[132:135]
	v_mfma_f32_16x16x32_bf16 v[128:131], v[84:87], v[164:167], v[128:131]
	v_mfma_f32_16x16x32_bf16 v[116:119], v[80:83], v[176:179], v[116:119]
	v_mfma_f32_16x16x32_bf16 v[112:115], v[84:87], v[176:179], v[112:115]
	v_mfma_f32_16x16x32_bf16 v[100:103], v[80:83], v[180:183], v[100:103]
	v_mfma_f32_16x16x32_bf16 v[96:99], v[84:87], v[180:183], v[96:99]
	v_mfma_f32_16x16x32_bf16 v[148:151], v[88:91], v[168:171], v[148:151]
	v_mfma_f32_16x16x32_bf16 v[144:147], v[92:95], v[168:171], v[144:147]
	v_mfma_f32_16x16x32_bf16 v[132:135], v[88:91], v[172:175], v[132:135]
	v_mfma_f32_16x16x32_bf16 v[128:131], v[92:95], v[172:175], v[128:131]
	v_mfma_f32_16x16x32_bf16 v[116:119], v[88:91], v[192:195], v[116:119]
	v_mfma_f32_16x16x32_bf16 v[112:115], v[92:95], v[192:195], v[112:115]
	v_mfma_f32_16x16x32_bf16 v[100:103], v[88:91], v[196:199], v[100:103]
	v_mfma_f32_16x16x32_bf16 v[96:99], v[92:95], v[196:199], v[96:99]
	s_setprio 0
	s_barrier
	s_add_u32 s40, s40, 0x160080
	s_addc_u32 s41, s41, 0
	v_mov_b32_e32 v160, v218
	s_nop 0
	s_nop 0
	v_xad_u32 v190, v160, 64, 0
	ds_read_b128 v[160:163], v191 offset:49152
	ds_read_b128 v[164:167], v191 offset:51200
	ds_read_b128 v[168:171], v190 offset:49152
	ds_read_b128 v[172:175], v190 offset:51200
	ds_read_b128 v[176:179], v191 offset:53248
	ds_read_b128 v[180:183], v191 offset:55296
	ds_read_b128 v[192:195], v190 offset:53248
	ds_read_b128 v[196:199], v190 offset:55296
	s_mov_b32 m0, s35
	s_nop 0
	global_load_lds_dwordx4 v214, s[46:47]
	s_mov_b32 m0, s33
	s_nop 0
	global_load_lds_dwordx4 v216, s[46:47]
	s_mov_b32 m0, s77
	s_nop 0
	global_load_lds_dwordx4 v214, s[40:41]
	s_mov_b32 m0, s3
	s_nop 0
	global_load_lds_dwordx4 v216, s[40:41]
	s_mov_b32 m0, s22
	s_nop 0
	global_load_lds_dwordx4 v184, s[36:37]
	s_mov_b32 m0, s2
	s_nop 0
	global_load_lds_dwordx4 v215, s[36:37]
	s_waitcnt vmcnt(8)
	s_waitcnt lgkmcnt(0)
	s_setprio 1
	s_barrier
	v_mfma_f32_16x16x32_bf16 v[60:63], v[64:67], v[160:163], v[60:63]
	v_mfma_f32_16x16x32_bf16 v[56:59], v[68:71], v[160:163], v[56:59]
	v_mfma_f32_16x16x32_bf16 v[44:47], v[64:67], v[164:167], v[44:47]
	v_mfma_f32_16x16x32_bf16 v[40:43], v[68:71], v[164:167], v[40:43]
	v_mfma_f32_16x16x32_bf16 v[28:31], v[64:67], v[176:179], v[28:31]
	v_mfma_f32_16x16x32_bf16 v[24:27], v[68:71], v[176:179], v[24:27]
	v_mfma_f32_16x16x32_bf16 v[12:15], v[64:67], v[180:183], v[12:15]
	v_mfma_f32_16x16x32_bf16 v[8:11], v[68:71], v[180:183], v[8:11]
	v_mfma_f32_16x16x32_bf16 v[60:63], v[72:75], v[168:171], v[60:63]
	v_mfma_f32_16x16x32_bf16 v[56:59], v[76:79], v[168:171], v[56:59]
	v_mfma_f32_16x16x32_bf16 v[44:47], v[72:75], v[172:175], v[44:47]
	v_mfma_f32_16x16x32_bf16 v[40:43], v[76:79], v[172:175], v[40:43]
	v_mfma_f32_16x16x32_bf16 v[28:31], v[72:75], v[192:195], v[28:31]
	v_mfma_f32_16x16x32_bf16 v[24:27], v[76:79], v[192:195], v[24:27]
	v_mfma_f32_16x16x32_bf16 v[12:15], v[72:75], v[196:199], v[12:15]
	v_mfma_f32_16x16x32_bf16 v[8:11], v[76:79], v[196:199], v[8:11]
	s_setprio 0
	s_setprio 1
	v_mfma_f32_16x16x32_bf16 v[52:55], v[80:83], v[160:163], v[52:55]
	v_mfma_f32_16x16x32_bf16 v[48:51], v[84:87], v[160:163], v[48:51]
	v_mfma_f32_16x16x32_bf16 v[36:39], v[80:83], v[164:167], v[36:39]
	v_mfma_f32_16x16x32_bf16 v[32:35], v[84:87], v[164:167], v[32:35]
	v_mfma_f32_16x16x32_bf16 v[20:23], v[80:83], v[176:179], v[20:23]
	v_mfma_f32_16x16x32_bf16 v[16:19], v[84:87], v[176:179], v[16:19]
	v_mfma_f32_16x16x32_bf16 v[4:7], v[80:83], v[180:183], v[4:7]
	v_mfma_f32_16x16x32_bf16 v[0:3], v[84:87], v[180:183], v[0:3]
	v_mfma_f32_16x16x32_bf16 v[52:55], v[88:91], v[168:171], v[52:55]
	v_mfma_f32_16x16x32_bf16 v[48:51], v[92:95], v[168:171], v[48:51]
	v_mfma_f32_16x16x32_bf16 v[36:39], v[88:91], v[172:175], v[36:39]
	v_mfma_f32_16x16x32_bf16 v[32:35], v[92:95], v[172:175], v[32:35]
	v_mfma_f32_16x16x32_bf16 v[20:23], v[88:91], v[192:195], v[20:23]
	v_mfma_f32_16x16x32_bf16 v[16:19], v[92:95], v[192:195], v[16:19]
	v_mfma_f32_16x16x32_bf16 v[4:7], v[88:91], v[196:199], v[4:7]
	v_mfma_f32_16x16x32_bf16 v[0:3], v[92:95], v[196:199], v[0:3]
	s_setprio 0
	s_barrier
	s_add_i32 s59, s59, 2
	s_add_u32 s16, s16, 0x100
	s_addc_u32 s17, s17, 0
	s_add_u32 s12, s12, 0x100
	s_addc_u32 s13, s13, 0
	s_cmpk_gt_u32 s59, 0x55
	s_cbranch_scc0 .LBB0_1552

; #define PG8_STAGE(bufoff, gbase, voff) do { _Pragma("unroll") for (int _i = 0; _i < 2; ++_i) \
;         dma16((const char*)(gbase), (voff)[_i], ldsb + (bufoff) + ldsw + _i * 8192); } while (0)
; #define PG8_LDA(dst, b, h) do { const int a1_ = opqv(aoff0) ^ 64; _Pragma("unroll") for (int m = 0; m < 4; ++m) { dst[m][0] = *(const LAS bf16x8*)(lds + PG8_SA(b, h) + aoff0 + m * 2048); dst[m][1] = *(const LAS bf16x8*)(lds + PG8_SA(b, h) + a1_ + m * 2048); } } while (0)
; #define PG8_LDB(dst, b, h) do { const int b1_ = opqv(boff0) ^ 64; _Pragma("unroll") for (int n = 0; n < 2; ++n) { dst[n][0] = *(const LAS bf16x8*)(lds + PG8_SB(b, h) + boff0 + n * 2048); dst[n][1] = *(const LAS bf16x8*)(lds + PG8_SB(b, h) + b1_ + n * 2048); } } while (0)
; #define PG8_MMA(ai, bj, At, Bt) do { __builtin_amdgcn_s_setprio(1); _Pragma("unroll") for (int m = 0; m < 4; ++m) _Pragma("unroll") for (int n = 0; n < 2; ++n) _Pragma("unroll") for (int k = 0; k < 2; ++k) \
;         acc[ai][bj][m][n] = __builtin_amdgcn_mfma_f32_16x16x32_bf16(Bt[n][k], At[m][k], acc[ai][bj][m][n], 0, 0, 0); __builtin_amdgcn_s_setprio(0); } while (0)
; template <class Epi>
; __device__ __forceinline__ void gemm_phase(LAS unsigned char* lds, const Gemm g, const StaticOrder& S, const Epi& E, int wave_) {
;     ...
;         const bool has_next = S.next(ui + 1, nxt);
;         const char* nA = has_next ? (const char*)g.A + (size_t)nxt.pm * tstepA : cA; const char* nB = has_next ? (const char*)g.Bt + (size_t)nxt.pn * tstepB : cB;
; #pragma unroll 1
;         for (int t = 0; t < nt; t += 2) {
;             const bool last = (t == nt - 2);
;             const char* a1 = cA + (size_t)(t + 1) * kstep;
;             const char* a2 = last ? nA : cA + (size_t)(t + 2) * kstep; const char* b2 = last ? nB : cB + (size_t)(t + 2) * kstep;
;             const char* a3 = a2 + kstep; const char* b3 = b2 + kstep;
;             PG8_STAGE(PG8_SA(1, 1), a1 + hstepA, voffA); PG8_LDB(B0, 0, 0); PG8_LDB(B1, 0, 1); PG8_SCHED; PG8_LDA(At, 0, 0);
;             PG8_WAIT_V(8); PG8_WAIT_L(0); PG8_BAR; PG8_MMA(0, 0, At, B0); PG8_MMA(0, 1, At, B1); PG8_BAR; PG8_SCHED;
;             PG8_STAGE(PG8_SB(0, 0), b2, voffB); PG8_STAGE(PG8_SB(0, 1), b2 + hstepB, voffB); PG8_STAGE(PG8_SA(0, 0), a2, voffA); PG8_LDA(At, 0, 1);
;             PG8_WAIT_V(8); PG8_WAIT_L(0); PG8_BAR; PG8_MMA(1, 0, At, B0); PG8_MMA(1, 1, At, B1); PG8_BAR; PG8_SCHED;
.LBB0_1775:
	s_ashr_i32 s59, s58, 31
	s_lshl_b64 s[16:17], s[58:59], 20
	s_add_u32 s60, s21, s16
	s_addc_u32 s61, s52, s17
	s_and_b64 s[16:17], s[44:45], exec
	s_cselect_b32 s16, s61, s47
	s_cselect_b32 s17, s60, s46
	s_ashr_i32 s57, s56, 31
	s_lshl_b64 s[48:49], s[56:57], 20
	s_add_u32 s62, s66, s48
	s_addc_u32 s63, s67, s49
	s_and_b64 s[48:49], s[44:45], exec
	s_cselect_b32 s57, s63, s13
	s_cselect_b32 s59, s62, s12
	s_add_u32 s75, s12, 0x100
	s_addc_u32 s78, s13, 0
	s_add_u32 s12, s46, 0x80080
	s_addc_u32 s13, s47, 0
	s_mov_b32 s79, -2
	s_add_u32 s46, s12, 0xfff80080
	s_addc_u32 s47, s13, -1
	s_cmp_eq_u32 s79, 28
	s_cselect_b32 s64, s17, s46
	s_cselect_b32 s65, s16, s47
	s_cselect_b32 s48, s59, s75
	s_cselect_b32 s49, s57, s78
	s_add_u32 s46, s64, 0x80
	v_mov_b32_e32 v88, v238
	s_addc_u32 s47, s65, 0
	v_add_u32_e32 v92, s23, v238
	v_xad_u32 v100, v88, 64, s23
	v_mov_b32_e32 v108, v238
	s_add_i32 s82, 0, 0x14000
	ds_read_b128 v[88:91], v92
	ds_read_b128 v[92:95], v92 offset:2048
	ds_read_b128 v[96:99], v100
	ds_read_b128 v[100:103], v100 offset:2048
	v_add_u32_e32 v112, s82, v238
	v_xad_u32 v124, v108, 64, s82
	ds_read_b128 v[108:111], v112
	ds_read_b128 v[112:115], v112 offset:2048
	ds_read_b128 v[120:123], v124
	ds_read_b128 v[124:127], v124 offset:2048
	v_mov_b32_e32 v160, v237
	v_add_u32_e32 v191, 0, v237
	v_xad_u32 v190, v160, 64, 0
	ds_read_b128 v[160:163], v191
	ds_read_b128 v[164:167], v191 offset:2048
	ds_read_b128 v[168:171], v190
	ds_read_b128 v[172:175], v190 offset:2048
	ds_read_b128 v[176:179], v191 offset:4096
	ds_read_b128 v[180:183], v191 offset:6144
	ds_read_b128 v[192:195], v190 offset:4096
	ds_read_b128 v[196:199], v190 offset:6144
	s_mov_b32 m0, s14
	s_nop 0
	global_load_lds_dwordx4 v184, s[12:13]
	s_mov_b32 m0, s15
	s_nop 0
	global_load_lds_dwordx4 v234, s[12:13]
	s_waitcnt vmcnt(8)
	s_waitcnt lgkmcnt(0)
	s_setprio 1
	s_barrier
	v_mfma_f32_16x16x32_bf16 v[156:159], v[88:91], v[160:163], 0
	v_mfma_f32_16x16x32_bf16 v[152:155], v[92:95], v[160:163], 0
	v_mfma_f32_16x16x32_bf16 v[148:151], v[88:91], v[164:167], 0
	v_mfma_f32_16x16x32_bf16 v[144:147], v[92:95], v[164:167], 0
	v_mfma_f32_16x16x32_bf16 v[140:143], v[88:91], v[176:179], 0
	v_mfma_f32_16x16x32_bf16 v[136:139], v[92:95], v[176:179], 0
	v_mfma_f32_16x16x32_bf16 v[132:135], v[88:91], v[180:183], 0
	v_mfma_f32_16x16x32_bf16 v[128:131], v[92:95], v[180:183], 0
	v_mfma_f32_16x16x32_bf16 v[156:159], v[96:99], v[168:171], v[156:159]
	v_mfma_f32_16x16x32_bf16 v[152:155], v[100:103], v[168:171], v[152:155]
	v_mfma_f32_16x16x32_bf16 v[148:151], v[96:99], v[172:175], v[148:151]
	v_mfma_f32_16x16x32_bf16 v[144:147], v[100:103], v[172:175], v[144:147]
	v_mfma_f32_16x16x32_bf16 v[140:143], v[96:99], v[192:195], v[140:143]
	v_mfma_f32_16x16x32_bf16 v[136:139], v[100:103], v[192:195], v[136:139]
	v_mfma_f32_16x16x32_bf16 v[132:135], v[96:99], v[196:199], v[132:135]
	v_mfma_f32_16x16x32_bf16 v[128:131], v[100:103], v[196:199], v[128:131]
	s_setprio 0
	s_setprio 1
	v_mfma_f32_16x16x32_bf16 v[60:63], v[108:111], v[160:163], 0
	v_mfma_f32_16x16x32_bf16 v[56:59], v[112:115], v[160:163], 0
	v_mfma_f32_16x16x32_bf16 v[52:55], v[108:111], v[164:167], 0
	v_mfma_f32_16x16x32_bf16 v[48:51], v[112:115], v[164:167], 0
	v_mfma_f32_16x16x32_bf16 v[44:47], v[108:111], v[176:179], 0
	v_mfma_f32_16x16x32_bf16 v[40:43], v[112:115], v[176:179], 0
	v_mfma_f32_16x16x32_bf16 v[36:39], v[108:111], v[180:183], 0
	v_mfma_f32_16x16x32_bf16 v[32:35], v[112:115], v[180:183], 0
	v_mfma_f32_16x16x32_bf16 v[60:63], v[120:123], v[168:171], v[60:63]
	v_mfma_f32_16x16x32_bf16 v[56:59], v[124:127], v[168:171], v[56:59]
	v_mfma_f32_16x16x32_bf16 v[52:55], v[120:123], v[172:175], v[52:55]
	v_mfma_f32_16x16x32_bf16 v[48:51], v[124:127], v[172:175], v[48:51]
	v_mfma_f32_16x16x32_bf16 v[44:47], v[120:123], v[192:195], v[44:47]
	v_mfma_f32_16x16x32_bf16 v[40:43], v[124:127], v[192:195], v[40:43]
	v_mfma_f32_16x16x32_bf16 v[36:39], v[120:123], v[196:199], v[36:39]
	v_mfma_f32_16x16x32_bf16 v[32:35], v[124:127], v[196:199], v[32:35]
	s_setprio 0
	s_barrier
	v_mov_b32_e32 v160, v237
	s_add_u32 s82, s48, 0x80000
	s_addc_u32 s83, s49, 0
	s_nop 0
	s_nop 0
	s_nop 0
	v_xad_u32 v190, v160, 64, 0
	ds_read_b128 v[160:163], v191 offset:16384
	ds_read_b128 v[164:167], v191 offset:18432
	ds_read_b128 v[168:171], v190 offset:16384
	ds_read_b128 v[172:175], v190 offset:18432
	ds_read_b128 v[176:179], v191 offset:20480
	ds_read_b128 v[180:183], v191 offset:22528
	ds_read_b128 v[192:195], v190 offset:20480
	ds_read_b128 v[196:199], v190 offset:22528
	s_mov_b32 m0, s80
	s_nop 0
	global_load_lds_dwordx4 v233, s[48:49]
	s_mov_b32 m0, s81
	s_nop 0
	global_load_lds_dwordx4 v235, s[48:49]
	s_mov_b32 m0, s29
	s_nop 0
	global_load_lds_dwordx4 v233, s[82:83]
	s_mov_b32 m0, s88
	s_nop 0
	global_load_lds_dwordx4 v235, s[82:83]
	s_mov_b32 m0, s76
	s_nop 0
	global_load_lds_dwordx4 v184, s[64:65]
	s_mov_b32 m0, s89
	s_nop 0
	global_load_lds_dwordx4 v234, s[64:65]
	s_waitcnt vmcnt(8)
	s_waitcnt lgkmcnt(0)
	s_setprio 1
	s_barrier
; #define PG8_STAGE(bufoff, gbase, voff) do { _Pragma("unroll") for (int _i = 0; _i < 2; ++_i) \
;         dma16((const char*)(gbase), (voff)[_i], ldsb + (bufoff) + ldsw + _i * 8192); } while (0)
; #define PG8_LDA(dst, b, h) do { const int a1_ = opqv(aoff0) ^ 64; _Pragma("unroll") for (int m = 0; m < 4; ++m) { dst[m][0] = *(const LAS bf16x8*)(lds + PG8_SA(b, h) + aoff0 + m * 2048); dst[m][1] = *(const LAS bf16x8*)(lds + PG8_SA(b, h) + a1_ + m * 2048); } } while (0)
; #define PG8_LDB(dst, b, h) do { const int b1_ = opqv(boff0) ^ 64; _Pragma("unroll") for (int n = 0; n < 2; ++n) { dst[n][0] = *(const LAS bf16x8*)(lds + PG8_SB(b, h) + boff0 + n * 2048); dst[n][1] = *(const LAS bf16x8*)(lds + PG8_SB(b, h) + b1_ + n * 2048); } } while (0)
; #define PG8_MMA(ai, bj, At, Bt) do { __builtin_amdgcn_s_setprio(1); _Pragma("unroll") for (int m = 0; m < 4; ++m) _Pragma("unroll") for (int n = 0; n < 2; ++n) _Pragma("unroll") for (int k = 0; k < 2; ++k) \
;         acc[ai][bj][m][n] = __builtin_amdgcn_mfma_f32_16x16x32_bf16(Bt[n][k], At[m][k], acc[ai][bj][m][n], 0, 0, 0); __builtin_amdgcn_s_setprio(0); } while (0)
; #define PG8_WAIT_V(n) asm volatile("s_waitcnt vmcnt(" #n ")" ::: "memory")
; #define PG8_WAIT_L(n) asm volatile("s_waitcnt lgkmcnt(" #n ")" ::: "memory")
; #define PG8_BAR __builtin_amdgcn_s_barrier()
; #define PG8_SCHED __builtin_amdgcn_sched_barrier(0)
; template <class Epi>
; __device__ __forceinline__ void gemm_phase(LAS unsigned char* lds, const Gemm g, const StaticOrder& S, const Epi& E, int wave_) {
;     ...
;             PG8_WAIT_V(8); PG8_WAIT_L(0); PG8_BAR; PG8_MMA(1, 0, At, B0); PG8_MMA(1, 1, At, B1); PG8_BAR; PG8_SCHED;
;             PG8_STAGE(PG8_SA(0, 1), a2 + hstepA, voffA); PG8_LDB(B0, 1, 0); PG8_LDB(B1, 1, 1); PG8_SCHED; PG8_LDA(At, 1, 0);
;             PG8_WAIT_V(8); PG8_WAIT_L(0); PG8_BAR; PG8_MMA(0, 0, At, B0); PG8_MMA(0, 1, At, B1); PG8_BAR; PG8_SCHED;
	v_mfma_f32_16x16x32_bf16 v[116:119], v[88:91], v[160:163], 0
	v_mfma_f32_16x16x32_bf16 v[104:107], v[92:95], v[160:163], 0
	v_mfma_f32_16x16x32_bf16 v[84:87], v[88:91], v[164:167], 0
	v_mfma_f32_16x16x32_bf16 v[80:83], v[92:95], v[164:167], 0
	v_mfma_f32_16x16x32_bf16 v[76:79], v[88:91], v[176:179], 0
	v_mfma_f32_16x16x32_bf16 v[72:75], v[92:95], v[176:179], 0
	v_mfma_f32_16x16x32_bf16 v[68:71], v[88:91], v[180:183], 0
	v_mfma_f32_16x16x32_bf16 v[64:67], v[92:95], v[180:183], 0
	v_mfma_f32_16x16x32_bf16 v[116:119], v[96:99], v[168:171], v[116:119]
	v_mfma_f32_16x16x32_bf16 v[104:107], v[100:103], v[168:171], v[104:107]
	v_mfma_f32_16x16x32_bf16 v[84:87], v[96:99], v[172:175], v[84:87]
	v_mfma_f32_16x16x32_bf16 v[80:83], v[100:103], v[172:175], v[80:83]
	v_mfma_f32_16x16x32_bf16 v[76:79], v[96:99], v[192:195], v[76:79]
	v_mfma_f32_16x16x32_bf16 v[72:75], v[100:103], v[192:195], v[72:75]
	v_mfma_f32_16x16x32_bf16 v[68:71], v[96:99], v[196:199], v[68:71]
	v_mfma_f32_16x16x32_bf16 v[64:67], v[100:103], v[196:199], v[64:67]
	s_setprio 0
	s_setprio 1
	v_mfma_f32_16x16x32_bf16 v[28:31], v[108:111], v[160:163], 0
	v_mfma_f32_16x16x32_bf16 v[24:27], v[112:115], v[160:163], 0
	v_mfma_f32_16x16x32_bf16 v[20:23], v[108:111], v[164:167], 0
	v_mfma_f32_16x16x32_bf16 v[16:19], v[112:115], v[164:167], 0
	v_mfma_f32_16x16x32_bf16 v[12:15], v[108:111], v[176:179], 0
	v_mfma_f32_16x16x32_bf16 v[8:11], v[112:115], v[176:179], 0
	v_mfma_f32_16x16x32_bf16 v[4:7], v[108:111], v[180:183], 0
	v_mfma_f32_16x16x32_bf16 v[0:3], v[112:115], v[180:183], 0
	v_mfma_f32_16x16x32_bf16 v[28:31], v[120:123], v[168:171], v[28:31]
	v_mfma_f32_16x16x32_bf16 v[24:27], v[124:127], v[168:171], v[24:27]
	v_mfma_f32_16x16x32_bf16 v[20:23], v[120:123], v[172:175], v[20:23]
	v_mfma_f32_16x16x32_bf16 v[16:19], v[124:127], v[172:175], v[16:19]
	v_mfma_f32_16x16x32_bf16 v[12:15], v[120:123], v[192:195], v[12:15]
	v_mfma_f32_16x16x32_bf16 v[8:11], v[124:127], v[192:195], v[8:11]
	v_mfma_f32_16x16x32_bf16 v[4:7], v[120:123], v[196:199], v[4:7]
	v_mfma_f32_16x16x32_bf16 v[0:3], v[124:127], v[196:199], v[0:3]
	s_setprio 0
	s_barrier
	s_add_u32 s64, s64, 0x80000
	s_addc_u32 s65, s65, 0
	s_mov_b32 m0, s1
	s_nop 0
	global_load_lds_dwordx4 v184, s[64:65]
	v_mov_b32_e32 v88, v238
	s_mov_b32 m0, s69
	s_nop 0
	global_load_lds_dwordx4 v234, s[64:65]
	v_add_u32_e32 v92, s34, v238
	v_xad_u32 v100, v88, 64, s34
	v_mov_b32_e32 v108, v238
	s_add_i32 s64, 0, 0x1c000
	ds_read_b128 v[88:91], v92
	ds_read_b128 v[92:95], v92 offset:2048
	ds_read_b128 v[96:99], v100
	ds_read_b128 v[100:103], v100 offset:2048
	v_add_u32_e32 v112, s64, v238
	v_xad_u32 v124, v108, 64, s64
	ds_read_b128 v[108:111], v112
	ds_read_b128 v[112:115], v112 offset:2048
	ds_read_b128 v[120:123], v124
	ds_read_b128 v[124:127], v124 offset:2048
	v_mov_b32_e32 v160, v237
	s_nop 0
	v_xad_u32 v190, v160, 64, 0
	ds_read_b128 v[160:163], v191 offset:32768
	ds_read_b128 v[164:167], v191 offset:34816
	ds_read_b128 v[168:171], v190 offset:32768
	ds_read_b128 v[172:175], v190 offset:34816
	ds_read_b128 v[176:179], v191 offset:36864
	ds_read_b128 v[180:183], v191 offset:38912
	ds_read_b128 v[192:195], v190 offset:36864
	ds_read_b128 v[196:199], v190 offset:38912
	s_waitcnt vmcnt(8)
	s_waitcnt lgkmcnt(0)
	s_setprio 1
	s_barrier
	v_mfma_f32_16x16x32_bf16 v[156:159], v[88:91], v[160:163], v[156:159]
	v_mfma_f32_16x16x32_bf16 v[152:155], v[92:95], v[160:163], v[152:155]
	v_mfma_f32_16x16x32_bf16 v[148:151], v[88:91], v[164:167], v[148:151]
	v_mfma_f32_16x16x32_bf16 v[144:147], v[92:95], v[164:167], v[144:147]
	v_mfma_f32_16x16x32_bf16 v[140:143], v[88:91], v[176:179], v[140:143]
	v_mfma_f32_16x16x32_bf16 v[136:139], v[92:95], v[176:179], v[136:139]
	v_mfma_f32_16x16x32_bf16 v[132:135], v[88:91], v[180:183], v[132:135]
	v_mfma_f32_16x16x32_bf16 v[128:131], v[92:95], v[180:183], v[128:131]
	v_mfma_f32_16x16x32_bf16 v[156:159], v[96:99], v[168:171], v[156:159]
	v_mfma_f32_16x16x32_bf16 v[152:155], v[100:103], v[168:171], v[152:155]
	v_mfma_f32_16x16x32_bf16 v[148:151], v[96:99], v[172:175], v[148:151]
	v_mfma_f32_16x16x32_bf16 v[144:147], v[100:103], v[172:175], v[144:147]
	v_mfma_f32_16x16x32_bf16 v[140:143], v[96:99], v[192:195], v[140:143]
	v_mfma_f32_16x16x32_bf16 v[136:139], v[100:103], v[192:195], v[136:139]
	v_mfma_f32_16x16x32_bf16 v[132:135], v[96:99], v[196:199], v[132:135]
	v_mfma_f32_16x16x32_bf16 v[128:131], v[100:103], v[196:199], v[128:131]
	s_setprio 0
	s_setprio 1
	v_mfma_f32_16x16x32_bf16 v[60:63], v[108:111], v[160:163], v[60:63]
	s_add_u32 s64, s48, 0x80
	s_addc_u32 s65, s49, 0
	v_mfma_f32_16x16x32_bf16 v[56:59], v[112:115], v[160:163], v[56:59]
	v_mfma_f32_16x16x32_bf16 v[52:55], v[108:111], v[164:167], v[52:55]
	v_mfma_f32_16x16x32_bf16 v[48:51], v[112:115], v[164:167], v[48:51]
	v_mfma_f32_16x16x32_bf16 v[44:47], v[108:111], v[176:179], v[44:47]
	v_mfma_f32_16x16x32_bf16 v[40:43], v[112:115], v[176:179], v[40:43]
	v_mfma_f32_16x16x32_bf16 v[36:39], v[108:111], v[180:183], v[36:39]
	v_mfma_f32_16x16x32_bf16 v[32:35], v[112:115], v[180:183], v[32:35]
	v_mfma_f32_16x16x32_bf16 v[60:63], v[120:123], v[168:171], v[60:63]
	v_mfma_f32_16x16x32_bf16 v[56:59], v[124:127], v[168:171], v[56:59]
	v_mfma_f32_16x16x32_bf16 v[52:55], v[120:123], v[172:175], v[52:55]
	v_mfma_f32_16x16x32_bf16 v[48:51], v[124:127], v[172:175], v[48:51]
	v_mfma_f32_16x16x32_bf16 v[44:47], v[120:123], v[192:195], v[44:47]
	v_mfma_f32_16x16x32_bf16 v[40:43], v[124:127], v[192:195], v[40:43]
	v_mfma_f32_16x16x32_bf16 v[36:39], v[120:123], v[196:199], v[36:39]
	v_mfma_f32_16x16x32_bf16 v[32:35], v[124:127], v[196:199], v[32:35]
	s_setprio 0
	s_barrier
; #define PG8_STAGE(bufoff, gbase, voff) do { _Pragma("unroll") for (int _i = 0; _i < 2; ++_i) \
;         dma16((const char*)(gbase), (voff)[_i], ldsb + (bufoff) + ldsw + _i * 8192); } while (0)
; #define PG8_LDA(dst, b, h) do { const int a1_ = opqv(aoff0) ^ 64; _Pragma("unroll") for (int m = 0; m < 4; ++m) { dst[m][0] = *(const LAS bf16x8*)(lds + PG8_SA(b, h) + aoff0 + m * 2048); dst[m][1] = *(const LAS bf16x8*)(lds + PG8_SA(b, h) + a1_ + m * 2048); } } while (0)
; #define PG8_LDB(dst, b, h) do { const int b1_ = opqv(boff0) ^ 64; _Pragma("unroll") for (int n = 0; n < 2; ++n) { dst[n][0] = *(const LAS bf16x8*)(lds + PG8_SB(b, h) + boff0 + n * 2048); dst[n][1] = *(const LAS bf16x8*)(lds + PG8_SB(b, h) + b1_ + n * 2048); } } while (0)
; #define PG8_WAIT_V(n) asm volatile("s_waitcnt vmcnt(" #n ")" ::: "memory")
; #define PG8_WAIT_L(n) asm volatile("s_waitcnt lgkmcnt(" #n ")" ::: "memory")
; #define PG8_BAR __builtin_amdgcn_s_barrier()
; #define PG8_SCHED __builtin_amdgcn_sched_barrier(0)
; template <class Epi>
; __device__ __forceinline__ void gemm_phase(LAS unsigned char* lds, const Gemm g, const StaticOrder& S, const Epi& E, int wave_) {
;     ...
;             const char* a2 = last ? nA : cA + (size_t)(t + 2) * kstep; const char* b2 = last ? nB : cB + (size_t)(t + 2) * kstep;
;             const char* a3 = a2 + kstep; const char* b3 = b2 + kstep;
;             PG8_STAGE(PG8_SA(1, 1), a1 + hstepA, voffA); PG8_LDB(B0, 0, 0); PG8_LDB(B1, 0, 1); PG8_SCHED; PG8_LDA(At, 0, 0);
;             PG8_WAIT_V(8); PG8_WAIT_L(0); PG8_BAR; PG8_MMA(0, 0, At, B0); PG8_MMA(0, 1, At, B1); PG8_BAR; PG8_SCHED;
;             PG8_STAGE(PG8_SB(0, 0), b2, voffB); PG8_STAGE(PG8_SB(0, 1), b2 + hstepB, voffB); PG8_STAGE(PG8_SA(0, 0), a2, voffA); PG8_LDA(At, 0, 1);
;             PG8_WAIT_V(8); PG8_WAIT_L(0); PG8_BAR; PG8_MMA(1, 0, At, B0); PG8_MMA(1, 1, At, B1); PG8_BAR; PG8_SCHED;
;             PG8_STAGE(PG8_SA(0, 1), a2 + hstepA, voffA); PG8_LDB(B0, 1, 0); PG8_LDB(B1, 1, 1); PG8_SCHED; PG8_LDA(At, 1, 0);
;             PG8_WAIT_V(8); PG8_WAIT_L(0); PG8_BAR; PG8_MMA(0, 0, At, B0); PG8_MMA(0, 1, At, B1); PG8_BAR; PG8_SCHED;
;             PG8_STAGE(PG8_SB(1, 0), b3, voffB); PG8_STAGE(PG8_SB(1, 1), b3 + hstepB, voffB); PG8_STAGE(PG8_SA(1, 0), a3, voffA); PG8_LDA(At, 1, 1);
;             PG8_WAIT_V(8); PG8_WAIT_L(0); PG8_BAR; PG8_MMA(1, 0, At, B0); PG8_MMA(1, 1, At, B1); PG8_BAR; PG8_SCHED;
	s_add_u32 s48, s48, 0x80080
	s_addc_u32 s49, s49, 0
	v_mov_b32_e32 v160, v237
	s_nop 0
	s_nop 0
	v_xad_u32 v190, v160, 64, 0
	ds_read_b128 v[160:163], v191 offset:49152
	ds_read_b128 v[164:167], v191 offset:51200
	ds_read_b128 v[168:171], v190 offset:49152
	ds_read_b128 v[172:175], v190 offset:51200
	ds_read_b128 v[176:179], v191 offset:53248
	ds_read_b128 v[180:183], v191 offset:55296
	ds_read_b128 v[192:195], v190 offset:53248
	ds_read_b128 v[196:199], v190 offset:55296
	s_mov_b32 m0, s35
	s_nop 0
	global_load_lds_dwordx4 v233, s[64:65]
	s_mov_b32 m0, s33
	s_nop 0
	global_load_lds_dwordx4 v235, s[64:65]
	s_mov_b32 m0, s77
	s_nop 0
	global_load_lds_dwordx4 v233, s[48:49]
	s_mov_b32 m0, s3
	s_nop 0
	global_load_lds_dwordx4 v235, s[48:49]
	s_mov_b32 m0, s22
	s_nop 0
	global_load_lds_dwordx4 v184, s[46:47]
	s_mov_b32 m0, s2
	s_nop 0
	global_load_lds_dwordx4 v234, s[46:47]
	s_waitcnt vmcnt(8)
	s_waitcnt lgkmcnt(0)
	s_setprio 1
	s_barrier
	v_mfma_f32_16x16x32_bf16 v[116:119], v[88:91], v[160:163], v[116:119]
	v_mfma_f32_16x16x32_bf16 v[104:107], v[92:95], v[160:163], v[104:107]
	v_mfma_f32_16x16x32_bf16 v[84:87], v[88:91], v[164:167], v[84:87]
	v_mfma_f32_16x16x32_bf16 v[80:83], v[92:95], v[164:167], v[80:83]
	v_mfma_f32_16x16x32_bf16 v[76:79], v[88:91], v[176:179], v[76:79]
	v_mfma_f32_16x16x32_bf16 v[72:75], v[92:95], v[176:179], v[72:75]
	v_mfma_f32_16x16x32_bf16 v[68:71], v[88:91], v[180:183], v[68:71]
	v_mfma_f32_16x16x32_bf16 v[64:67], v[92:95], v[180:183], v[64:67]
	v_mfma_f32_16x16x32_bf16 v[116:119], v[96:99], v[168:171], v[116:119]
	v_mfma_f32_16x16x32_bf16 v[104:107], v[100:103], v[168:171], v[104:107]
	v_mfma_f32_16x16x32_bf16 v[84:87], v[96:99], v[172:175], v[84:87]
	v_mfma_f32_16x16x32_bf16 v[80:83], v[100:103], v[172:175], v[80:83]
	v_mfma_f32_16x16x32_bf16 v[76:79], v[96:99], v[192:195], v[76:79]
	v_mfma_f32_16x16x32_bf16 v[72:75], v[100:103], v[192:195], v[72:75]
	v_mfma_f32_16x16x32_bf16 v[68:71], v[96:99], v[196:199], v[68:71]
	v_mfma_f32_16x16x32_bf16 v[64:67], v[100:103], v[196:199], v[64:67]
	s_setprio 0
	s_setprio 1
	v_mfma_f32_16x16x32_bf16 v[28:31], v[108:111], v[160:163], v[28:31]
	v_mfma_f32_16x16x32_bf16 v[24:27], v[112:115], v[160:163], v[24:27]
	v_mfma_f32_16x16x32_bf16 v[20:23], v[108:111], v[164:167], v[20:23]
	v_mfma_f32_16x16x32_bf16 v[16:19], v[112:115], v[164:167], v[16:19]
	v_mfma_f32_16x16x32_bf16 v[12:15], v[108:111], v[176:179], v[12:15]
	v_mfma_f32_16x16x32_bf16 v[8:11], v[112:115], v[176:179], v[8:11]
	v_mfma_f32_16x16x32_bf16 v[4:7], v[108:111], v[180:183], v[4:7]
	v_mfma_f32_16x16x32_bf16 v[0:3], v[112:115], v[180:183], v[0:3]
	v_mfma_f32_16x16x32_bf16 v[28:31], v[120:123], v[168:171], v[28:31]
	v_mfma_f32_16x16x32_bf16 v[24:27], v[124:127], v[168:171], v[24:27]
	v_mfma_f32_16x16x32_bf16 v[20:23], v[120:123], v[172:175], v[20:23]
	v_mfma_f32_16x16x32_bf16 v[16:19], v[124:127], v[172:175], v[16:19]
	v_mfma_f32_16x16x32_bf16 v[12:15], v[120:123], v[192:195], v[12:15]
	v_mfma_f32_16x16x32_bf16 v[8:11], v[124:127], v[192:195], v[8:11]
	v_mfma_f32_16x16x32_bf16 v[4:7], v[120:123], v[196:199], v[4:7]
	v_mfma_f32_16x16x32_bf16 v[0:3], v[124:127], v[196:199], v[0:3]
	s_setprio 0
	s_barrier
	s_add_i32 s79, s79, 2
	s_add_u32 s75, s75, 0x100
	s_addc_u32 s78, s78, 0
	s_add_u32 s12, s12, 0x100
	s_addc_u32 s13, s13, 0
	s_cmp_gt_u32 s79, 29
	s_cbranch_scc0 .LBB0_1776
	s_branch .Lpeel_exit_0
.LBB0_1776:
	s_add_u32 s46, s12, 0xfff80080
	s_addc_u32 s47, s13, -1
	s_cmp_eq_u32 s79, 28
	s_cselect_b32 s64, s17, s46
	s_cselect_b32 s65, s16, s47
	s_cselect_b32 s48, s59, s75
	s_cselect_b32 s49, s57, s78
	s_add_u32 s46, s64, 0x80
	v_mov_b32_e32 v88, v238
	s_addc_u32 s47, s65, 0
	v_add_u32_e32 v92, s23, v238
	v_xad_u32 v100, v88, 64, s23
	v_mov_b32_e32 v108, v238
	s_add_i32 s82, 0, 0x14000
	ds_read_b128 v[88:91], v92
	ds_read_b128 v[92:95], v92 offset:2048
	ds_read_b128 v[96:99], v100
	ds_read_b128 v[100:103], v100 offset:2048
	v_add_u32_e32 v112, s82, v238
	v_xad_u32 v124, v108, 64, s82
	ds_read_b128 v[108:111], v112
	ds_read_b128 v[112:115], v112 offset:2048
	ds_read_b128 v[120:123], v124
	ds_read_b128 v[124:127], v124 offset:2048
	v_mov_b32_e32 v160, v237
	v_add_u32_e32 v191, 0, v237
	v_xad_u32 v190, v160, 64, 0
	ds_read_b128 v[160:163], v191
	ds_read_b128 v[164:167], v191 offset:2048
	ds_read_b128 v[168:171], v190
	ds_read_b128 v[172:175], v190 offset:2048
	ds_read_b128 v[176:179], v191 offset:4096
	ds_read_b128 v[180:183], v191 offset:6144
	ds_read_b128 v[192:195], v190 offset:4096
	ds_read_b128 v[196:199], v190 offset:6144
	s_mov_b32 m0, s14
	s_nop 0
	global_load_lds_dwordx4 v184, s[12:13]
	s_mov_b32 m0, s15
	s_nop 0
	global_load_lds_dwordx4 v234, s[12:13]
	s_waitcnt vmcnt(8)
	s_waitcnt lgkmcnt(0)
	s_setprio 1
	s_barrier
; #define PG8_STAGE(bufoff, gbase, voff) do { _Pragma("unroll") for (int _i = 0; _i < 2; ++_i) \
;         dma16((const char*)(gbase), (voff)[_i], ldsb + (bufoff) + ldsw + _i * 8192); } while (0)
; #define PG8_LDA(dst, b, h) do { const int a1_ = opqv(aoff0) ^ 64; _Pragma("unroll") for (int m = 0; m < 4; ++m) { dst[m][0] = *(const LAS bf16x8*)(lds + PG8_SA(b, h) + aoff0 + m * 2048); dst[m][1] = *(const LAS bf16x8*)(lds + PG8_SA(b, h) + a1_ + m * 2048); } } while (0)
; #define PG8_LDB(dst, b, h) do { const int b1_ = opqv(boff0) ^ 64; _Pragma("unroll") for (int n = 0; n < 2; ++n) { dst[n][0] = *(const LAS bf16x8*)(lds + PG8_SB(b, h) + boff0 + n * 2048); dst[n][1] = *(const LAS bf16x8*)(lds + PG8_SB(b, h) + b1_ + n * 2048); } } while (0)
; #define PG8_MMA(ai, bj, At, Bt) do { __builtin_amdgcn_s_setprio(1); _Pragma("unroll") for (int m = 0; m < 4; ++m) _Pragma("unroll") for (int n = 0; n < 2; ++n) _Pragma("unroll") for (int k = 0; k < 2; ++k) \
;         acc[ai][bj][m][n] = __builtin_amdgcn_mfma_f32_16x16x32_bf16(Bt[n][k], At[m][k], acc[ai][bj][m][n], 0, 0, 0); __builtin_amdgcn_s_setprio(0); } while (0)
; #define PG8_WAIT_V(n) asm volatile("s_waitcnt vmcnt(" #n ")" ::: "memory")
; #define PG8_WAIT_L(n) asm volatile("s_waitcnt lgkmcnt(" #n ")" ::: "memory")
; #define PG8_BAR __builtin_amdgcn_s_barrier()
; #define PG8_SCHED __builtin_amdgcn_sched_barrier(0)
; template <class Epi>
; __device__ __forceinline__ void gemm_phase(LAS unsigned char* lds, const Gemm g, const StaticOrder& S, const Epi& E, int wave_) {
;     ...
;             PG8_WAIT_V(8); PG8_WAIT_L(0); PG8_BAR; PG8_MMA(0, 0, At, B0); PG8_MMA(0, 1, At, B1); PG8_BAR; PG8_SCHED;
;             PG8_STAGE(PG8_SB(0, 0), b2, voffB); PG8_STAGE(PG8_SB(0, 1), b2 + hstepB, voffB); PG8_STAGE(PG8_SA(0, 0), a2, voffA); PG8_LDA(At, 0, 1);
;             PG8_WAIT_V(8); PG8_WAIT_L(0); PG8_BAR; PG8_MMA(1, 0, At, B0); PG8_MMA(1, 1, At, B1); PG8_BAR; PG8_SCHED;
;             PG8_STAGE(PG8_SA(0, 1), a2 + hstepA, voffA); PG8_LDB(B0, 1, 0); PG8_LDB(B1, 1, 1); PG8_SCHED; PG8_LDA(At, 1, 0);
;             PG8_WAIT_V(8); PG8_WAIT_L(0); PG8_BAR; PG8_MMA(0, 0, At, B0); PG8_MMA(0, 1, At, B1); PG8_BAR; PG8_SCHED;
	v_mfma_f32_16x16x32_bf16 v[156:159], v[88:91], v[160:163], v[156:159]
	v_mfma_f32_16x16x32_bf16 v[152:155], v[92:95], v[160:163], v[152:155]
	v_mfma_f32_16x16x32_bf16 v[148:151], v[88:91], v[164:167], v[148:151]
	v_mfma_f32_16x16x32_bf16 v[144:147], v[92:95], v[164:167], v[144:147]
	v_mfma_f32_16x16x32_bf16 v[140:143], v[88:91], v[176:179], v[140:143]
	v_mfma_f32_16x16x32_bf16 v[136:139], v[92:95], v[176:179], v[136:139]
	v_mfma_f32_16x16x32_bf16 v[132:135], v[88:91], v[180:183], v[132:135]
	v_mfma_f32_16x16x32_bf16 v[128:131], v[92:95], v[180:183], v[128:131]
	v_mfma_f32_16x16x32_bf16 v[156:159], v[96:99], v[168:171], v[156:159]
	v_mfma_f32_16x16x32_bf16 v[152:155], v[100:103], v[168:171], v[152:155]
	v_mfma_f32_16x16x32_bf16 v[148:151], v[96:99], v[172:175], v[148:151]
	v_mfma_f32_16x16x32_bf16 v[144:147], v[100:103], v[172:175], v[144:147]
	v_mfma_f32_16x16x32_bf16 v[140:143], v[96:99], v[192:195], v[140:143]
	v_mfma_f32_16x16x32_bf16 v[136:139], v[100:103], v[192:195], v[136:139]
	v_mfma_f32_16x16x32_bf16 v[132:135], v[96:99], v[196:199], v[132:135]
	v_mfma_f32_16x16x32_bf16 v[128:131], v[100:103], v[196:199], v[128:131]
	s_setprio 0
	s_setprio 1
	v_mfma_f32_16x16x32_bf16 v[60:63], v[108:111], v[160:163], v[60:63]
	v_mfma_f32_16x16x32_bf16 v[56:59], v[112:115], v[160:163], v[56:59]
	v_mfma_f32_16x16x32_bf16 v[52:55], v[108:111], v[164:167], v[52:55]
	v_mfma_f32_16x16x32_bf16 v[48:51], v[112:115], v[164:167], v[48:51]
	v_mfma_f32_16x16x32_bf16 v[44:47], v[108:111], v[176:179], v[44:47]
	v_mfma_f32_16x16x32_bf16 v[40:43], v[112:115], v[176:179], v[40:43]
	v_mfma_f32_16x16x32_bf16 v[36:39], v[108:111], v[180:183], v[36:39]
	v_mfma_f32_16x16x32_bf16 v[32:35], v[112:115], v[180:183], v[32:35]
	v_mfma_f32_16x16x32_bf16 v[60:63], v[120:123], v[168:171], v[60:63]
	v_mfma_f32_16x16x32_bf16 v[56:59], v[124:127], v[168:171], v[56:59]
	v_mfma_f32_16x16x32_bf16 v[52:55], v[120:123], v[172:175], v[52:55]
	v_mfma_f32_16x16x32_bf16 v[48:51], v[124:127], v[172:175], v[48:51]
	v_mfma_f32_16x16x32_bf16 v[44:47], v[120:123], v[192:195], v[44:47]
	v_mfma_f32_16x16x32_bf16 v[40:43], v[124:127], v[192:195], v[40:43]
	v_mfma_f32_16x16x32_bf16 v[36:39], v[120:123], v[196:199], v[36:39]
	v_mfma_f32_16x16x32_bf16 v[32:35], v[124:127], v[196:199], v[32:35]
	s_setprio 0
	s_barrier
	v_mov_b32_e32 v160, v237
	s_add_u32 s82, s48, 0x80000
	s_addc_u32 s83, s49, 0
	s_nop 0
	s_nop 0
	s_nop 0
	v_xad_u32 v190, v160, 64, 0
	ds_read_b128 v[160:163], v191 offset:16384
	ds_read_b128 v[164:167], v191 offset:18432
	ds_read_b128 v[168:171], v190 offset:16384
	ds_read_b128 v[172:175], v190 offset:18432
	ds_read_b128 v[176:179], v191 offset:20480
	ds_read_b128 v[180:183], v191 offset:22528
	ds_read_b128 v[192:195], v190 offset:20480
	ds_read_b128 v[196:199], v190 offset:22528
	s_mov_b32 m0, s80
	s_nop 0
	global_load_lds_dwordx4 v233, s[48:49]
	s_mov_b32 m0, s81
	s_nop 0
	global_load_lds_dwordx4 v235, s[48:49]
	s_mov_b32 m0, s29
	s_nop 0
	global_load_lds_dwordx4 v233, s[82:83]
	s_mov_b32 m0, s88
	s_nop 0
	global_load_lds_dwordx4 v235, s[82:83]
	s_mov_b32 m0, s76
	s_nop 0
	global_load_lds_dwordx4 v184, s[64:65]
	s_mov_b32 m0, s89
	s_nop 0
	global_load_lds_dwordx4 v234, s[64:65]
	s_waitcnt vmcnt(8)
	s_waitcnt lgkmcnt(0)
	s_setprio 1
	s_barrier
	v_mfma_f32_16x16x32_bf16 v[116:119], v[88:91], v[160:163], v[116:119]
	v_mfma_f32_16x16x32_bf16 v[104:107], v[92:95], v[160:163], v[104:107]
	v_mfma_f32_16x16x32_bf16 v[84:87], v[88:91], v[164:167], v[84:87]
	v_mfma_f32_16x16x32_bf16 v[80:83], v[92:95], v[164:167], v[80:83]
	v_mfma_f32_16x16x32_bf16 v[76:79], v[88:91], v[176:179], v[76:79]
	v_mfma_f32_16x16x32_bf16 v[72:75], v[92:95], v[176:179], v[72:75]
	v_mfma_f32_16x16x32_bf16 v[68:71], v[88:91], v[180:183], v[68:71]
	v_mfma_f32_16x16x32_bf16 v[64:67], v[92:95], v[180:183], v[64:67]
	v_mfma_f32_16x16x32_bf16 v[116:119], v[96:99], v[168:171], v[116:119]
	v_mfma_f32_16x16x32_bf16 v[104:107], v[100:103], v[168:171], v[104:107]
	v_mfma_f32_16x16x32_bf16 v[84:87], v[96:99], v[172:175], v[84:87]
	v_mfma_f32_16x16x32_bf16 v[80:83], v[100:103], v[172:175], v[80:83]
	v_mfma_f32_16x16x32_bf16 v[76:79], v[96:99], v[192:195], v[76:79]
	v_mfma_f32_16x16x32_bf16 v[72:75], v[100:103], v[192:195], v[72:75]
	v_mfma_f32_16x16x32_bf16 v[68:71], v[96:99], v[196:199], v[68:71]
	v_mfma_f32_16x16x32_bf16 v[64:67], v[100:103], v[196:199], v[64:67]
	s_setprio 0
	s_setprio 1
	v_mfma_f32_16x16x32_bf16 v[28:31], v[108:111], v[160:163], v[28:31]
	v_mfma_f32_16x16x32_bf16 v[24:27], v[112:115], v[160:163], v[24:27]
	v_mfma_f32_16x16x32_bf16 v[20:23], v[108:111], v[164:167], v[20:23]
	v_mfma_f32_16x16x32_bf16 v[16:19], v[112:115], v[164:167], v[16:19]
	v_mfma_f32_16x16x32_bf16 v[12:15], v[108:111], v[176:179], v[12:15]
	v_mfma_f32_16x16x32_bf16 v[8:11], v[112:115], v[176:179], v[8:11]
	v_mfma_f32_16x16x32_bf16 v[4:7], v[108:111], v[180:183], v[4:7]
	v_mfma_f32_16x16x32_bf16 v[0:3], v[112:115], v[180:183], v[0:3]
	v_mfma_f32_16x16x32_bf16 v[28:31], v[120:123], v[168:171], v[28:31]
	v_mfma_f32_16x16x32_bf16 v[24:27], v[124:127], v[168:171], v[24:27]
	v_mfma_f32_16x16x32_bf16 v[20:23], v[120:123], v[172:175], v[20:23]
	v_mfma_f32_16x16x32_bf16 v[16:19], v[124:127], v[172:175], v[16:19]
	v_mfma_f32_16x16x32_bf16 v[12:15], v[120:123], v[192:195], v[12:15]
	v_mfma_f32_16x16x32_bf16 v[8:11], v[124:127], v[192:195], v[8:11]
	v_mfma_f32_16x16x32_bf16 v[4:7], v[120:123], v[196:199], v[4:7]
	v_mfma_f32_16x16x32_bf16 v[0:3], v[124:127], v[196:199], v[0:3]
	s_setprio 0
	s_barrier
; #define PG8_STAGE(bufoff, gbase, voff) do { _Pragma("unroll") for (int _i = 0; _i < 2; ++_i) \
;         dma16((const char*)(gbase), (voff)[_i], ldsb + (bufoff) + ldsw + _i * 8192); } while (0)
; #define PG8_LDA(dst, b, h) do { const int a1_ = opqv(aoff0) ^ 64; _Pragma("unroll") for (int m = 0; m < 4; ++m) { dst[m][0] = *(const LAS bf16x8*)(lds + PG8_SA(b, h) + aoff0 + m * 2048); dst[m][1] = *(const LAS bf16x8*)(lds + PG8_SA(b, h) + a1_ + m * 2048); } } while (0)
; #define PG8_LDB(dst, b, h) do { const int b1_ = opqv(boff0) ^ 64; _Pragma("unroll") for (int n = 0; n < 2; ++n) { dst[n][0] = *(const LAS bf16x8*)(lds + PG8_SB(b, h) + boff0 + n * 2048); dst[n][1] = *(const LAS bf16x8*)(lds + PG8_SB(b, h) + b1_ + n * 2048); } } while (0)
; #define PG8_MMA(ai, bj, At, Bt) do { __builtin_amdgcn_s_setprio(1); _Pragma("unroll") for (int m = 0; m < 4; ++m) _Pragma("unroll") for (int n = 0; n < 2; ++n) _Pragma("unroll") for (int k = 0; k < 2; ++k) \
;         acc[ai][bj][m][n] = __builtin_amdgcn_mfma_f32_16x16x32_bf16(Bt[n][k], At[m][k], acc[ai][bj][m][n], 0, 0, 0); __builtin_amdgcn_s_setprio(0); } while (0)
; #define PG8_WAIT_V(n) asm volatile("s_waitcnt vmcnt(" #n ")" ::: "memory")
; #define PG8_WAIT_L(n) asm volatile("s_waitcnt lgkmcnt(" #n ")" ::: "memory")
; #define PG8_BAR __builtin_amdgcn_s_barrier()
; #define PG8_SCHED __builtin_amdgcn_sched_barrier(0)
; template <class Epi>
; __device__ __forceinline__ void gemm_phase(LAS unsigned char* lds, const Gemm g, const StaticOrder& S, const Epi& E, int wave_) {
;     ...
;             PG8_STAGE(PG8_SA(0, 1), a2 + hstepA, voffA); PG8_LDB(B0, 1, 0); PG8_LDB(B1, 1, 1); PG8_SCHED; PG8_LDA(At, 1, 0);
;             PG8_WAIT_V(8); PG8_WAIT_L(0); PG8_BAR; PG8_MMA(0, 0, At, B0); PG8_MMA(0, 1, At, B1); PG8_BAR; PG8_SCHED;
;             PG8_STAGE(PG8_SB(1, 0), b3, voffB); PG8_STAGE(PG8_SB(1, 1), b3 + hstepB, voffB); PG8_STAGE(PG8_SA(1, 0), a3, voffA); PG8_LDA(At, 1, 1);
;             PG8_WAIT_V(8); PG8_WAIT_L(0); PG8_BAR; PG8_MMA(1, 0, At, B0); PG8_MMA(1, 1, At, B1); PG8_BAR; PG8_SCHED;
;         }
	s_add_u32 s64, s64, 0x80000
	s_addc_u32 s65, s65, 0
	s_mov_b32 m0, s1
	s_nop 0
	global_load_lds_dwordx4 v184, s[64:65]
	v_mov_b32_e32 v88, v238
	s_mov_b32 m0, s69
	s_nop 0
	global_load_lds_dwordx4 v234, s[64:65]
	v_add_u32_e32 v92, s34, v238
	v_xad_u32 v100, v88, 64, s34
	v_mov_b32_e32 v108, v238
	s_add_i32 s64, 0, 0x1c000
	ds_read_b128 v[88:91], v92
	ds_read_b128 v[92:95], v92 offset:2048
	ds_read_b128 v[96:99], v100
	ds_read_b128 v[100:103], v100 offset:2048
	v_add_u32_e32 v112, s64, v238
	v_xad_u32 v124, v108, 64, s64
	ds_read_b128 v[108:111], v112
	ds_read_b128 v[112:115], v112 offset:2048
	ds_read_b128 v[120:123], v124
	ds_read_b128 v[124:127], v124 offset:2048
	v_mov_b32_e32 v160, v237
	s_nop 0
	v_xad_u32 v190, v160, 64, 0
	ds_read_b128 v[160:163], v191 offset:32768
	ds_read_b128 v[164:167], v191 offset:34816
	ds_read_b128 v[168:171], v190 offset:32768
	ds_read_b128 v[172:175], v190 offset:34816
	ds_read_b128 v[176:179], v191 offset:36864
	ds_read_b128 v[180:183], v191 offset:38912
	ds_read_b128 v[192:195], v190 offset:36864
	ds_read_b128 v[196:199], v190 offset:38912
	s_waitcnt vmcnt(8)
	s_waitcnt lgkmcnt(0)
	s_setprio 1
	s_barrier
	v_mfma_f32_16x16x32_bf16 v[156:159], v[88:91], v[160:163], v[156:159]
	v_mfma_f32_16x16x32_bf16 v[152:155], v[92:95], v[160:163], v[152:155]
	v_mfma_f32_16x16x32_bf16 v[148:151], v[88:91], v[164:167], v[148:151]
	v_mfma_f32_16x16x32_bf16 v[144:147], v[92:95], v[164:167], v[144:147]
	v_mfma_f32_16x16x32_bf16 v[140:143], v[88:91], v[176:179], v[140:143]
	v_mfma_f32_16x16x32_bf16 v[136:139], v[92:95], v[176:179], v[136:139]
	v_mfma_f32_16x16x32_bf16 v[132:135], v[88:91], v[180:183], v[132:135]
	v_mfma_f32_16x16x32_bf16 v[128:131], v[92:95], v[180:183], v[128:131]
	v_mfma_f32_16x16x32_bf16 v[156:159], v[96:99], v[168:171], v[156:159]
	v_mfma_f32_16x16x32_bf16 v[152:155], v[100:103], v[168:171], v[152:155]
	v_mfma_f32_16x16x32_bf16 v[148:151], v[96:99], v[172:175], v[148:151]
	v_mfma_f32_16x16x32_bf16 v[144:147], v[100:103], v[172:175], v[144:147]
	v_mfma_f32_16x16x32_bf16 v[140:143], v[96:99], v[192:195], v[140:143]
	v_mfma_f32_16x16x32_bf16 v[136:139], v[100:103], v[192:195], v[136:139]
	v_mfma_f32_16x16x32_bf16 v[132:135], v[96:99], v[196:199], v[132:135]
	v_mfma_f32_16x16x32_bf16 v[128:131], v[100:103], v[196:199], v[128:131]
	s_setprio 0
	s_setprio 1
	v_mfma_f32_16x16x32_bf16 v[60:63], v[108:111], v[160:163], v[60:63]
	s_add_u32 s64, s48, 0x80
	s_addc_u32 s65, s49, 0
	v_mfma_f32_16x16x32_bf16 v[56:59], v[112:115], v[160:163], v[56:59]
	v_mfma_f32_16x16x32_bf16 v[52:55], v[108:111], v[164:167], v[52:55]
	v_mfma_f32_16x16x32_bf16 v[48:51], v[112:115], v[164:167], v[48:51]
	v_mfma_f32_16x16x32_bf16 v[44:47], v[108:111], v[176:179], v[44:47]
	v_mfma_f32_16x16x32_bf16 v[40:43], v[112:115], v[176:179], v[40:43]
	v_mfma_f32_16x16x32_bf16 v[36:39], v[108:111], v[180:183], v[36:39]
	v_mfma_f32_16x16x32_bf16 v[32:35], v[112:115], v[180:183], v[32:35]
	v_mfma_f32_16x16x32_bf16 v[60:63], v[120:123], v[168:171], v[60:63]
	v_mfma_f32_16x16x32_bf16 v[56:59], v[124:127], v[168:171], v[56:59]
	v_mfma_f32_16x16x32_bf16 v[52:55], v[120:123], v[172:175], v[52:55]
	v_mfma_f32_16x16x32_bf16 v[48:51], v[124:127], v[172:175], v[48:51]
	v_mfma_f32_16x16x32_bf16 v[44:47], v[120:123], v[192:195], v[44:47]
	v_mfma_f32_16x16x32_bf16 v[40:43], v[124:127], v[192:195], v[40:43]
	v_mfma_f32_16x16x32_bf16 v[36:39], v[120:123], v[196:199], v[36:39]
	v_mfma_f32_16x16x32_bf16 v[32:35], v[124:127], v[196:199], v[32:35]
	s_setprio 0
	s_barrier
	s_add_u32 s48, s48, 0x80080
	s_addc_u32 s49, s49, 0
	v_mov_b32_e32 v160, v237
	s_nop 0
	s_nop 0
	v_xad_u32 v190, v160, 64, 0
	ds_read_b128 v[160:163], v191 offset:49152
	ds_read_b128 v[164:167], v191 offset:51200
	ds_read_b128 v[168:171], v190 offset:49152
	ds_read_b128 v[172:175], v190 offset:51200
	ds_read_b128 v[176:179], v191 offset:53248
	ds_read_b128 v[180:183], v191 offset:55296
	ds_read_b128 v[192:195], v190 offset:53248
	ds_read_b128 v[196:199], v190 offset:55296
	s_mov_b32 m0, s35
	s_nop 0
	global_load_lds_dwordx4 v233, s[64:65]
	s_mov_b32 m0, s33
	s_nop 0
	global_load_lds_dwordx4 v235, s[64:65]
	s_mov_b32 m0, s77
	s_nop 0
	global_load_lds_dwordx4 v233, s[48:49]
	s_mov_b32 m0, s3
	s_nop 0
	global_load_lds_dwordx4 v235, s[48:49]
	s_mov_b32 m0, s22
	s_nop 0
	global_load_lds_dwordx4 v184, s[46:47]
	s_mov_b32 m0, s2
	s_nop 0
	global_load_lds_dwordx4 v234, s[46:47]
	s_waitcnt vmcnt(8)
	s_waitcnt lgkmcnt(0)
	s_setprio 1
	s_barrier
	v_mfma_f32_16x16x32_bf16 v[116:119], v[88:91], v[160:163], v[116:119]
	v_mfma_f32_16x16x32_bf16 v[104:107], v[92:95], v[160:163], v[104:107]
	v_mfma_f32_16x16x32_bf16 v[84:87], v[88:91], v[164:167], v[84:87]
	v_mfma_f32_16x16x32_bf16 v[80:83], v[92:95], v[164:167], v[80:83]
	v_mfma_f32_16x16x32_bf16 v[76:79], v[88:91], v[176:179], v[76:79]
	v_mfma_f32_16x16x32_bf16 v[72:75], v[92:95], v[176:179], v[72:75]
	v_mfma_f32_16x16x32_bf16 v[68:71], v[88:91], v[180:183], v[68:71]
	v_mfma_f32_16x16x32_bf16 v[64:67], v[92:95], v[180:183], v[64:67]
	v_mfma_f32_16x16x32_bf16 v[116:119], v[96:99], v[168:171], v[116:119]
	v_mfma_f32_16x16x32_bf16 v[104:107], v[100:103], v[168:171], v[104:107]
	v_mfma_f32_16x16x32_bf16 v[84:87], v[96:99], v[172:175], v[84:87]
	v_mfma_f32_16x16x32_bf16 v[80:83], v[100:103], v[172:175], v[80:83]
	v_mfma_f32_16x16x32_bf16 v[76:79], v[96:99], v[192:195], v[76:79]
	v_mfma_f32_16x16x32_bf16 v[72:75], v[100:103], v[192:195], v[72:75]
	v_mfma_f32_16x16x32_bf16 v[68:71], v[96:99], v[196:199], v[68:71]
	v_mfma_f32_16x16x32_bf16 v[64:67], v[100:103], v[196:199], v[64:67]
	s_setprio 0
	s_setprio 1
	v_mfma_f32_16x16x32_bf16 v[28:31], v[108:111], v[160:163], v[28:31]
	v_mfma_f32_16x16x32_bf16 v[24:27], v[112:115], v[160:163], v[24:27]
	v_mfma_f32_16x16x32_bf16 v[20:23], v[108:111], v[164:167], v[20:23]
	v_mfma_f32_16x16x32_bf16 v[16:19], v[112:115], v[164:167], v[16:19]
	v_mfma_f32_16x16x32_bf16 v[12:15], v[108:111], v[176:179], v[12:15]
	v_mfma_f32_16x16x32_bf16 v[8:11], v[112:115], v[176:179], v[8:11]
	v_mfma_f32_16x16x32_bf16 v[4:7], v[108:111], v[180:183], v[4:7]
	v_mfma_f32_16x16x32_bf16 v[0:3], v[112:115], v[180:183], v[0:3]
	v_mfma_f32_16x16x32_bf16 v[28:31], v[120:123], v[168:171], v[28:31]
	v_mfma_f32_16x16x32_bf16 v[24:27], v[124:127], v[168:171], v[24:27]
	v_mfma_f32_16x16x32_bf16 v[20:23], v[120:123], v[172:175], v[20:23]
	v_mfma_f32_16x16x32_bf16 v[16:19], v[124:127], v[172:175], v[16:19]
	v_mfma_f32_16x16x32_bf16 v[12:15], v[120:123], v[192:195], v[12:15]
	v_mfma_f32_16x16x32_bf16 v[8:11], v[124:127], v[192:195], v[8:11]
	v_mfma_f32_16x16x32_bf16 v[4:7], v[120:123], v[196:199], v[4:7]
	v_mfma_f32_16x16x32_bf16 v[0:3], v[124:127], v[196:199], v[0:3]
	s_setprio 0
	s_barrier
	s_add_i32 s79, s79, 2
	s_add_u32 s75, s75, 0x100
	s_addc_u32 s78, s78, 0
	s_add_u32 s12, s12, 0x100
	s_addc_u32 s13, s13, 0
	s_cmp_gt_u32 s79, 29
	s_cbranch_scc0 .LBB0_1776
